# G tile layout changed to 1 KB contiguous per store/load instruction (C1 stores, C2 gate loads); single-path C1 with interleaved epilogue
# speedup vs baseline: 1.1861x; 1.0209x over previous
.Lc1_start:
	v_mov_b32_e32 v238, 0x200f0
	ds_read_b64 v[236:237], v238
	s_waitcnt lgkmcnt(0)
	v_readfirstlane_b32 s20, v236
	v_readfirstlane_b32 s21, v237
	s_barrier
	v_and_b32_e32 v236, 63, v0
	v_lshrrev_b32_e32 v237, 6, v0
	v_lshrrev_b32_e32 v238, 3, v236
	v_lshrrev_b32_e32 v239, 4, v236
	s_nop 0
	v_readfirstlane_b32 s0, v237
	v_add_u32_e32 v200, 0, v239
	v_xor_b32_e32 v200, v200, v236
	v_and_b32_e32 v200, 7, v200
	v_lshlrev_b32_e32 v200, 4, v200
	v_lshl_add_u32 v130, v237, 5, v238
	v_add_u32_e32 v130, 0, v130
	v_mul_u32_u24_e32 v130, 0x800, v130
	v_add_u32_e32 v200, v200, v130
	v_add_u32_e32 v201, 4, v239
	v_xor_b32_e32 v201, v201, v236
	v_and_b32_e32 v201, 7, v201
	v_lshlrev_b32_e32 v201, 4, v201
	v_lshl_add_u32 v130, v237, 5, v238
	v_add_u32_e32 v130, 8, v130
	v_mul_u32_u24_e32 v130, 0x800, v130
	v_add_u32_e32 v201, v201, v130
	v_add_u32_e32 v202, 8, v239
	v_xor_b32_e32 v202, v202, v236
	v_and_b32_e32 v202, 7, v202
	v_lshlrev_b32_e32 v202, 4, v202
	v_lshl_add_u32 v130, v237, 5, v238
	v_add_u32_e32 v130, 16, v130
	v_mul_u32_u24_e32 v130, 0x800, v130
	v_add_u32_e32 v202, v202, v130
	v_add_u32_e32 v203, 12, v239
	v_xor_b32_e32 v203, v203, v236
	v_and_b32_e32 v203, 7, v203
	v_lshlrev_b32_e32 v203, 4, v203
	v_lshl_add_u32 v130, v237, 5, v238
	v_add_u32_e32 v130, 24, v130
	v_mul_u32_u24_e32 v130, 0x800, v130
	v_add_u32_e32 v203, v203, v130
	v_add_u32_e32 v204, 0, v239
	v_xor_b32_e32 v204, v204, v236
	v_and_b32_e32 v204, 7, v204
	v_lshlrev_b32_e32 v204, 4, v204
	v_lshl_add_u32 v130, v237, 4, v238
	v_add_u32_e32 v130, 0, v130
	v_mul_u32_u24_e32 v130, 0x800, v130
	v_add_u32_e32 v204, v204, v130
	v_add_u32_e32 v205, 4, v239
	v_xor_b32_e32 v205, v205, v236
	v_and_b32_e32 v205, 7, v205
	v_lshlrev_b32_e32 v205, 4, v205
	v_lshl_add_u32 v130, v237, 4, v238
	v_add_u32_e32 v130, 8, v130
	v_mul_u32_u24_e32 v130, 0x800, v130
	v_add_u32_e32 v205, v205, v130
	v_and_b32_e32 v238, 15, v236
	v_lshrrev_b32_e32 v130, 1, v238
	v_xor_b32_e32 v130, v130, v239
	v_lshlrev_b32_e32 v130, 4, v130
	v_lshrrev_b32_e32 v236, 1, v237
	v_lshl_add_u32 v236, v236, 6, v238
	v_lshl_add_u32 v236, v236, 7, v130
	v_and_b32_e32 v237, 1, v237
	v_lshl_add_u32 v237, v237, 6, v238
	v_lshl_add_u32 v237, v237, 7, v130
	v_add_u32_e32 v218, 0x100, v236
	v_xor_b32_e32 v225, 64, v218
	v_add_u32_e32 v230, 0x8100, v237
	v_xor_b32_e32 v233, 64, v230
	v_add_u32_e32 v219, 0xc100, v236
	v_xor_b32_e32 v228, 64, v219
	v_add_u32_e32 v231, 0x14100, v237
	v_xor_b32_e32 v234, 64, v231
	v_add_u32_e32 v224, 0x18100, v236
	v_xor_b32_e32 v229, 64, v224
	v_add_u32_e32 v232, 0x20100, v237
	v_xor_b32_e32 v235, 64, v232
	s_lshl_b32 s1, s0, 12
	s_add_u32 s8, s1, 0x100
	s_lshl_b32 s1, s0, 11
	s_add_u32 s9, s1, 0x8100
	v_and_b32_e32 v236, 63, v0
	v_lshrrev_b32_e32 v237, 6, v0
	v_and_b32_e32 v238, 15, v236
	v_lshrrev_b32_e32 v239, 4, v236
	v_lshlrev_b32_e32 v240, 13, v237
	v_lshl_add_u32 v240, v236, 4, v240
	v_add_u32_e32 v241, 0x1000, v240
	s_and_b32 s1, s2, 7
	s_lshr_b32 s22, s2, 3
	s_and_b32 s23, s22, 3
	s_lshl_b32 s1, s1, 2
	s_add_u32 s1, s1, s23
	s_lshr_b32 s22, s22, 2
	s_lshl_b32 s23, s1, 19
	s_add_u32 s4, s26, s23
	s_addc_u32 s5, s27, 0
	v_readlane_b32 s6, v254, 57
	v_readlane_b32 s7, v254, 58
	s_lshl_b32 s23, s22, 20
	s_add_u32 s23, s23, 0x640000
	s_nop 0
	s_add_u32 s6, s6, s23
	s_addc_u32 s7, s7, 0
	s_lshr_b32 s23, s22, 1
	s_lshl_b32 s23, s23, 5
	s_add_u32 s23, s23, s1
	s_lshl_b32 s23, s23, 3
	s_and_b32 s24, s22, 1
	s_lshl_b32 s24, s24, 2
	s_add_u32 s23, s23, s24
	s_lshl_b32 s13, s23, 16
	s_mov_b32 s12, 0xbfb8aa3b
	s_mov_b32 m0, s8
	s_nop 0
	global_load_lds_dwordx4 v200, s[4:5]
	s_add_u32 m0, s8, 0x400
	s_nop 0
	global_load_lds_dwordx4 v201, s[4:5]
	s_add_u32 m0, s8, 0x800
	s_nop 0
	global_load_lds_dwordx4 v202, s[4:5]
	s_add_u32 m0, s8, 0xc00
	s_nop 0
	global_load_lds_dwordx4 v203, s[4:5]
	s_mov_b32 m0, s9
	s_nop 0
	global_load_lds_dwordx4 v204, s[6:7]
	s_add_u32 m0, s9, 0x400
	s_nop 0
	global_load_lds_dwordx4 v205, s[6:7]
	s_add_u32 s4, s4, 0x80
	s_addc_u32 s5, s5, 0
	s_add_u32 s6, s6, 0x80
	s_addc_u32 s7, s7, 0
	s_add_u32 m0, s8, 0xc000
	s_nop 0
	global_load_lds_dwordx4 v200, s[4:5]
	s_add_u32 m0, s8, 0xc400
	s_nop 0
	global_load_lds_dwordx4 v201, s[4:5]
	s_add_u32 m0, s8, 0xc800
	s_nop 0
	global_load_lds_dwordx4 v202, s[4:5]
	s_add_u32 m0, s8, 0xcc00
	s_nop 0
	global_load_lds_dwordx4 v203, s[4:5]
	s_add_u32 m0, s9, 0xc000
	s_nop 0
	global_load_lds_dwordx4 v204, s[6:7]
	s_add_u32 m0, s9, 0xc400
	s_nop 0
	global_load_lds_dwordx4 v205, s[6:7]
	s_add_u32 s4, s4, 0x80
	s_addc_u32 s5, s5, 0
	s_add_u32 s6, s6, 0x80
	s_addc_u32 s7, s7, 0
	s_add_u32 m0, s8, 0x18000
	s_nop 0
	global_load_lds_dwordx4 v200, s[4:5]
	s_add_u32 m0, s8, 0x18400
	s_nop 0
	global_load_lds_dwordx4 v201, s[4:5]
	s_add_u32 m0, s8, 0x18800
	s_nop 0
	global_load_lds_dwordx4 v202, s[4:5]
	s_add_u32 m0, s8, 0x18c00
	s_nop 0
	global_load_lds_dwordx4 v203, s[4:5]
	s_add_u32 m0, s9, 0x18000
	s_nop 0
	global_load_lds_dwordx4 v204, s[6:7]
	s_add_u32 m0, s9, 0x18400
	s_nop 0
	global_load_lds_dwordx4 v205, s[6:7]
	s_add_u32 s4, s4, 0x80
	s_addc_u32 s5, s5, 0
	s_add_u32 s6, s6, 0x80
	s_addc_u32 s7, s7, 0
	s_waitcnt vmcnt(12)
	s_barrier
	ds_read_b128 v[136:139], v218 offset:0
	ds_read_b128 v[140:143], v218 offset:2048
	ds_read_b128 v[144:147], v218 offset:4096
	ds_read_b128 v[148:151], v218 offset:6144
	ds_read_b128 v[152:155], v230 offset:0
	ds_read_b128 v[156:159], v230 offset:2048
	ds_read_b128 v[160:163], v230 offset:4096
	ds_read_b128 v[164:167], v230 offset:6144
	s_waitcnt lgkmcnt(0)
	v_mfma_f32_16x16x32_bf16 v[2:5], v[152:155], v[136:139], 0
	ds_read_b128 v[168:171], v225 offset:0
	v_mfma_f32_16x16x32_bf16 v[6:9], v[156:159], v[136:139], 0
	ds_read_b128 v[172:175], v225 offset:2048
	v_mfma_f32_16x16x32_bf16 v[10:13], v[160:163], v[136:139], 0
	ds_read_b128 v[176:179], v225 offset:4096
	v_mfma_f32_16x16x32_bf16 v[14:17], v[164:167], v[136:139], 0
	ds_read_b128 v[180:183], v225 offset:6144
	v_mfma_f32_16x16x32_bf16 v[18:21], v[152:155], v[140:143], 0
	ds_read_b128 v[184:187], v233 offset:0
	v_mfma_f32_16x16x32_bf16 v[22:25], v[156:159], v[140:143], 0
	ds_read_b128 v[188:191], v233 offset:2048
	v_mfma_f32_16x16x32_bf16 v[26:29], v[160:163], v[140:143], 0
	ds_read_b128 v[192:195], v233 offset:4096
	v_mfma_f32_16x16x32_bf16 v[30:33], v[164:167], v[140:143], 0
	ds_read_b128 v[196:199], v233 offset:6144
	v_mfma_f32_16x16x32_bf16 v[34:37], v[152:155], v[144:147], 0
	v_mfma_f32_16x16x32_bf16 v[38:41], v[156:159], v[144:147], 0
	v_mfma_f32_16x16x32_bf16 v[42:45], v[160:163], v[144:147], 0
	v_mfma_f32_16x16x32_bf16 v[46:49], v[164:167], v[144:147], 0
	v_mfma_f32_16x16x32_bf16 v[50:53], v[152:155], v[148:151], 0
	v_mfma_f32_16x16x32_bf16 v[54:57], v[156:159], v[148:151], 0
	v_mfma_f32_16x16x32_bf16 v[58:61], v[160:163], v[148:151], 0
	v_mfma_f32_16x16x32_bf16 v[62:65], v[164:167], v[148:151], 0
	s_waitcnt vmcnt(6) lgkmcnt(0)
	s_barrier
	v_mfma_f32_16x16x32_bf16 v[2:5], v[184:187], v[168:171], v[2:5]
	ds_read_b128 v[136:139], v219 offset:0
	v_mfma_f32_16x16x32_bf16 v[6:9], v[188:191], v[168:171], v[6:9]
	ds_read_b128 v[140:143], v219 offset:2048
	v_mfma_f32_16x16x32_bf16 v[10:13], v[192:195], v[168:171], v[10:13]
	ds_read_b128 v[144:147], v219 offset:4096
	v_mfma_f32_16x16x32_bf16 v[14:17], v[196:199], v[168:171], v[14:17]
	ds_read_b128 v[148:151], v219 offset:6144
	v_mfma_f32_16x16x32_bf16 v[18:21], v[184:187], v[172:175], v[18:21]
	ds_read_b128 v[152:155], v231 offset:0
	v_mfma_f32_16x16x32_bf16 v[22:25], v[188:191], v[172:175], v[22:25]
	ds_read_b128 v[156:159], v231 offset:2048
	v_mfma_f32_16x16x32_bf16 v[26:29], v[192:195], v[172:175], v[26:29]
	ds_read_b128 v[160:163], v231 offset:4096
	v_mfma_f32_16x16x32_bf16 v[30:33], v[196:199], v[172:175], v[30:33]
	ds_read_b128 v[164:167], v231 offset:6144
	s_mov_b32 m0, s8
	v_mfma_f32_16x16x32_bf16 v[34:37], v[184:187], v[176:179], v[34:37]
	global_load_lds_dwordx4 v200, s[4:5]
	s_add_u32 m0, s8, 0x400
	v_mfma_f32_16x16x32_bf16 v[38:41], v[188:191], v[176:179], v[38:41]
	global_load_lds_dwordx4 v201, s[4:5]
	s_add_u32 m0, s8, 0x800
	v_mfma_f32_16x16x32_bf16 v[42:45], v[192:195], v[176:179], v[42:45]
	global_load_lds_dwordx4 v202, s[4:5]
	s_add_u32 m0, s8, 0xc00
	v_mfma_f32_16x16x32_bf16 v[46:49], v[196:199], v[176:179], v[46:49]
	global_load_lds_dwordx4 v203, s[4:5]
	s_mov_b32 m0, s9
	v_mfma_f32_16x16x32_bf16 v[50:53], v[184:187], v[180:183], v[50:53]
	global_load_lds_dwordx4 v204, s[6:7]
	s_add_u32 m0, s9, 0x400
	v_mfma_f32_16x16x32_bf16 v[54:57], v[188:191], v[180:183], v[54:57]
	global_load_lds_dwordx4 v205, s[6:7]
	v_mfma_f32_16x16x32_bf16 v[58:61], v[192:195], v[180:183], v[58:61]
	s_add_u32 s4, s4, 0x80
	s_addc_u32 s5, s5, 0
	v_mfma_f32_16x16x32_bf16 v[62:65], v[196:199], v[180:183], v[62:65]
	s_add_u32 s6, s6, 0x80
	s_addc_u32 s7, s7, 0
	s_waitcnt lgkmcnt(0)
	v_mfma_f32_16x16x32_bf16 v[2:5], v[152:155], v[136:139], v[2:5]
	ds_read_b128 v[168:171], v228 offset:0
	v_mfma_f32_16x16x32_bf16 v[6:9], v[156:159], v[136:139], v[6:9]
	ds_read_b128 v[172:175], v228 offset:2048
	v_mfma_f32_16x16x32_bf16 v[10:13], v[160:163], v[136:139], v[10:13]
	ds_read_b128 v[176:179], v228 offset:4096
	v_mfma_f32_16x16x32_bf16 v[14:17], v[164:167], v[136:139], v[14:17]
	ds_read_b128 v[180:183], v228 offset:6144
	v_mfma_f32_16x16x32_bf16 v[18:21], v[152:155], v[140:143], v[18:21]
	ds_read_b128 v[184:187], v234 offset:0
	v_mfma_f32_16x16x32_bf16 v[22:25], v[156:159], v[140:143], v[22:25]
	ds_read_b128 v[188:191], v234 offset:2048
	v_mfma_f32_16x16x32_bf16 v[26:29], v[160:163], v[140:143], v[26:29]
	ds_read_b128 v[192:195], v234 offset:4096
	v_mfma_f32_16x16x32_bf16 v[30:33], v[164:167], v[140:143], v[30:33]
	ds_read_b128 v[196:199], v234 offset:6144
	v_mfma_f32_16x16x32_bf16 v[34:37], v[152:155], v[144:147], v[34:37]
	v_mfma_f32_16x16x32_bf16 v[38:41], v[156:159], v[144:147], v[38:41]
	v_mfma_f32_16x16x32_bf16 v[42:45], v[160:163], v[144:147], v[42:45]
	v_mfma_f32_16x16x32_bf16 v[46:49], v[164:167], v[144:147], v[46:49]
	v_mfma_f32_16x16x32_bf16 v[50:53], v[152:155], v[148:151], v[50:53]
	v_mfma_f32_16x16x32_bf16 v[54:57], v[156:159], v[148:151], v[54:57]
	v_mfma_f32_16x16x32_bf16 v[58:61], v[160:163], v[148:151], v[58:61]
	v_mfma_f32_16x16x32_bf16 v[62:65], v[164:167], v[148:151], v[62:65]
	s_waitcnt vmcnt(6) lgkmcnt(0)
	s_barrier
	v_mfma_f32_16x16x32_bf16 v[2:5], v[184:187], v[168:171], v[2:5]
	ds_read_b128 v[136:139], v224 offset:0
	v_mfma_f32_16x16x32_bf16 v[6:9], v[188:191], v[168:171], v[6:9]
	ds_read_b128 v[140:143], v224 offset:2048
	v_mfma_f32_16x16x32_bf16 v[10:13], v[192:195], v[168:171], v[10:13]
	ds_read_b128 v[144:147], v224 offset:4096
	v_mfma_f32_16x16x32_bf16 v[14:17], v[196:199], v[168:171], v[14:17]
	ds_read_b128 v[148:151], v224 offset:6144
	v_mfma_f32_16x16x32_bf16 v[18:21], v[184:187], v[172:175], v[18:21]
	ds_read_b128 v[152:155], v232 offset:0
	v_mfma_f32_16x16x32_bf16 v[22:25], v[188:191], v[172:175], v[22:25]
	ds_read_b128 v[156:159], v232 offset:2048
	v_mfma_f32_16x16x32_bf16 v[26:29], v[192:195], v[172:175], v[26:29]
	ds_read_b128 v[160:163], v232 offset:4096
	v_mfma_f32_16x16x32_bf16 v[30:33], v[196:199], v[172:175], v[30:33]
	ds_read_b128 v[164:167], v232 offset:6144
	s_add_u32 m0, s8, 0xc000
	v_mfma_f32_16x16x32_bf16 v[34:37], v[184:187], v[176:179], v[34:37]
	global_load_lds_dwordx4 v200, s[4:5]
	s_add_u32 m0, s8, 0xc400
	v_mfma_f32_16x16x32_bf16 v[38:41], v[188:191], v[176:179], v[38:41]
	global_load_lds_dwordx4 v201, s[4:5]
	s_add_u32 m0, s8, 0xc800
	v_mfma_f32_16x16x32_bf16 v[42:45], v[192:195], v[176:179], v[42:45]
	global_load_lds_dwordx4 v202, s[4:5]
	s_add_u32 m0, s8, 0xcc00
	v_mfma_f32_16x16x32_bf16 v[46:49], v[196:199], v[176:179], v[46:49]
	global_load_lds_dwordx4 v203, s[4:5]
	s_add_u32 m0, s9, 0xc000
	v_mfma_f32_16x16x32_bf16 v[50:53], v[184:187], v[180:183], v[50:53]
	global_load_lds_dwordx4 v204, s[6:7]
	s_add_u32 m0, s9, 0xc400
	v_mfma_f32_16x16x32_bf16 v[54:57], v[188:191], v[180:183], v[54:57]
	global_load_lds_dwordx4 v205, s[6:7]
	v_mfma_f32_16x16x32_bf16 v[58:61], v[192:195], v[180:183], v[58:61]
	s_add_u32 s4, s4, 0x80
	s_addc_u32 s5, s5, 0
	v_mfma_f32_16x16x32_bf16 v[62:65], v[196:199], v[180:183], v[62:65]
	s_add_u32 s6, s6, 0x80
	s_addc_u32 s7, s7, 0
	s_waitcnt lgkmcnt(0)
	v_mfma_f32_16x16x32_bf16 v[2:5], v[152:155], v[136:139], v[2:5]
	ds_read_b128 v[168:171], v229 offset:0
	v_mfma_f32_16x16x32_bf16 v[6:9], v[156:159], v[136:139], v[6:9]
	ds_read_b128 v[172:175], v229 offset:2048
	v_mfma_f32_16x16x32_bf16 v[10:13], v[160:163], v[136:139], v[10:13]
	ds_read_b128 v[176:179], v229 offset:4096
	v_mfma_f32_16x16x32_bf16 v[14:17], v[164:167], v[136:139], v[14:17]
	ds_read_b128 v[180:183], v229 offset:6144
	v_mfma_f32_16x16x32_bf16 v[18:21], v[152:155], v[140:143], v[18:21]
	ds_read_b128 v[184:187], v235 offset:0
	v_mfma_f32_16x16x32_bf16 v[22:25], v[156:159], v[140:143], v[22:25]
	ds_read_b128 v[188:191], v235 offset:2048
	v_mfma_f32_16x16x32_bf16 v[26:29], v[160:163], v[140:143], v[26:29]
	ds_read_b128 v[192:195], v235 offset:4096
	v_mfma_f32_16x16x32_bf16 v[30:33], v[164:167], v[140:143], v[30:33]
	ds_read_b128 v[196:199], v235 offset:6144
	v_mfma_f32_16x16x32_bf16 v[34:37], v[152:155], v[144:147], v[34:37]
	v_mfma_f32_16x16x32_bf16 v[38:41], v[156:159], v[144:147], v[38:41]
	v_mfma_f32_16x16x32_bf16 v[42:45], v[160:163], v[144:147], v[42:45]
	v_mfma_f32_16x16x32_bf16 v[46:49], v[164:167], v[144:147], v[46:49]
	v_mfma_f32_16x16x32_bf16 v[50:53], v[152:155], v[148:151], v[50:53]
	v_mfma_f32_16x16x32_bf16 v[54:57], v[156:159], v[148:151], v[54:57]
	v_mfma_f32_16x16x32_bf16 v[58:61], v[160:163], v[148:151], v[58:61]
	v_mfma_f32_16x16x32_bf16 v[62:65], v[164:167], v[148:151], v[62:65]
	s_waitcnt vmcnt(6) lgkmcnt(0)
	s_barrier
	v_mfma_f32_16x16x32_bf16 v[2:5], v[184:187], v[168:171], v[2:5]
	ds_read_b128 v[136:139], v218 offset:0
	v_mfma_f32_16x16x32_bf16 v[6:9], v[188:191], v[168:171], v[6:9]
	ds_read_b128 v[140:143], v218 offset:2048
	v_mfma_f32_16x16x32_bf16 v[10:13], v[192:195], v[168:171], v[10:13]
	ds_read_b128 v[144:147], v218 offset:4096
	v_mfma_f32_16x16x32_bf16 v[14:17], v[196:199], v[168:171], v[14:17]
	ds_read_b128 v[148:151], v218 offset:6144
	v_mfma_f32_16x16x32_bf16 v[18:21], v[184:187], v[172:175], v[18:21]
	ds_read_b128 v[152:155], v230 offset:0
	v_mfma_f32_16x16x32_bf16 v[22:25], v[188:191], v[172:175], v[22:25]
	ds_read_b128 v[156:159], v230 offset:2048
	v_mfma_f32_16x16x32_bf16 v[26:29], v[192:195], v[172:175], v[26:29]
	ds_read_b128 v[160:163], v230 offset:4096
	v_mfma_f32_16x16x32_bf16 v[30:33], v[196:199], v[172:175], v[30:33]
	ds_read_b128 v[164:167], v230 offset:6144
	s_add_u32 m0, s8, 0x18000
	v_mfma_f32_16x16x32_bf16 v[34:37], v[184:187], v[176:179], v[34:37]
	global_load_lds_dwordx4 v200, s[4:5]
	s_add_u32 m0, s8, 0x18400
	v_mfma_f32_16x16x32_bf16 v[38:41], v[188:191], v[176:179], v[38:41]
	global_load_lds_dwordx4 v201, s[4:5]
	s_add_u32 m0, s8, 0x18800
	v_mfma_f32_16x16x32_bf16 v[42:45], v[192:195], v[176:179], v[42:45]
	global_load_lds_dwordx4 v202, s[4:5]
	s_add_u32 m0, s8, 0x18c00
	v_mfma_f32_16x16x32_bf16 v[46:49], v[196:199], v[176:179], v[46:49]
	global_load_lds_dwordx4 v203, s[4:5]
	s_add_u32 m0, s9, 0x18000
	v_mfma_f32_16x16x32_bf16 v[50:53], v[184:187], v[180:183], v[50:53]
	global_load_lds_dwordx4 v204, s[6:7]
	s_add_u32 m0, s9, 0x18400
	v_mfma_f32_16x16x32_bf16 v[54:57], v[188:191], v[180:183], v[54:57]
	global_load_lds_dwordx4 v205, s[6:7]
	v_mfma_f32_16x16x32_bf16 v[58:61], v[192:195], v[180:183], v[58:61]
	s_add_u32 s4, s4, 0x80
	s_addc_u32 s5, s5, 0
	v_mfma_f32_16x16x32_bf16 v[62:65], v[196:199], v[180:183], v[62:65]
	s_add_u32 s6, s6, 0x80
	s_addc_u32 s7, s7, 0
	s_waitcnt lgkmcnt(0)
	v_mfma_f32_16x16x32_bf16 v[2:5], v[152:155], v[136:139], v[2:5]
	ds_read_b128 v[168:171], v225 offset:0
	v_mfma_f32_16x16x32_bf16 v[6:9], v[156:159], v[136:139], v[6:9]
	ds_read_b128 v[172:175], v225 offset:2048
	v_mfma_f32_16x16x32_bf16 v[10:13], v[160:163], v[136:139], v[10:13]
	ds_read_b128 v[176:179], v225 offset:4096
	v_mfma_f32_16x16x32_bf16 v[14:17], v[164:167], v[136:139], v[14:17]
	ds_read_b128 v[180:183], v225 offset:6144
	v_mfma_f32_16x16x32_bf16 v[18:21], v[152:155], v[140:143], v[18:21]
	ds_read_b128 v[184:187], v233 offset:0
	v_mfma_f32_16x16x32_bf16 v[22:25], v[156:159], v[140:143], v[22:25]
	ds_read_b128 v[188:191], v233 offset:2048
	v_mfma_f32_16x16x32_bf16 v[26:29], v[160:163], v[140:143], v[26:29]
	ds_read_b128 v[192:195], v233 offset:4096
	v_mfma_f32_16x16x32_bf16 v[30:33], v[164:167], v[140:143], v[30:33]
	ds_read_b128 v[196:199], v233 offset:6144
	v_mfma_f32_16x16x32_bf16 v[34:37], v[152:155], v[144:147], v[34:37]
	v_mfma_f32_16x16x32_bf16 v[38:41], v[156:159], v[144:147], v[38:41]
	v_mfma_f32_16x16x32_bf16 v[42:45], v[160:163], v[144:147], v[42:45]
	v_mfma_f32_16x16x32_bf16 v[46:49], v[164:167], v[144:147], v[46:49]
	v_mfma_f32_16x16x32_bf16 v[50:53], v[152:155], v[148:151], v[50:53]
	v_mfma_f32_16x16x32_bf16 v[54:57], v[156:159], v[148:151], v[54:57]
	v_mfma_f32_16x16x32_bf16 v[58:61], v[160:163], v[148:151], v[58:61]
	v_mfma_f32_16x16x32_bf16 v[62:65], v[164:167], v[148:151], v[62:65]
	s_waitcnt vmcnt(6) lgkmcnt(0)
	s_barrier
	v_mfma_f32_16x16x32_bf16 v[2:5], v[184:187], v[168:171], v[2:5]
	ds_read_b128 v[136:139], v219 offset:0
	v_mfma_f32_16x16x32_bf16 v[6:9], v[188:191], v[168:171], v[6:9]
	ds_read_b128 v[140:143], v219 offset:2048
	v_mfma_f32_16x16x32_bf16 v[10:13], v[192:195], v[168:171], v[10:13]
	ds_read_b128 v[144:147], v219 offset:4096
	v_mfma_f32_16x16x32_bf16 v[14:17], v[196:199], v[168:171], v[14:17]
	ds_read_b128 v[148:151], v219 offset:6144
	v_mfma_f32_16x16x32_bf16 v[18:21], v[184:187], v[172:175], v[18:21]
	ds_read_b128 v[152:155], v231 offset:0
	v_mfma_f32_16x16x32_bf16 v[22:25], v[188:191], v[172:175], v[22:25]
	ds_read_b128 v[156:159], v231 offset:2048
	v_mfma_f32_16x16x32_bf16 v[26:29], v[192:195], v[172:175], v[26:29]
	ds_read_b128 v[160:163], v231 offset:4096
	v_mfma_f32_16x16x32_bf16 v[30:33], v[196:199], v[172:175], v[30:33]
	ds_read_b128 v[164:167], v231 offset:6144
	s_mov_b32 m0, s8
	v_mfma_f32_16x16x32_bf16 v[34:37], v[184:187], v[176:179], v[34:37]
	global_load_lds_dwordx4 v200, s[4:5]
	s_add_u32 m0, s8, 0x400
	v_mfma_f32_16x16x32_bf16 v[38:41], v[188:191], v[176:179], v[38:41]
	global_load_lds_dwordx4 v201, s[4:5]
	s_add_u32 m0, s8, 0x800
	v_mfma_f32_16x16x32_bf16 v[42:45], v[192:195], v[176:179], v[42:45]
	global_load_lds_dwordx4 v202, s[4:5]
	s_add_u32 m0, s8, 0xc00
	v_mfma_f32_16x16x32_bf16 v[46:49], v[196:199], v[176:179], v[46:49]
	global_load_lds_dwordx4 v203, s[4:5]
	s_mov_b32 m0, s9
	v_mfma_f32_16x16x32_bf16 v[50:53], v[184:187], v[180:183], v[50:53]
	global_load_lds_dwordx4 v204, s[6:7]
	s_add_u32 m0, s9, 0x400
	v_mfma_f32_16x16x32_bf16 v[54:57], v[188:191], v[180:183], v[54:57]
	global_load_lds_dwordx4 v205, s[6:7]
	v_mfma_f32_16x16x32_bf16 v[58:61], v[192:195], v[180:183], v[58:61]
	s_add_u32 s4, s4, 0x80
	s_addc_u32 s5, s5, 0
	v_mfma_f32_16x16x32_bf16 v[62:65], v[196:199], v[180:183], v[62:65]
	s_add_u32 s6, s6, 0x80
	s_addc_u32 s7, s7, 0
	s_waitcnt lgkmcnt(0)
	v_mfma_f32_16x16x32_bf16 v[2:5], v[152:155], v[136:139], v[2:5]
	ds_read_b128 v[168:171], v228 offset:0
	v_mfma_f32_16x16x32_bf16 v[6:9], v[156:159], v[136:139], v[6:9]
	ds_read_b128 v[172:175], v228 offset:2048
	v_mfma_f32_16x16x32_bf16 v[10:13], v[160:163], v[136:139], v[10:13]
	ds_read_b128 v[176:179], v228 offset:4096
	v_mfma_f32_16x16x32_bf16 v[14:17], v[164:167], v[136:139], v[14:17]
	ds_read_b128 v[180:183], v228 offset:6144
	v_mfma_f32_16x16x32_bf16 v[18:21], v[152:155], v[140:143], v[18:21]
	ds_read_b128 v[184:187], v234 offset:0
	v_mfma_f32_16x16x32_bf16 v[22:25], v[156:159], v[140:143], v[22:25]
	ds_read_b128 v[188:191], v234 offset:2048
	v_mfma_f32_16x16x32_bf16 v[26:29], v[160:163], v[140:143], v[26:29]
	ds_read_b128 v[192:195], v234 offset:4096
	v_mfma_f32_16x16x32_bf16 v[30:33], v[164:167], v[140:143], v[30:33]
	ds_read_b128 v[196:199], v234 offset:6144
	v_mfma_f32_16x16x32_bf16 v[34:37], v[152:155], v[144:147], v[34:37]
	v_mfma_f32_16x16x32_bf16 v[38:41], v[156:159], v[144:147], v[38:41]
	v_mfma_f32_16x16x32_bf16 v[42:45], v[160:163], v[144:147], v[42:45]
	v_mfma_f32_16x16x32_bf16 v[46:49], v[164:167], v[144:147], v[46:49]
	v_mfma_f32_16x16x32_bf16 v[50:53], v[152:155], v[148:151], v[50:53]
	v_mfma_f32_16x16x32_bf16 v[54:57], v[156:159], v[148:151], v[54:57]
	v_mfma_f32_16x16x32_bf16 v[58:61], v[160:163], v[148:151], v[58:61]
	v_mfma_f32_16x16x32_bf16 v[62:65], v[164:167], v[148:151], v[62:65]
	s_waitcnt vmcnt(6) lgkmcnt(0)
	s_barrier
	v_mfma_f32_16x16x32_bf16 v[2:5], v[184:187], v[168:171], v[2:5]
	ds_read_b128 v[136:139], v224 offset:0
	v_mfma_f32_16x16x32_bf16 v[6:9], v[188:191], v[168:171], v[6:9]
	ds_read_b128 v[140:143], v224 offset:2048
	v_mfma_f32_16x16x32_bf16 v[10:13], v[192:195], v[168:171], v[10:13]
	ds_read_b128 v[144:147], v224 offset:4096
	v_mfma_f32_16x16x32_bf16 v[14:17], v[196:199], v[168:171], v[14:17]
	ds_read_b128 v[148:151], v224 offset:6144
	v_mfma_f32_16x16x32_bf16 v[18:21], v[184:187], v[172:175], v[18:21]
	ds_read_b128 v[152:155], v232 offset:0
	v_mfma_f32_16x16x32_bf16 v[22:25], v[188:191], v[172:175], v[22:25]
	ds_read_b128 v[156:159], v232 offset:2048
	v_mfma_f32_16x16x32_bf16 v[26:29], v[192:195], v[172:175], v[26:29]
	ds_read_b128 v[160:163], v232 offset:4096
	v_mfma_f32_16x16x32_bf16 v[30:33], v[196:199], v[172:175], v[30:33]
	ds_read_b128 v[164:167], v232 offset:6144
	s_add_u32 m0, s8, 0xc000
	v_mfma_f32_16x16x32_bf16 v[34:37], v[184:187], v[176:179], v[34:37]
	global_load_lds_dwordx4 v200, s[4:5]
	s_add_u32 m0, s8, 0xc400
	v_mfma_f32_16x16x32_bf16 v[38:41], v[188:191], v[176:179], v[38:41]
	global_load_lds_dwordx4 v201, s[4:5]
	s_add_u32 m0, s8, 0xc800
	v_mfma_f32_16x16x32_bf16 v[42:45], v[192:195], v[176:179], v[42:45]
	global_load_lds_dwordx4 v202, s[4:5]
	s_add_u32 m0, s8, 0xcc00
	v_mfma_f32_16x16x32_bf16 v[46:49], v[196:199], v[176:179], v[46:49]
	global_load_lds_dwordx4 v203, s[4:5]
	s_add_u32 m0, s9, 0xc000
	v_mfma_f32_16x16x32_bf16 v[50:53], v[184:187], v[180:183], v[50:53]
	global_load_lds_dwordx4 v204, s[6:7]
	s_add_u32 m0, s9, 0xc400
	v_mfma_f32_16x16x32_bf16 v[54:57], v[188:191], v[180:183], v[54:57]
	global_load_lds_dwordx4 v205, s[6:7]
	v_mfma_f32_16x16x32_bf16 v[58:61], v[192:195], v[180:183], v[58:61]
	s_add_u32 s4, s4, 0x80
	s_addc_u32 s5, s5, 0
	v_mfma_f32_16x16x32_bf16 v[62:65], v[196:199], v[180:183], v[62:65]
	s_add_u32 s6, s6, 0x80
	s_addc_u32 s7, s7, 0
	s_waitcnt lgkmcnt(0)
	v_mfma_f32_16x16x32_bf16 v[2:5], v[152:155], v[136:139], v[2:5]
	ds_read_b128 v[168:171], v229 offset:0
	v_mfma_f32_16x16x32_bf16 v[6:9], v[156:159], v[136:139], v[6:9]
	ds_read_b128 v[172:175], v229 offset:2048
	v_mfma_f32_16x16x32_bf16 v[10:13], v[160:163], v[136:139], v[10:13]
	ds_read_b128 v[176:179], v229 offset:4096
	v_mfma_f32_16x16x32_bf16 v[14:17], v[164:167], v[136:139], v[14:17]
	ds_read_b128 v[180:183], v229 offset:6144
	v_mfma_f32_16x16x32_bf16 v[18:21], v[152:155], v[140:143], v[18:21]
	ds_read_b128 v[184:187], v235 offset:0
	v_mfma_f32_16x16x32_bf16 v[22:25], v[156:159], v[140:143], v[22:25]
	ds_read_b128 v[188:191], v235 offset:2048
	v_mfma_f32_16x16x32_bf16 v[26:29], v[160:163], v[140:143], v[26:29]
	ds_read_b128 v[192:195], v235 offset:4096
	v_mfma_f32_16x16x32_bf16 v[30:33], v[164:167], v[140:143], v[30:33]
	ds_read_b128 v[196:199], v235 offset:6144
	v_mfma_f32_16x16x32_bf16 v[34:37], v[152:155], v[144:147], v[34:37]
	v_mfma_f32_16x16x32_bf16 v[38:41], v[156:159], v[144:147], v[38:41]
	v_mfma_f32_16x16x32_bf16 v[42:45], v[160:163], v[144:147], v[42:45]
	v_mfma_f32_16x16x32_bf16 v[46:49], v[164:167], v[144:147], v[46:49]
	v_mfma_f32_16x16x32_bf16 v[50:53], v[152:155], v[148:151], v[50:53]
	v_mfma_f32_16x16x32_bf16 v[54:57], v[156:159], v[148:151], v[54:57]
	v_mfma_f32_16x16x32_bf16 v[58:61], v[160:163], v[148:151], v[58:61]
	v_mfma_f32_16x16x32_bf16 v[62:65], v[164:167], v[148:151], v[62:65]
	s_waitcnt vmcnt(6) lgkmcnt(0)
	s_barrier
	v_mfma_f32_16x16x32_bf16 v[2:5], v[184:187], v[168:171], v[2:5]
	ds_read_b128 v[136:139], v218 offset:0
	v_mfma_f32_16x16x32_bf16 v[6:9], v[188:191], v[168:171], v[6:9]
	ds_read_b128 v[140:143], v218 offset:2048
	v_mfma_f32_16x16x32_bf16 v[10:13], v[192:195], v[168:171], v[10:13]
	ds_read_b128 v[144:147], v218 offset:4096
	v_mfma_f32_16x16x32_bf16 v[14:17], v[196:199], v[168:171], v[14:17]
	ds_read_b128 v[148:151], v218 offset:6144
	v_mfma_f32_16x16x32_bf16 v[18:21], v[184:187], v[172:175], v[18:21]
	ds_read_b128 v[152:155], v230 offset:0
	v_mfma_f32_16x16x32_bf16 v[22:25], v[188:191], v[172:175], v[22:25]
	ds_read_b128 v[156:159], v230 offset:2048
	v_mfma_f32_16x16x32_bf16 v[26:29], v[192:195], v[172:175], v[26:29]
	ds_read_b128 v[160:163], v230 offset:4096
	v_mfma_f32_16x16x32_bf16 v[30:33], v[196:199], v[172:175], v[30:33]
	ds_read_b128 v[164:167], v230 offset:6144
	s_add_u32 m0, s8, 0x18000
	v_mfma_f32_16x16x32_bf16 v[34:37], v[184:187], v[176:179], v[34:37]
	global_load_lds_dwordx4 v200, s[4:5]
	s_add_u32 m0, s8, 0x18400
	v_mfma_f32_16x16x32_bf16 v[38:41], v[188:191], v[176:179], v[38:41]
	global_load_lds_dwordx4 v201, s[4:5]
	s_add_u32 m0, s8, 0x18800
	v_mfma_f32_16x16x32_bf16 v[42:45], v[192:195], v[176:179], v[42:45]
	global_load_lds_dwordx4 v202, s[4:5]
	s_add_u32 m0, s8, 0x18c00
	v_mfma_f32_16x16x32_bf16 v[46:49], v[196:199], v[176:179], v[46:49]
	global_load_lds_dwordx4 v203, s[4:5]
	s_add_u32 m0, s9, 0x18000
	v_mfma_f32_16x16x32_bf16 v[50:53], v[184:187], v[180:183], v[50:53]
	global_load_lds_dwordx4 v204, s[6:7]
	s_add_u32 m0, s9, 0x18400
	v_mfma_f32_16x16x32_bf16 v[54:57], v[188:191], v[180:183], v[54:57]
	global_load_lds_dwordx4 v205, s[6:7]
	v_mfma_f32_16x16x32_bf16 v[58:61], v[192:195], v[180:183], v[58:61]
	s_add_u32 s4, s4, 0x80
	s_addc_u32 s5, s5, 0
	v_mfma_f32_16x16x32_bf16 v[62:65], v[196:199], v[180:183], v[62:65]
	s_add_u32 s6, s6, 0x80
	s_addc_u32 s7, s7, 0
	s_waitcnt lgkmcnt(0)
	v_mfma_f32_16x16x32_bf16 v[2:5], v[152:155], v[136:139], v[2:5]
	ds_read_b128 v[168:171], v225 offset:0
	v_mfma_f32_16x16x32_bf16 v[6:9], v[156:159], v[136:139], v[6:9]
	ds_read_b128 v[172:175], v225 offset:2048
	v_mfma_f32_16x16x32_bf16 v[10:13], v[160:163], v[136:139], v[10:13]
	ds_read_b128 v[176:179], v225 offset:4096
	v_mfma_f32_16x16x32_bf16 v[14:17], v[164:167], v[136:139], v[14:17]
	ds_read_b128 v[180:183], v225 offset:6144
	v_mfma_f32_16x16x32_bf16 v[18:21], v[152:155], v[140:143], v[18:21]
	ds_read_b128 v[184:187], v233 offset:0
	v_mfma_f32_16x16x32_bf16 v[22:25], v[156:159], v[140:143], v[22:25]
	ds_read_b128 v[188:191], v233 offset:2048
	v_mfma_f32_16x16x32_bf16 v[26:29], v[160:163], v[140:143], v[26:29]
	ds_read_b128 v[192:195], v233 offset:4096
	v_mfma_f32_16x16x32_bf16 v[30:33], v[164:167], v[140:143], v[30:33]
	ds_read_b128 v[196:199], v233 offset:6144
	v_mfma_f32_16x16x32_bf16 v[34:37], v[152:155], v[144:147], v[34:37]
	v_mfma_f32_16x16x32_bf16 v[38:41], v[156:159], v[144:147], v[38:41]
	v_mfma_f32_16x16x32_bf16 v[42:45], v[160:163], v[144:147], v[42:45]
	v_mfma_f32_16x16x32_bf16 v[46:49], v[164:167], v[144:147], v[46:49]
	v_mfma_f32_16x16x32_bf16 v[50:53], v[152:155], v[148:151], v[50:53]
	v_mfma_f32_16x16x32_bf16 v[54:57], v[156:159], v[148:151], v[54:57]
	v_mfma_f32_16x16x32_bf16 v[58:61], v[160:163], v[148:151], v[58:61]
	v_mfma_f32_16x16x32_bf16 v[62:65], v[164:167], v[148:151], v[62:65]
	s_waitcnt vmcnt(6) lgkmcnt(0)
	s_barrier
	v_mfma_f32_16x16x32_bf16 v[2:5], v[184:187], v[168:171], v[2:5]
	ds_read_b128 v[136:139], v219 offset:0
	v_mfma_f32_16x16x32_bf16 v[6:9], v[188:191], v[168:171], v[6:9]
	ds_read_b128 v[140:143], v219 offset:2048
	v_mfma_f32_16x16x32_bf16 v[10:13], v[192:195], v[168:171], v[10:13]
	ds_read_b128 v[144:147], v219 offset:4096
	v_mfma_f32_16x16x32_bf16 v[14:17], v[196:199], v[168:171], v[14:17]
	ds_read_b128 v[148:151], v219 offset:6144
	v_mfma_f32_16x16x32_bf16 v[18:21], v[184:187], v[172:175], v[18:21]
	ds_read_b128 v[152:155], v231 offset:0
	v_mfma_f32_16x16x32_bf16 v[22:25], v[188:191], v[172:175], v[22:25]
	ds_read_b128 v[156:159], v231 offset:2048
	v_mfma_f32_16x16x32_bf16 v[26:29], v[192:195], v[172:175], v[26:29]
	ds_read_b128 v[160:163], v231 offset:4096
	v_mfma_f32_16x16x32_bf16 v[30:33], v[196:199], v[172:175], v[30:33]
	ds_read_b128 v[164:167], v231 offset:6144
	s_mov_b32 m0, s8
	v_mfma_f32_16x16x32_bf16 v[34:37], v[184:187], v[176:179], v[34:37]
	global_load_lds_dwordx4 v200, s[4:5]
	s_add_u32 m0, s8, 0x400
	v_mfma_f32_16x16x32_bf16 v[38:41], v[188:191], v[176:179], v[38:41]
	global_load_lds_dwordx4 v201, s[4:5]
	s_add_u32 m0, s8, 0x800
	v_mfma_f32_16x16x32_bf16 v[42:45], v[192:195], v[176:179], v[42:45]
	global_load_lds_dwordx4 v202, s[4:5]
	s_add_u32 m0, s8, 0xc00
	v_mfma_f32_16x16x32_bf16 v[46:49], v[196:199], v[176:179], v[46:49]
	global_load_lds_dwordx4 v203, s[4:5]
	s_mov_b32 m0, s9
	v_mfma_f32_16x16x32_bf16 v[50:53], v[184:187], v[180:183], v[50:53]
	global_load_lds_dwordx4 v204, s[6:7]
	s_add_u32 m0, s9, 0x400
	v_mfma_f32_16x16x32_bf16 v[54:57], v[188:191], v[180:183], v[54:57]
	global_load_lds_dwordx4 v205, s[6:7]
	v_mfma_f32_16x16x32_bf16 v[58:61], v[192:195], v[180:183], v[58:61]
	s_add_u32 s4, s4, 0x80
	s_addc_u32 s5, s5, 0
	v_mfma_f32_16x16x32_bf16 v[62:65], v[196:199], v[180:183], v[62:65]
	s_add_u32 s6, s6, 0x80
	s_addc_u32 s7, s7, 0
	s_waitcnt lgkmcnt(0)
	v_mfma_f32_16x16x32_bf16 v[2:5], v[152:155], v[136:139], v[2:5]
	ds_read_b128 v[168:171], v228 offset:0
	v_mfma_f32_16x16x32_bf16 v[6:9], v[156:159], v[136:139], v[6:9]
	ds_read_b128 v[172:175], v228 offset:2048
	v_mfma_f32_16x16x32_bf16 v[10:13], v[160:163], v[136:139], v[10:13]
	ds_read_b128 v[176:179], v228 offset:4096
	v_mfma_f32_16x16x32_bf16 v[14:17], v[164:167], v[136:139], v[14:17]
	ds_read_b128 v[180:183], v228 offset:6144
	v_mfma_f32_16x16x32_bf16 v[18:21], v[152:155], v[140:143], v[18:21]
	ds_read_b128 v[184:187], v234 offset:0
	v_mfma_f32_16x16x32_bf16 v[22:25], v[156:159], v[140:143], v[22:25]
	ds_read_b128 v[188:191], v234 offset:2048
	v_mfma_f32_16x16x32_bf16 v[26:29], v[160:163], v[140:143], v[26:29]
	ds_read_b128 v[192:195], v234 offset:4096
	v_mfma_f32_16x16x32_bf16 v[30:33], v[164:167], v[140:143], v[30:33]
	ds_read_b128 v[196:199], v234 offset:6144
	v_mfma_f32_16x16x32_bf16 v[34:37], v[152:155], v[144:147], v[34:37]
	v_mfma_f32_16x16x32_bf16 v[38:41], v[156:159], v[144:147], v[38:41]
	v_mfma_f32_16x16x32_bf16 v[42:45], v[160:163], v[144:147], v[42:45]
	v_mfma_f32_16x16x32_bf16 v[46:49], v[164:167], v[144:147], v[46:49]
	v_mfma_f32_16x16x32_bf16 v[50:53], v[152:155], v[148:151], v[50:53]
	v_mfma_f32_16x16x32_bf16 v[54:57], v[156:159], v[148:151], v[54:57]
	v_mfma_f32_16x16x32_bf16 v[58:61], v[160:163], v[148:151], v[58:61]
	v_mfma_f32_16x16x32_bf16 v[62:65], v[164:167], v[148:151], v[62:65]
	s_waitcnt vmcnt(6) lgkmcnt(0)
	s_barrier
	v_mfma_f32_16x16x32_bf16 v[2:5], v[184:187], v[168:171], v[2:5]
	ds_read_b128 v[136:139], v224 offset:0
	v_mfma_f32_16x16x32_bf16 v[6:9], v[188:191], v[168:171], v[6:9]
	ds_read_b128 v[140:143], v224 offset:2048
	v_mfma_f32_16x16x32_bf16 v[10:13], v[192:195], v[168:171], v[10:13]
	ds_read_b128 v[144:147], v224 offset:4096
	v_mfma_f32_16x16x32_bf16 v[14:17], v[196:199], v[168:171], v[14:17]
	ds_read_b128 v[148:151], v224 offset:6144
	v_mfma_f32_16x16x32_bf16 v[18:21], v[184:187], v[172:175], v[18:21]
	ds_read_b128 v[152:155], v232 offset:0
	v_mfma_f32_16x16x32_bf16 v[22:25], v[188:191], v[172:175], v[22:25]
	ds_read_b128 v[156:159], v232 offset:2048
	v_mfma_f32_16x16x32_bf16 v[26:29], v[192:195], v[172:175], v[26:29]
	ds_read_b128 v[160:163], v232 offset:4096
	v_mfma_f32_16x16x32_bf16 v[30:33], v[196:199], v[172:175], v[30:33]
	ds_read_b128 v[164:167], v232 offset:6144
	s_add_u32 m0, s8, 0xc000
	v_mfma_f32_16x16x32_bf16 v[34:37], v[184:187], v[176:179], v[34:37]
	global_load_lds_dwordx4 v200, s[4:5]
	s_add_u32 m0, s8, 0xc400
	v_mfma_f32_16x16x32_bf16 v[38:41], v[188:191], v[176:179], v[38:41]
	global_load_lds_dwordx4 v201, s[4:5]
	s_add_u32 m0, s8, 0xc800
	v_mfma_f32_16x16x32_bf16 v[42:45], v[192:195], v[176:179], v[42:45]
	global_load_lds_dwordx4 v202, s[4:5]
	s_add_u32 m0, s8, 0xcc00
	v_mfma_f32_16x16x32_bf16 v[46:49], v[196:199], v[176:179], v[46:49]
	global_load_lds_dwordx4 v203, s[4:5]
	s_add_u32 m0, s9, 0xc000
	v_mfma_f32_16x16x32_bf16 v[50:53], v[184:187], v[180:183], v[50:53]
	global_load_lds_dwordx4 v204, s[6:7]
	s_add_u32 m0, s9, 0xc400
	v_mfma_f32_16x16x32_bf16 v[54:57], v[188:191], v[180:183], v[54:57]
	global_load_lds_dwordx4 v205, s[6:7]
	v_mfma_f32_16x16x32_bf16 v[58:61], v[192:195], v[180:183], v[58:61]
	s_add_u32 s4, s4, 0x80
	s_addc_u32 s5, s5, 0
	v_mfma_f32_16x16x32_bf16 v[62:65], v[196:199], v[180:183], v[62:65]
	s_add_u32 s6, s6, 0x80
	s_addc_u32 s7, s7, 0
	s_waitcnt lgkmcnt(0)
	v_mfma_f32_16x16x32_bf16 v[2:5], v[152:155], v[136:139], v[2:5]
	ds_read_b128 v[168:171], v229 offset:0
	v_mfma_f32_16x16x32_bf16 v[6:9], v[156:159], v[136:139], v[6:9]
	ds_read_b128 v[172:175], v229 offset:2048
	v_mfma_f32_16x16x32_bf16 v[10:13], v[160:163], v[136:139], v[10:13]
	ds_read_b128 v[176:179], v229 offset:4096
	v_mfma_f32_16x16x32_bf16 v[14:17], v[164:167], v[136:139], v[14:17]
	ds_read_b128 v[180:183], v229 offset:6144
	v_mfma_f32_16x16x32_bf16 v[18:21], v[152:155], v[140:143], v[18:21]
	ds_read_b128 v[184:187], v235 offset:0
	v_mfma_f32_16x16x32_bf16 v[22:25], v[156:159], v[140:143], v[22:25]
	ds_read_b128 v[188:191], v235 offset:2048
	v_mfma_f32_16x16x32_bf16 v[26:29], v[160:163], v[140:143], v[26:29]
	ds_read_b128 v[192:195], v235 offset:4096
	v_mfma_f32_16x16x32_bf16 v[30:33], v[164:167], v[140:143], v[30:33]
	ds_read_b128 v[196:199], v235 offset:6144
	v_mfma_f32_16x16x32_bf16 v[34:37], v[152:155], v[144:147], v[34:37]
	v_mfma_f32_16x16x32_bf16 v[38:41], v[156:159], v[144:147], v[38:41]
	v_mfma_f32_16x16x32_bf16 v[42:45], v[160:163], v[144:147], v[42:45]
	v_mfma_f32_16x16x32_bf16 v[46:49], v[164:167], v[144:147], v[46:49]
	v_mfma_f32_16x16x32_bf16 v[50:53], v[152:155], v[148:151], v[50:53]
	v_mfma_f32_16x16x32_bf16 v[54:57], v[156:159], v[148:151], v[54:57]
	v_mfma_f32_16x16x32_bf16 v[58:61], v[160:163], v[148:151], v[58:61]
	v_mfma_f32_16x16x32_bf16 v[62:65], v[164:167], v[148:151], v[62:65]
	s_waitcnt vmcnt(6) lgkmcnt(0)
	s_barrier
	v_mfma_f32_16x16x32_bf16 v[2:5], v[184:187], v[168:171], v[2:5]
	ds_read_b128 v[136:139], v218 offset:0
	v_mfma_f32_16x16x32_bf16 v[6:9], v[188:191], v[168:171], v[6:9]
	ds_read_b128 v[140:143], v218 offset:2048
	v_mfma_f32_16x16x32_bf16 v[10:13], v[192:195], v[168:171], v[10:13]
	ds_read_b128 v[144:147], v218 offset:4096
	v_mfma_f32_16x16x32_bf16 v[14:17], v[196:199], v[168:171], v[14:17]
	ds_read_b128 v[148:151], v218 offset:6144
	v_mfma_f32_16x16x32_bf16 v[18:21], v[184:187], v[172:175], v[18:21]
	ds_read_b128 v[152:155], v230 offset:0
	v_mfma_f32_16x16x32_bf16 v[22:25], v[188:191], v[172:175], v[22:25]
	ds_read_b128 v[156:159], v230 offset:2048
	v_mfma_f32_16x16x32_bf16 v[26:29], v[192:195], v[172:175], v[26:29]
	ds_read_b128 v[160:163], v230 offset:4096
	v_mfma_f32_16x16x32_bf16 v[30:33], v[196:199], v[172:175], v[30:33]
	ds_read_b128 v[164:167], v230 offset:6144
	s_add_u32 m0, s8, 0x18000
	v_mfma_f32_16x16x32_bf16 v[34:37], v[184:187], v[176:179], v[34:37]
	global_load_lds_dwordx4 v200, s[4:5]
	s_add_u32 m0, s8, 0x18400
	v_mfma_f32_16x16x32_bf16 v[38:41], v[188:191], v[176:179], v[38:41]
	global_load_lds_dwordx4 v201, s[4:5]
	s_add_u32 m0, s8, 0x18800
	v_mfma_f32_16x16x32_bf16 v[42:45], v[192:195], v[176:179], v[42:45]
	global_load_lds_dwordx4 v202, s[4:5]
	s_add_u32 m0, s8, 0x18c00
	v_mfma_f32_16x16x32_bf16 v[46:49], v[196:199], v[176:179], v[46:49]
	global_load_lds_dwordx4 v203, s[4:5]
	s_add_u32 m0, s9, 0x18000
	v_mfma_f32_16x16x32_bf16 v[50:53], v[184:187], v[180:183], v[50:53]
	global_load_lds_dwordx4 v204, s[6:7]
	s_add_u32 m0, s9, 0x18400
	v_mfma_f32_16x16x32_bf16 v[54:57], v[188:191], v[180:183], v[54:57]
	global_load_lds_dwordx4 v205, s[6:7]
	v_mfma_f32_16x16x32_bf16 v[58:61], v[192:195], v[180:183], v[58:61]
	s_add_u32 s4, s4, 0x80
	s_addc_u32 s5, s5, 0
	v_mfma_f32_16x16x32_bf16 v[62:65], v[196:199], v[180:183], v[62:65]
	s_add_u32 s6, s6, 0x80
	s_addc_u32 s7, s7, 0
	s_waitcnt lgkmcnt(0)
	v_mfma_f32_16x16x32_bf16 v[2:5], v[152:155], v[136:139], v[2:5]
	ds_read_b128 v[168:171], v225 offset:0
	v_mfma_f32_16x16x32_bf16 v[6:9], v[156:159], v[136:139], v[6:9]
	ds_read_b128 v[172:175], v225 offset:2048
	v_mfma_f32_16x16x32_bf16 v[10:13], v[160:163], v[136:139], v[10:13]
	ds_read_b128 v[176:179], v225 offset:4096
	v_mfma_f32_16x16x32_bf16 v[14:17], v[164:167], v[136:139], v[14:17]
	ds_read_b128 v[180:183], v225 offset:6144
	v_mfma_f32_16x16x32_bf16 v[18:21], v[152:155], v[140:143], v[18:21]
	ds_read_b128 v[184:187], v233 offset:0
	v_mfma_f32_16x16x32_bf16 v[22:25], v[156:159], v[140:143], v[22:25]
	ds_read_b128 v[188:191], v233 offset:2048
	v_mfma_f32_16x16x32_bf16 v[26:29], v[160:163], v[140:143], v[26:29]
	ds_read_b128 v[192:195], v233 offset:4096
	v_mfma_f32_16x16x32_bf16 v[30:33], v[164:167], v[140:143], v[30:33]
	ds_read_b128 v[196:199], v233 offset:6144
	v_mfma_f32_16x16x32_bf16 v[34:37], v[152:155], v[144:147], v[34:37]
	v_mfma_f32_16x16x32_bf16 v[38:41], v[156:159], v[144:147], v[38:41]
	v_mfma_f32_16x16x32_bf16 v[42:45], v[160:163], v[144:147], v[42:45]
	v_mfma_f32_16x16x32_bf16 v[46:49], v[164:167], v[144:147], v[46:49]
	v_mfma_f32_16x16x32_bf16 v[50:53], v[152:155], v[148:151], v[50:53]
	v_mfma_f32_16x16x32_bf16 v[54:57], v[156:159], v[148:151], v[54:57]
	v_mfma_f32_16x16x32_bf16 v[58:61], v[160:163], v[148:151], v[58:61]
	v_mfma_f32_16x16x32_bf16 v[62:65], v[164:167], v[148:151], v[62:65]
	s_waitcnt vmcnt(6) lgkmcnt(0)
	s_barrier
	v_mfma_f32_16x16x32_bf16 v[2:5], v[184:187], v[168:171], v[2:5]
	ds_read_b128 v[136:139], v219 offset:0
	v_mfma_f32_16x16x32_bf16 v[6:9], v[188:191], v[168:171], v[6:9]
	ds_read_b128 v[140:143], v219 offset:2048
	v_mfma_f32_16x16x32_bf16 v[10:13], v[192:195], v[168:171], v[10:13]
	ds_read_b128 v[144:147], v219 offset:4096
	v_mfma_f32_16x16x32_bf16 v[14:17], v[196:199], v[168:171], v[14:17]
	ds_read_b128 v[148:151], v219 offset:6144
	v_mfma_f32_16x16x32_bf16 v[18:21], v[184:187], v[172:175], v[18:21]
	ds_read_b128 v[152:155], v231 offset:0
	v_mfma_f32_16x16x32_bf16 v[22:25], v[188:191], v[172:175], v[22:25]
	ds_read_b128 v[156:159], v231 offset:2048
	v_mfma_f32_16x16x32_bf16 v[26:29], v[192:195], v[172:175], v[26:29]
	ds_read_b128 v[160:163], v231 offset:4096
	v_mfma_f32_16x16x32_bf16 v[30:33], v[196:199], v[172:175], v[30:33]
	ds_read_b128 v[164:167], v231 offset:6144
	s_mov_b32 m0, s8
	v_mfma_f32_16x16x32_bf16 v[34:37], v[184:187], v[176:179], v[34:37]
	global_load_lds_dwordx4 v200, s[4:5]
	s_add_u32 m0, s8, 0x400
	v_mfma_f32_16x16x32_bf16 v[38:41], v[188:191], v[176:179], v[38:41]
	global_load_lds_dwordx4 v201, s[4:5]
	s_add_u32 m0, s8, 0x800
	v_mfma_f32_16x16x32_bf16 v[42:45], v[192:195], v[176:179], v[42:45]
	global_load_lds_dwordx4 v202, s[4:5]
	s_add_u32 m0, s8, 0xc00
	v_mfma_f32_16x16x32_bf16 v[46:49], v[196:199], v[176:179], v[46:49]
	global_load_lds_dwordx4 v203, s[4:5]
	s_mov_b32 m0, s9
	v_mfma_f32_16x16x32_bf16 v[50:53], v[184:187], v[180:183], v[50:53]
	global_load_lds_dwordx4 v204, s[6:7]
	s_add_u32 m0, s9, 0x400
	v_mfma_f32_16x16x32_bf16 v[54:57], v[188:191], v[180:183], v[54:57]
	global_load_lds_dwordx4 v205, s[6:7]
	v_mfma_f32_16x16x32_bf16 v[58:61], v[192:195], v[180:183], v[58:61]
	s_add_u32 s4, s4, 0x80
	s_addc_u32 s5, s5, 0
	v_mfma_f32_16x16x32_bf16 v[62:65], v[196:199], v[180:183], v[62:65]
	s_add_u32 s6, s6, 0x80
	s_addc_u32 s7, s7, 0
	s_waitcnt lgkmcnt(0)
	v_mfma_f32_16x16x32_bf16 v[2:5], v[152:155], v[136:139], v[2:5]
	ds_read_b128 v[168:171], v228 offset:0
	v_mfma_f32_16x16x32_bf16 v[6:9], v[156:159], v[136:139], v[6:9]
	ds_read_b128 v[172:175], v228 offset:2048
	v_mfma_f32_16x16x32_bf16 v[10:13], v[160:163], v[136:139], v[10:13]
	ds_read_b128 v[176:179], v228 offset:4096
	v_mfma_f32_16x16x32_bf16 v[14:17], v[164:167], v[136:139], v[14:17]
	ds_read_b128 v[180:183], v228 offset:6144
	v_mfma_f32_16x16x32_bf16 v[18:21], v[152:155], v[140:143], v[18:21]
	ds_read_b128 v[184:187], v234 offset:0
	v_mfma_f32_16x16x32_bf16 v[22:25], v[156:159], v[140:143], v[22:25]
	ds_read_b128 v[188:191], v234 offset:2048
	v_mfma_f32_16x16x32_bf16 v[26:29], v[160:163], v[140:143], v[26:29]
	ds_read_b128 v[192:195], v234 offset:4096
	v_mfma_f32_16x16x32_bf16 v[30:33], v[164:167], v[140:143], v[30:33]
	ds_read_b128 v[196:199], v234 offset:6144
	v_mfma_f32_16x16x32_bf16 v[34:37], v[152:155], v[144:147], v[34:37]
	v_mfma_f32_16x16x32_bf16 v[38:41], v[156:159], v[144:147], v[38:41]
	v_mfma_f32_16x16x32_bf16 v[42:45], v[160:163], v[144:147], v[42:45]
	v_mfma_f32_16x16x32_bf16 v[46:49], v[164:167], v[144:147], v[46:49]
	v_mfma_f32_16x16x32_bf16 v[50:53], v[152:155], v[148:151], v[50:53]
	v_mfma_f32_16x16x32_bf16 v[54:57], v[156:159], v[148:151], v[54:57]
	v_mfma_f32_16x16x32_bf16 v[58:61], v[160:163], v[148:151], v[58:61]
	v_mfma_f32_16x16x32_bf16 v[62:65], v[164:167], v[148:151], v[62:65]
	s_waitcnt vmcnt(6) lgkmcnt(0)
	s_barrier
	v_mfma_f32_16x16x32_bf16 v[2:5], v[184:187], v[168:171], v[2:5]
	ds_read_b128 v[136:139], v224 offset:0
	v_mfma_f32_16x16x32_bf16 v[6:9], v[188:191], v[168:171], v[6:9]
	ds_read_b128 v[140:143], v224 offset:2048
	v_mfma_f32_16x16x32_bf16 v[10:13], v[192:195], v[168:171], v[10:13]
	ds_read_b128 v[144:147], v224 offset:4096
	v_mfma_f32_16x16x32_bf16 v[14:17], v[196:199], v[168:171], v[14:17]
	ds_read_b128 v[148:151], v224 offset:6144
	v_mfma_f32_16x16x32_bf16 v[18:21], v[184:187], v[172:175], v[18:21]
	ds_read_b128 v[152:155], v232 offset:0
	v_mfma_f32_16x16x32_bf16 v[22:25], v[188:191], v[172:175], v[22:25]
	ds_read_b128 v[156:159], v232 offset:2048
	v_mfma_f32_16x16x32_bf16 v[26:29], v[192:195], v[172:175], v[26:29]
	ds_read_b128 v[160:163], v232 offset:4096
	v_mfma_f32_16x16x32_bf16 v[30:33], v[196:199], v[172:175], v[30:33]
	ds_read_b128 v[164:167], v232 offset:6144
	s_add_u32 m0, s8, 0xc000
	v_mfma_f32_16x16x32_bf16 v[34:37], v[184:187], v[176:179], v[34:37]
	global_load_lds_dwordx4 v200, s[4:5]
	s_add_u32 m0, s8, 0xc400
	v_mfma_f32_16x16x32_bf16 v[38:41], v[188:191], v[176:179], v[38:41]
	global_load_lds_dwordx4 v201, s[4:5]
	s_add_u32 m0, s8, 0xc800
	v_mfma_f32_16x16x32_bf16 v[42:45], v[192:195], v[176:179], v[42:45]
	global_load_lds_dwordx4 v202, s[4:5]
	s_add_u32 m0, s8, 0xcc00
	v_mfma_f32_16x16x32_bf16 v[46:49], v[196:199], v[176:179], v[46:49]
	global_load_lds_dwordx4 v203, s[4:5]
	s_add_u32 m0, s9, 0xc000
	v_mfma_f32_16x16x32_bf16 v[50:53], v[184:187], v[180:183], v[50:53]
	global_load_lds_dwordx4 v204, s[6:7]
	s_add_u32 m0, s9, 0xc400
	v_mfma_f32_16x16x32_bf16 v[54:57], v[188:191], v[180:183], v[54:57]
	global_load_lds_dwordx4 v205, s[6:7]
	v_mfma_f32_16x16x32_bf16 v[58:61], v[192:195], v[180:183], v[58:61]
	s_add_u32 s4, s4, 0x80
	s_addc_u32 s5, s5, 0
	v_mfma_f32_16x16x32_bf16 v[62:65], v[196:199], v[180:183], v[62:65]
	s_add_u32 s6, s6, 0x80
	s_addc_u32 s7, s7, 0
	s_waitcnt lgkmcnt(0)
	v_mfma_f32_16x16x32_bf16 v[2:5], v[152:155], v[136:139], v[2:5]
	ds_read_b128 v[168:171], v229 offset:0
	v_mfma_f32_16x16x32_bf16 v[6:9], v[156:159], v[136:139], v[6:9]
	ds_read_b128 v[172:175], v229 offset:2048
	v_mfma_f32_16x16x32_bf16 v[10:13], v[160:163], v[136:139], v[10:13]
	ds_read_b128 v[176:179], v229 offset:4096
	v_mfma_f32_16x16x32_bf16 v[14:17], v[164:167], v[136:139], v[14:17]
	ds_read_b128 v[180:183], v229 offset:6144
	v_mfma_f32_16x16x32_bf16 v[18:21], v[152:155], v[140:143], v[18:21]
	ds_read_b128 v[184:187], v235 offset:0
	v_mfma_f32_16x16x32_bf16 v[22:25], v[156:159], v[140:143], v[22:25]
	ds_read_b128 v[188:191], v235 offset:2048
	v_mfma_f32_16x16x32_bf16 v[26:29], v[160:163], v[140:143], v[26:29]
	ds_read_b128 v[192:195], v235 offset:4096
	v_mfma_f32_16x16x32_bf16 v[30:33], v[164:167], v[140:143], v[30:33]
	ds_read_b128 v[196:199], v235 offset:6144
	v_mfma_f32_16x16x32_bf16 v[34:37], v[152:155], v[144:147], v[34:37]
	v_mfma_f32_16x16x32_bf16 v[38:41], v[156:159], v[144:147], v[38:41]
	v_mfma_f32_16x16x32_bf16 v[42:45], v[160:163], v[144:147], v[42:45]
	v_mfma_f32_16x16x32_bf16 v[46:49], v[164:167], v[144:147], v[46:49]
	v_mfma_f32_16x16x32_bf16 v[50:53], v[152:155], v[148:151], v[50:53]
	v_mfma_f32_16x16x32_bf16 v[54:57], v[156:159], v[148:151], v[54:57]
	v_mfma_f32_16x16x32_bf16 v[58:61], v[160:163], v[148:151], v[58:61]
	v_mfma_f32_16x16x32_bf16 v[62:65], v[164:167], v[148:151], v[62:65]
	s_waitcnt vmcnt(6) lgkmcnt(0)
	s_barrier
	v_mfma_f32_16x16x32_bf16 v[2:5], v[184:187], v[168:171], v[2:5]
	ds_read_b128 v[136:139], v218 offset:0
	v_mfma_f32_16x16x32_bf16 v[6:9], v[188:191], v[168:171], v[6:9]
	ds_read_b128 v[140:143], v218 offset:2048
	v_mfma_f32_16x16x32_bf16 v[10:13], v[192:195], v[168:171], v[10:13]
	ds_read_b128 v[144:147], v218 offset:4096
	v_mfma_f32_16x16x32_bf16 v[14:17], v[196:199], v[168:171], v[14:17]
	ds_read_b128 v[148:151], v218 offset:6144
	v_mfma_f32_16x16x32_bf16 v[18:21], v[184:187], v[172:175], v[18:21]
	ds_read_b128 v[152:155], v230 offset:0
	v_mfma_f32_16x16x32_bf16 v[22:25], v[188:191], v[172:175], v[22:25]
	ds_read_b128 v[156:159], v230 offset:2048
	v_mfma_f32_16x16x32_bf16 v[26:29], v[192:195], v[172:175], v[26:29]
	ds_read_b128 v[160:163], v230 offset:4096
	v_mfma_f32_16x16x32_bf16 v[30:33], v[196:199], v[172:175], v[30:33]
	ds_read_b128 v[164:167], v230 offset:6144
	s_add_u32 m0, s8, 0x18000
	v_mfma_f32_16x16x32_bf16 v[34:37], v[184:187], v[176:179], v[34:37]
	global_load_lds_dwordx4 v200, s[4:5]
	s_add_u32 m0, s8, 0x18400
	v_mfma_f32_16x16x32_bf16 v[38:41], v[188:191], v[176:179], v[38:41]
	global_load_lds_dwordx4 v201, s[4:5]
	s_add_u32 m0, s8, 0x18800
	v_mfma_f32_16x16x32_bf16 v[42:45], v[192:195], v[176:179], v[42:45]
	global_load_lds_dwordx4 v202, s[4:5]
	s_add_u32 m0, s8, 0x18c00
	v_mfma_f32_16x16x32_bf16 v[46:49], v[196:199], v[176:179], v[46:49]
	global_load_lds_dwordx4 v203, s[4:5]
	s_add_u32 m0, s9, 0x18000
	v_mfma_f32_16x16x32_bf16 v[50:53], v[184:187], v[180:183], v[50:53]
	global_load_lds_dwordx4 v204, s[6:7]
	s_add_u32 m0, s9, 0x18400
	v_mfma_f32_16x16x32_bf16 v[54:57], v[188:191], v[180:183], v[54:57]
	global_load_lds_dwordx4 v205, s[6:7]
	v_mfma_f32_16x16x32_bf16 v[58:61], v[192:195], v[180:183], v[58:61]
	s_add_u32 s4, s4, 0x80
	s_addc_u32 s5, s5, 0
	v_mfma_f32_16x16x32_bf16 v[62:65], v[196:199], v[180:183], v[62:65]
	s_add_u32 s6, s6, 0x80
	s_addc_u32 s7, s7, 0
	s_waitcnt lgkmcnt(0)
	v_mfma_f32_16x16x32_bf16 v[2:5], v[152:155], v[136:139], v[2:5]
	ds_read_b128 v[168:171], v225 offset:0
	v_mfma_f32_16x16x32_bf16 v[6:9], v[156:159], v[136:139], v[6:9]
	ds_read_b128 v[172:175], v225 offset:2048
	v_mfma_f32_16x16x32_bf16 v[10:13], v[160:163], v[136:139], v[10:13]
	ds_read_b128 v[176:179], v225 offset:4096
	v_mfma_f32_16x16x32_bf16 v[14:17], v[164:167], v[136:139], v[14:17]
	ds_read_b128 v[180:183], v225 offset:6144
	v_mfma_f32_16x16x32_bf16 v[18:21], v[152:155], v[140:143], v[18:21]
	ds_read_b128 v[184:187], v233 offset:0
	v_mfma_f32_16x16x32_bf16 v[22:25], v[156:159], v[140:143], v[22:25]
	ds_read_b128 v[188:191], v233 offset:2048
	v_mfma_f32_16x16x32_bf16 v[26:29], v[160:163], v[140:143], v[26:29]
	ds_read_b128 v[192:195], v233 offset:4096
	v_mfma_f32_16x16x32_bf16 v[30:33], v[164:167], v[140:143], v[30:33]
	ds_read_b128 v[196:199], v233 offset:6144
	v_mfma_f32_16x16x32_bf16 v[34:37], v[152:155], v[144:147], v[34:37]
	v_mfma_f32_16x16x32_bf16 v[38:41], v[156:159], v[144:147], v[38:41]
	v_mfma_f32_16x16x32_bf16 v[42:45], v[160:163], v[144:147], v[42:45]
	v_mfma_f32_16x16x32_bf16 v[46:49], v[164:167], v[144:147], v[46:49]
	v_mfma_f32_16x16x32_bf16 v[50:53], v[152:155], v[148:151], v[50:53]
	v_mfma_f32_16x16x32_bf16 v[54:57], v[156:159], v[148:151], v[54:57]
	v_mfma_f32_16x16x32_bf16 v[58:61], v[160:163], v[148:151], v[58:61]
	v_mfma_f32_16x16x32_bf16 v[62:65], v[164:167], v[148:151], v[62:65]
	s_waitcnt vmcnt(6) lgkmcnt(0)
	s_barrier
	v_mfma_f32_16x16x32_bf16 v[2:5], v[184:187], v[168:171], v[2:5]
	ds_read_b128 v[136:139], v219 offset:0
	v_mfma_f32_16x16x32_bf16 v[6:9], v[188:191], v[168:171], v[6:9]
	ds_read_b128 v[140:143], v219 offset:2048
	v_mfma_f32_16x16x32_bf16 v[10:13], v[192:195], v[168:171], v[10:13]
	ds_read_b128 v[144:147], v219 offset:4096
	v_mfma_f32_16x16x32_bf16 v[14:17], v[196:199], v[168:171], v[14:17]
	ds_read_b128 v[148:151], v219 offset:6144
	v_mfma_f32_16x16x32_bf16 v[18:21], v[184:187], v[172:175], v[18:21]
	ds_read_b128 v[152:155], v231 offset:0
	v_mfma_f32_16x16x32_bf16 v[22:25], v[188:191], v[172:175], v[22:25]
	ds_read_b128 v[156:159], v231 offset:2048
	v_mfma_f32_16x16x32_bf16 v[26:29], v[192:195], v[172:175], v[26:29]
	ds_read_b128 v[160:163], v231 offset:4096
	v_mfma_f32_16x16x32_bf16 v[30:33], v[196:199], v[172:175], v[30:33]
	ds_read_b128 v[164:167], v231 offset:6144
	s_mov_b32 m0, s8
	v_mfma_f32_16x16x32_bf16 v[34:37], v[184:187], v[176:179], v[34:37]
	global_load_lds_dwordx4 v200, s[4:5]
	s_add_u32 m0, s8, 0x400
	v_mfma_f32_16x16x32_bf16 v[38:41], v[188:191], v[176:179], v[38:41]
	global_load_lds_dwordx4 v201, s[4:5]
	s_add_u32 m0, s8, 0x800
	v_mfma_f32_16x16x32_bf16 v[42:45], v[192:195], v[176:179], v[42:45]
	global_load_lds_dwordx4 v202, s[4:5]
	s_add_u32 m0, s8, 0xc00
	v_mfma_f32_16x16x32_bf16 v[46:49], v[196:199], v[176:179], v[46:49]
	global_load_lds_dwordx4 v203, s[4:5]
	s_mov_b32 m0, s9
	v_mfma_f32_16x16x32_bf16 v[50:53], v[184:187], v[180:183], v[50:53]
	global_load_lds_dwordx4 v204, s[6:7]
	s_add_u32 m0, s9, 0x400
	v_mfma_f32_16x16x32_bf16 v[54:57], v[188:191], v[180:183], v[54:57]
	global_load_lds_dwordx4 v205, s[6:7]
	v_mfma_f32_16x16x32_bf16 v[58:61], v[192:195], v[180:183], v[58:61]
	s_sub_u32 s4, s4, 0x780
	s_subb_u32 s5, s5, 0
	v_mfma_f32_16x16x32_bf16 v[62:65], v[196:199], v[180:183], v[62:65]
	s_add_u32 s6, s6, 0x3f880
	s_addc_u32 s7, s7, 0
	s_waitcnt lgkmcnt(0)
	v_mfma_f32_16x16x32_bf16 v[2:5], v[152:155], v[136:139], v[2:5]
	ds_read_b128 v[168:171], v228 offset:0
	v_mfma_f32_16x16x32_bf16 v[6:9], v[156:159], v[136:139], v[6:9]
	ds_read_b128 v[172:175], v228 offset:2048
	v_mfma_f32_16x16x32_bf16 v[10:13], v[160:163], v[136:139], v[10:13]
	ds_read_b128 v[176:179], v228 offset:4096
	v_mfma_f32_16x16x32_bf16 v[14:17], v[164:167], v[136:139], v[14:17]
	ds_read_b128 v[180:183], v228 offset:6144
	v_mfma_f32_16x16x32_bf16 v[18:21], v[152:155], v[140:143], v[18:21]
	ds_read_b128 v[184:187], v234 offset:0
	v_mfma_f32_16x16x32_bf16 v[22:25], v[156:159], v[140:143], v[22:25]
	ds_read_b128 v[188:191], v234 offset:2048
	v_mfma_f32_16x16x32_bf16 v[26:29], v[160:163], v[140:143], v[26:29]
	ds_read_b128 v[192:195], v234 offset:4096
	v_mfma_f32_16x16x32_bf16 v[30:33], v[164:167], v[140:143], v[30:33]
	ds_read_b128 v[196:199], v234 offset:6144
	v_mfma_f32_16x16x32_bf16 v[34:37], v[152:155], v[144:147], v[34:37]
	v_mfma_f32_16x16x32_bf16 v[38:41], v[156:159], v[144:147], v[38:41]
	v_mfma_f32_16x16x32_bf16 v[42:45], v[160:163], v[144:147], v[42:45]
	v_mfma_f32_16x16x32_bf16 v[46:49], v[164:167], v[144:147], v[46:49]
	v_mfma_f32_16x16x32_bf16 v[50:53], v[152:155], v[148:151], v[50:53]
	v_mfma_f32_16x16x32_bf16 v[54:57], v[156:159], v[148:151], v[54:57]
	v_mfma_f32_16x16x32_bf16 v[58:61], v[160:163], v[148:151], v[58:61]
	v_mfma_f32_16x16x32_bf16 v[62:65], v[164:167], v[148:151], v[62:65]
	s_waitcnt vmcnt(6) lgkmcnt(0)
	s_barrier
	v_mfma_f32_16x16x32_bf16 v[2:5], v[184:187], v[168:171], v[2:5]
	ds_read_b128 v[136:139], v224 offset:0
	v_mfma_f32_16x16x32_bf16 v[6:9], v[188:191], v[168:171], v[6:9]
	ds_read_b128 v[140:143], v224 offset:2048
	v_mfma_f32_16x16x32_bf16 v[10:13], v[192:195], v[168:171], v[10:13]
	ds_read_b128 v[144:147], v224 offset:4096
	v_mfma_f32_16x16x32_bf16 v[14:17], v[196:199], v[168:171], v[14:17]
	ds_read_b128 v[148:151], v224 offset:6144
	v_mfma_f32_16x16x32_bf16 v[18:21], v[184:187], v[172:175], v[18:21]
	ds_read_b128 v[152:155], v232 offset:0
	v_mfma_f32_16x16x32_bf16 v[22:25], v[188:191], v[172:175], v[22:25]
	ds_read_b128 v[156:159], v232 offset:2048
	v_mfma_f32_16x16x32_bf16 v[26:29], v[192:195], v[172:175], v[26:29]
	ds_read_b128 v[160:163], v232 offset:4096
	v_mfma_f32_16x16x32_bf16 v[30:33], v[196:199], v[172:175], v[30:33]
	ds_read_b128 v[164:167], v232 offset:6144
	s_add_u32 m0, s8, 0xc000
	v_mfma_f32_16x16x32_bf16 v[34:37], v[184:187], v[176:179], v[34:37]
	global_load_lds_dwordx4 v200, s[4:5]
	s_add_u32 m0, s8, 0xc400
	v_mfma_f32_16x16x32_bf16 v[38:41], v[188:191], v[176:179], v[38:41]
	global_load_lds_dwordx4 v201, s[4:5]
	s_add_u32 m0, s8, 0xc800
	v_mfma_f32_16x16x32_bf16 v[42:45], v[192:195], v[176:179], v[42:45]
	global_load_lds_dwordx4 v202, s[4:5]
	s_add_u32 m0, s8, 0xcc00
	v_mfma_f32_16x16x32_bf16 v[46:49], v[196:199], v[176:179], v[46:49]
	global_load_lds_dwordx4 v203, s[4:5]
	s_add_u32 m0, s9, 0xc000
	v_mfma_f32_16x16x32_bf16 v[50:53], v[184:187], v[180:183], v[50:53]
	global_load_lds_dwordx4 v204, s[6:7]
	s_add_u32 m0, s9, 0xc400
	v_mfma_f32_16x16x32_bf16 v[54:57], v[188:191], v[180:183], v[54:57]
	global_load_lds_dwordx4 v205, s[6:7]
	v_mfma_f32_16x16x32_bf16 v[58:61], v[192:195], v[180:183], v[58:61]
	s_add_u32 s4, s4, 0x80
	s_addc_u32 s5, s5, 0
	v_mfma_f32_16x16x32_bf16 v[62:65], v[196:199], v[180:183], v[62:65]
	s_add_u32 s6, s6, 0x80
	s_addc_u32 s7, s7, 0
	s_waitcnt lgkmcnt(0)
	v_mfma_f32_16x16x32_bf16 v[2:5], v[152:155], v[136:139], v[2:5]
	ds_read_b128 v[168:171], v229 offset:0
	v_mfma_f32_16x16x32_bf16 v[6:9], v[156:159], v[136:139], v[6:9]
	ds_read_b128 v[172:175], v229 offset:2048
	v_mfma_f32_16x16x32_bf16 v[10:13], v[160:163], v[136:139], v[10:13]
	ds_read_b128 v[176:179], v229 offset:4096
	v_mfma_f32_16x16x32_bf16 v[14:17], v[164:167], v[136:139], v[14:17]
	ds_read_b128 v[180:183], v229 offset:6144
	v_mfma_f32_16x16x32_bf16 v[18:21], v[152:155], v[140:143], v[18:21]
	ds_read_b128 v[184:187], v235 offset:0
	v_mfma_f32_16x16x32_bf16 v[22:25], v[156:159], v[140:143], v[22:25]
	ds_read_b128 v[188:191], v235 offset:2048
	v_mfma_f32_16x16x32_bf16 v[26:29], v[160:163], v[140:143], v[26:29]
	ds_read_b128 v[192:195], v235 offset:4096
	v_mfma_f32_16x16x32_bf16 v[30:33], v[164:167], v[140:143], v[30:33]
	ds_read_b128 v[196:199], v235 offset:6144
	v_mfma_f32_16x16x32_bf16 v[34:37], v[152:155], v[144:147], v[34:37]
	v_mfma_f32_16x16x32_bf16 v[38:41], v[156:159], v[144:147], v[38:41]
	v_mfma_f32_16x16x32_bf16 v[42:45], v[160:163], v[144:147], v[42:45]
	v_mfma_f32_16x16x32_bf16 v[46:49], v[164:167], v[144:147], v[46:49]
	v_mfma_f32_16x16x32_bf16 v[50:53], v[152:155], v[148:151], v[50:53]
	v_mfma_f32_16x16x32_bf16 v[54:57], v[156:159], v[148:151], v[54:57]
	v_mfma_f32_16x16x32_bf16 v[58:61], v[160:163], v[148:151], v[58:61]
	v_mfma_f32_16x16x32_bf16 v[62:65], v[164:167], v[148:151], v[62:65]
	s_waitcnt vmcnt(6) lgkmcnt(0)
	s_barrier
	v_mfma_f32_16x16x32_bf16 v[2:5], v[184:187], v[168:171], v[2:5]
	ds_read_b128 v[136:139], v218 offset:0
	v_mfma_f32_16x16x32_bf16 v[6:9], v[188:191], v[168:171], v[6:9]
	ds_read_b128 v[140:143], v218 offset:2048
	v_mfma_f32_16x16x32_bf16 v[10:13], v[192:195], v[168:171], v[10:13]
	ds_read_b128 v[144:147], v218 offset:4096
	v_mfma_f32_16x16x32_bf16 v[14:17], v[196:199], v[168:171], v[14:17]
	ds_read_b128 v[148:151], v218 offset:6144
	v_mfma_f32_16x16x32_bf16 v[18:21], v[184:187], v[172:175], v[18:21]
	ds_read_b128 v[152:155], v230 offset:0
	v_mfma_f32_16x16x32_bf16 v[22:25], v[188:191], v[172:175], v[22:25]
	ds_read_b128 v[156:159], v230 offset:2048
	v_mfma_f32_16x16x32_bf16 v[26:29], v[192:195], v[172:175], v[26:29]
	ds_read_b128 v[160:163], v230 offset:4096
	v_mfma_f32_16x16x32_bf16 v[30:33], v[196:199], v[172:175], v[30:33]
	ds_read_b128 v[164:167], v230 offset:6144
	s_add_u32 m0, s8, 0x18000
	v_mfma_f32_16x16x32_bf16 v[34:37], v[184:187], v[176:179], v[34:37]
	global_load_lds_dwordx4 v200, s[4:5]
	s_add_u32 m0, s8, 0x18400
	v_mfma_f32_16x16x32_bf16 v[38:41], v[188:191], v[176:179], v[38:41]
	global_load_lds_dwordx4 v201, s[4:5]
	s_add_u32 m0, s8, 0x18800
	v_mfma_f32_16x16x32_bf16 v[42:45], v[192:195], v[176:179], v[42:45]
	global_load_lds_dwordx4 v202, s[4:5]
	s_add_u32 m0, s8, 0x18c00
	v_mfma_f32_16x16x32_bf16 v[46:49], v[196:199], v[176:179], v[46:49]
	global_load_lds_dwordx4 v203, s[4:5]
	s_add_u32 m0, s9, 0x18000
	v_mfma_f32_16x16x32_bf16 v[50:53], v[184:187], v[180:183], v[50:53]
	global_load_lds_dwordx4 v204, s[6:7]
	s_add_u32 m0, s9, 0x18400
	v_mfma_f32_16x16x32_bf16 v[54:57], v[188:191], v[180:183], v[54:57]
	global_load_lds_dwordx4 v205, s[6:7]
	v_mfma_f32_16x16x32_bf16 v[58:61], v[192:195], v[180:183], v[58:61]
	s_add_u32 s4, s4, 0x80
	s_addc_u32 s5, s5, 0
	v_mfma_f32_16x16x32_bf16 v[62:65], v[196:199], v[180:183], v[62:65]
	s_add_u32 s6, s6, 0x80
	s_addc_u32 s7, s7, 0
	s_waitcnt lgkmcnt(0)
	v_mfma_f32_16x16x32_bf16 v[2:5], v[152:155], v[136:139], v[2:5]
	ds_read_b128 v[168:171], v225 offset:0
	v_mfma_f32_16x16x32_bf16 v[6:9], v[156:159], v[136:139], v[6:9]
	ds_read_b128 v[172:175], v225 offset:2048
	v_mfma_f32_16x16x32_bf16 v[10:13], v[160:163], v[136:139], v[10:13]
	ds_read_b128 v[176:179], v225 offset:4096
	v_mfma_f32_16x16x32_bf16 v[14:17], v[164:167], v[136:139], v[14:17]
	ds_read_b128 v[180:183], v225 offset:6144
	v_mfma_f32_16x16x32_bf16 v[18:21], v[152:155], v[140:143], v[18:21]
	ds_read_b128 v[184:187], v233 offset:0
	v_mfma_f32_16x16x32_bf16 v[22:25], v[156:159], v[140:143], v[22:25]
	ds_read_b128 v[188:191], v233 offset:2048
	v_mfma_f32_16x16x32_bf16 v[26:29], v[160:163], v[140:143], v[26:29]
	ds_read_b128 v[192:195], v233 offset:4096
	v_mfma_f32_16x16x32_bf16 v[30:33], v[164:167], v[140:143], v[30:33]
	ds_read_b128 v[196:199], v233 offset:6144
	v_mfma_f32_16x16x32_bf16 v[34:37], v[152:155], v[144:147], v[34:37]
	v_mfma_f32_16x16x32_bf16 v[38:41], v[156:159], v[144:147], v[38:41]
	v_mfma_f32_16x16x32_bf16 v[42:45], v[160:163], v[144:147], v[42:45]
	v_mfma_f32_16x16x32_bf16 v[46:49], v[164:167], v[144:147], v[46:49]
	v_mfma_f32_16x16x32_bf16 v[50:53], v[152:155], v[148:151], v[50:53]
	v_mfma_f32_16x16x32_bf16 v[54:57], v[156:159], v[148:151], v[54:57]
	v_mfma_f32_16x16x32_bf16 v[58:61], v[160:163], v[148:151], v[58:61]
	v_mfma_f32_16x16x32_bf16 v[62:65], v[164:167], v[148:151], v[62:65]
	s_waitcnt vmcnt(6) lgkmcnt(0)
	s_barrier
	v_mfma_f32_16x16x32_bf16 v[2:5], v[184:187], v[168:171], v[2:5]
	ds_read_b128 v[136:139], v219 offset:0
	v_mfma_f32_16x16x32_bf16 v[6:9], v[188:191], v[168:171], v[6:9]
	ds_read_b128 v[140:143], v219 offset:2048
	v_mfma_f32_16x16x32_bf16 v[10:13], v[192:195], v[168:171], v[10:13]
	ds_read_b128 v[144:147], v219 offset:4096
	v_mfma_f32_16x16x32_bf16 v[14:17], v[196:199], v[168:171], v[14:17]
	ds_read_b128 v[148:151], v219 offset:6144
	v_mfma_f32_16x16x32_bf16 v[18:21], v[184:187], v[172:175], v[18:21]
	ds_read_b128 v[152:155], v231 offset:0
	v_mfma_f32_16x16x32_bf16 v[22:25], v[188:191], v[172:175], v[22:25]
	ds_read_b128 v[156:159], v231 offset:2048
	v_mfma_f32_16x16x32_bf16 v[26:29], v[192:195], v[172:175], v[26:29]
	ds_read_b128 v[160:163], v231 offset:4096
	v_mfma_f32_16x16x32_bf16 v[30:33], v[196:199], v[172:175], v[30:33]
	ds_read_b128 v[164:167], v231 offset:6144
	s_mov_b32 m0, s8
	v_mfma_f32_16x16x32_bf16 v[34:37], v[184:187], v[176:179], v[34:37]
	global_load_lds_dwordx4 v200, s[4:5]
	s_add_u32 m0, s8, 0x400
	v_mfma_f32_16x16x32_bf16 v[38:41], v[188:191], v[176:179], v[38:41]
	global_load_lds_dwordx4 v201, s[4:5]
	s_add_u32 m0, s8, 0x800
	v_mfma_f32_16x16x32_bf16 v[42:45], v[192:195], v[176:179], v[42:45]
	global_load_lds_dwordx4 v202, s[4:5]
	s_add_u32 m0, s8, 0xc00
	v_mfma_f32_16x16x32_bf16 v[46:49], v[196:199], v[176:179], v[46:49]
	global_load_lds_dwordx4 v203, s[4:5]
	s_mov_b32 m0, s9
	v_mfma_f32_16x16x32_bf16 v[50:53], v[184:187], v[180:183], v[50:53]
	global_load_lds_dwordx4 v204, s[6:7]
	s_add_u32 m0, s9, 0x400
	v_mfma_f32_16x16x32_bf16 v[54:57], v[188:191], v[180:183], v[54:57]
	global_load_lds_dwordx4 v205, s[6:7]
	v_mfma_f32_16x16x32_bf16 v[58:61], v[192:195], v[180:183], v[58:61]
	s_add_u32 s4, s4, 0x80
	s_addc_u32 s5, s5, 0
	v_mfma_f32_16x16x32_bf16 v[62:65], v[196:199], v[180:183], v[62:65]
	s_add_u32 s6, s6, 0x80
	s_addc_u32 s7, s7, 0
	s_waitcnt lgkmcnt(0)
	v_mfma_f32_16x16x32_bf16 v[66:69], v[152:155], v[136:139], 0
	ds_read_b128 v[168:171], v228 offset:0
	v_mfma_f32_16x16x32_bf16 v[70:73], v[156:159], v[136:139], 0
	ds_read_b128 v[172:175], v228 offset:2048
	s_add_u32 s10, s28, s13
	s_addc_u32 s11, s29, 0
	v_mfma_f32_16x16x32_bf16 v[74:77], v[160:163], v[136:139], 0
	ds_read_b128 v[176:179], v228 offset:4096
	s_add_u32 s13, s13, 0x10000
	v_mfma_f32_16x16x32_bf16 v[78:81], v[164:167], v[136:139], 0
	ds_read_b128 v[180:183], v228 offset:6144
	v_mul_f32_e32 v2, s12, v2
	v_mfma_f32_16x16x32_bf16 v[82:85], v[152:155], v[140:143], 0
	ds_read_b128 v[184:187], v234 offset:0
	v_mfma_f32_16x16x32_bf16 v[86:89], v[156:159], v[140:143], 0
	ds_read_b128 v[188:191], v234 offset:2048
	v_mul_f32_e32 v3, s12, v3
	v_mfma_f32_16x16x32_bf16 v[90:93], v[160:163], v[140:143], 0
	ds_read_b128 v[192:195], v234 offset:4096
	v_mul_f32_e32 v4, s12, v4
	v_mfma_f32_16x16x32_bf16 v[94:97], v[164:167], v[140:143], 0
	ds_read_b128 v[196:199], v234 offset:6144
	v_mul_f32_e32 v5, s12, v5
	v_mfma_f32_16x16x32_bf16 v[98:101], v[152:155], v[144:147], 0
	v_mfma_f32_16x16x32_bf16 v[102:105], v[156:159], v[144:147], 0
	v_mul_f32_e32 v6, s12, v6
	v_mfma_f32_16x16x32_bf16 v[106:109], v[160:163], v[144:147], 0
	v_mul_f32_e32 v7, s12, v7
	v_mfma_f32_16x16x32_bf16 v[110:113], v[164:167], v[144:147], 0
	v_mul_f32_e32 v8, s12, v8
	v_mfma_f32_16x16x32_bf16 v[114:117], v[152:155], v[148:151], 0
	v_mfma_f32_16x16x32_bf16 v[118:121], v[156:159], v[148:151], 0
	v_mul_f32_e32 v9, s12, v9
	v_mfma_f32_16x16x32_bf16 v[122:125], v[160:163], v[148:151], 0
	v_exp_f32_e32 v2, v2
	v_mfma_f32_16x16x32_bf16 v[126:129], v[164:167], v[148:151], 0
	v_exp_f32_e32 v3, v3
	s_waitcnt vmcnt(6) lgkmcnt(0)
	s_barrier
	v_mfma_f32_16x16x32_bf16 v[66:69], v[184:187], v[168:171], v[66:69]
	ds_read_b128 v[136:139], v224 offset:0
	v_mfma_f32_16x16x32_bf16 v[70:73], v[188:191], v[168:171], v[70:73]
	ds_read_b128 v[140:143], v224 offset:2048
	v_mfma_f32_16x16x32_bf16 v[74:77], v[192:195], v[168:171], v[74:77]
	ds_read_b128 v[144:147], v224 offset:4096
	v_exp_f32_e32 v4, v4
	v_mfma_f32_16x16x32_bf16 v[78:81], v[196:199], v[168:171], v[78:81]
	ds_read_b128 v[148:151], v224 offset:6144
	v_mfma_f32_16x16x32_bf16 v[82:85], v[184:187], v[172:175], v[82:85]
	ds_read_b128 v[152:155], v232 offset:0
	v_exp_f32_e32 v5, v5
	v_mfma_f32_16x16x32_bf16 v[86:89], v[188:191], v[172:175], v[86:89]
	ds_read_b128 v[156:159], v232 offset:2048
	v_mfma_f32_16x16x32_bf16 v[90:93], v[192:195], v[172:175], v[90:93]
	ds_read_b128 v[160:163], v232 offset:4096
	v_exp_f32_e32 v6, v6
	v_mfma_f32_16x16x32_bf16 v[94:97], v[196:199], v[172:175], v[94:97]
	ds_read_b128 v[164:167], v232 offset:6144
	s_add_u32 m0, s8, 0xc000
	v_mfma_f32_16x16x32_bf16 v[98:101], v[184:187], v[176:179], v[98:101]
	global_load_lds_dwordx4 v200, s[4:5]
	s_add_u32 m0, s8, 0xc400
	v_mfma_f32_16x16x32_bf16 v[102:105], v[188:191], v[176:179], v[102:105]
	global_load_lds_dwordx4 v201, s[4:5]
	v_exp_f32_e32 v7, v7
	s_add_u32 m0, s8, 0xc800
	v_mfma_f32_16x16x32_bf16 v[106:109], v[192:195], v[176:179], v[106:109]
	global_load_lds_dwordx4 v202, s[4:5]
	s_add_u32 m0, s8, 0xcc00
	v_mfma_f32_16x16x32_bf16 v[110:113], v[196:199], v[176:179], v[110:113]
	global_load_lds_dwordx4 v203, s[4:5]
	v_exp_f32_e32 v8, v8
	s_add_u32 m0, s9, 0xc000
	v_mfma_f32_16x16x32_bf16 v[114:117], v[184:187], v[180:183], v[114:117]
	global_load_lds_dwordx4 v204, s[6:7]
	s_add_u32 m0, s9, 0xc400
	v_mfma_f32_16x16x32_bf16 v[118:121], v[188:191], v[180:183], v[118:121]
	global_load_lds_dwordx4 v205, s[6:7]
	v_exp_f32_e32 v9, v9
	v_mfma_f32_16x16x32_bf16 v[122:125], v[192:195], v[180:183], v[122:125]
	s_add_u32 s4, s4, 0x80
	s_addc_u32 s5, s5, 0
	v_mfma_f32_16x16x32_bf16 v[126:129], v[196:199], v[180:183], v[126:129]
	s_add_u32 s6, s6, 0x80
	s_addc_u32 s7, s7, 0
	v_add_f32_e32 v2, 1.0, v2
	s_waitcnt lgkmcnt(0)
	v_mfma_f32_16x16x32_bf16 v[66:69], v[152:155], v[136:139], v[66:69]
	ds_read_b128 v[168:171], v229 offset:0
	v_mfma_f32_16x16x32_bf16 v[70:73], v[156:159], v[136:139], v[70:73]
	ds_read_b128 v[172:175], v229 offset:2048
	v_add_f32_e32 v3, 1.0, v3
	v_mfma_f32_16x16x32_bf16 v[74:77], v[160:163], v[136:139], v[74:77]
	ds_read_b128 v[176:179], v229 offset:4096
	v_add_f32_e32 v4, 1.0, v4
	v_mfma_f32_16x16x32_bf16 v[78:81], v[164:167], v[136:139], v[78:81]
	ds_read_b128 v[180:183], v229 offset:6144
	v_add_f32_e32 v5, 1.0, v5
	v_mfma_f32_16x16x32_bf16 v[82:85], v[152:155], v[140:143], v[82:85]
	ds_read_b128 v[184:187], v235 offset:0
	v_mfma_f32_16x16x32_bf16 v[86:89], v[156:159], v[140:143], v[86:89]
	ds_read_b128 v[188:191], v235 offset:2048
	v_add_f32_e32 v6, 1.0, v6
	v_mfma_f32_16x16x32_bf16 v[90:93], v[160:163], v[140:143], v[90:93]
	ds_read_b128 v[192:195], v235 offset:4096
	v_add_f32_e32 v7, 1.0, v7
	v_mfma_f32_16x16x32_bf16 v[94:97], v[164:167], v[140:143], v[94:97]
	ds_read_b128 v[196:199], v235 offset:6144
	v_add_f32_e32 v8, 1.0, v8
	v_mfma_f32_16x16x32_bf16 v[98:101], v[152:155], v[144:147], v[98:101]
	v_mfma_f32_16x16x32_bf16 v[102:105], v[156:159], v[144:147], v[102:105]
	v_add_f32_e32 v9, 1.0, v9
	v_mfma_f32_16x16x32_bf16 v[106:109], v[160:163], v[144:147], v[106:109]
	v_rcp_f32_e32 v2, v2
	v_mfma_f32_16x16x32_bf16 v[110:113], v[164:167], v[144:147], v[110:113]
	v_rcp_f32_e32 v3, v3
	v_mfma_f32_16x16x32_bf16 v[114:117], v[152:155], v[148:151], v[114:117]
	v_mfma_f32_16x16x32_bf16 v[118:121], v[156:159], v[148:151], v[118:121]
	v_rcp_f32_e32 v4, v4
	v_mfma_f32_16x16x32_bf16 v[122:125], v[160:163], v[148:151], v[122:125]
	v_rcp_f32_e32 v5, v5
	v_mfma_f32_16x16x32_bf16 v[126:129], v[164:167], v[148:151], v[126:129]
	v_rcp_f32_e32 v6, v6
	s_waitcnt vmcnt(6) lgkmcnt(0)
	s_barrier
	v_mfma_f32_16x16x32_bf16 v[66:69], v[184:187], v[168:171], v[66:69]
	ds_read_b128 v[136:139], v218 offset:0
	v_mfma_f32_16x16x32_bf16 v[70:73], v[188:191], v[168:171], v[70:73]
	ds_read_b128 v[140:143], v218 offset:2048
	v_mfma_f32_16x16x32_bf16 v[74:77], v[192:195], v[168:171], v[74:77]
	ds_read_b128 v[144:147], v218 offset:4096
	v_rcp_f32_e32 v7, v7
	v_mfma_f32_16x16x32_bf16 v[78:81], v[196:199], v[168:171], v[78:81]
	ds_read_b128 v[148:151], v218 offset:6144
	v_mfma_f32_16x16x32_bf16 v[82:85], v[184:187], v[172:175], v[82:85]
	ds_read_b128 v[152:155], v230 offset:0
	v_rcp_f32_e32 v8, v8
	v_mfma_f32_16x16x32_bf16 v[86:89], v[188:191], v[172:175], v[86:89]
	ds_read_b128 v[156:159], v230 offset:2048
	v_mfma_f32_16x16x32_bf16 v[90:93], v[192:195], v[172:175], v[90:93]
	ds_read_b128 v[160:163], v230 offset:4096
	v_rcp_f32_e32 v9, v9
	v_mfma_f32_16x16x32_bf16 v[94:97], v[196:199], v[172:175], v[94:97]
	ds_read_b128 v[164:167], v230 offset:6144
	s_add_u32 m0, s8, 0x18000
	v_mfma_f32_16x16x32_bf16 v[98:101], v[184:187], v[176:179], v[98:101]
	global_load_lds_dwordx4 v200, s[4:5]
	s_add_u32 m0, s8, 0x18400
	v_mfma_f32_16x16x32_bf16 v[102:105], v[188:191], v[176:179], v[102:105]
	global_load_lds_dwordx4 v201, s[4:5]
	v_cvt_pk_bf16_f32 v2, v2, v3
	s_add_u32 m0, s8, 0x18800
	v_mfma_f32_16x16x32_bf16 v[106:109], v[192:195], v[176:179], v[106:109]
	global_load_lds_dwordx4 v202, s[4:5]
	s_add_u32 m0, s8, 0x18c00
	v_mfma_f32_16x16x32_bf16 v[110:113], v[196:199], v[176:179], v[110:113]
	global_load_lds_dwordx4 v203, s[4:5]
	v_cvt_pk_bf16_f32 v3, v4, v5
	s_add_u32 m0, s9, 0x18000
	v_mfma_f32_16x16x32_bf16 v[114:117], v[184:187], v[180:183], v[114:117]
	global_load_lds_dwordx4 v204, s[6:7]
	s_add_u32 m0, s9, 0x18400
	v_mfma_f32_16x16x32_bf16 v[118:121], v[188:191], v[180:183], v[118:121]
	global_load_lds_dwordx4 v205, s[6:7]
	v_cvt_pk_bf16_f32 v4, v6, v7
	v_mfma_f32_16x16x32_bf16 v[122:125], v[192:195], v[180:183], v[122:125]
	s_add_u32 s4, s4, 0x80
	s_addc_u32 s5, s5, 0
	v_mfma_f32_16x16x32_bf16 v[126:129], v[196:199], v[180:183], v[126:129]
	s_add_u32 s6, s6, 0x80
	s_addc_u32 s7, s7, 0
	v_cvt_pk_bf16_f32 v5, v8, v9
	s_waitcnt lgkmcnt(0)
	v_mfma_f32_16x16x32_bf16 v[66:69], v[152:155], v[136:139], v[66:69]
	ds_read_b128 v[168:171], v225 offset:0
	v_mfma_f32_16x16x32_bf16 v[70:73], v[156:159], v[136:139], v[70:73]
	ds_read_b128 v[172:175], v225 offset:2048
	global_store_dwordx4 v240, v[2:5], s[10:11] offset:0
	v_mfma_f32_16x16x32_bf16 v[74:77], v[160:163], v[136:139], v[74:77]
	ds_read_b128 v[176:179], v225 offset:4096
	v_mul_f32_e32 v10, s12, v10
	v_mfma_f32_16x16x32_bf16 v[78:81], v[164:167], v[136:139], v[78:81]
	ds_read_b128 v[180:183], v225 offset:6144
	v_mul_f32_e32 v11, s12, v11
	v_mfma_f32_16x16x32_bf16 v[82:85], v[152:155], v[140:143], v[82:85]
	ds_read_b128 v[184:187], v233 offset:0
	v_mfma_f32_16x16x32_bf16 v[86:89], v[156:159], v[140:143], v[86:89]
	ds_read_b128 v[188:191], v233 offset:2048
	v_mul_f32_e32 v12, s12, v12
	v_mfma_f32_16x16x32_bf16 v[90:93], v[160:163], v[140:143], v[90:93]
	ds_read_b128 v[192:195], v233 offset:4096
	v_mul_f32_e32 v13, s12, v13
	v_mfma_f32_16x16x32_bf16 v[94:97], v[164:167], v[140:143], v[94:97]
	ds_read_b128 v[196:199], v233 offset:6144
	v_mul_f32_e32 v14, s12, v14
	v_mfma_f32_16x16x32_bf16 v[98:101], v[152:155], v[144:147], v[98:101]
	v_mfma_f32_16x16x32_bf16 v[102:105], v[156:159], v[144:147], v[102:105]
	v_mul_f32_e32 v15, s12, v15
	v_mfma_f32_16x16x32_bf16 v[106:109], v[160:163], v[144:147], v[106:109]
	v_mul_f32_e32 v16, s12, v16
	v_mfma_f32_16x16x32_bf16 v[110:113], v[164:167], v[144:147], v[110:113]
	v_mul_f32_e32 v17, s12, v17
	v_mfma_f32_16x16x32_bf16 v[114:117], v[152:155], v[148:151], v[114:117]
	v_mfma_f32_16x16x32_bf16 v[118:121], v[156:159], v[148:151], v[118:121]
	v_exp_f32_e32 v10, v10
	v_mfma_f32_16x16x32_bf16 v[122:125], v[160:163], v[148:151], v[122:125]
	v_exp_f32_e32 v11, v11
	v_mfma_f32_16x16x32_bf16 v[126:129], v[164:167], v[148:151], v[126:129]
	v_exp_f32_e32 v12, v12
	s_waitcnt vmcnt(7) lgkmcnt(0)
	s_barrier
	v_mfma_f32_16x16x32_bf16 v[66:69], v[184:187], v[168:171], v[66:69]
	ds_read_b128 v[136:139], v219 offset:0
	v_mfma_f32_16x16x32_bf16 v[70:73], v[188:191], v[168:171], v[70:73]
	ds_read_b128 v[140:143], v219 offset:2048
	v_mfma_f32_16x16x32_bf16 v[74:77], v[192:195], v[168:171], v[74:77]
	ds_read_b128 v[144:147], v219 offset:4096
	v_exp_f32_e32 v13, v13
	v_mfma_f32_16x16x32_bf16 v[78:81], v[196:199], v[168:171], v[78:81]
	ds_read_b128 v[148:151], v219 offset:6144
	v_mfma_f32_16x16x32_bf16 v[82:85], v[184:187], v[172:175], v[82:85]
	ds_read_b128 v[152:155], v231 offset:0
	v_exp_f32_e32 v14, v14
	v_mfma_f32_16x16x32_bf16 v[86:89], v[188:191], v[172:175], v[86:89]
	ds_read_b128 v[156:159], v231 offset:2048
	v_mfma_f32_16x16x32_bf16 v[90:93], v[192:195], v[172:175], v[90:93]
	ds_read_b128 v[160:163], v231 offset:4096
	v_exp_f32_e32 v15, v15
	v_mfma_f32_16x16x32_bf16 v[94:97], v[196:199], v[172:175], v[94:97]
	ds_read_b128 v[164:167], v231 offset:6144
	s_mov_b32 m0, s8
	v_mfma_f32_16x16x32_bf16 v[98:101], v[184:187], v[176:179], v[98:101]
	global_load_lds_dwordx4 v200, s[4:5]
	s_add_u32 m0, s8, 0x400
	v_mfma_f32_16x16x32_bf16 v[102:105], v[188:191], v[176:179], v[102:105]
	global_load_lds_dwordx4 v201, s[4:5]
	v_exp_f32_e32 v16, v16
	s_add_u32 m0, s8, 0x800
	v_mfma_f32_16x16x32_bf16 v[106:109], v[192:195], v[176:179], v[106:109]
	global_load_lds_dwordx4 v202, s[4:5]
	s_add_u32 m0, s8, 0xc00
	v_mfma_f32_16x16x32_bf16 v[110:113], v[196:199], v[176:179], v[110:113]
	global_load_lds_dwordx4 v203, s[4:5]
	v_exp_f32_e32 v17, v17
	s_mov_b32 m0, s9
	v_mfma_f32_16x16x32_bf16 v[114:117], v[184:187], v[180:183], v[114:117]
	global_load_lds_dwordx4 v204, s[6:7]
	s_add_u32 m0, s9, 0x400
	v_mfma_f32_16x16x32_bf16 v[118:121], v[188:191], v[180:183], v[118:121]
	global_load_lds_dwordx4 v205, s[6:7]
	v_add_f32_e32 v10, 1.0, v10
	v_mfma_f32_16x16x32_bf16 v[122:125], v[192:195], v[180:183], v[122:125]
	s_add_u32 s4, s4, 0x80
	s_addc_u32 s5, s5, 0
	v_mfma_f32_16x16x32_bf16 v[126:129], v[196:199], v[180:183], v[126:129]
	s_add_u32 s6, s6, 0x80
	s_addc_u32 s7, s7, 0
	v_add_f32_e32 v11, 1.0, v11
	s_waitcnt lgkmcnt(0)
	v_mfma_f32_16x16x32_bf16 v[66:69], v[152:155], v[136:139], v[66:69]
	ds_read_b128 v[168:171], v228 offset:0
	v_mfma_f32_16x16x32_bf16 v[70:73], v[156:159], v[136:139], v[70:73]
	ds_read_b128 v[172:175], v228 offset:2048
	v_add_f32_e32 v12, 1.0, v12
	v_mfma_f32_16x16x32_bf16 v[74:77], v[160:163], v[136:139], v[74:77]
	ds_read_b128 v[176:179], v228 offset:4096
	v_add_f32_e32 v13, 1.0, v13
	v_mfma_f32_16x16x32_bf16 v[78:81], v[164:167], v[136:139], v[78:81]
	ds_read_b128 v[180:183], v228 offset:6144
	v_add_f32_e32 v14, 1.0, v14
	v_mfma_f32_16x16x32_bf16 v[82:85], v[152:155], v[140:143], v[82:85]
	ds_read_b128 v[184:187], v234 offset:0
	v_mfma_f32_16x16x32_bf16 v[86:89], v[156:159], v[140:143], v[86:89]
	ds_read_b128 v[188:191], v234 offset:2048
	v_add_f32_e32 v15, 1.0, v15
	v_mfma_f32_16x16x32_bf16 v[90:93], v[160:163], v[140:143], v[90:93]
	ds_read_b128 v[192:195], v234 offset:4096
	v_add_f32_e32 v16, 1.0, v16
	v_mfma_f32_16x16x32_bf16 v[94:97], v[164:167], v[140:143], v[94:97]
	ds_read_b128 v[196:199], v234 offset:6144
	v_add_f32_e32 v17, 1.0, v17
	v_mfma_f32_16x16x32_bf16 v[98:101], v[152:155], v[144:147], v[98:101]
	v_mfma_f32_16x16x32_bf16 v[102:105], v[156:159], v[144:147], v[102:105]
	v_rcp_f32_e32 v10, v10
	v_mfma_f32_16x16x32_bf16 v[106:109], v[160:163], v[144:147], v[106:109]
	v_rcp_f32_e32 v11, v11
	v_mfma_f32_16x16x32_bf16 v[110:113], v[164:167], v[144:147], v[110:113]
	v_rcp_f32_e32 v12, v12
	v_mfma_f32_16x16x32_bf16 v[114:117], v[152:155], v[148:151], v[114:117]
	v_mfma_f32_16x16x32_bf16 v[118:121], v[156:159], v[148:151], v[118:121]
	v_rcp_f32_e32 v13, v13
	v_mfma_f32_16x16x32_bf16 v[122:125], v[160:163], v[148:151], v[122:125]
	v_rcp_f32_e32 v14, v14
	v_mfma_f32_16x16x32_bf16 v[126:129], v[164:167], v[148:151], v[126:129]
	v_rcp_f32_e32 v15, v15
	s_waitcnt vmcnt(7) lgkmcnt(0)
	s_barrier
	v_mfma_f32_16x16x32_bf16 v[66:69], v[184:187], v[168:171], v[66:69]
	ds_read_b128 v[136:139], v224 offset:0
	v_mfma_f32_16x16x32_bf16 v[70:73], v[188:191], v[168:171], v[70:73]
	ds_read_b128 v[140:143], v224 offset:2048
	v_mfma_f32_16x16x32_bf16 v[74:77], v[192:195], v[168:171], v[74:77]
	ds_read_b128 v[144:147], v224 offset:4096
	v_rcp_f32_e32 v16, v16
	v_mfma_f32_16x16x32_bf16 v[78:81], v[196:199], v[168:171], v[78:81]
	ds_read_b128 v[148:151], v224 offset:6144
	v_mfma_f32_16x16x32_bf16 v[82:85], v[184:187], v[172:175], v[82:85]
	ds_read_b128 v[152:155], v232 offset:0
	v_rcp_f32_e32 v17, v17
	v_mfma_f32_16x16x32_bf16 v[86:89], v[188:191], v[172:175], v[86:89]
	ds_read_b128 v[156:159], v232 offset:2048
	v_mfma_f32_16x16x32_bf16 v[90:93], v[192:195], v[172:175], v[90:93]
	ds_read_b128 v[160:163], v232 offset:4096
	v_cvt_pk_bf16_f32 v10, v10, v11
	v_mfma_f32_16x16x32_bf16 v[94:97], v[196:199], v[172:175], v[94:97]
	ds_read_b128 v[164:167], v232 offset:6144
	s_add_u32 m0, s8, 0xc000
	v_mfma_f32_16x16x32_bf16 v[98:101], v[184:187], v[176:179], v[98:101]
	global_load_lds_dwordx4 v200, s[4:5]
	s_add_u32 m0, s8, 0xc400
	v_mfma_f32_16x16x32_bf16 v[102:105], v[188:191], v[176:179], v[102:105]
	global_load_lds_dwordx4 v201, s[4:5]
	v_cvt_pk_bf16_f32 v11, v12, v13
	s_add_u32 m0, s8, 0xc800
	v_mfma_f32_16x16x32_bf16 v[106:109], v[192:195], v[176:179], v[106:109]
	global_load_lds_dwordx4 v202, s[4:5]
	s_add_u32 m0, s8, 0xcc00
	v_mfma_f32_16x16x32_bf16 v[110:113], v[196:199], v[176:179], v[110:113]
	global_load_lds_dwordx4 v203, s[4:5]
	v_cvt_pk_bf16_f32 v12, v14, v15
	s_add_u32 m0, s9, 0xc000
	v_mfma_f32_16x16x32_bf16 v[114:117], v[184:187], v[180:183], v[114:117]
	global_load_lds_dwordx4 v204, s[6:7]
	s_add_u32 m0, s9, 0xc400
	v_mfma_f32_16x16x32_bf16 v[118:121], v[188:191], v[180:183], v[118:121]
	global_load_lds_dwordx4 v205, s[6:7]
	v_cvt_pk_bf16_f32 v13, v16, v17
	v_mfma_f32_16x16x32_bf16 v[122:125], v[192:195], v[180:183], v[122:125]
	s_add_u32 s4, s4, 0x80
	s_addc_u32 s5, s5, 0
	v_mfma_f32_16x16x32_bf16 v[126:129], v[196:199], v[180:183], v[126:129]
	s_add_u32 s6, s6, 0x80
	s_addc_u32 s7, s7, 0
	global_store_dwordx4 v240, v[10:13], s[10:11] offset:1024
	s_waitcnt lgkmcnt(0)
	v_mfma_f32_16x16x32_bf16 v[66:69], v[152:155], v[136:139], v[66:69]
	ds_read_b128 v[168:171], v229 offset:0
	v_mfma_f32_16x16x32_bf16 v[70:73], v[156:159], v[136:139], v[70:73]
	ds_read_b128 v[172:175], v229 offset:2048
	v_mul_f32_e32 v18, s12, v18
	v_mfma_f32_16x16x32_bf16 v[74:77], v[160:163], v[136:139], v[74:77]
	ds_read_b128 v[176:179], v229 offset:4096
	v_mul_f32_e32 v19, s12, v19
	v_mfma_f32_16x16x32_bf16 v[78:81], v[164:167], v[136:139], v[78:81]
	ds_read_b128 v[180:183], v229 offset:6144
	v_mul_f32_e32 v20, s12, v20
	v_mfma_f32_16x16x32_bf16 v[82:85], v[152:155], v[140:143], v[82:85]
	ds_read_b128 v[184:187], v235 offset:0
	v_mfma_f32_16x16x32_bf16 v[86:89], v[156:159], v[140:143], v[86:89]
	ds_read_b128 v[188:191], v235 offset:2048
	v_mul_f32_e32 v21, s12, v21
	v_mfma_f32_16x16x32_bf16 v[90:93], v[160:163], v[140:143], v[90:93]
	ds_read_b128 v[192:195], v235 offset:4096
	v_mul_f32_e32 v22, s12, v22
	v_mfma_f32_16x16x32_bf16 v[94:97], v[164:167], v[140:143], v[94:97]
	ds_read_b128 v[196:199], v235 offset:6144
	v_mul_f32_e32 v23, s12, v23
	v_mfma_f32_16x16x32_bf16 v[98:101], v[152:155], v[144:147], v[98:101]
	v_mfma_f32_16x16x32_bf16 v[102:105], v[156:159], v[144:147], v[102:105]
	v_mul_f32_e32 v24, s12, v24
	v_mfma_f32_16x16x32_bf16 v[106:109], v[160:163], v[144:147], v[106:109]
	v_mul_f32_e32 v25, s12, v25
	v_mfma_f32_16x16x32_bf16 v[110:113], v[164:167], v[144:147], v[110:113]
	v_exp_f32_e32 v18, v18
	v_mfma_f32_16x16x32_bf16 v[114:117], v[152:155], v[148:151], v[114:117]
	v_mfma_f32_16x16x32_bf16 v[118:121], v[156:159], v[148:151], v[118:121]
	v_exp_f32_e32 v19, v19
	v_mfma_f32_16x16x32_bf16 v[122:125], v[160:163], v[148:151], v[122:125]
	v_exp_f32_e32 v20, v20
	v_mfma_f32_16x16x32_bf16 v[126:129], v[164:167], v[148:151], v[126:129]
	v_exp_f32_e32 v21, v21
	s_waitcnt vmcnt(7) lgkmcnt(0)
	s_barrier
	v_mfma_f32_16x16x32_bf16 v[66:69], v[184:187], v[168:171], v[66:69]
	ds_read_b128 v[136:139], v218 offset:0
	v_mfma_f32_16x16x32_bf16 v[70:73], v[188:191], v[168:171], v[70:73]
	ds_read_b128 v[140:143], v218 offset:2048
	v_mfma_f32_16x16x32_bf16 v[74:77], v[192:195], v[168:171], v[74:77]
	ds_read_b128 v[144:147], v218 offset:4096
	v_exp_f32_e32 v22, v22
	v_mfma_f32_16x16x32_bf16 v[78:81], v[196:199], v[168:171], v[78:81]
	ds_read_b128 v[148:151], v218 offset:6144
	v_mfma_f32_16x16x32_bf16 v[82:85], v[184:187], v[172:175], v[82:85]
	ds_read_b128 v[152:155], v230 offset:0
	v_exp_f32_e32 v23, v23
	v_mfma_f32_16x16x32_bf16 v[86:89], v[188:191], v[172:175], v[86:89]
	ds_read_b128 v[156:159], v230 offset:2048
	v_mfma_f32_16x16x32_bf16 v[90:93], v[192:195], v[172:175], v[90:93]
	ds_read_b128 v[160:163], v230 offset:4096
	v_exp_f32_e32 v24, v24
	v_mfma_f32_16x16x32_bf16 v[94:97], v[196:199], v[172:175], v[94:97]
	ds_read_b128 v[164:167], v230 offset:6144
	s_add_u32 m0, s8, 0x18000
	v_mfma_f32_16x16x32_bf16 v[98:101], v[184:187], v[176:179], v[98:101]
	global_load_lds_dwordx4 v200, s[4:5]
	s_add_u32 m0, s8, 0x18400
	v_mfma_f32_16x16x32_bf16 v[102:105], v[188:191], v[176:179], v[102:105]
	global_load_lds_dwordx4 v201, s[4:5]
	v_exp_f32_e32 v25, v25
	s_add_u32 m0, s8, 0x18800
	v_mfma_f32_16x16x32_bf16 v[106:109], v[192:195], v[176:179], v[106:109]
	global_load_lds_dwordx4 v202, s[4:5]
	s_add_u32 m0, s8, 0x18c00
	v_mfma_f32_16x16x32_bf16 v[110:113], v[196:199], v[176:179], v[110:113]
	global_load_lds_dwordx4 v203, s[4:5]
	v_add_f32_e32 v18, 1.0, v18
	s_add_u32 m0, s9, 0x18000
	v_mfma_f32_16x16x32_bf16 v[114:117], v[184:187], v[180:183], v[114:117]
	global_load_lds_dwordx4 v204, s[6:7]
	s_add_u32 m0, s9, 0x18400
	v_mfma_f32_16x16x32_bf16 v[118:121], v[188:191], v[180:183], v[118:121]
	global_load_lds_dwordx4 v205, s[6:7]
	v_add_f32_e32 v19, 1.0, v19
	v_mfma_f32_16x16x32_bf16 v[122:125], v[192:195], v[180:183], v[122:125]
	s_add_u32 s4, s4, 0x80
	s_addc_u32 s5, s5, 0
	v_mfma_f32_16x16x32_bf16 v[126:129], v[196:199], v[180:183], v[126:129]
	s_add_u32 s6, s6, 0x80
	s_addc_u32 s7, s7, 0
	v_add_f32_e32 v20, 1.0, v20
	s_waitcnt lgkmcnt(0)
	v_mfma_f32_16x16x32_bf16 v[66:69], v[152:155], v[136:139], v[66:69]
	ds_read_b128 v[168:171], v225 offset:0
	v_mfma_f32_16x16x32_bf16 v[70:73], v[156:159], v[136:139], v[70:73]
	ds_read_b128 v[172:175], v225 offset:2048
	v_add_f32_e32 v21, 1.0, v21
	v_mfma_f32_16x16x32_bf16 v[74:77], v[160:163], v[136:139], v[74:77]
	ds_read_b128 v[176:179], v225 offset:4096
	v_add_f32_e32 v22, 1.0, v22
	v_mfma_f32_16x16x32_bf16 v[78:81], v[164:167], v[136:139], v[78:81]
	ds_read_b128 v[180:183], v225 offset:6144
	v_add_f32_e32 v23, 1.0, v23
	v_mfma_f32_16x16x32_bf16 v[82:85], v[152:155], v[140:143], v[82:85]
	ds_read_b128 v[184:187], v233 offset:0
	v_mfma_f32_16x16x32_bf16 v[86:89], v[156:159], v[140:143], v[86:89]
	ds_read_b128 v[188:191], v233 offset:2048
	v_add_f32_e32 v24, 1.0, v24
	v_mfma_f32_16x16x32_bf16 v[90:93], v[160:163], v[140:143], v[90:93]
	ds_read_b128 v[192:195], v233 offset:4096
	v_add_f32_e32 v25, 1.0, v25
	v_mfma_f32_16x16x32_bf16 v[94:97], v[164:167], v[140:143], v[94:97]
	ds_read_b128 v[196:199], v233 offset:6144
	v_rcp_f32_e32 v18, v18
	v_mfma_f32_16x16x32_bf16 v[98:101], v[152:155], v[144:147], v[98:101]
	v_mfma_f32_16x16x32_bf16 v[102:105], v[156:159], v[144:147], v[102:105]
	v_rcp_f32_e32 v19, v19
	v_mfma_f32_16x16x32_bf16 v[106:109], v[160:163], v[144:147], v[106:109]
	v_rcp_f32_e32 v20, v20
	v_mfma_f32_16x16x32_bf16 v[110:113], v[164:167], v[144:147], v[110:113]
	v_rcp_f32_e32 v21, v21
	v_mfma_f32_16x16x32_bf16 v[114:117], v[152:155], v[148:151], v[114:117]
	v_mfma_f32_16x16x32_bf16 v[118:121], v[156:159], v[148:151], v[118:121]
	v_rcp_f32_e32 v22, v22
	v_mfma_f32_16x16x32_bf16 v[122:125], v[160:163], v[148:151], v[122:125]
	v_rcp_f32_e32 v23, v23
	v_mfma_f32_16x16x32_bf16 v[126:129], v[164:167], v[148:151], v[126:129]
	v_rcp_f32_e32 v24, v24
	s_waitcnt vmcnt(7) lgkmcnt(0)
	s_barrier
	v_mfma_f32_16x16x32_bf16 v[66:69], v[184:187], v[168:171], v[66:69]
	ds_read_b128 v[136:139], v219 offset:0
	v_mfma_f32_16x16x32_bf16 v[70:73], v[188:191], v[168:171], v[70:73]
	ds_read_b128 v[140:143], v219 offset:2048
	v_mfma_f32_16x16x32_bf16 v[74:77], v[192:195], v[168:171], v[74:77]
	ds_read_b128 v[144:147], v219 offset:4096
	v_rcp_f32_e32 v25, v25
	v_mfma_f32_16x16x32_bf16 v[78:81], v[196:199], v[168:171], v[78:81]
	ds_read_b128 v[148:151], v219 offset:6144
	v_mfma_f32_16x16x32_bf16 v[82:85], v[184:187], v[172:175], v[82:85]
	ds_read_b128 v[152:155], v231 offset:0
	v_cvt_pk_bf16_f32 v18, v18, v19
	v_mfma_f32_16x16x32_bf16 v[86:89], v[188:191], v[172:175], v[86:89]
	ds_read_b128 v[156:159], v231 offset:2048
	v_mfma_f32_16x16x32_bf16 v[90:93], v[192:195], v[172:175], v[90:93]
	ds_read_b128 v[160:163], v231 offset:4096
	v_cvt_pk_bf16_f32 v19, v20, v21
	v_mfma_f32_16x16x32_bf16 v[94:97], v[196:199], v[172:175], v[94:97]
	ds_read_b128 v[164:167], v231 offset:6144
	s_mov_b32 m0, s8
	v_mfma_f32_16x16x32_bf16 v[98:101], v[184:187], v[176:179], v[98:101]
	global_load_lds_dwordx4 v200, s[4:5]
	s_add_u32 m0, s8, 0x400
	v_mfma_f32_16x16x32_bf16 v[102:105], v[188:191], v[176:179], v[102:105]
	global_load_lds_dwordx4 v201, s[4:5]
	v_cvt_pk_bf16_f32 v20, v22, v23
	s_add_u32 m0, s8, 0x800
	v_mfma_f32_16x16x32_bf16 v[106:109], v[192:195], v[176:179], v[106:109]
	global_load_lds_dwordx4 v202, s[4:5]
	s_add_u32 m0, s8, 0xc00
	v_mfma_f32_16x16x32_bf16 v[110:113], v[196:199], v[176:179], v[110:113]
	global_load_lds_dwordx4 v203, s[4:5]
	v_cvt_pk_bf16_f32 v21, v24, v25
	s_mov_b32 m0, s9
	v_mfma_f32_16x16x32_bf16 v[114:117], v[184:187], v[180:183], v[114:117]
	global_load_lds_dwordx4 v204, s[6:7]
	s_add_u32 m0, s9, 0x400
	v_mfma_f32_16x16x32_bf16 v[118:121], v[188:191], v[180:183], v[118:121]
	global_load_lds_dwordx4 v205, s[6:7]
	global_store_dwordx4 v240, v[18:21], s[10:11] offset:2048
	v_mfma_f32_16x16x32_bf16 v[122:125], v[192:195], v[180:183], v[122:125]
	s_add_u32 s4, s4, 0x80
	s_addc_u32 s5, s5, 0
	v_mfma_f32_16x16x32_bf16 v[126:129], v[196:199], v[180:183], v[126:129]
	s_add_u32 s6, s6, 0x80
	s_addc_u32 s7, s7, 0
	v_mul_f32_e32 v26, s12, v26
	s_waitcnt lgkmcnt(0)
	v_mfma_f32_16x16x32_bf16 v[66:69], v[152:155], v[136:139], v[66:69]
	ds_read_b128 v[168:171], v228 offset:0
	v_mfma_f32_16x16x32_bf16 v[70:73], v[156:159], v[136:139], v[70:73]
	ds_read_b128 v[172:175], v228 offset:2048
	v_mul_f32_e32 v27, s12, v27
	v_mfma_f32_16x16x32_bf16 v[74:77], v[160:163], v[136:139], v[74:77]
	ds_read_b128 v[176:179], v228 offset:4096
	v_mul_f32_e32 v28, s12, v28
	v_mfma_f32_16x16x32_bf16 v[78:81], v[164:167], v[136:139], v[78:81]
	ds_read_b128 v[180:183], v228 offset:6144
	v_mul_f32_e32 v29, s12, v29
	v_mfma_f32_16x16x32_bf16 v[82:85], v[152:155], v[140:143], v[82:85]
	ds_read_b128 v[184:187], v234 offset:0
	v_mfma_f32_16x16x32_bf16 v[86:89], v[156:159], v[140:143], v[86:89]
	ds_read_b128 v[188:191], v234 offset:2048
	v_mul_f32_e32 v30, s12, v30
	v_mfma_f32_16x16x32_bf16 v[90:93], v[160:163], v[140:143], v[90:93]
	ds_read_b128 v[192:195], v234 offset:4096
	v_mul_f32_e32 v31, s12, v31
	v_mfma_f32_16x16x32_bf16 v[94:97], v[164:167], v[140:143], v[94:97]
	ds_read_b128 v[196:199], v234 offset:6144
	v_mul_f32_e32 v32, s12, v32
	v_mfma_f32_16x16x32_bf16 v[98:101], v[152:155], v[144:147], v[98:101]
	v_mfma_f32_16x16x32_bf16 v[102:105], v[156:159], v[144:147], v[102:105]
	v_mul_f32_e32 v33, s12, v33
	v_mfma_f32_16x16x32_bf16 v[106:109], v[160:163], v[144:147], v[106:109]
	v_exp_f32_e32 v26, v26
	v_mfma_f32_16x16x32_bf16 v[110:113], v[164:167], v[144:147], v[110:113]
	v_exp_f32_e32 v27, v27
	v_mfma_f32_16x16x32_bf16 v[114:117], v[152:155], v[148:151], v[114:117]
	v_mfma_f32_16x16x32_bf16 v[118:121], v[156:159], v[148:151], v[118:121]
	v_exp_f32_e32 v28, v28
	v_mfma_f32_16x16x32_bf16 v[122:125], v[160:163], v[148:151], v[122:125]
	v_exp_f32_e32 v29, v29
	v_mfma_f32_16x16x32_bf16 v[126:129], v[164:167], v[148:151], v[126:129]
	v_exp_f32_e32 v30, v30
	s_waitcnt vmcnt(7) lgkmcnt(0)
	s_barrier
	v_mfma_f32_16x16x32_bf16 v[66:69], v[184:187], v[168:171], v[66:69]
	ds_read_b128 v[136:139], v224 offset:0
	v_mfma_f32_16x16x32_bf16 v[70:73], v[188:191], v[168:171], v[70:73]
	ds_read_b128 v[140:143], v224 offset:2048
	v_mfma_f32_16x16x32_bf16 v[74:77], v[192:195], v[168:171], v[74:77]
	ds_read_b128 v[144:147], v224 offset:4096
	v_exp_f32_e32 v31, v31
	v_mfma_f32_16x16x32_bf16 v[78:81], v[196:199], v[168:171], v[78:81]
	ds_read_b128 v[148:151], v224 offset:6144
	v_mfma_f32_16x16x32_bf16 v[82:85], v[184:187], v[172:175], v[82:85]
	ds_read_b128 v[152:155], v232 offset:0
	v_exp_f32_e32 v32, v32
	v_mfma_f32_16x16x32_bf16 v[86:89], v[188:191], v[172:175], v[86:89]
	ds_read_b128 v[156:159], v232 offset:2048
	v_mfma_f32_16x16x32_bf16 v[90:93], v[192:195], v[172:175], v[90:93]
	ds_read_b128 v[160:163], v232 offset:4096
	v_exp_f32_e32 v33, v33
	v_mfma_f32_16x16x32_bf16 v[94:97], v[196:199], v[172:175], v[94:97]
	ds_read_b128 v[164:167], v232 offset:6144
	s_add_u32 m0, s8, 0xc000
	v_mfma_f32_16x16x32_bf16 v[98:101], v[184:187], v[176:179], v[98:101]
	global_load_lds_dwordx4 v200, s[4:5]
	s_add_u32 m0, s8, 0xc400
	v_mfma_f32_16x16x32_bf16 v[102:105], v[188:191], v[176:179], v[102:105]
	global_load_lds_dwordx4 v201, s[4:5]
	v_add_f32_e32 v26, 1.0, v26
	s_add_u32 m0, s8, 0xc800
	v_mfma_f32_16x16x32_bf16 v[106:109], v[192:195], v[176:179], v[106:109]
	global_load_lds_dwordx4 v202, s[4:5]
	s_add_u32 m0, s8, 0xcc00
	v_mfma_f32_16x16x32_bf16 v[110:113], v[196:199], v[176:179], v[110:113]
	global_load_lds_dwordx4 v203, s[4:5]
	v_add_f32_e32 v27, 1.0, v27
	s_add_u32 m0, s9, 0xc000
	v_mfma_f32_16x16x32_bf16 v[114:117], v[184:187], v[180:183], v[114:117]
	global_load_lds_dwordx4 v204, s[6:7]
	s_add_u32 m0, s9, 0xc400
	v_mfma_f32_16x16x32_bf16 v[118:121], v[188:191], v[180:183], v[118:121]
	global_load_lds_dwordx4 v205, s[6:7]
	v_add_f32_e32 v28, 1.0, v28
	v_mfma_f32_16x16x32_bf16 v[122:125], v[192:195], v[180:183], v[122:125]
	s_add_u32 s4, s4, 0x80
	s_addc_u32 s5, s5, 0
	v_mfma_f32_16x16x32_bf16 v[126:129], v[196:199], v[180:183], v[126:129]
	s_add_u32 s6, s6, 0x80
	s_addc_u32 s7, s7, 0
	v_add_f32_e32 v29, 1.0, v29
	s_waitcnt lgkmcnt(0)
	v_mfma_f32_16x16x32_bf16 v[66:69], v[152:155], v[136:139], v[66:69]
	ds_read_b128 v[168:171], v229 offset:0
	v_mfma_f32_16x16x32_bf16 v[70:73], v[156:159], v[136:139], v[70:73]
	ds_read_b128 v[172:175], v229 offset:2048
	v_add_f32_e32 v30, 1.0, v30
	v_mfma_f32_16x16x32_bf16 v[74:77], v[160:163], v[136:139], v[74:77]
	ds_read_b128 v[176:179], v229 offset:4096
	v_add_f32_e32 v31, 1.0, v31
	v_mfma_f32_16x16x32_bf16 v[78:81], v[164:167], v[136:139], v[78:81]
	ds_read_b128 v[180:183], v229 offset:6144
	v_add_f32_e32 v32, 1.0, v32
	v_mfma_f32_16x16x32_bf16 v[82:85], v[152:155], v[140:143], v[82:85]
	ds_read_b128 v[184:187], v235 offset:0
	v_mfma_f32_16x16x32_bf16 v[86:89], v[156:159], v[140:143], v[86:89]
	ds_read_b128 v[188:191], v235 offset:2048
	v_add_f32_e32 v33, 1.0, v33
	v_mfma_f32_16x16x32_bf16 v[90:93], v[160:163], v[140:143], v[90:93]
	ds_read_b128 v[192:195], v235 offset:4096
	v_rcp_f32_e32 v26, v26
	v_mfma_f32_16x16x32_bf16 v[94:97], v[164:167], v[140:143], v[94:97]
	ds_read_b128 v[196:199], v235 offset:6144
	v_rcp_f32_e32 v27, v27
	v_mfma_f32_16x16x32_bf16 v[98:101], v[152:155], v[144:147], v[98:101]
	v_mfma_f32_16x16x32_bf16 v[102:105], v[156:159], v[144:147], v[102:105]
	v_rcp_f32_e32 v28, v28
	v_mfma_f32_16x16x32_bf16 v[106:109], v[160:163], v[144:147], v[106:109]
	v_rcp_f32_e32 v29, v29
	v_mfma_f32_16x16x32_bf16 v[110:113], v[164:167], v[144:147], v[110:113]
	v_rcp_f32_e32 v30, v30
	v_mfma_f32_16x16x32_bf16 v[114:117], v[152:155], v[148:151], v[114:117]
	v_mfma_f32_16x16x32_bf16 v[118:121], v[156:159], v[148:151], v[118:121]
	v_rcp_f32_e32 v31, v31
	v_mfma_f32_16x16x32_bf16 v[122:125], v[160:163], v[148:151], v[122:125]
	v_rcp_f32_e32 v32, v32
	v_mfma_f32_16x16x32_bf16 v[126:129], v[164:167], v[148:151], v[126:129]
	v_rcp_f32_e32 v33, v33
	s_waitcnt vmcnt(7) lgkmcnt(0)
	s_barrier
	v_mfma_f32_16x16x32_bf16 v[66:69], v[184:187], v[168:171], v[66:69]
	ds_read_b128 v[136:139], v218 offset:0
	v_mfma_f32_16x16x32_bf16 v[70:73], v[188:191], v[168:171], v[70:73]
	ds_read_b128 v[140:143], v218 offset:2048
	v_mfma_f32_16x16x32_bf16 v[74:77], v[192:195], v[168:171], v[74:77]
	ds_read_b128 v[144:147], v218 offset:4096
	v_cvt_pk_bf16_f32 v26, v26, v27
	v_mfma_f32_16x16x32_bf16 v[78:81], v[196:199], v[168:171], v[78:81]
	ds_read_b128 v[148:151], v218 offset:6144
	v_mfma_f32_16x16x32_bf16 v[82:85], v[184:187], v[172:175], v[82:85]
	ds_read_b128 v[152:155], v230 offset:0
	v_cvt_pk_bf16_f32 v27, v28, v29
	v_mfma_f32_16x16x32_bf16 v[86:89], v[188:191], v[172:175], v[86:89]
	ds_read_b128 v[156:159], v230 offset:2048
	v_mfma_f32_16x16x32_bf16 v[90:93], v[192:195], v[172:175], v[90:93]
	ds_read_b128 v[160:163], v230 offset:4096
	v_cvt_pk_bf16_f32 v28, v30, v31
	v_mfma_f32_16x16x32_bf16 v[94:97], v[196:199], v[172:175], v[94:97]
	ds_read_b128 v[164:167], v230 offset:6144
	s_add_u32 m0, s8, 0x18000
	v_mfma_f32_16x16x32_bf16 v[98:101], v[184:187], v[176:179], v[98:101]
	global_load_lds_dwordx4 v200, s[4:5]
	s_add_u32 m0, s8, 0x18400
	v_mfma_f32_16x16x32_bf16 v[102:105], v[188:191], v[176:179], v[102:105]
	global_load_lds_dwordx4 v201, s[4:5]
	v_cvt_pk_bf16_f32 v29, v32, v33
	s_add_u32 m0, s8, 0x18800
	v_mfma_f32_16x16x32_bf16 v[106:109], v[192:195], v[176:179], v[106:109]
	global_load_lds_dwordx4 v202, s[4:5]
	s_add_u32 m0, s8, 0x18c00
	v_mfma_f32_16x16x32_bf16 v[110:113], v[196:199], v[176:179], v[110:113]
	global_load_lds_dwordx4 v203, s[4:5]
	global_store_dwordx4 v240, v[26:29], s[10:11] offset:3072
	s_add_u32 m0, s9, 0x18000
	v_mfma_f32_16x16x32_bf16 v[114:117], v[184:187], v[180:183], v[114:117]
	global_load_lds_dwordx4 v204, s[6:7]
	s_add_u32 m0, s9, 0x18400
	v_mfma_f32_16x16x32_bf16 v[118:121], v[188:191], v[180:183], v[118:121]
	global_load_lds_dwordx4 v205, s[6:7]
	v_mul_f32_e32 v34, s12, v34
	v_mfma_f32_16x16x32_bf16 v[122:125], v[192:195], v[180:183], v[122:125]
	s_add_u32 s4, s4, 0x80
	s_addc_u32 s5, s5, 0
	v_mfma_f32_16x16x32_bf16 v[126:129], v[196:199], v[180:183], v[126:129]
	s_add_u32 s6, s6, 0x80
	s_addc_u32 s7, s7, 0
	v_mul_f32_e32 v35, s12, v35
	s_waitcnt lgkmcnt(0)
	v_mfma_f32_16x16x32_bf16 v[66:69], v[152:155], v[136:139], v[66:69]
	ds_read_b128 v[168:171], v225 offset:0
	v_mfma_f32_16x16x32_bf16 v[70:73], v[156:159], v[136:139], v[70:73]
	ds_read_b128 v[172:175], v225 offset:2048
	v_mul_f32_e32 v36, s12, v36
	v_mfma_f32_16x16x32_bf16 v[74:77], v[160:163], v[136:139], v[74:77]
	ds_read_b128 v[176:179], v225 offset:4096
	v_mul_f32_e32 v37, s12, v37
	v_mfma_f32_16x16x32_bf16 v[78:81], v[164:167], v[136:139], v[78:81]
	ds_read_b128 v[180:183], v225 offset:6144
	v_mul_f32_e32 v38, s12, v38
	v_mfma_f32_16x16x32_bf16 v[82:85], v[152:155], v[140:143], v[82:85]
	ds_read_b128 v[184:187], v233 offset:0
	v_mfma_f32_16x16x32_bf16 v[86:89], v[156:159], v[140:143], v[86:89]
	ds_read_b128 v[188:191], v233 offset:2048
	v_mul_f32_e32 v39, s12, v39
	v_mfma_f32_16x16x32_bf16 v[90:93], v[160:163], v[140:143], v[90:93]
	ds_read_b128 v[192:195], v233 offset:4096
	v_mul_f32_e32 v40, s12, v40
	v_mfma_f32_16x16x32_bf16 v[94:97], v[164:167], v[140:143], v[94:97]
	ds_read_b128 v[196:199], v233 offset:6144
	v_mul_f32_e32 v41, s12, v41
	v_mfma_f32_16x16x32_bf16 v[98:101], v[152:155], v[144:147], v[98:101]
	v_mfma_f32_16x16x32_bf16 v[102:105], v[156:159], v[144:147], v[102:105]
	v_exp_f32_e32 v34, v34
	v_mfma_f32_16x16x32_bf16 v[106:109], v[160:163], v[144:147], v[106:109]
	v_exp_f32_e32 v35, v35
	v_mfma_f32_16x16x32_bf16 v[110:113], v[164:167], v[144:147], v[110:113]
	v_exp_f32_e32 v36, v36
	v_mfma_f32_16x16x32_bf16 v[114:117], v[152:155], v[148:151], v[114:117]
	v_mfma_f32_16x16x32_bf16 v[118:121], v[156:159], v[148:151], v[118:121]
	v_exp_f32_e32 v37, v37
	v_mfma_f32_16x16x32_bf16 v[122:125], v[160:163], v[148:151], v[122:125]
	v_exp_f32_e32 v38, v38
	v_mfma_f32_16x16x32_bf16 v[126:129], v[164:167], v[148:151], v[126:129]
	v_exp_f32_e32 v39, v39
	s_waitcnt vmcnt(7) lgkmcnt(0)
	s_barrier
	v_mfma_f32_16x16x32_bf16 v[66:69], v[184:187], v[168:171], v[66:69]
	ds_read_b128 v[136:139], v219 offset:0
	v_mfma_f32_16x16x32_bf16 v[70:73], v[188:191], v[168:171], v[70:73]
	ds_read_b128 v[140:143], v219 offset:2048
	v_mfma_f32_16x16x32_bf16 v[74:77], v[192:195], v[168:171], v[74:77]
	ds_read_b128 v[144:147], v219 offset:4096
	v_exp_f32_e32 v40, v40
	v_mfma_f32_16x16x32_bf16 v[78:81], v[196:199], v[168:171], v[78:81]
	ds_read_b128 v[148:151], v219 offset:6144
	v_mfma_f32_16x16x32_bf16 v[82:85], v[184:187], v[172:175], v[82:85]
	ds_read_b128 v[152:155], v231 offset:0
	v_exp_f32_e32 v41, v41
	v_mfma_f32_16x16x32_bf16 v[86:89], v[188:191], v[172:175], v[86:89]
	ds_read_b128 v[156:159], v231 offset:2048
	v_mfma_f32_16x16x32_bf16 v[90:93], v[192:195], v[172:175], v[90:93]
	ds_read_b128 v[160:163], v231 offset:4096
	v_add_f32_e32 v34, 1.0, v34
	v_mfma_f32_16x16x32_bf16 v[94:97], v[196:199], v[172:175], v[94:97]
	ds_read_b128 v[164:167], v231 offset:6144
	s_mov_b32 m0, s8
	v_mfma_f32_16x16x32_bf16 v[98:101], v[184:187], v[176:179], v[98:101]
	global_load_lds_dwordx4 v200, s[4:5]
	s_add_u32 m0, s8, 0x400
	v_mfma_f32_16x16x32_bf16 v[102:105], v[188:191], v[176:179], v[102:105]
	global_load_lds_dwordx4 v201, s[4:5]
	v_add_f32_e32 v35, 1.0, v35
	s_add_u32 m0, s8, 0x800
	v_mfma_f32_16x16x32_bf16 v[106:109], v[192:195], v[176:179], v[106:109]
	global_load_lds_dwordx4 v202, s[4:5]
	s_add_u32 m0, s8, 0xc00
	v_mfma_f32_16x16x32_bf16 v[110:113], v[196:199], v[176:179], v[110:113]
	global_load_lds_dwordx4 v203, s[4:5]
	v_add_f32_e32 v36, 1.0, v36
	s_mov_b32 m0, s9
	v_mfma_f32_16x16x32_bf16 v[114:117], v[184:187], v[180:183], v[114:117]
	global_load_lds_dwordx4 v204, s[6:7]
	s_add_u32 m0, s9, 0x400
	v_mfma_f32_16x16x32_bf16 v[118:121], v[188:191], v[180:183], v[118:121]
	global_load_lds_dwordx4 v205, s[6:7]
	v_add_f32_e32 v37, 1.0, v37
	v_mfma_f32_16x16x32_bf16 v[122:125], v[192:195], v[180:183], v[122:125]
	s_add_u32 s4, s4, 0x80
	s_addc_u32 s5, s5, 0
	v_mfma_f32_16x16x32_bf16 v[126:129], v[196:199], v[180:183], v[126:129]
	s_add_u32 s6, s6, 0x80
	s_addc_u32 s7, s7, 0
	v_add_f32_e32 v38, 1.0, v38
	s_waitcnt lgkmcnt(0)
	v_mfma_f32_16x16x32_bf16 v[66:69], v[152:155], v[136:139], v[66:69]
	ds_read_b128 v[168:171], v228 offset:0
	v_mfma_f32_16x16x32_bf16 v[70:73], v[156:159], v[136:139], v[70:73]
	ds_read_b128 v[172:175], v228 offset:2048
	v_add_f32_e32 v39, 1.0, v39
	v_mfma_f32_16x16x32_bf16 v[74:77], v[160:163], v[136:139], v[74:77]
	ds_read_b128 v[176:179], v228 offset:4096
	v_add_f32_e32 v40, 1.0, v40
	v_mfma_f32_16x16x32_bf16 v[78:81], v[164:167], v[136:139], v[78:81]
	ds_read_b128 v[180:183], v228 offset:6144
	v_add_f32_e32 v41, 1.0, v41
	v_mfma_f32_16x16x32_bf16 v[82:85], v[152:155], v[140:143], v[82:85]
	ds_read_b128 v[184:187], v234 offset:0
	v_mfma_f32_16x16x32_bf16 v[86:89], v[156:159], v[140:143], v[86:89]
	ds_read_b128 v[188:191], v234 offset:2048
	v_rcp_f32_e32 v34, v34
	v_mfma_f32_16x16x32_bf16 v[90:93], v[160:163], v[140:143], v[90:93]
	ds_read_b128 v[192:195], v234 offset:4096
	v_rcp_f32_e32 v35, v35
	v_mfma_f32_16x16x32_bf16 v[94:97], v[164:167], v[140:143], v[94:97]
	ds_read_b128 v[196:199], v234 offset:6144
	v_rcp_f32_e32 v36, v36
	v_mfma_f32_16x16x32_bf16 v[98:101], v[152:155], v[144:147], v[98:101]
	v_mfma_f32_16x16x32_bf16 v[102:105], v[156:159], v[144:147], v[102:105]
	v_rcp_f32_e32 v37, v37
	v_mfma_f32_16x16x32_bf16 v[106:109], v[160:163], v[144:147], v[106:109]
	v_rcp_f32_e32 v38, v38
	v_mfma_f32_16x16x32_bf16 v[110:113], v[164:167], v[144:147], v[110:113]
	v_rcp_f32_e32 v39, v39
	v_mfma_f32_16x16x32_bf16 v[114:117], v[152:155], v[148:151], v[114:117]
	v_mfma_f32_16x16x32_bf16 v[118:121], v[156:159], v[148:151], v[118:121]
	v_rcp_f32_e32 v40, v40
	v_mfma_f32_16x16x32_bf16 v[122:125], v[160:163], v[148:151], v[122:125]
	v_rcp_f32_e32 v41, v41
	v_mfma_f32_16x16x32_bf16 v[126:129], v[164:167], v[148:151], v[126:129]
	v_cvt_pk_bf16_f32 v34, v34, v35
	s_waitcnt vmcnt(6) lgkmcnt(0)
	s_barrier
	v_mfma_f32_16x16x32_bf16 v[66:69], v[184:187], v[168:171], v[66:69]
	ds_read_b128 v[136:139], v224 offset:0
	v_mfma_f32_16x16x32_bf16 v[70:73], v[188:191], v[168:171], v[70:73]
	ds_read_b128 v[140:143], v224 offset:2048
	v_mfma_f32_16x16x32_bf16 v[74:77], v[192:195], v[168:171], v[74:77]
	ds_read_b128 v[144:147], v224 offset:4096
	v_cvt_pk_bf16_f32 v35, v36, v37
	v_mfma_f32_16x16x32_bf16 v[78:81], v[196:199], v[168:171], v[78:81]
	ds_read_b128 v[148:151], v224 offset:6144
	v_mfma_f32_16x16x32_bf16 v[82:85], v[184:187], v[172:175], v[82:85]
	ds_read_b128 v[152:155], v232 offset:0
	v_cvt_pk_bf16_f32 v36, v38, v39
	v_mfma_f32_16x16x32_bf16 v[86:89], v[188:191], v[172:175], v[86:89]
	ds_read_b128 v[156:159], v232 offset:2048
	v_mfma_f32_16x16x32_bf16 v[90:93], v[192:195], v[172:175], v[90:93]
	ds_read_b128 v[160:163], v232 offset:4096
	v_cvt_pk_bf16_f32 v37, v40, v41
	v_mfma_f32_16x16x32_bf16 v[94:97], v[196:199], v[172:175], v[94:97]
	ds_read_b128 v[164:167], v232 offset:6144
	s_add_u32 m0, s8, 0xc000
	v_mfma_f32_16x16x32_bf16 v[98:101], v[184:187], v[176:179], v[98:101]
	global_load_lds_dwordx4 v200, s[4:5]
	s_add_u32 m0, s8, 0xc400
	v_mfma_f32_16x16x32_bf16 v[102:105], v[188:191], v[176:179], v[102:105]
	global_load_lds_dwordx4 v201, s[4:5]
	global_store_dwordx4 v241, v[34:37], s[10:11] offset:0
	s_add_u32 m0, s8, 0xc800
	v_mfma_f32_16x16x32_bf16 v[106:109], v[192:195], v[176:179], v[106:109]
	global_load_lds_dwordx4 v202, s[4:5]
	s_add_u32 m0, s8, 0xcc00
	v_mfma_f32_16x16x32_bf16 v[110:113], v[196:199], v[176:179], v[110:113]
	global_load_lds_dwordx4 v203, s[4:5]
	v_mul_f32_e32 v42, s12, v42
	s_add_u32 m0, s9, 0xc000
	v_mfma_f32_16x16x32_bf16 v[114:117], v[184:187], v[180:183], v[114:117]
	global_load_lds_dwordx4 v204, s[6:7]
	s_add_u32 m0, s9, 0xc400
	v_mfma_f32_16x16x32_bf16 v[118:121], v[188:191], v[180:183], v[118:121]
	global_load_lds_dwordx4 v205, s[6:7]
	v_mul_f32_e32 v43, s12, v43
	v_mfma_f32_16x16x32_bf16 v[122:125], v[192:195], v[180:183], v[122:125]
	s_add_u32 s4, s4, 0x80
	s_addc_u32 s5, s5, 0
	v_mfma_f32_16x16x32_bf16 v[126:129], v[196:199], v[180:183], v[126:129]
	s_add_u32 s6, s6, 0x80
	s_addc_u32 s7, s7, 0
	v_mul_f32_e32 v44, s12, v44
	s_waitcnt lgkmcnt(0)
	v_mfma_f32_16x16x32_bf16 v[66:69], v[152:155], v[136:139], v[66:69]
	ds_read_b128 v[168:171], v229 offset:0
	v_mfma_f32_16x16x32_bf16 v[70:73], v[156:159], v[136:139], v[70:73]
	ds_read_b128 v[172:175], v229 offset:2048
	v_mul_f32_e32 v45, s12, v45
	v_mfma_f32_16x16x32_bf16 v[74:77], v[160:163], v[136:139], v[74:77]
	ds_read_b128 v[176:179], v229 offset:4096
	v_mul_f32_e32 v46, s12, v46
	v_mfma_f32_16x16x32_bf16 v[78:81], v[164:167], v[136:139], v[78:81]
	ds_read_b128 v[180:183], v229 offset:6144
	v_mul_f32_e32 v47, s12, v47
	v_mfma_f32_16x16x32_bf16 v[82:85], v[152:155], v[140:143], v[82:85]
	ds_read_b128 v[184:187], v235 offset:0
	v_mfma_f32_16x16x32_bf16 v[86:89], v[156:159], v[140:143], v[86:89]
	ds_read_b128 v[188:191], v235 offset:2048
	v_mul_f32_e32 v48, s12, v48
	v_mfma_f32_16x16x32_bf16 v[90:93], v[160:163], v[140:143], v[90:93]
	ds_read_b128 v[192:195], v235 offset:4096
	v_mul_f32_e32 v49, s12, v49
	v_mfma_f32_16x16x32_bf16 v[94:97], v[164:167], v[140:143], v[94:97]
	ds_read_b128 v[196:199], v235 offset:6144
	v_exp_f32_e32 v42, v42
	v_mfma_f32_16x16x32_bf16 v[98:101], v[152:155], v[144:147], v[98:101]
	v_mfma_f32_16x16x32_bf16 v[102:105], v[156:159], v[144:147], v[102:105]
	v_exp_f32_e32 v43, v43
	v_mfma_f32_16x16x32_bf16 v[106:109], v[160:163], v[144:147], v[106:109]
	v_exp_f32_e32 v44, v44
	v_mfma_f32_16x16x32_bf16 v[110:113], v[164:167], v[144:147], v[110:113]
	v_exp_f32_e32 v45, v45
	v_mfma_f32_16x16x32_bf16 v[114:117], v[152:155], v[148:151], v[114:117]
	v_mfma_f32_16x16x32_bf16 v[118:121], v[156:159], v[148:151], v[118:121]
	v_exp_f32_e32 v46, v46
	v_mfma_f32_16x16x32_bf16 v[122:125], v[160:163], v[148:151], v[122:125]
	v_exp_f32_e32 v47, v47
	v_mfma_f32_16x16x32_bf16 v[126:129], v[164:167], v[148:151], v[126:129]
	v_exp_f32_e32 v48, v48
	s_waitcnt vmcnt(7) lgkmcnt(0)
	s_barrier
	v_mfma_f32_16x16x32_bf16 v[66:69], v[184:187], v[168:171], v[66:69]
	ds_read_b128 v[136:139], v218 offset:0
	v_mfma_f32_16x16x32_bf16 v[70:73], v[188:191], v[168:171], v[70:73]
	ds_read_b128 v[140:143], v218 offset:2048
	v_mfma_f32_16x16x32_bf16 v[74:77], v[192:195], v[168:171], v[74:77]
	ds_read_b128 v[144:147], v218 offset:4096
	v_exp_f32_e32 v49, v49
	v_mfma_f32_16x16x32_bf16 v[78:81], v[196:199], v[168:171], v[78:81]
	ds_read_b128 v[148:151], v218 offset:6144
	v_mfma_f32_16x16x32_bf16 v[82:85], v[184:187], v[172:175], v[82:85]
	ds_read_b128 v[152:155], v230 offset:0
	v_add_f32_e32 v42, 1.0, v42
	v_mfma_f32_16x16x32_bf16 v[86:89], v[188:191], v[172:175], v[86:89]
	ds_read_b128 v[156:159], v230 offset:2048
	v_mfma_f32_16x16x32_bf16 v[90:93], v[192:195], v[172:175], v[90:93]
	ds_read_b128 v[160:163], v230 offset:4096
	v_add_f32_e32 v43, 1.0, v43
	v_mfma_f32_16x16x32_bf16 v[94:97], v[196:199], v[172:175], v[94:97]
	ds_read_b128 v[164:167], v230 offset:6144
	s_add_u32 m0, s8, 0x18000
	v_mfma_f32_16x16x32_bf16 v[98:101], v[184:187], v[176:179], v[98:101]
	global_load_lds_dwordx4 v200, s[4:5]
	s_add_u32 m0, s8, 0x18400
	v_mfma_f32_16x16x32_bf16 v[102:105], v[188:191], v[176:179], v[102:105]
	global_load_lds_dwordx4 v201, s[4:5]
	v_add_f32_e32 v44, 1.0, v44
	s_add_u32 m0, s8, 0x18800
	v_mfma_f32_16x16x32_bf16 v[106:109], v[192:195], v[176:179], v[106:109]
	global_load_lds_dwordx4 v202, s[4:5]
	s_add_u32 m0, s8, 0x18c00
	v_mfma_f32_16x16x32_bf16 v[110:113], v[196:199], v[176:179], v[110:113]
	global_load_lds_dwordx4 v203, s[4:5]
	v_add_f32_e32 v45, 1.0, v45
	s_add_u32 m0, s9, 0x18000
	v_mfma_f32_16x16x32_bf16 v[114:117], v[184:187], v[180:183], v[114:117]
	global_load_lds_dwordx4 v204, s[6:7]
	s_add_u32 m0, s9, 0x18400
	v_mfma_f32_16x16x32_bf16 v[118:121], v[188:191], v[180:183], v[118:121]
	global_load_lds_dwordx4 v205, s[6:7]
	v_add_f32_e32 v46, 1.0, v46
	v_mfma_f32_16x16x32_bf16 v[122:125], v[192:195], v[180:183], v[122:125]
	s_add_u32 s4, s4, 0x80
	s_addc_u32 s5, s5, 0
	v_mfma_f32_16x16x32_bf16 v[126:129], v[196:199], v[180:183], v[126:129]
	s_add_u32 s6, s6, 0x80
	s_addc_u32 s7, s7, 0
	v_add_f32_e32 v47, 1.0, v47
	s_waitcnt lgkmcnt(0)
	v_mfma_f32_16x16x32_bf16 v[66:69], v[152:155], v[136:139], v[66:69]
	ds_read_b128 v[168:171], v225 offset:0
	v_mfma_f32_16x16x32_bf16 v[70:73], v[156:159], v[136:139], v[70:73]
	ds_read_b128 v[172:175], v225 offset:2048
	v_add_f32_e32 v48, 1.0, v48
	v_mfma_f32_16x16x32_bf16 v[74:77], v[160:163], v[136:139], v[74:77]
	ds_read_b128 v[176:179], v225 offset:4096
	v_add_f32_e32 v49, 1.0, v49
	v_mfma_f32_16x16x32_bf16 v[78:81], v[164:167], v[136:139], v[78:81]
	ds_read_b128 v[180:183], v225 offset:6144
	v_rcp_f32_e32 v42, v42
	v_mfma_f32_16x16x32_bf16 v[82:85], v[152:155], v[140:143], v[82:85]
	ds_read_b128 v[184:187], v233 offset:0
	v_mfma_f32_16x16x32_bf16 v[86:89], v[156:159], v[140:143], v[86:89]
	ds_read_b128 v[188:191], v233 offset:2048
	v_rcp_f32_e32 v43, v43
	v_mfma_f32_16x16x32_bf16 v[90:93], v[160:163], v[140:143], v[90:93]
	ds_read_b128 v[192:195], v233 offset:4096
	v_rcp_f32_e32 v44, v44
	v_mfma_f32_16x16x32_bf16 v[94:97], v[164:167], v[140:143], v[94:97]
	ds_read_b128 v[196:199], v233 offset:6144
	v_rcp_f32_e32 v45, v45
	v_mfma_f32_16x16x32_bf16 v[98:101], v[152:155], v[144:147], v[98:101]
	v_mfma_f32_16x16x32_bf16 v[102:105], v[156:159], v[144:147], v[102:105]
	v_rcp_f32_e32 v46, v46
	v_mfma_f32_16x16x32_bf16 v[106:109], v[160:163], v[144:147], v[106:109]
	v_rcp_f32_e32 v47, v47
	v_mfma_f32_16x16x32_bf16 v[110:113], v[164:167], v[144:147], v[110:113]
	v_rcp_f32_e32 v48, v48
	v_mfma_f32_16x16x32_bf16 v[114:117], v[152:155], v[148:151], v[114:117]
	v_mfma_f32_16x16x32_bf16 v[118:121], v[156:159], v[148:151], v[118:121]
	v_rcp_f32_e32 v49, v49
	v_mfma_f32_16x16x32_bf16 v[122:125], v[160:163], v[148:151], v[122:125]
	v_cvt_pk_bf16_f32 v42, v42, v43
	v_mfma_f32_16x16x32_bf16 v[126:129], v[164:167], v[148:151], v[126:129]
	v_cvt_pk_bf16_f32 v43, v44, v45
	s_waitcnt vmcnt(6) lgkmcnt(0)
	s_barrier
	v_mfma_f32_16x16x32_bf16 v[66:69], v[184:187], v[168:171], v[66:69]
	ds_read_b128 v[136:139], v219 offset:0
	v_mfma_f32_16x16x32_bf16 v[70:73], v[188:191], v[168:171], v[70:73]
	ds_read_b128 v[140:143], v219 offset:2048
	v_mfma_f32_16x16x32_bf16 v[74:77], v[192:195], v[168:171], v[74:77]
	ds_read_b128 v[144:147], v219 offset:4096
	v_cvt_pk_bf16_f32 v44, v46, v47
	v_mfma_f32_16x16x32_bf16 v[78:81], v[196:199], v[168:171], v[78:81]
	ds_read_b128 v[148:151], v219 offset:6144
	v_mfma_f32_16x16x32_bf16 v[82:85], v[184:187], v[172:175], v[82:85]
	ds_read_b128 v[152:155], v231 offset:0
	v_cvt_pk_bf16_f32 v45, v48, v49
	v_mfma_f32_16x16x32_bf16 v[86:89], v[188:191], v[172:175], v[86:89]
	ds_read_b128 v[156:159], v231 offset:2048
	v_mfma_f32_16x16x32_bf16 v[90:93], v[192:195], v[172:175], v[90:93]
	ds_read_b128 v[160:163], v231 offset:4096
	global_store_dwordx4 v241, v[42:45], s[10:11] offset:1024
	v_mfma_f32_16x16x32_bf16 v[94:97], v[196:199], v[172:175], v[94:97]
	ds_read_b128 v[164:167], v231 offset:6144
	s_mov_b32 m0, s8
	v_mfma_f32_16x16x32_bf16 v[98:101], v[184:187], v[176:179], v[98:101]
	global_load_lds_dwordx4 v200, s[4:5]
	s_add_u32 m0, s8, 0x400
	v_mfma_f32_16x16x32_bf16 v[102:105], v[188:191], v[176:179], v[102:105]
	global_load_lds_dwordx4 v201, s[4:5]
	v_mul_f32_e32 v50, s12, v50
	s_add_u32 m0, s8, 0x800
	v_mfma_f32_16x16x32_bf16 v[106:109], v[192:195], v[176:179], v[106:109]
	global_load_lds_dwordx4 v202, s[4:5]
	s_add_u32 m0, s8, 0xc00
	v_mfma_f32_16x16x32_bf16 v[110:113], v[196:199], v[176:179], v[110:113]
	global_load_lds_dwordx4 v203, s[4:5]
	v_mul_f32_e32 v51, s12, v51
	s_mov_b32 m0, s9
	v_mfma_f32_16x16x32_bf16 v[114:117], v[184:187], v[180:183], v[114:117]
	global_load_lds_dwordx4 v204, s[6:7]
	s_add_u32 m0, s9, 0x400
	v_mfma_f32_16x16x32_bf16 v[118:121], v[188:191], v[180:183], v[118:121]
	global_load_lds_dwordx4 v205, s[6:7]
	v_mul_f32_e32 v52, s12, v52
	v_mfma_f32_16x16x32_bf16 v[122:125], v[192:195], v[180:183], v[122:125]
	s_add_u32 s4, s4, 0x80
	s_addc_u32 s5, s5, 0
	v_mfma_f32_16x16x32_bf16 v[126:129], v[196:199], v[180:183], v[126:129]
	s_add_u32 s6, s6, 0x80
	s_addc_u32 s7, s7, 0
	v_mul_f32_e32 v53, s12, v53
	s_waitcnt lgkmcnt(0)
	v_mfma_f32_16x16x32_bf16 v[66:69], v[152:155], v[136:139], v[66:69]
	ds_read_b128 v[168:171], v228 offset:0
	v_mfma_f32_16x16x32_bf16 v[70:73], v[156:159], v[136:139], v[70:73]
	ds_read_b128 v[172:175], v228 offset:2048
	v_mul_f32_e32 v54, s12, v54
	v_mfma_f32_16x16x32_bf16 v[74:77], v[160:163], v[136:139], v[74:77]
	ds_read_b128 v[176:179], v228 offset:4096
	v_mul_f32_e32 v55, s12, v55
	v_mfma_f32_16x16x32_bf16 v[78:81], v[164:167], v[136:139], v[78:81]
	ds_read_b128 v[180:183], v228 offset:6144
	v_mul_f32_e32 v56, s12, v56
	v_mfma_f32_16x16x32_bf16 v[82:85], v[152:155], v[140:143], v[82:85]
	ds_read_b128 v[184:187], v234 offset:0
	v_mfma_f32_16x16x32_bf16 v[86:89], v[156:159], v[140:143], v[86:89]
	ds_read_b128 v[188:191], v234 offset:2048
	v_mul_f32_e32 v57, s12, v57
	v_mfma_f32_16x16x32_bf16 v[90:93], v[160:163], v[140:143], v[90:93]
	ds_read_b128 v[192:195], v234 offset:4096
	v_exp_f32_e32 v50, v50
	v_mfma_f32_16x16x32_bf16 v[94:97], v[164:167], v[140:143], v[94:97]
	ds_read_b128 v[196:199], v234 offset:6144
	v_exp_f32_e32 v51, v51
	v_mfma_f32_16x16x32_bf16 v[98:101], v[152:155], v[144:147], v[98:101]
	v_mfma_f32_16x16x32_bf16 v[102:105], v[156:159], v[144:147], v[102:105]
	v_exp_f32_e32 v52, v52
	v_mfma_f32_16x16x32_bf16 v[106:109], v[160:163], v[144:147], v[106:109]
	v_exp_f32_e32 v53, v53
	v_mfma_f32_16x16x32_bf16 v[110:113], v[164:167], v[144:147], v[110:113]
	v_exp_f32_e32 v54, v54
	v_mfma_f32_16x16x32_bf16 v[114:117], v[152:155], v[148:151], v[114:117]
	v_mfma_f32_16x16x32_bf16 v[118:121], v[156:159], v[148:151], v[118:121]
	v_exp_f32_e32 v55, v55
	v_mfma_f32_16x16x32_bf16 v[122:125], v[160:163], v[148:151], v[122:125]
	v_exp_f32_e32 v56, v56
	v_mfma_f32_16x16x32_bf16 v[126:129], v[164:167], v[148:151], v[126:129]
	v_exp_f32_e32 v57, v57
	s_waitcnt vmcnt(7) lgkmcnt(0)
	s_barrier
	v_mfma_f32_16x16x32_bf16 v[66:69], v[184:187], v[168:171], v[66:69]
	ds_read_b128 v[136:139], v224 offset:0
	v_mfma_f32_16x16x32_bf16 v[70:73], v[188:191], v[168:171], v[70:73]
	ds_read_b128 v[140:143], v224 offset:2048
	v_mfma_f32_16x16x32_bf16 v[74:77], v[192:195], v[168:171], v[74:77]
	ds_read_b128 v[144:147], v224 offset:4096
	v_add_f32_e32 v50, 1.0, v50
	v_mfma_f32_16x16x32_bf16 v[78:81], v[196:199], v[168:171], v[78:81]
	ds_read_b128 v[148:151], v224 offset:6144
	v_mfma_f32_16x16x32_bf16 v[82:85], v[184:187], v[172:175], v[82:85]
	ds_read_b128 v[152:155], v232 offset:0
	v_add_f32_e32 v51, 1.0, v51
	v_mfma_f32_16x16x32_bf16 v[86:89], v[188:191], v[172:175], v[86:89]
	ds_read_b128 v[156:159], v232 offset:2048
	v_mfma_f32_16x16x32_bf16 v[90:93], v[192:195], v[172:175], v[90:93]
	ds_read_b128 v[160:163], v232 offset:4096
	v_add_f32_e32 v52, 1.0, v52
	v_mfma_f32_16x16x32_bf16 v[94:97], v[196:199], v[172:175], v[94:97]
	ds_read_b128 v[164:167], v232 offset:6144
	s_add_u32 m0, s8, 0xc000
	v_mfma_f32_16x16x32_bf16 v[98:101], v[184:187], v[176:179], v[98:101]
	global_load_lds_dwordx4 v200, s[4:5]
	s_add_u32 m0, s8, 0xc400
	v_mfma_f32_16x16x32_bf16 v[102:105], v[188:191], v[176:179], v[102:105]
	global_load_lds_dwordx4 v201, s[4:5]
	v_add_f32_e32 v53, 1.0, v53
	s_add_u32 m0, s8, 0xc800
	v_mfma_f32_16x16x32_bf16 v[106:109], v[192:195], v[176:179], v[106:109]
	global_load_lds_dwordx4 v202, s[4:5]
	s_add_u32 m0, s8, 0xcc00
	v_mfma_f32_16x16x32_bf16 v[110:113], v[196:199], v[176:179], v[110:113]
	global_load_lds_dwordx4 v203, s[4:5]
	v_add_f32_e32 v54, 1.0, v54
	s_add_u32 m0, s9, 0xc000
	v_mfma_f32_16x16x32_bf16 v[114:117], v[184:187], v[180:183], v[114:117]
	global_load_lds_dwordx4 v204, s[6:7]
	s_add_u32 m0, s9, 0xc400
	v_mfma_f32_16x16x32_bf16 v[118:121], v[188:191], v[180:183], v[118:121]
	global_load_lds_dwordx4 v205, s[6:7]
	v_add_f32_e32 v55, 1.0, v55
	v_mfma_f32_16x16x32_bf16 v[122:125], v[192:195], v[180:183], v[122:125]
	s_sub_u32 s4, s4, 0x780
	s_subb_u32 s5, s5, 0
	v_mfma_f32_16x16x32_bf16 v[126:129], v[196:199], v[180:183], v[126:129]
	s_add_u32 s6, s6, 0x3f880
	s_addc_u32 s7, s7, 0
	v_add_f32_e32 v56, 1.0, v56
	s_waitcnt lgkmcnt(0)
	v_mfma_f32_16x16x32_bf16 v[66:69], v[152:155], v[136:139], v[66:69]
	ds_read_b128 v[168:171], v229 offset:0
	v_mfma_f32_16x16x32_bf16 v[70:73], v[156:159], v[136:139], v[70:73]
	ds_read_b128 v[172:175], v229 offset:2048
	v_add_f32_e32 v57, 1.0, v57
	v_mfma_f32_16x16x32_bf16 v[74:77], v[160:163], v[136:139], v[74:77]
	ds_read_b128 v[176:179], v229 offset:4096
	v_rcp_f32_e32 v50, v50
	v_mfma_f32_16x16x32_bf16 v[78:81], v[164:167], v[136:139], v[78:81]
	ds_read_b128 v[180:183], v229 offset:6144
	v_rcp_f32_e32 v51, v51
	v_mfma_f32_16x16x32_bf16 v[82:85], v[152:155], v[140:143], v[82:85]
	ds_read_b128 v[184:187], v235 offset:0
	v_mfma_f32_16x16x32_bf16 v[86:89], v[156:159], v[140:143], v[86:89]
	ds_read_b128 v[188:191], v235 offset:2048
	v_rcp_f32_e32 v52, v52
	v_mfma_f32_16x16x32_bf16 v[90:93], v[160:163], v[140:143], v[90:93]
	ds_read_b128 v[192:195], v235 offset:4096
	v_rcp_f32_e32 v53, v53
	v_mfma_f32_16x16x32_bf16 v[94:97], v[164:167], v[140:143], v[94:97]
	ds_read_b128 v[196:199], v235 offset:6144
	v_rcp_f32_e32 v54, v54
	v_mfma_f32_16x16x32_bf16 v[98:101], v[152:155], v[144:147], v[98:101]
	v_mfma_f32_16x16x32_bf16 v[102:105], v[156:159], v[144:147], v[102:105]
	v_rcp_f32_e32 v55, v55
	v_mfma_f32_16x16x32_bf16 v[106:109], v[160:163], v[144:147], v[106:109]
	v_rcp_f32_e32 v56, v56
	v_mfma_f32_16x16x32_bf16 v[110:113], v[164:167], v[144:147], v[110:113]
	v_rcp_f32_e32 v57, v57
	v_mfma_f32_16x16x32_bf16 v[114:117], v[152:155], v[148:151], v[114:117]
	v_mfma_f32_16x16x32_bf16 v[118:121], v[156:159], v[148:151], v[118:121]
	v_cvt_pk_bf16_f32 v50, v50, v51
	v_mfma_f32_16x16x32_bf16 v[122:125], v[160:163], v[148:151], v[122:125]
	v_cvt_pk_bf16_f32 v51, v52, v53
	v_mfma_f32_16x16x32_bf16 v[126:129], v[164:167], v[148:151], v[126:129]
	v_cvt_pk_bf16_f32 v52, v54, v55
	s_waitcnt vmcnt(6) lgkmcnt(0)
	s_barrier
	v_mfma_f32_16x16x32_bf16 v[66:69], v[184:187], v[168:171], v[66:69]
	ds_read_b128 v[136:139], v218 offset:0
	v_mfma_f32_16x16x32_bf16 v[70:73], v[188:191], v[168:171], v[70:73]
	ds_read_b128 v[140:143], v218 offset:2048
	v_mfma_f32_16x16x32_bf16 v[74:77], v[192:195], v[168:171], v[74:77]
	ds_read_b128 v[144:147], v218 offset:4096
	v_cvt_pk_bf16_f32 v53, v56, v57
	v_mfma_f32_16x16x32_bf16 v[78:81], v[196:199], v[168:171], v[78:81]
	ds_read_b128 v[148:151], v218 offset:6144
	v_mfma_f32_16x16x32_bf16 v[82:85], v[184:187], v[172:175], v[82:85]
	ds_read_b128 v[152:155], v230 offset:0
	global_store_dwordx4 v241, v[50:53], s[10:11] offset:2048
	v_mfma_f32_16x16x32_bf16 v[86:89], v[188:191], v[172:175], v[86:89]
	ds_read_b128 v[156:159], v230 offset:2048
	v_mfma_f32_16x16x32_bf16 v[90:93], v[192:195], v[172:175], v[90:93]
	ds_read_b128 v[160:163], v230 offset:4096
	v_mul_f32_e32 v58, s12, v58
	v_mfma_f32_16x16x32_bf16 v[94:97], v[196:199], v[172:175], v[94:97]
	ds_read_b128 v[164:167], v230 offset:6144
	s_add_u32 m0, s8, 0x18000
	v_mfma_f32_16x16x32_bf16 v[98:101], v[184:187], v[176:179], v[98:101]
	global_load_lds_dwordx4 v200, s[4:5]
	s_add_u32 m0, s8, 0x18400
	v_mfma_f32_16x16x32_bf16 v[102:105], v[188:191], v[176:179], v[102:105]
	global_load_lds_dwordx4 v201, s[4:5]
	v_mul_f32_e32 v59, s12, v59
	s_add_u32 m0, s8, 0x18800
	v_mfma_f32_16x16x32_bf16 v[106:109], v[192:195], v[176:179], v[106:109]
	global_load_lds_dwordx4 v202, s[4:5]
	s_add_u32 m0, s8, 0x18c00
	v_mfma_f32_16x16x32_bf16 v[110:113], v[196:199], v[176:179], v[110:113]
	global_load_lds_dwordx4 v203, s[4:5]
	v_mul_f32_e32 v60, s12, v60
	s_add_u32 m0, s9, 0x18000
	v_mfma_f32_16x16x32_bf16 v[114:117], v[184:187], v[180:183], v[114:117]
	global_load_lds_dwordx4 v204, s[6:7]
	s_add_u32 m0, s9, 0x18400
	v_mfma_f32_16x16x32_bf16 v[118:121], v[188:191], v[180:183], v[118:121]
	global_load_lds_dwordx4 v205, s[6:7]
	v_mul_f32_e32 v61, s12, v61
	v_mfma_f32_16x16x32_bf16 v[122:125], v[192:195], v[180:183], v[122:125]
	s_add_u32 s4, s4, 0x80
	s_addc_u32 s5, s5, 0
	v_mfma_f32_16x16x32_bf16 v[126:129], v[196:199], v[180:183], v[126:129]
	s_add_u32 s6, s6, 0x80
	s_addc_u32 s7, s7, 0
	v_mul_f32_e32 v62, s12, v62
	s_waitcnt lgkmcnt(0)
	v_mfma_f32_16x16x32_bf16 v[66:69], v[152:155], v[136:139], v[66:69]
	ds_read_b128 v[168:171], v225 offset:0
	v_mfma_f32_16x16x32_bf16 v[70:73], v[156:159], v[136:139], v[70:73]
	ds_read_b128 v[172:175], v225 offset:2048
	v_mul_f32_e32 v63, s12, v63
	v_mfma_f32_16x16x32_bf16 v[74:77], v[160:163], v[136:139], v[74:77]
	ds_read_b128 v[176:179], v225 offset:4096
	v_mul_f32_e32 v64, s12, v64
	v_mfma_f32_16x16x32_bf16 v[78:81], v[164:167], v[136:139], v[78:81]
	ds_read_b128 v[180:183], v225 offset:6144
	v_mul_f32_e32 v65, s12, v65
	v_mfma_f32_16x16x32_bf16 v[82:85], v[152:155], v[140:143], v[82:85]
	ds_read_b128 v[184:187], v233 offset:0
	v_mfma_f32_16x16x32_bf16 v[86:89], v[156:159], v[140:143], v[86:89]
	ds_read_b128 v[188:191], v233 offset:2048
	v_exp_f32_e32 v58, v58
	v_mfma_f32_16x16x32_bf16 v[90:93], v[160:163], v[140:143], v[90:93]
	ds_read_b128 v[192:195], v233 offset:4096
	v_exp_f32_e32 v59, v59
	v_mfma_f32_16x16x32_bf16 v[94:97], v[164:167], v[140:143], v[94:97]
	ds_read_b128 v[196:199], v233 offset:6144
	v_exp_f32_e32 v60, v60
	v_mfma_f32_16x16x32_bf16 v[98:101], v[152:155], v[144:147], v[98:101]
	v_mfma_f32_16x16x32_bf16 v[102:105], v[156:159], v[144:147], v[102:105]
	v_exp_f32_e32 v61, v61
	v_mfma_f32_16x16x32_bf16 v[106:109], v[160:163], v[144:147], v[106:109]
	v_exp_f32_e32 v62, v62
	v_mfma_f32_16x16x32_bf16 v[110:113], v[164:167], v[144:147], v[110:113]
	v_exp_f32_e32 v63, v63
	v_mfma_f32_16x16x32_bf16 v[114:117], v[152:155], v[148:151], v[114:117]
	v_mfma_f32_16x16x32_bf16 v[118:121], v[156:159], v[148:151], v[118:121]
	v_exp_f32_e32 v64, v64
	v_mfma_f32_16x16x32_bf16 v[122:125], v[160:163], v[148:151], v[122:125]
	v_exp_f32_e32 v65, v65
	v_mfma_f32_16x16x32_bf16 v[126:129], v[164:167], v[148:151], v[126:129]
	v_add_f32_e32 v58, 1.0, v58
	s_waitcnt vmcnt(7) lgkmcnt(0)
	s_barrier
	v_mfma_f32_16x16x32_bf16 v[66:69], v[184:187], v[168:171], v[66:69]
	ds_read_b128 v[136:139], v219 offset:0
	v_mfma_f32_16x16x32_bf16 v[70:73], v[188:191], v[168:171], v[70:73]
	ds_read_b128 v[140:143], v219 offset:2048
	v_mfma_f32_16x16x32_bf16 v[74:77], v[192:195], v[168:171], v[74:77]
	ds_read_b128 v[144:147], v219 offset:4096
	v_add_f32_e32 v59, 1.0, v59
	v_mfma_f32_16x16x32_bf16 v[78:81], v[196:199], v[168:171], v[78:81]
	ds_read_b128 v[148:151], v219 offset:6144
	v_mfma_f32_16x16x32_bf16 v[82:85], v[184:187], v[172:175], v[82:85]
	ds_read_b128 v[152:155], v231 offset:0
	v_add_f32_e32 v60, 1.0, v60
	v_mfma_f32_16x16x32_bf16 v[86:89], v[188:191], v[172:175], v[86:89]
	ds_read_b128 v[156:159], v231 offset:2048
	v_mfma_f32_16x16x32_bf16 v[90:93], v[192:195], v[172:175], v[90:93]
	ds_read_b128 v[160:163], v231 offset:4096
	v_add_f32_e32 v61, 1.0, v61
	v_mfma_f32_16x16x32_bf16 v[94:97], v[196:199], v[172:175], v[94:97]
	ds_read_b128 v[164:167], v231 offset:6144
	s_mov_b32 m0, s8
	v_mfma_f32_16x16x32_bf16 v[98:101], v[184:187], v[176:179], v[98:101]
	global_load_lds_dwordx4 v200, s[4:5]
	s_add_u32 m0, s8, 0x400
	v_mfma_f32_16x16x32_bf16 v[102:105], v[188:191], v[176:179], v[102:105]
	global_load_lds_dwordx4 v201, s[4:5]
	v_add_f32_e32 v62, 1.0, v62
	s_add_u32 m0, s8, 0x800
	v_mfma_f32_16x16x32_bf16 v[106:109], v[192:195], v[176:179], v[106:109]
	global_load_lds_dwordx4 v202, s[4:5]
	s_add_u32 m0, s8, 0xc00
	v_mfma_f32_16x16x32_bf16 v[110:113], v[196:199], v[176:179], v[110:113]
	global_load_lds_dwordx4 v203, s[4:5]
	v_add_f32_e32 v63, 1.0, v63
	s_mov_b32 m0, s9
	v_mfma_f32_16x16x32_bf16 v[114:117], v[184:187], v[180:183], v[114:117]
	global_load_lds_dwordx4 v204, s[6:7]
	s_add_u32 m0, s9, 0x400
	v_mfma_f32_16x16x32_bf16 v[118:121], v[188:191], v[180:183], v[118:121]
	global_load_lds_dwordx4 v205, s[6:7]
	v_add_f32_e32 v64, 1.0, v64
	v_mfma_f32_16x16x32_bf16 v[122:125], v[192:195], v[180:183], v[122:125]
	s_add_u32 s4, s4, 0x80
	s_addc_u32 s5, s5, 0
	v_mfma_f32_16x16x32_bf16 v[126:129], v[196:199], v[180:183], v[126:129]
	s_add_u32 s6, s6, 0x80
	s_addc_u32 s7, s7, 0
	v_add_f32_e32 v65, 1.0, v65
	s_waitcnt lgkmcnt(0)
	v_mfma_f32_16x16x32_bf16 v[66:69], v[152:155], v[136:139], v[66:69]
	ds_read_b128 v[168:171], v228 offset:0
	v_mfma_f32_16x16x32_bf16 v[70:73], v[156:159], v[136:139], v[70:73]
	ds_read_b128 v[172:175], v228 offset:2048
	v_rcp_f32_e32 v58, v58
	v_mfma_f32_16x16x32_bf16 v[74:77], v[160:163], v[136:139], v[74:77]
	ds_read_b128 v[176:179], v228 offset:4096
	v_rcp_f32_e32 v59, v59
	v_mfma_f32_16x16x32_bf16 v[78:81], v[164:167], v[136:139], v[78:81]
	ds_read_b128 v[180:183], v228 offset:6144
	v_rcp_f32_e32 v60, v60
	v_mfma_f32_16x16x32_bf16 v[82:85], v[152:155], v[140:143], v[82:85]
	ds_read_b128 v[184:187], v234 offset:0
	v_mfma_f32_16x16x32_bf16 v[86:89], v[156:159], v[140:143], v[86:89]
	ds_read_b128 v[188:191], v234 offset:2048
	v_rcp_f32_e32 v61, v61
	v_mfma_f32_16x16x32_bf16 v[90:93], v[160:163], v[140:143], v[90:93]
	ds_read_b128 v[192:195], v234 offset:4096
	v_rcp_f32_e32 v62, v62
	v_mfma_f32_16x16x32_bf16 v[94:97], v[164:167], v[140:143], v[94:97]
	ds_read_b128 v[196:199], v234 offset:6144
	v_rcp_f32_e32 v63, v63
	v_mfma_f32_16x16x32_bf16 v[98:101], v[152:155], v[144:147], v[98:101]
	v_mfma_f32_16x16x32_bf16 v[102:105], v[156:159], v[144:147], v[102:105]
	v_rcp_f32_e32 v64, v64
	v_mfma_f32_16x16x32_bf16 v[106:109], v[160:163], v[144:147], v[106:109]
	v_rcp_f32_e32 v65, v65
	v_mfma_f32_16x16x32_bf16 v[110:113], v[164:167], v[144:147], v[110:113]
	v_cvt_pk_bf16_f32 v58, v58, v59
	v_mfma_f32_16x16x32_bf16 v[114:117], v[152:155], v[148:151], v[114:117]
	v_mfma_f32_16x16x32_bf16 v[118:121], v[156:159], v[148:151], v[118:121]
	v_cvt_pk_bf16_f32 v59, v60, v61
	v_mfma_f32_16x16x32_bf16 v[122:125], v[160:163], v[148:151], v[122:125]
	v_cvt_pk_bf16_f32 v60, v62, v63
	v_mfma_f32_16x16x32_bf16 v[126:129], v[164:167], v[148:151], v[126:129]
	v_cvt_pk_bf16_f32 v61, v64, v65
	s_waitcnt vmcnt(6) lgkmcnt(0)
	s_barrier
	v_mfma_f32_16x16x32_bf16 v[66:69], v[184:187], v[168:171], v[66:69]
	ds_read_b128 v[136:139], v224 offset:0
	v_mfma_f32_16x16x32_bf16 v[70:73], v[188:191], v[168:171], v[70:73]
	ds_read_b128 v[140:143], v224 offset:2048
	v_mfma_f32_16x16x32_bf16 v[74:77], v[192:195], v[168:171], v[74:77]
	ds_read_b128 v[144:147], v224 offset:4096
	v_mfma_f32_16x16x32_bf16 v[78:81], v[196:199], v[168:171], v[78:81]
	ds_read_b128 v[148:151], v224 offset:6144
	v_mfma_f32_16x16x32_bf16 v[82:85], v[184:187], v[172:175], v[82:85]
	ds_read_b128 v[152:155], v232 offset:0
	v_mfma_f32_16x16x32_bf16 v[86:89], v[188:191], v[172:175], v[86:89]
	ds_read_b128 v[156:159], v232 offset:2048
	v_mfma_f32_16x16x32_bf16 v[90:93], v[192:195], v[172:175], v[90:93]
	ds_read_b128 v[160:163], v232 offset:4096
	v_mfma_f32_16x16x32_bf16 v[94:97], v[196:199], v[172:175], v[94:97]
	ds_read_b128 v[164:167], v232 offset:6144
	s_add_u32 m0, s8, 0xc000
	v_mfma_f32_16x16x32_bf16 v[98:101], v[184:187], v[176:179], v[98:101]
	global_load_lds_dwordx4 v200, s[4:5]
	s_add_u32 m0, s8, 0xc400
	v_mfma_f32_16x16x32_bf16 v[102:105], v[188:191], v[176:179], v[102:105]
	global_load_lds_dwordx4 v201, s[4:5]
	s_add_u32 m0, s8, 0xc800
	v_mfma_f32_16x16x32_bf16 v[106:109], v[192:195], v[176:179], v[106:109]
	global_load_lds_dwordx4 v202, s[4:5]
	s_add_u32 m0, s8, 0xcc00
	v_mfma_f32_16x16x32_bf16 v[110:113], v[196:199], v[176:179], v[110:113]
	global_load_lds_dwordx4 v203, s[4:5]
	s_add_u32 m0, s9, 0xc000
	v_mfma_f32_16x16x32_bf16 v[114:117], v[184:187], v[180:183], v[114:117]
	global_load_lds_dwordx4 v204, s[6:7]
	s_add_u32 m0, s9, 0xc400
	v_mfma_f32_16x16x32_bf16 v[118:121], v[188:191], v[180:183], v[118:121]
	global_load_lds_dwordx4 v205, s[6:7]
	v_mfma_f32_16x16x32_bf16 v[122:125], v[192:195], v[180:183], v[122:125]
	s_add_u32 s4, s4, 0x80
	s_addc_u32 s5, s5, 0
	v_mfma_f32_16x16x32_bf16 v[126:129], v[196:199], v[180:183], v[126:129]
	s_add_u32 s6, s6, 0x80
	s_addc_u32 s7, s7, 0
	global_store_dwordx4 v241, v[58:61], s[10:11] offset:3072
	s_waitcnt lgkmcnt(0)
	v_mfma_f32_16x16x32_bf16 v[2:5], v[152:155], v[136:139], 0
	ds_read_b128 v[168:171], v229 offset:0
	v_mfma_f32_16x16x32_bf16 v[6:9], v[156:159], v[136:139], 0
	ds_read_b128 v[172:175], v229 offset:2048
	s_add_u32 s10, s28, s13
	s_addc_u32 s11, s29, 0
	v_mfma_f32_16x16x32_bf16 v[10:13], v[160:163], v[136:139], 0
	ds_read_b128 v[176:179], v229 offset:4096
	s_add_u32 s13, s13, 0x10000
	v_mfma_f32_16x16x32_bf16 v[14:17], v[164:167], v[136:139], 0
	ds_read_b128 v[180:183], v229 offset:6144
	v_mul_f32_e32 v66, s12, v66
	v_mfma_f32_16x16x32_bf16 v[18:21], v[152:155], v[140:143], 0
	ds_read_b128 v[184:187], v235 offset:0
	v_mfma_f32_16x16x32_bf16 v[22:25], v[156:159], v[140:143], 0
	ds_read_b128 v[188:191], v235 offset:2048
	v_mul_f32_e32 v67, s12, v67
	v_mfma_f32_16x16x32_bf16 v[26:29], v[160:163], v[140:143], 0
	ds_read_b128 v[192:195], v235 offset:4096
	v_mul_f32_e32 v68, s12, v68
	v_mfma_f32_16x16x32_bf16 v[30:33], v[164:167], v[140:143], 0
	ds_read_b128 v[196:199], v235 offset:6144
	v_mul_f32_e32 v69, s12, v69
	v_mfma_f32_16x16x32_bf16 v[34:37], v[152:155], v[144:147], 0
	v_mfma_f32_16x16x32_bf16 v[38:41], v[156:159], v[144:147], 0
	v_mul_f32_e32 v70, s12, v70
	v_mfma_f32_16x16x32_bf16 v[42:45], v[160:163], v[144:147], 0
	v_mul_f32_e32 v71, s12, v71
	v_mfma_f32_16x16x32_bf16 v[46:49], v[164:167], v[144:147], 0
	v_mul_f32_e32 v72, s12, v72
	v_mfma_f32_16x16x32_bf16 v[50:53], v[152:155], v[148:151], 0
	v_mfma_f32_16x16x32_bf16 v[54:57], v[156:159], v[148:151], 0
	v_mul_f32_e32 v73, s12, v73
	v_mfma_f32_16x16x32_bf16 v[58:61], v[160:163], v[148:151], 0
	v_exp_f32_e32 v66, v66
	v_mfma_f32_16x16x32_bf16 v[62:65], v[164:167], v[148:151], 0
	v_exp_f32_e32 v67, v67
	s_waitcnt vmcnt(7) lgkmcnt(0)
	s_barrier
	v_mfma_f32_16x16x32_bf16 v[2:5], v[184:187], v[168:171], v[2:5]
	ds_read_b128 v[136:139], v218 offset:0
	v_mfma_f32_16x16x32_bf16 v[6:9], v[188:191], v[168:171], v[6:9]
	ds_read_b128 v[140:143], v218 offset:2048
	v_mfma_f32_16x16x32_bf16 v[10:13], v[192:195], v[168:171], v[10:13]
	ds_read_b128 v[144:147], v218 offset:4096
	v_exp_f32_e32 v68, v68
	v_mfma_f32_16x16x32_bf16 v[14:17], v[196:199], v[168:171], v[14:17]
	ds_read_b128 v[148:151], v218 offset:6144
	v_mfma_f32_16x16x32_bf16 v[18:21], v[184:187], v[172:175], v[18:21]
	ds_read_b128 v[152:155], v230 offset:0
	v_exp_f32_e32 v69, v69
	v_mfma_f32_16x16x32_bf16 v[22:25], v[188:191], v[172:175], v[22:25]
	ds_read_b128 v[156:159], v230 offset:2048
	v_mfma_f32_16x16x32_bf16 v[26:29], v[192:195], v[172:175], v[26:29]
	ds_read_b128 v[160:163], v230 offset:4096
	v_exp_f32_e32 v70, v70
	v_mfma_f32_16x16x32_bf16 v[30:33], v[196:199], v[172:175], v[30:33]
	ds_read_b128 v[164:167], v230 offset:6144
	s_add_u32 m0, s8, 0x18000
	v_mfma_f32_16x16x32_bf16 v[34:37], v[184:187], v[176:179], v[34:37]
	global_load_lds_dwordx4 v200, s[4:5]
	s_add_u32 m0, s8, 0x18400
	v_mfma_f32_16x16x32_bf16 v[38:41], v[188:191], v[176:179], v[38:41]
	global_load_lds_dwordx4 v201, s[4:5]
	v_exp_f32_e32 v71, v71
	s_add_u32 m0, s8, 0x18800
	v_mfma_f32_16x16x32_bf16 v[42:45], v[192:195], v[176:179], v[42:45]
	global_load_lds_dwordx4 v202, s[4:5]
	s_add_u32 m0, s8, 0x18c00
	v_mfma_f32_16x16x32_bf16 v[46:49], v[196:199], v[176:179], v[46:49]
	global_load_lds_dwordx4 v203, s[4:5]
	v_exp_f32_e32 v72, v72
	s_add_u32 m0, s9, 0x18000
	v_mfma_f32_16x16x32_bf16 v[50:53], v[184:187], v[180:183], v[50:53]
	global_load_lds_dwordx4 v204, s[6:7]
	s_add_u32 m0, s9, 0x18400
	v_mfma_f32_16x16x32_bf16 v[54:57], v[188:191], v[180:183], v[54:57]
	global_load_lds_dwordx4 v205, s[6:7]
	v_exp_f32_e32 v73, v73
	v_mfma_f32_16x16x32_bf16 v[58:61], v[192:195], v[180:183], v[58:61]
	s_add_u32 s4, s4, 0x80
	s_addc_u32 s5, s5, 0
	v_mfma_f32_16x16x32_bf16 v[62:65], v[196:199], v[180:183], v[62:65]
	s_add_u32 s6, s6, 0x80
	s_addc_u32 s7, s7, 0
	v_add_f32_e32 v66, 1.0, v66
	s_waitcnt lgkmcnt(0)
	v_mfma_f32_16x16x32_bf16 v[2:5], v[152:155], v[136:139], v[2:5]
	ds_read_b128 v[168:171], v225 offset:0
	v_mfma_f32_16x16x32_bf16 v[6:9], v[156:159], v[136:139], v[6:9]
	ds_read_b128 v[172:175], v225 offset:2048
	v_add_f32_e32 v67, 1.0, v67
	v_mfma_f32_16x16x32_bf16 v[10:13], v[160:163], v[136:139], v[10:13]
	ds_read_b128 v[176:179], v225 offset:4096
	v_add_f32_e32 v68, 1.0, v68
	v_mfma_f32_16x16x32_bf16 v[14:17], v[164:167], v[136:139], v[14:17]
	ds_read_b128 v[180:183], v225 offset:6144
	v_add_f32_e32 v69, 1.0, v69
	v_mfma_f32_16x16x32_bf16 v[18:21], v[152:155], v[140:143], v[18:21]
	ds_read_b128 v[184:187], v233 offset:0
	v_mfma_f32_16x16x32_bf16 v[22:25], v[156:159], v[140:143], v[22:25]
	ds_read_b128 v[188:191], v233 offset:2048
	v_add_f32_e32 v70, 1.0, v70
	v_mfma_f32_16x16x32_bf16 v[26:29], v[160:163], v[140:143], v[26:29]
	ds_read_b128 v[192:195], v233 offset:4096
	v_add_f32_e32 v71, 1.0, v71
	v_mfma_f32_16x16x32_bf16 v[30:33], v[164:167], v[140:143], v[30:33]
	ds_read_b128 v[196:199], v233 offset:6144
	v_add_f32_e32 v72, 1.0, v72
	v_mfma_f32_16x16x32_bf16 v[34:37], v[152:155], v[144:147], v[34:37]
	v_mfma_f32_16x16x32_bf16 v[38:41], v[156:159], v[144:147], v[38:41]
	v_add_f32_e32 v73, 1.0, v73
	v_mfma_f32_16x16x32_bf16 v[42:45], v[160:163], v[144:147], v[42:45]
	v_rcp_f32_e32 v66, v66
	v_mfma_f32_16x16x32_bf16 v[46:49], v[164:167], v[144:147], v[46:49]
	v_rcp_f32_e32 v67, v67
	v_mfma_f32_16x16x32_bf16 v[50:53], v[152:155], v[148:151], v[50:53]
	v_mfma_f32_16x16x32_bf16 v[54:57], v[156:159], v[148:151], v[54:57]
	v_rcp_f32_e32 v68, v68
	v_mfma_f32_16x16x32_bf16 v[58:61], v[160:163], v[148:151], v[58:61]
	v_rcp_f32_e32 v69, v69
	v_mfma_f32_16x16x32_bf16 v[62:65], v[164:167], v[148:151], v[62:65]
	v_rcp_f32_e32 v70, v70
	s_waitcnt vmcnt(7) lgkmcnt(0)
	s_barrier
	v_mfma_f32_16x16x32_bf16 v[2:5], v[184:187], v[168:171], v[2:5]
	ds_read_b128 v[136:139], v219 offset:0
	v_mfma_f32_16x16x32_bf16 v[6:9], v[188:191], v[168:171], v[6:9]
	ds_read_b128 v[140:143], v219 offset:2048
	v_mfma_f32_16x16x32_bf16 v[10:13], v[192:195], v[168:171], v[10:13]
	ds_read_b128 v[144:147], v219 offset:4096
	v_rcp_f32_e32 v71, v71
	v_mfma_f32_16x16x32_bf16 v[14:17], v[196:199], v[168:171], v[14:17]
	ds_read_b128 v[148:151], v219 offset:6144
	v_mfma_f32_16x16x32_bf16 v[18:21], v[184:187], v[172:175], v[18:21]
	ds_read_b128 v[152:155], v231 offset:0
	v_rcp_f32_e32 v72, v72
	v_mfma_f32_16x16x32_bf16 v[22:25], v[188:191], v[172:175], v[22:25]
	ds_read_b128 v[156:159], v231 offset:2048
	v_mfma_f32_16x16x32_bf16 v[26:29], v[192:195], v[172:175], v[26:29]
	ds_read_b128 v[160:163], v231 offset:4096
	v_rcp_f32_e32 v73, v73
	v_mfma_f32_16x16x32_bf16 v[30:33], v[196:199], v[172:175], v[30:33]
	ds_read_b128 v[164:167], v231 offset:6144
	s_mov_b32 m0, s8
	v_mfma_f32_16x16x32_bf16 v[34:37], v[184:187], v[176:179], v[34:37]
	global_load_lds_dwordx4 v200, s[4:5]
	s_add_u32 m0, s8, 0x400
	v_mfma_f32_16x16x32_bf16 v[38:41], v[188:191], v[176:179], v[38:41]
	global_load_lds_dwordx4 v201, s[4:5]
	v_cvt_pk_bf16_f32 v66, v66, v67
	s_add_u32 m0, s8, 0x800
	v_mfma_f32_16x16x32_bf16 v[42:45], v[192:195], v[176:179], v[42:45]
	global_load_lds_dwordx4 v202, s[4:5]
	s_add_u32 m0, s8, 0xc00
	v_mfma_f32_16x16x32_bf16 v[46:49], v[196:199], v[176:179], v[46:49]
	global_load_lds_dwordx4 v203, s[4:5]
	v_cvt_pk_bf16_f32 v67, v68, v69
	s_mov_b32 m0, s9
	v_mfma_f32_16x16x32_bf16 v[50:53], v[184:187], v[180:183], v[50:53]
	global_load_lds_dwordx4 v204, s[6:7]
	s_add_u32 m0, s9, 0x400
	v_mfma_f32_16x16x32_bf16 v[54:57], v[188:191], v[180:183], v[54:57]
	global_load_lds_dwordx4 v205, s[6:7]
	v_cvt_pk_bf16_f32 v68, v70, v71
	v_mfma_f32_16x16x32_bf16 v[58:61], v[192:195], v[180:183], v[58:61]
	s_add_u32 s4, s4, 0x80
	s_addc_u32 s5, s5, 0
	v_mfma_f32_16x16x32_bf16 v[62:65], v[196:199], v[180:183], v[62:65]
	s_add_u32 s6, s6, 0x80
	s_addc_u32 s7, s7, 0
	v_cvt_pk_bf16_f32 v69, v72, v73
	s_waitcnt lgkmcnt(0)
	v_mfma_f32_16x16x32_bf16 v[2:5], v[152:155], v[136:139], v[2:5]
	ds_read_b128 v[168:171], v228 offset:0
	v_mfma_f32_16x16x32_bf16 v[6:9], v[156:159], v[136:139], v[6:9]
	ds_read_b128 v[172:175], v228 offset:2048
	global_store_dwordx4 v240, v[66:69], s[10:11] offset:0
	v_mfma_f32_16x16x32_bf16 v[10:13], v[160:163], v[136:139], v[10:13]
	ds_read_b128 v[176:179], v228 offset:4096
	v_mul_f32_e32 v74, s12, v74
	v_mfma_f32_16x16x32_bf16 v[14:17], v[164:167], v[136:139], v[14:17]
	ds_read_b128 v[180:183], v228 offset:6144
	v_mul_f32_e32 v75, s12, v75
	v_mfma_f32_16x16x32_bf16 v[18:21], v[152:155], v[140:143], v[18:21]
	ds_read_b128 v[184:187], v234 offset:0
	v_mfma_f32_16x16x32_bf16 v[22:25], v[156:159], v[140:143], v[22:25]
	ds_read_b128 v[188:191], v234 offset:2048
	v_mul_f32_e32 v76, s12, v76
	v_mfma_f32_16x16x32_bf16 v[26:29], v[160:163], v[140:143], v[26:29]
	ds_read_b128 v[192:195], v234 offset:4096
	v_mul_f32_e32 v77, s12, v77
	v_mfma_f32_16x16x32_bf16 v[30:33], v[164:167], v[140:143], v[30:33]
	ds_read_b128 v[196:199], v234 offset:6144
	v_mul_f32_e32 v78, s12, v78
	v_mfma_f32_16x16x32_bf16 v[34:37], v[152:155], v[144:147], v[34:37]
	v_mfma_f32_16x16x32_bf16 v[38:41], v[156:159], v[144:147], v[38:41]
	v_mul_f32_e32 v79, s12, v79
	v_mfma_f32_16x16x32_bf16 v[42:45], v[160:163], v[144:147], v[42:45]
	v_mul_f32_e32 v80, s12, v80
	v_mfma_f32_16x16x32_bf16 v[46:49], v[164:167], v[144:147], v[46:49]
	v_mul_f32_e32 v81, s12, v81
	v_mfma_f32_16x16x32_bf16 v[50:53], v[152:155], v[148:151], v[50:53]
	v_mfma_f32_16x16x32_bf16 v[54:57], v[156:159], v[148:151], v[54:57]
	v_exp_f32_e32 v74, v74
	v_mfma_f32_16x16x32_bf16 v[58:61], v[160:163], v[148:151], v[58:61]
	v_exp_f32_e32 v75, v75
	v_mfma_f32_16x16x32_bf16 v[62:65], v[164:167], v[148:151], v[62:65]
	v_exp_f32_e32 v76, v76
	s_waitcnt vmcnt(7) lgkmcnt(0)
	s_barrier
	v_mfma_f32_16x16x32_bf16 v[2:5], v[184:187], v[168:171], v[2:5]
	ds_read_b128 v[136:139], v224 offset:0
	v_mfma_f32_16x16x32_bf16 v[6:9], v[188:191], v[168:171], v[6:9]
	ds_read_b128 v[140:143], v224 offset:2048
	v_mfma_f32_16x16x32_bf16 v[10:13], v[192:195], v[168:171], v[10:13]
	ds_read_b128 v[144:147], v224 offset:4096
	v_exp_f32_e32 v77, v77
	v_mfma_f32_16x16x32_bf16 v[14:17], v[196:199], v[168:171], v[14:17]
	ds_read_b128 v[148:151], v224 offset:6144
	v_mfma_f32_16x16x32_bf16 v[18:21], v[184:187], v[172:175], v[18:21]
	ds_read_b128 v[152:155], v232 offset:0
	v_exp_f32_e32 v78, v78
	v_mfma_f32_16x16x32_bf16 v[22:25], v[188:191], v[172:175], v[22:25]
	ds_read_b128 v[156:159], v232 offset:2048
	v_mfma_f32_16x16x32_bf16 v[26:29], v[192:195], v[172:175], v[26:29]
	ds_read_b128 v[160:163], v232 offset:4096
	v_exp_f32_e32 v79, v79
	v_mfma_f32_16x16x32_bf16 v[30:33], v[196:199], v[172:175], v[30:33]
	ds_read_b128 v[164:167], v232 offset:6144
	s_add_u32 m0, s8, 0xc000
	v_mfma_f32_16x16x32_bf16 v[34:37], v[184:187], v[176:179], v[34:37]
	global_load_lds_dwordx4 v200, s[4:5]
	s_add_u32 m0, s8, 0xc400
	v_mfma_f32_16x16x32_bf16 v[38:41], v[188:191], v[176:179], v[38:41]
	global_load_lds_dwordx4 v201, s[4:5]
	v_exp_f32_e32 v80, v80
	s_add_u32 m0, s8, 0xc800
	v_mfma_f32_16x16x32_bf16 v[42:45], v[192:195], v[176:179], v[42:45]
	global_load_lds_dwordx4 v202, s[4:5]
	s_add_u32 m0, s8, 0xcc00
	v_mfma_f32_16x16x32_bf16 v[46:49], v[196:199], v[176:179], v[46:49]
	global_load_lds_dwordx4 v203, s[4:5]
	v_exp_f32_e32 v81, v81
	s_add_u32 m0, s9, 0xc000
	v_mfma_f32_16x16x32_bf16 v[50:53], v[184:187], v[180:183], v[50:53]
	global_load_lds_dwordx4 v204, s[6:7]
	s_add_u32 m0, s9, 0xc400
	v_mfma_f32_16x16x32_bf16 v[54:57], v[188:191], v[180:183], v[54:57]
	global_load_lds_dwordx4 v205, s[6:7]
	v_add_f32_e32 v74, 1.0, v74
	v_mfma_f32_16x16x32_bf16 v[58:61], v[192:195], v[180:183], v[58:61]
	s_add_u32 s4, s4, 0x80
	s_addc_u32 s5, s5, 0
	v_mfma_f32_16x16x32_bf16 v[62:65], v[196:199], v[180:183], v[62:65]
	s_add_u32 s6, s6, 0x80
	s_addc_u32 s7, s7, 0
	v_add_f32_e32 v75, 1.0, v75
	s_waitcnt lgkmcnt(0)
	v_mfma_f32_16x16x32_bf16 v[2:5], v[152:155], v[136:139], v[2:5]
	ds_read_b128 v[168:171], v229 offset:0
	v_mfma_f32_16x16x32_bf16 v[6:9], v[156:159], v[136:139], v[6:9]
	ds_read_b128 v[172:175], v229 offset:2048
	v_add_f32_e32 v76, 1.0, v76
	v_mfma_f32_16x16x32_bf16 v[10:13], v[160:163], v[136:139], v[10:13]
	ds_read_b128 v[176:179], v229 offset:4096
	v_add_f32_e32 v77, 1.0, v77
	v_mfma_f32_16x16x32_bf16 v[14:17], v[164:167], v[136:139], v[14:17]
	ds_read_b128 v[180:183], v229 offset:6144
	v_add_f32_e32 v78, 1.0, v78
	v_mfma_f32_16x16x32_bf16 v[18:21], v[152:155], v[140:143], v[18:21]
	ds_read_b128 v[184:187], v235 offset:0
	v_mfma_f32_16x16x32_bf16 v[22:25], v[156:159], v[140:143], v[22:25]
	ds_read_b128 v[188:191], v235 offset:2048
	v_add_f32_e32 v79, 1.0, v79
	v_mfma_f32_16x16x32_bf16 v[26:29], v[160:163], v[140:143], v[26:29]
	ds_read_b128 v[192:195], v235 offset:4096
	v_add_f32_e32 v80, 1.0, v80
	v_mfma_f32_16x16x32_bf16 v[30:33], v[164:167], v[140:143], v[30:33]
	ds_read_b128 v[196:199], v235 offset:6144
	v_add_f32_e32 v81, 1.0, v81
	v_mfma_f32_16x16x32_bf16 v[34:37], v[152:155], v[144:147], v[34:37]
	v_mfma_f32_16x16x32_bf16 v[38:41], v[156:159], v[144:147], v[38:41]
	v_rcp_f32_e32 v74, v74
	v_mfma_f32_16x16x32_bf16 v[42:45], v[160:163], v[144:147], v[42:45]
	v_rcp_f32_e32 v75, v75
	v_mfma_f32_16x16x32_bf16 v[46:49], v[164:167], v[144:147], v[46:49]
	v_rcp_f32_e32 v76, v76
	v_mfma_f32_16x16x32_bf16 v[50:53], v[152:155], v[148:151], v[50:53]
	v_mfma_f32_16x16x32_bf16 v[54:57], v[156:159], v[148:151], v[54:57]
	v_rcp_f32_e32 v77, v77
	v_mfma_f32_16x16x32_bf16 v[58:61], v[160:163], v[148:151], v[58:61]
	v_rcp_f32_e32 v78, v78
	v_mfma_f32_16x16x32_bf16 v[62:65], v[164:167], v[148:151], v[62:65]
	v_rcp_f32_e32 v79, v79
	s_waitcnt vmcnt(7) lgkmcnt(0)
	s_barrier
	v_mfma_f32_16x16x32_bf16 v[2:5], v[184:187], v[168:171], v[2:5]
	ds_read_b128 v[136:139], v218 offset:0
	v_mfma_f32_16x16x32_bf16 v[6:9], v[188:191], v[168:171], v[6:9]
	ds_read_b128 v[140:143], v218 offset:2048
	v_mfma_f32_16x16x32_bf16 v[10:13], v[192:195], v[168:171], v[10:13]
	ds_read_b128 v[144:147], v218 offset:4096
	v_rcp_f32_e32 v80, v80
	v_mfma_f32_16x16x32_bf16 v[14:17], v[196:199], v[168:171], v[14:17]
	ds_read_b128 v[148:151], v218 offset:6144
	v_mfma_f32_16x16x32_bf16 v[18:21], v[184:187], v[172:175], v[18:21]
	ds_read_b128 v[152:155], v230 offset:0
	v_rcp_f32_e32 v81, v81
	v_mfma_f32_16x16x32_bf16 v[22:25], v[188:191], v[172:175], v[22:25]
	ds_read_b128 v[156:159], v230 offset:2048
	v_mfma_f32_16x16x32_bf16 v[26:29], v[192:195], v[172:175], v[26:29]
	ds_read_b128 v[160:163], v230 offset:4096
	v_cvt_pk_bf16_f32 v74, v74, v75
	v_mfma_f32_16x16x32_bf16 v[30:33], v[196:199], v[172:175], v[30:33]
	ds_read_b128 v[164:167], v230 offset:6144
	s_add_u32 m0, s8, 0x18000
	v_mfma_f32_16x16x32_bf16 v[34:37], v[184:187], v[176:179], v[34:37]
	global_load_lds_dwordx4 v200, s[4:5]
	s_add_u32 m0, s8, 0x18400
	v_mfma_f32_16x16x32_bf16 v[38:41], v[188:191], v[176:179], v[38:41]
	global_load_lds_dwordx4 v201, s[4:5]
	v_cvt_pk_bf16_f32 v75, v76, v77
	s_add_u32 m0, s8, 0x18800
	v_mfma_f32_16x16x32_bf16 v[42:45], v[192:195], v[176:179], v[42:45]
	global_load_lds_dwordx4 v202, s[4:5]
	s_add_u32 m0, s8, 0x18c00
	v_mfma_f32_16x16x32_bf16 v[46:49], v[196:199], v[176:179], v[46:49]
	global_load_lds_dwordx4 v203, s[4:5]
	v_cvt_pk_bf16_f32 v76, v78, v79
	s_add_u32 m0, s9, 0x18000
	v_mfma_f32_16x16x32_bf16 v[50:53], v[184:187], v[180:183], v[50:53]
	global_load_lds_dwordx4 v204, s[6:7]
	s_add_u32 m0, s9, 0x18400
	v_mfma_f32_16x16x32_bf16 v[54:57], v[188:191], v[180:183], v[54:57]
	global_load_lds_dwordx4 v205, s[6:7]
	v_cvt_pk_bf16_f32 v77, v80, v81
	v_mfma_f32_16x16x32_bf16 v[58:61], v[192:195], v[180:183], v[58:61]
	s_add_u32 s4, s4, 0x80
	s_addc_u32 s5, s5, 0
	v_mfma_f32_16x16x32_bf16 v[62:65], v[196:199], v[180:183], v[62:65]
	s_add_u32 s6, s6, 0x80
	s_addc_u32 s7, s7, 0
	global_store_dwordx4 v240, v[74:77], s[10:11] offset:1024
	s_waitcnt lgkmcnt(0)
	v_mfma_f32_16x16x32_bf16 v[2:5], v[152:155], v[136:139], v[2:5]
	ds_read_b128 v[168:171], v225 offset:0
	v_mfma_f32_16x16x32_bf16 v[6:9], v[156:159], v[136:139], v[6:9]
	ds_read_b128 v[172:175], v225 offset:2048
	v_mul_f32_e32 v82, s12, v82
	v_mfma_f32_16x16x32_bf16 v[10:13], v[160:163], v[136:139], v[10:13]
	ds_read_b128 v[176:179], v225 offset:4096
	v_mul_f32_e32 v83, s12, v83
	v_mfma_f32_16x16x32_bf16 v[14:17], v[164:167], v[136:139], v[14:17]
	ds_read_b128 v[180:183], v225 offset:6144
	v_mul_f32_e32 v84, s12, v84
	v_mfma_f32_16x16x32_bf16 v[18:21], v[152:155], v[140:143], v[18:21]
	ds_read_b128 v[184:187], v233 offset:0
	v_mfma_f32_16x16x32_bf16 v[22:25], v[156:159], v[140:143], v[22:25]
	ds_read_b128 v[188:191], v233 offset:2048
	v_mul_f32_e32 v85, s12, v85
	v_mfma_f32_16x16x32_bf16 v[26:29], v[160:163], v[140:143], v[26:29]
	ds_read_b128 v[192:195], v233 offset:4096
	v_mul_f32_e32 v86, s12, v86
	v_mfma_f32_16x16x32_bf16 v[30:33], v[164:167], v[140:143], v[30:33]
	ds_read_b128 v[196:199], v233 offset:6144
	v_mul_f32_e32 v87, s12, v87
	v_mfma_f32_16x16x32_bf16 v[34:37], v[152:155], v[144:147], v[34:37]
	v_mfma_f32_16x16x32_bf16 v[38:41], v[156:159], v[144:147], v[38:41]
	v_mul_f32_e32 v88, s12, v88
	v_mfma_f32_16x16x32_bf16 v[42:45], v[160:163], v[144:147], v[42:45]
	v_mul_f32_e32 v89, s12, v89
	v_mfma_f32_16x16x32_bf16 v[46:49], v[164:167], v[144:147], v[46:49]
	v_exp_f32_e32 v82, v82
	v_mfma_f32_16x16x32_bf16 v[50:53], v[152:155], v[148:151], v[50:53]
	v_mfma_f32_16x16x32_bf16 v[54:57], v[156:159], v[148:151], v[54:57]
	v_exp_f32_e32 v83, v83
	v_mfma_f32_16x16x32_bf16 v[58:61], v[160:163], v[148:151], v[58:61]
	v_exp_f32_e32 v84, v84
	v_mfma_f32_16x16x32_bf16 v[62:65], v[164:167], v[148:151], v[62:65]
	v_exp_f32_e32 v85, v85
	s_waitcnt vmcnt(7) lgkmcnt(0)
	s_barrier
	v_mfma_f32_16x16x32_bf16 v[2:5], v[184:187], v[168:171], v[2:5]
	ds_read_b128 v[136:139], v219 offset:0
	v_mfma_f32_16x16x32_bf16 v[6:9], v[188:191], v[168:171], v[6:9]
	ds_read_b128 v[140:143], v219 offset:2048
	v_mfma_f32_16x16x32_bf16 v[10:13], v[192:195], v[168:171], v[10:13]
	ds_read_b128 v[144:147], v219 offset:4096
	v_exp_f32_e32 v86, v86
	v_mfma_f32_16x16x32_bf16 v[14:17], v[196:199], v[168:171], v[14:17]
	ds_read_b128 v[148:151], v219 offset:6144
	v_mfma_f32_16x16x32_bf16 v[18:21], v[184:187], v[172:175], v[18:21]
	ds_read_b128 v[152:155], v231 offset:0
	v_exp_f32_e32 v87, v87
	v_mfma_f32_16x16x32_bf16 v[22:25], v[188:191], v[172:175], v[22:25]
	ds_read_b128 v[156:159], v231 offset:2048
	v_mfma_f32_16x16x32_bf16 v[26:29], v[192:195], v[172:175], v[26:29]
	ds_read_b128 v[160:163], v231 offset:4096
	v_exp_f32_e32 v88, v88
	v_mfma_f32_16x16x32_bf16 v[30:33], v[196:199], v[172:175], v[30:33]
	ds_read_b128 v[164:167], v231 offset:6144
	s_mov_b32 m0, s8
	v_mfma_f32_16x16x32_bf16 v[34:37], v[184:187], v[176:179], v[34:37]
	global_load_lds_dwordx4 v200, s[4:5]
	s_add_u32 m0, s8, 0x400
	v_mfma_f32_16x16x32_bf16 v[38:41], v[188:191], v[176:179], v[38:41]
	global_load_lds_dwordx4 v201, s[4:5]
	v_exp_f32_e32 v89, v89
	s_add_u32 m0, s8, 0x800
	v_mfma_f32_16x16x32_bf16 v[42:45], v[192:195], v[176:179], v[42:45]
	global_load_lds_dwordx4 v202, s[4:5]
	s_add_u32 m0, s8, 0xc00
	v_mfma_f32_16x16x32_bf16 v[46:49], v[196:199], v[176:179], v[46:49]
	global_load_lds_dwordx4 v203, s[4:5]
	v_add_f32_e32 v82, 1.0, v82
	s_mov_b32 m0, s9
	v_mfma_f32_16x16x32_bf16 v[50:53], v[184:187], v[180:183], v[50:53]
	global_load_lds_dwordx4 v204, s[6:7]
	s_add_u32 m0, s9, 0x400
	v_mfma_f32_16x16x32_bf16 v[54:57], v[188:191], v[180:183], v[54:57]
	global_load_lds_dwordx4 v205, s[6:7]
	v_add_f32_e32 v83, 1.0, v83
	v_mfma_f32_16x16x32_bf16 v[58:61], v[192:195], v[180:183], v[58:61]
	s_add_u32 s4, s4, 0x80
	s_addc_u32 s5, s5, 0
	v_mfma_f32_16x16x32_bf16 v[62:65], v[196:199], v[180:183], v[62:65]
	s_add_u32 s6, s6, 0x80
	s_addc_u32 s7, s7, 0
	v_add_f32_e32 v84, 1.0, v84
	s_waitcnt lgkmcnt(0)
	v_mfma_f32_16x16x32_bf16 v[2:5], v[152:155], v[136:139], v[2:5]
	ds_read_b128 v[168:171], v228 offset:0
	v_mfma_f32_16x16x32_bf16 v[6:9], v[156:159], v[136:139], v[6:9]
	ds_read_b128 v[172:175], v228 offset:2048
	v_add_f32_e32 v85, 1.0, v85
	v_mfma_f32_16x16x32_bf16 v[10:13], v[160:163], v[136:139], v[10:13]
	ds_read_b128 v[176:179], v228 offset:4096
	v_add_f32_e32 v86, 1.0, v86
	v_mfma_f32_16x16x32_bf16 v[14:17], v[164:167], v[136:139], v[14:17]
	ds_read_b128 v[180:183], v228 offset:6144
	v_add_f32_e32 v87, 1.0, v87
	v_mfma_f32_16x16x32_bf16 v[18:21], v[152:155], v[140:143], v[18:21]
	ds_read_b128 v[184:187], v234 offset:0
	v_mfma_f32_16x16x32_bf16 v[22:25], v[156:159], v[140:143], v[22:25]
	ds_read_b128 v[188:191], v234 offset:2048
	v_add_f32_e32 v88, 1.0, v88
	v_mfma_f32_16x16x32_bf16 v[26:29], v[160:163], v[140:143], v[26:29]
	ds_read_b128 v[192:195], v234 offset:4096
	v_add_f32_e32 v89, 1.0, v89
	v_mfma_f32_16x16x32_bf16 v[30:33], v[164:167], v[140:143], v[30:33]
	ds_read_b128 v[196:199], v234 offset:6144
	v_rcp_f32_e32 v82, v82
	v_mfma_f32_16x16x32_bf16 v[34:37], v[152:155], v[144:147], v[34:37]
	v_mfma_f32_16x16x32_bf16 v[38:41], v[156:159], v[144:147], v[38:41]
	v_rcp_f32_e32 v83, v83
	v_mfma_f32_16x16x32_bf16 v[42:45], v[160:163], v[144:147], v[42:45]
	v_rcp_f32_e32 v84, v84
	v_mfma_f32_16x16x32_bf16 v[46:49], v[164:167], v[144:147], v[46:49]
	v_rcp_f32_e32 v85, v85
	v_mfma_f32_16x16x32_bf16 v[50:53], v[152:155], v[148:151], v[50:53]
	v_mfma_f32_16x16x32_bf16 v[54:57], v[156:159], v[148:151], v[54:57]
	v_rcp_f32_e32 v86, v86
	v_mfma_f32_16x16x32_bf16 v[58:61], v[160:163], v[148:151], v[58:61]
	v_rcp_f32_e32 v87, v87
	v_mfma_f32_16x16x32_bf16 v[62:65], v[164:167], v[148:151], v[62:65]
	v_rcp_f32_e32 v88, v88
	s_waitcnt vmcnt(7) lgkmcnt(0)
	s_barrier
	v_mfma_f32_16x16x32_bf16 v[2:5], v[184:187], v[168:171], v[2:5]
	ds_read_b128 v[136:139], v224 offset:0
	v_mfma_f32_16x16x32_bf16 v[6:9], v[188:191], v[168:171], v[6:9]
	ds_read_b128 v[140:143], v224 offset:2048
	v_mfma_f32_16x16x32_bf16 v[10:13], v[192:195], v[168:171], v[10:13]
	ds_read_b128 v[144:147], v224 offset:4096
	v_rcp_f32_e32 v89, v89
	v_mfma_f32_16x16x32_bf16 v[14:17], v[196:199], v[168:171], v[14:17]
	ds_read_b128 v[148:151], v224 offset:6144
	v_mfma_f32_16x16x32_bf16 v[18:21], v[184:187], v[172:175], v[18:21]
	ds_read_b128 v[152:155], v232 offset:0
	v_cvt_pk_bf16_f32 v82, v82, v83
	v_mfma_f32_16x16x32_bf16 v[22:25], v[188:191], v[172:175], v[22:25]
	ds_read_b128 v[156:159], v232 offset:2048
	v_mfma_f32_16x16x32_bf16 v[26:29], v[192:195], v[172:175], v[26:29]
	ds_read_b128 v[160:163], v232 offset:4096
	v_cvt_pk_bf16_f32 v83, v84, v85
	v_mfma_f32_16x16x32_bf16 v[30:33], v[196:199], v[172:175], v[30:33]
	ds_read_b128 v[164:167], v232 offset:6144
	s_add_u32 m0, s8, 0xc000
	v_mfma_f32_16x16x32_bf16 v[34:37], v[184:187], v[176:179], v[34:37]
	global_load_lds_dwordx4 v200, s[4:5]
	s_add_u32 m0, s8, 0xc400
	v_mfma_f32_16x16x32_bf16 v[38:41], v[188:191], v[176:179], v[38:41]
	global_load_lds_dwordx4 v201, s[4:5]
	v_cvt_pk_bf16_f32 v84, v86, v87
	s_add_u32 m0, s8, 0xc800
	v_mfma_f32_16x16x32_bf16 v[42:45], v[192:195], v[176:179], v[42:45]
	global_load_lds_dwordx4 v202, s[4:5]
	s_add_u32 m0, s8, 0xcc00
	v_mfma_f32_16x16x32_bf16 v[46:49], v[196:199], v[176:179], v[46:49]
	global_load_lds_dwordx4 v203, s[4:5]
	v_cvt_pk_bf16_f32 v85, v88, v89
	s_add_u32 m0, s9, 0xc000
	v_mfma_f32_16x16x32_bf16 v[50:53], v[184:187], v[180:183], v[50:53]
	global_load_lds_dwordx4 v204, s[6:7]
	s_add_u32 m0, s9, 0xc400
	v_mfma_f32_16x16x32_bf16 v[54:57], v[188:191], v[180:183], v[54:57]
	global_load_lds_dwordx4 v205, s[6:7]
	global_store_dwordx4 v240, v[82:85], s[10:11] offset:2048
	v_mfma_f32_16x16x32_bf16 v[58:61], v[192:195], v[180:183], v[58:61]
	s_add_u32 s4, s4, 0x80
	s_addc_u32 s5, s5, 0
	v_mfma_f32_16x16x32_bf16 v[62:65], v[196:199], v[180:183], v[62:65]
	s_add_u32 s6, s6, 0x80
	s_addc_u32 s7, s7, 0
	v_mul_f32_e32 v90, s12, v90
	s_waitcnt lgkmcnt(0)
	v_mfma_f32_16x16x32_bf16 v[2:5], v[152:155], v[136:139], v[2:5]
	ds_read_b128 v[168:171], v229 offset:0
	v_mfma_f32_16x16x32_bf16 v[6:9], v[156:159], v[136:139], v[6:9]
	ds_read_b128 v[172:175], v229 offset:2048
	v_mul_f32_e32 v91, s12, v91
	v_mfma_f32_16x16x32_bf16 v[10:13], v[160:163], v[136:139], v[10:13]
	ds_read_b128 v[176:179], v229 offset:4096
	v_mul_f32_e32 v92, s12, v92
	v_mfma_f32_16x16x32_bf16 v[14:17], v[164:167], v[136:139], v[14:17]
	ds_read_b128 v[180:183], v229 offset:6144
	v_mul_f32_e32 v93, s12, v93
	v_mfma_f32_16x16x32_bf16 v[18:21], v[152:155], v[140:143], v[18:21]
	ds_read_b128 v[184:187], v235 offset:0
	v_mfma_f32_16x16x32_bf16 v[22:25], v[156:159], v[140:143], v[22:25]
	ds_read_b128 v[188:191], v235 offset:2048
	v_mul_f32_e32 v94, s12, v94
	v_mfma_f32_16x16x32_bf16 v[26:29], v[160:163], v[140:143], v[26:29]
	ds_read_b128 v[192:195], v235 offset:4096
	v_mul_f32_e32 v95, s12, v95
	v_mfma_f32_16x16x32_bf16 v[30:33], v[164:167], v[140:143], v[30:33]
	ds_read_b128 v[196:199], v235 offset:6144
	v_mul_f32_e32 v96, s12, v96
	v_mfma_f32_16x16x32_bf16 v[34:37], v[152:155], v[144:147], v[34:37]
	v_mfma_f32_16x16x32_bf16 v[38:41], v[156:159], v[144:147], v[38:41]
	v_mul_f32_e32 v97, s12, v97
	v_mfma_f32_16x16x32_bf16 v[42:45], v[160:163], v[144:147], v[42:45]
	v_exp_f32_e32 v90, v90
	v_mfma_f32_16x16x32_bf16 v[46:49], v[164:167], v[144:147], v[46:49]
	v_exp_f32_e32 v91, v91
	v_mfma_f32_16x16x32_bf16 v[50:53], v[152:155], v[148:151], v[50:53]
	v_mfma_f32_16x16x32_bf16 v[54:57], v[156:159], v[148:151], v[54:57]
	v_exp_f32_e32 v92, v92
	v_mfma_f32_16x16x32_bf16 v[58:61], v[160:163], v[148:151], v[58:61]
	v_exp_f32_e32 v93, v93
	v_mfma_f32_16x16x32_bf16 v[62:65], v[164:167], v[148:151], v[62:65]
	v_exp_f32_e32 v94, v94
	s_waitcnt vmcnt(7) lgkmcnt(0)
	s_barrier
	v_mfma_f32_16x16x32_bf16 v[2:5], v[184:187], v[168:171], v[2:5]
	ds_read_b128 v[136:139], v218 offset:0
	v_mfma_f32_16x16x32_bf16 v[6:9], v[188:191], v[168:171], v[6:9]
	ds_read_b128 v[140:143], v218 offset:2048
	v_mfma_f32_16x16x32_bf16 v[10:13], v[192:195], v[168:171], v[10:13]
	ds_read_b128 v[144:147], v218 offset:4096
	v_exp_f32_e32 v95, v95
	v_mfma_f32_16x16x32_bf16 v[14:17], v[196:199], v[168:171], v[14:17]
	ds_read_b128 v[148:151], v218 offset:6144
	v_mfma_f32_16x16x32_bf16 v[18:21], v[184:187], v[172:175], v[18:21]
	ds_read_b128 v[152:155], v230 offset:0
	v_exp_f32_e32 v96, v96
	v_mfma_f32_16x16x32_bf16 v[22:25], v[188:191], v[172:175], v[22:25]
	ds_read_b128 v[156:159], v230 offset:2048
	v_mfma_f32_16x16x32_bf16 v[26:29], v[192:195], v[172:175], v[26:29]
	ds_read_b128 v[160:163], v230 offset:4096
	v_exp_f32_e32 v97, v97
	v_mfma_f32_16x16x32_bf16 v[30:33], v[196:199], v[172:175], v[30:33]
	ds_read_b128 v[164:167], v230 offset:6144
	s_add_u32 m0, s8, 0x18000
	v_mfma_f32_16x16x32_bf16 v[34:37], v[184:187], v[176:179], v[34:37]
	global_load_lds_dwordx4 v200, s[4:5]
	s_add_u32 m0, s8, 0x18400
	v_mfma_f32_16x16x32_bf16 v[38:41], v[188:191], v[176:179], v[38:41]
	global_load_lds_dwordx4 v201, s[4:5]
	v_add_f32_e32 v90, 1.0, v90
	s_add_u32 m0, s8, 0x18800
	v_mfma_f32_16x16x32_bf16 v[42:45], v[192:195], v[176:179], v[42:45]
	global_load_lds_dwordx4 v202, s[4:5]
	s_add_u32 m0, s8, 0x18c00
	v_mfma_f32_16x16x32_bf16 v[46:49], v[196:199], v[176:179], v[46:49]
	global_load_lds_dwordx4 v203, s[4:5]
	v_add_f32_e32 v91, 1.0, v91
	s_add_u32 m0, s9, 0x18000
	v_mfma_f32_16x16x32_bf16 v[50:53], v[184:187], v[180:183], v[50:53]
	global_load_lds_dwordx4 v204, s[6:7]
	s_add_u32 m0, s9, 0x18400
	v_mfma_f32_16x16x32_bf16 v[54:57], v[188:191], v[180:183], v[54:57]
	global_load_lds_dwordx4 v205, s[6:7]
	v_add_f32_e32 v92, 1.0, v92
	v_mfma_f32_16x16x32_bf16 v[58:61], v[192:195], v[180:183], v[58:61]
	s_add_u32 s4, s4, 0x80
	s_addc_u32 s5, s5, 0
	v_mfma_f32_16x16x32_bf16 v[62:65], v[196:199], v[180:183], v[62:65]
	s_add_u32 s6, s6, 0x80
	s_addc_u32 s7, s7, 0
	v_add_f32_e32 v93, 1.0, v93
	s_waitcnt lgkmcnt(0)
	v_mfma_f32_16x16x32_bf16 v[2:5], v[152:155], v[136:139], v[2:5]
	ds_read_b128 v[168:171], v225 offset:0
	v_mfma_f32_16x16x32_bf16 v[6:9], v[156:159], v[136:139], v[6:9]
	ds_read_b128 v[172:175], v225 offset:2048
	v_add_f32_e32 v94, 1.0, v94
	v_mfma_f32_16x16x32_bf16 v[10:13], v[160:163], v[136:139], v[10:13]
	ds_read_b128 v[176:179], v225 offset:4096
	v_add_f32_e32 v95, 1.0, v95
	v_mfma_f32_16x16x32_bf16 v[14:17], v[164:167], v[136:139], v[14:17]
	ds_read_b128 v[180:183], v225 offset:6144
	v_add_f32_e32 v96, 1.0, v96
	v_mfma_f32_16x16x32_bf16 v[18:21], v[152:155], v[140:143], v[18:21]
	ds_read_b128 v[184:187], v233 offset:0
	v_mfma_f32_16x16x32_bf16 v[22:25], v[156:159], v[140:143], v[22:25]
	ds_read_b128 v[188:191], v233 offset:2048
	v_add_f32_e32 v97, 1.0, v97
	v_mfma_f32_16x16x32_bf16 v[26:29], v[160:163], v[140:143], v[26:29]
	ds_read_b128 v[192:195], v233 offset:4096
	v_rcp_f32_e32 v90, v90
	v_mfma_f32_16x16x32_bf16 v[30:33], v[164:167], v[140:143], v[30:33]
	ds_read_b128 v[196:199], v233 offset:6144
	v_rcp_f32_e32 v91, v91
	v_mfma_f32_16x16x32_bf16 v[34:37], v[152:155], v[144:147], v[34:37]
	v_mfma_f32_16x16x32_bf16 v[38:41], v[156:159], v[144:147], v[38:41]
	v_rcp_f32_e32 v92, v92
	v_mfma_f32_16x16x32_bf16 v[42:45], v[160:163], v[144:147], v[42:45]
	v_rcp_f32_e32 v93, v93
	v_mfma_f32_16x16x32_bf16 v[46:49], v[164:167], v[144:147], v[46:49]
	v_rcp_f32_e32 v94, v94
	v_mfma_f32_16x16x32_bf16 v[50:53], v[152:155], v[148:151], v[50:53]
	v_mfma_f32_16x16x32_bf16 v[54:57], v[156:159], v[148:151], v[54:57]
	v_rcp_f32_e32 v95, v95
	v_mfma_f32_16x16x32_bf16 v[58:61], v[160:163], v[148:151], v[58:61]
	v_rcp_f32_e32 v96, v96
	v_mfma_f32_16x16x32_bf16 v[62:65], v[164:167], v[148:151], v[62:65]
	v_rcp_f32_e32 v97, v97
	s_waitcnt vmcnt(7) lgkmcnt(0)
	s_barrier
	v_mfma_f32_16x16x32_bf16 v[2:5], v[184:187], v[168:171], v[2:5]
	ds_read_b128 v[136:139], v219 offset:0
	v_mfma_f32_16x16x32_bf16 v[6:9], v[188:191], v[168:171], v[6:9]
	ds_read_b128 v[140:143], v219 offset:2048
	v_mfma_f32_16x16x32_bf16 v[10:13], v[192:195], v[168:171], v[10:13]
	ds_read_b128 v[144:147], v219 offset:4096
	v_cvt_pk_bf16_f32 v90, v90, v91
	v_mfma_f32_16x16x32_bf16 v[14:17], v[196:199], v[168:171], v[14:17]
	ds_read_b128 v[148:151], v219 offset:6144
	v_mfma_f32_16x16x32_bf16 v[18:21], v[184:187], v[172:175], v[18:21]
	ds_read_b128 v[152:155], v231 offset:0
	v_cvt_pk_bf16_f32 v91, v92, v93
	v_mfma_f32_16x16x32_bf16 v[22:25], v[188:191], v[172:175], v[22:25]
	ds_read_b128 v[156:159], v231 offset:2048
	v_mfma_f32_16x16x32_bf16 v[26:29], v[192:195], v[172:175], v[26:29]
	ds_read_b128 v[160:163], v231 offset:4096
	v_cvt_pk_bf16_f32 v92, v94, v95
	v_mfma_f32_16x16x32_bf16 v[30:33], v[196:199], v[172:175], v[30:33]
	ds_read_b128 v[164:167], v231 offset:6144
	s_mov_b32 m0, s8
	v_mfma_f32_16x16x32_bf16 v[34:37], v[184:187], v[176:179], v[34:37]
	global_load_lds_dwordx4 v200, s[4:5]
	s_add_u32 m0, s8, 0x400
	v_mfma_f32_16x16x32_bf16 v[38:41], v[188:191], v[176:179], v[38:41]
	global_load_lds_dwordx4 v201, s[4:5]
	v_cvt_pk_bf16_f32 v93, v96, v97
	s_add_u32 m0, s8, 0x800
	v_mfma_f32_16x16x32_bf16 v[42:45], v[192:195], v[176:179], v[42:45]
	global_load_lds_dwordx4 v202, s[4:5]
	s_add_u32 m0, s8, 0xc00
	v_mfma_f32_16x16x32_bf16 v[46:49], v[196:199], v[176:179], v[46:49]
	global_load_lds_dwordx4 v203, s[4:5]
	global_store_dwordx4 v240, v[90:93], s[10:11] offset:3072
	s_mov_b32 m0, s9
	v_mfma_f32_16x16x32_bf16 v[50:53], v[184:187], v[180:183], v[50:53]
	global_load_lds_dwordx4 v204, s[6:7]
	s_add_u32 m0, s9, 0x400
	v_mfma_f32_16x16x32_bf16 v[54:57], v[188:191], v[180:183], v[54:57]
	global_load_lds_dwordx4 v205, s[6:7]
	v_mul_f32_e32 v98, s12, v98
	v_mfma_f32_16x16x32_bf16 v[58:61], v[192:195], v[180:183], v[58:61]
	s_add_u32 s4, s4, 0x80
	s_addc_u32 s5, s5, 0
	v_mfma_f32_16x16x32_bf16 v[62:65], v[196:199], v[180:183], v[62:65]
	s_add_u32 s6, s6, 0x80
	s_addc_u32 s7, s7, 0
	v_mul_f32_e32 v99, s12, v99
	s_waitcnt lgkmcnt(0)
	v_mfma_f32_16x16x32_bf16 v[2:5], v[152:155], v[136:139], v[2:5]
	ds_read_b128 v[168:171], v228 offset:0
	v_mfma_f32_16x16x32_bf16 v[6:9], v[156:159], v[136:139], v[6:9]
	ds_read_b128 v[172:175], v228 offset:2048
	v_mul_f32_e32 v100, s12, v100
	v_mfma_f32_16x16x32_bf16 v[10:13], v[160:163], v[136:139], v[10:13]
	ds_read_b128 v[176:179], v228 offset:4096
	v_mul_f32_e32 v101, s12, v101
	v_mfma_f32_16x16x32_bf16 v[14:17], v[164:167], v[136:139], v[14:17]
	ds_read_b128 v[180:183], v228 offset:6144
	v_mul_f32_e32 v102, s12, v102
	v_mfma_f32_16x16x32_bf16 v[18:21], v[152:155], v[140:143], v[18:21]
	ds_read_b128 v[184:187], v234 offset:0
	v_mfma_f32_16x16x32_bf16 v[22:25], v[156:159], v[140:143], v[22:25]
	ds_read_b128 v[188:191], v234 offset:2048
	v_mul_f32_e32 v103, s12, v103
	v_mfma_f32_16x16x32_bf16 v[26:29], v[160:163], v[140:143], v[26:29]
	ds_read_b128 v[192:195], v234 offset:4096
	v_mul_f32_e32 v104, s12, v104
	v_mfma_f32_16x16x32_bf16 v[30:33], v[164:167], v[140:143], v[30:33]
	ds_read_b128 v[196:199], v234 offset:6144
	v_mul_f32_e32 v105, s12, v105
	v_mfma_f32_16x16x32_bf16 v[34:37], v[152:155], v[144:147], v[34:37]
	v_mfma_f32_16x16x32_bf16 v[38:41], v[156:159], v[144:147], v[38:41]
	v_exp_f32_e32 v98, v98
	v_mfma_f32_16x16x32_bf16 v[42:45], v[160:163], v[144:147], v[42:45]
	v_exp_f32_e32 v99, v99
	v_mfma_f32_16x16x32_bf16 v[46:49], v[164:167], v[144:147], v[46:49]
	v_exp_f32_e32 v100, v100
	v_mfma_f32_16x16x32_bf16 v[50:53], v[152:155], v[148:151], v[50:53]
	v_mfma_f32_16x16x32_bf16 v[54:57], v[156:159], v[148:151], v[54:57]
	v_exp_f32_e32 v101, v101
	v_mfma_f32_16x16x32_bf16 v[58:61], v[160:163], v[148:151], v[58:61]
	v_exp_f32_e32 v102, v102
	v_mfma_f32_16x16x32_bf16 v[62:65], v[164:167], v[148:151], v[62:65]
	v_exp_f32_e32 v103, v103
	s_waitcnt vmcnt(7) lgkmcnt(0)
	s_barrier
	v_mfma_f32_16x16x32_bf16 v[2:5], v[184:187], v[168:171], v[2:5]
	ds_read_b128 v[136:139], v224 offset:0
	v_mfma_f32_16x16x32_bf16 v[6:9], v[188:191], v[168:171], v[6:9]
	ds_read_b128 v[140:143], v224 offset:2048
	v_mfma_f32_16x16x32_bf16 v[10:13], v[192:195], v[168:171], v[10:13]
	ds_read_b128 v[144:147], v224 offset:4096
	v_exp_f32_e32 v104, v104
	v_mfma_f32_16x16x32_bf16 v[14:17], v[196:199], v[168:171], v[14:17]
	ds_read_b128 v[148:151], v224 offset:6144
	v_mfma_f32_16x16x32_bf16 v[18:21], v[184:187], v[172:175], v[18:21]
	ds_read_b128 v[152:155], v232 offset:0
	v_exp_f32_e32 v105, v105
	v_mfma_f32_16x16x32_bf16 v[22:25], v[188:191], v[172:175], v[22:25]
	ds_read_b128 v[156:159], v232 offset:2048
	v_mfma_f32_16x16x32_bf16 v[26:29], v[192:195], v[172:175], v[26:29]
	ds_read_b128 v[160:163], v232 offset:4096
	v_add_f32_e32 v98, 1.0, v98
	v_mfma_f32_16x16x32_bf16 v[30:33], v[196:199], v[172:175], v[30:33]
	ds_read_b128 v[164:167], v232 offset:6144
	s_add_u32 m0, s8, 0xc000
	v_mfma_f32_16x16x32_bf16 v[34:37], v[184:187], v[176:179], v[34:37]
	global_load_lds_dwordx4 v200, s[4:5]
	s_add_u32 m0, s8, 0xc400
	v_mfma_f32_16x16x32_bf16 v[38:41], v[188:191], v[176:179], v[38:41]
	global_load_lds_dwordx4 v201, s[4:5]
	v_add_f32_e32 v99, 1.0, v99
	s_add_u32 m0, s8, 0xc800
	v_mfma_f32_16x16x32_bf16 v[42:45], v[192:195], v[176:179], v[42:45]
	global_load_lds_dwordx4 v202, s[4:5]
	s_add_u32 m0, s8, 0xcc00
	v_mfma_f32_16x16x32_bf16 v[46:49], v[196:199], v[176:179], v[46:49]
	global_load_lds_dwordx4 v203, s[4:5]
	v_add_f32_e32 v100, 1.0, v100
	s_add_u32 m0, s9, 0xc000
	v_mfma_f32_16x16x32_bf16 v[50:53], v[184:187], v[180:183], v[50:53]
	global_load_lds_dwordx4 v204, s[6:7]
	s_add_u32 m0, s9, 0xc400
	v_mfma_f32_16x16x32_bf16 v[54:57], v[188:191], v[180:183], v[54:57]
	global_load_lds_dwordx4 v205, s[6:7]
	v_add_f32_e32 v101, 1.0, v101
	v_mfma_f32_16x16x32_bf16 v[58:61], v[192:195], v[180:183], v[58:61]
	s_add_u32 s4, s4, 0x80
	s_addc_u32 s5, s5, 0
	v_mfma_f32_16x16x32_bf16 v[62:65], v[196:199], v[180:183], v[62:65]
	s_add_u32 s6, s6, 0x80
	s_addc_u32 s7, s7, 0
	v_add_f32_e32 v102, 1.0, v102
	s_waitcnt lgkmcnt(0)
	v_mfma_f32_16x16x32_bf16 v[2:5], v[152:155], v[136:139], v[2:5]
	ds_read_b128 v[168:171], v229 offset:0
	v_mfma_f32_16x16x32_bf16 v[6:9], v[156:159], v[136:139], v[6:9]
	ds_read_b128 v[172:175], v229 offset:2048
	v_add_f32_e32 v103, 1.0, v103
	v_mfma_f32_16x16x32_bf16 v[10:13], v[160:163], v[136:139], v[10:13]
	ds_read_b128 v[176:179], v229 offset:4096
	v_add_f32_e32 v104, 1.0, v104
	v_mfma_f32_16x16x32_bf16 v[14:17], v[164:167], v[136:139], v[14:17]
	ds_read_b128 v[180:183], v229 offset:6144
	v_add_f32_e32 v105, 1.0, v105
	v_mfma_f32_16x16x32_bf16 v[18:21], v[152:155], v[140:143], v[18:21]
	ds_read_b128 v[184:187], v235 offset:0
	v_mfma_f32_16x16x32_bf16 v[22:25], v[156:159], v[140:143], v[22:25]
	ds_read_b128 v[188:191], v235 offset:2048
	v_rcp_f32_e32 v98, v98
	v_mfma_f32_16x16x32_bf16 v[26:29], v[160:163], v[140:143], v[26:29]
	ds_read_b128 v[192:195], v235 offset:4096
	v_rcp_f32_e32 v99, v99
	v_mfma_f32_16x16x32_bf16 v[30:33], v[164:167], v[140:143], v[30:33]
	ds_read_b128 v[196:199], v235 offset:6144
	v_rcp_f32_e32 v100, v100
	v_mfma_f32_16x16x32_bf16 v[34:37], v[152:155], v[144:147], v[34:37]
	v_mfma_f32_16x16x32_bf16 v[38:41], v[156:159], v[144:147], v[38:41]
	v_rcp_f32_e32 v101, v101
	v_mfma_f32_16x16x32_bf16 v[42:45], v[160:163], v[144:147], v[42:45]
	v_rcp_f32_e32 v102, v102
	v_mfma_f32_16x16x32_bf16 v[46:49], v[164:167], v[144:147], v[46:49]
	v_rcp_f32_e32 v103, v103
	v_mfma_f32_16x16x32_bf16 v[50:53], v[152:155], v[148:151], v[50:53]
	v_mfma_f32_16x16x32_bf16 v[54:57], v[156:159], v[148:151], v[54:57]
	v_rcp_f32_e32 v104, v104
	v_mfma_f32_16x16x32_bf16 v[58:61], v[160:163], v[148:151], v[58:61]
	v_rcp_f32_e32 v105, v105
	v_mfma_f32_16x16x32_bf16 v[62:65], v[164:167], v[148:151], v[62:65]
	v_cvt_pk_bf16_f32 v98, v98, v99
	s_waitcnt vmcnt(6) lgkmcnt(0)
	s_barrier
	v_mfma_f32_16x16x32_bf16 v[2:5], v[184:187], v[168:171], v[2:5]
	ds_read_b128 v[136:139], v218 offset:0
	v_mfma_f32_16x16x32_bf16 v[6:9], v[188:191], v[168:171], v[6:9]
	ds_read_b128 v[140:143], v218 offset:2048
	v_mfma_f32_16x16x32_bf16 v[10:13], v[192:195], v[168:171], v[10:13]
	ds_read_b128 v[144:147], v218 offset:4096
	v_cvt_pk_bf16_f32 v99, v100, v101
	v_mfma_f32_16x16x32_bf16 v[14:17], v[196:199], v[168:171], v[14:17]
	ds_read_b128 v[148:151], v218 offset:6144
	v_mfma_f32_16x16x32_bf16 v[18:21], v[184:187], v[172:175], v[18:21]
	ds_read_b128 v[152:155], v230 offset:0
	v_cvt_pk_bf16_f32 v100, v102, v103
	v_mfma_f32_16x16x32_bf16 v[22:25], v[188:191], v[172:175], v[22:25]
	ds_read_b128 v[156:159], v230 offset:2048
	v_mfma_f32_16x16x32_bf16 v[26:29], v[192:195], v[172:175], v[26:29]
	ds_read_b128 v[160:163], v230 offset:4096
	v_cvt_pk_bf16_f32 v101, v104, v105
	v_mfma_f32_16x16x32_bf16 v[30:33], v[196:199], v[172:175], v[30:33]
	ds_read_b128 v[164:167], v230 offset:6144
	s_add_u32 m0, s8, 0x18000
	v_mfma_f32_16x16x32_bf16 v[34:37], v[184:187], v[176:179], v[34:37]
	global_load_lds_dwordx4 v200, s[4:5]
	s_add_u32 m0, s8, 0x18400
	v_mfma_f32_16x16x32_bf16 v[38:41], v[188:191], v[176:179], v[38:41]
	global_load_lds_dwordx4 v201, s[4:5]
	global_store_dwordx4 v241, v[98:101], s[10:11] offset:0
	s_add_u32 m0, s8, 0x18800
	v_mfma_f32_16x16x32_bf16 v[42:45], v[192:195], v[176:179], v[42:45]
	global_load_lds_dwordx4 v202, s[4:5]
	s_add_u32 m0, s8, 0x18c00
	v_mfma_f32_16x16x32_bf16 v[46:49], v[196:199], v[176:179], v[46:49]
	global_load_lds_dwordx4 v203, s[4:5]
	v_mul_f32_e32 v106, s12, v106
	s_add_u32 m0, s9, 0x18000
	v_mfma_f32_16x16x32_bf16 v[50:53], v[184:187], v[180:183], v[50:53]
	global_load_lds_dwordx4 v204, s[6:7]
	s_add_u32 m0, s9, 0x18400
	v_mfma_f32_16x16x32_bf16 v[54:57], v[188:191], v[180:183], v[54:57]
	global_load_lds_dwordx4 v205, s[6:7]
	v_mul_f32_e32 v107, s12, v107
	v_mfma_f32_16x16x32_bf16 v[58:61], v[192:195], v[180:183], v[58:61]
	s_add_u32 s4, s4, 0x80
	s_addc_u32 s5, s5, 0
	v_mfma_f32_16x16x32_bf16 v[62:65], v[196:199], v[180:183], v[62:65]
	s_add_u32 s6, s6, 0x80
	s_addc_u32 s7, s7, 0
	v_mul_f32_e32 v108, s12, v108
	s_waitcnt lgkmcnt(0)
	v_mfma_f32_16x16x32_bf16 v[2:5], v[152:155], v[136:139], v[2:5]
	ds_read_b128 v[168:171], v225 offset:0
	v_mfma_f32_16x16x32_bf16 v[6:9], v[156:159], v[136:139], v[6:9]
	ds_read_b128 v[172:175], v225 offset:2048
	v_mul_f32_e32 v109, s12, v109
	v_mfma_f32_16x16x32_bf16 v[10:13], v[160:163], v[136:139], v[10:13]
	ds_read_b128 v[176:179], v225 offset:4096
	v_mul_f32_e32 v110, s12, v110
	v_mfma_f32_16x16x32_bf16 v[14:17], v[164:167], v[136:139], v[14:17]
	ds_read_b128 v[180:183], v225 offset:6144
	v_mul_f32_e32 v111, s12, v111
	v_mfma_f32_16x16x32_bf16 v[18:21], v[152:155], v[140:143], v[18:21]
	ds_read_b128 v[184:187], v233 offset:0
	v_mfma_f32_16x16x32_bf16 v[22:25], v[156:159], v[140:143], v[22:25]
	ds_read_b128 v[188:191], v233 offset:2048
	v_mul_f32_e32 v112, s12, v112
	v_mfma_f32_16x16x32_bf16 v[26:29], v[160:163], v[140:143], v[26:29]
	ds_read_b128 v[192:195], v233 offset:4096
	v_mul_f32_e32 v113, s12, v113
	v_mfma_f32_16x16x32_bf16 v[30:33], v[164:167], v[140:143], v[30:33]
	ds_read_b128 v[196:199], v233 offset:6144
	v_exp_f32_e32 v106, v106
	v_mfma_f32_16x16x32_bf16 v[34:37], v[152:155], v[144:147], v[34:37]
	v_mfma_f32_16x16x32_bf16 v[38:41], v[156:159], v[144:147], v[38:41]
	v_exp_f32_e32 v107, v107
	v_mfma_f32_16x16x32_bf16 v[42:45], v[160:163], v[144:147], v[42:45]
	v_exp_f32_e32 v108, v108
	v_mfma_f32_16x16x32_bf16 v[46:49], v[164:167], v[144:147], v[46:49]
	v_exp_f32_e32 v109, v109
	v_mfma_f32_16x16x32_bf16 v[50:53], v[152:155], v[148:151], v[50:53]
	v_mfma_f32_16x16x32_bf16 v[54:57], v[156:159], v[148:151], v[54:57]
	v_exp_f32_e32 v110, v110
	v_mfma_f32_16x16x32_bf16 v[58:61], v[160:163], v[148:151], v[58:61]
	v_exp_f32_e32 v111, v111
	v_mfma_f32_16x16x32_bf16 v[62:65], v[164:167], v[148:151], v[62:65]
	v_exp_f32_e32 v112, v112
	s_waitcnt vmcnt(7) lgkmcnt(0)
	s_barrier
	v_mfma_f32_16x16x32_bf16 v[2:5], v[184:187], v[168:171], v[2:5]
	ds_read_b128 v[136:139], v219 offset:0
	v_mfma_f32_16x16x32_bf16 v[6:9], v[188:191], v[168:171], v[6:9]
	ds_read_b128 v[140:143], v219 offset:2048
	v_mfma_f32_16x16x32_bf16 v[10:13], v[192:195], v[168:171], v[10:13]
	ds_read_b128 v[144:147], v219 offset:4096
	v_exp_f32_e32 v113, v113
	v_mfma_f32_16x16x32_bf16 v[14:17], v[196:199], v[168:171], v[14:17]
	ds_read_b128 v[148:151], v219 offset:6144
	v_mfma_f32_16x16x32_bf16 v[18:21], v[184:187], v[172:175], v[18:21]
	ds_read_b128 v[152:155], v231 offset:0
	v_add_f32_e32 v106, 1.0, v106
	v_mfma_f32_16x16x32_bf16 v[22:25], v[188:191], v[172:175], v[22:25]
	ds_read_b128 v[156:159], v231 offset:2048
	v_mfma_f32_16x16x32_bf16 v[26:29], v[192:195], v[172:175], v[26:29]
	ds_read_b128 v[160:163], v231 offset:4096
	v_add_f32_e32 v107, 1.0, v107
	v_mfma_f32_16x16x32_bf16 v[30:33], v[196:199], v[172:175], v[30:33]
	ds_read_b128 v[164:167], v231 offset:6144
	s_mov_b32 m0, s8
	v_mfma_f32_16x16x32_bf16 v[34:37], v[184:187], v[176:179], v[34:37]
	global_load_lds_dwordx4 v200, s[4:5]
	s_add_u32 m0, s8, 0x400
	v_mfma_f32_16x16x32_bf16 v[38:41], v[188:191], v[176:179], v[38:41]
	global_load_lds_dwordx4 v201, s[4:5]
	v_add_f32_e32 v108, 1.0, v108
	s_add_u32 m0, s8, 0x800
	v_mfma_f32_16x16x32_bf16 v[42:45], v[192:195], v[176:179], v[42:45]
	global_load_lds_dwordx4 v202, s[4:5]
	s_add_u32 m0, s8, 0xc00
	v_mfma_f32_16x16x32_bf16 v[46:49], v[196:199], v[176:179], v[46:49]
	global_load_lds_dwordx4 v203, s[4:5]
	v_add_f32_e32 v109, 1.0, v109
	s_mov_b32 m0, s9
	v_mfma_f32_16x16x32_bf16 v[50:53], v[184:187], v[180:183], v[50:53]
	global_load_lds_dwordx4 v204, s[6:7]
	s_add_u32 m0, s9, 0x400
	v_mfma_f32_16x16x32_bf16 v[54:57], v[188:191], v[180:183], v[54:57]
	global_load_lds_dwordx4 v205, s[6:7]
	v_add_f32_e32 v110, 1.0, v110
	v_mfma_f32_16x16x32_bf16 v[58:61], v[192:195], v[180:183], v[58:61]
	s_add_u32 s4, s4, 0x80
	s_addc_u32 s5, s5, 0
	v_mfma_f32_16x16x32_bf16 v[62:65], v[196:199], v[180:183], v[62:65]
	s_add_u32 s6, s6, 0x80
	s_addc_u32 s7, s7, 0
	v_add_f32_e32 v111, 1.0, v111
	s_waitcnt lgkmcnt(0)
	v_mfma_f32_16x16x32_bf16 v[2:5], v[152:155], v[136:139], v[2:5]
	ds_read_b128 v[168:171], v228 offset:0
	v_mfma_f32_16x16x32_bf16 v[6:9], v[156:159], v[136:139], v[6:9]
	ds_read_b128 v[172:175], v228 offset:2048
	v_add_f32_e32 v112, 1.0, v112
	v_mfma_f32_16x16x32_bf16 v[10:13], v[160:163], v[136:139], v[10:13]
	ds_read_b128 v[176:179], v228 offset:4096
	v_add_f32_e32 v113, 1.0, v113
	v_mfma_f32_16x16x32_bf16 v[14:17], v[164:167], v[136:139], v[14:17]
	ds_read_b128 v[180:183], v228 offset:6144
	v_rcp_f32_e32 v106, v106
	v_mfma_f32_16x16x32_bf16 v[18:21], v[152:155], v[140:143], v[18:21]
	ds_read_b128 v[184:187], v234 offset:0
	v_mfma_f32_16x16x32_bf16 v[22:25], v[156:159], v[140:143], v[22:25]
	ds_read_b128 v[188:191], v234 offset:2048
	v_rcp_f32_e32 v107, v107
	v_mfma_f32_16x16x32_bf16 v[26:29], v[160:163], v[140:143], v[26:29]
	ds_read_b128 v[192:195], v234 offset:4096
	v_rcp_f32_e32 v108, v108
	v_mfma_f32_16x16x32_bf16 v[30:33], v[164:167], v[140:143], v[30:33]
	ds_read_b128 v[196:199], v234 offset:6144
	v_rcp_f32_e32 v109, v109
	v_mfma_f32_16x16x32_bf16 v[34:37], v[152:155], v[144:147], v[34:37]
	v_mfma_f32_16x16x32_bf16 v[38:41], v[156:159], v[144:147], v[38:41]
	v_rcp_f32_e32 v110, v110
	v_mfma_f32_16x16x32_bf16 v[42:45], v[160:163], v[144:147], v[42:45]
	v_rcp_f32_e32 v111, v111
	v_mfma_f32_16x16x32_bf16 v[46:49], v[164:167], v[144:147], v[46:49]
	v_rcp_f32_e32 v112, v112
	v_mfma_f32_16x16x32_bf16 v[50:53], v[152:155], v[148:151], v[50:53]
	v_mfma_f32_16x16x32_bf16 v[54:57], v[156:159], v[148:151], v[54:57]
	v_rcp_f32_e32 v113, v113
	v_mfma_f32_16x16x32_bf16 v[58:61], v[160:163], v[148:151], v[58:61]
	v_cvt_pk_bf16_f32 v106, v106, v107
	v_mfma_f32_16x16x32_bf16 v[62:65], v[164:167], v[148:151], v[62:65]
	v_cvt_pk_bf16_f32 v107, v108, v109
	s_waitcnt vmcnt(6) lgkmcnt(0)
	s_barrier
	v_mfma_f32_16x16x32_bf16 v[2:5], v[184:187], v[168:171], v[2:5]
	ds_read_b128 v[136:139], v224 offset:0
	v_mfma_f32_16x16x32_bf16 v[6:9], v[188:191], v[168:171], v[6:9]
	ds_read_b128 v[140:143], v224 offset:2048
	v_mfma_f32_16x16x32_bf16 v[10:13], v[192:195], v[168:171], v[10:13]
	ds_read_b128 v[144:147], v224 offset:4096
	v_cvt_pk_bf16_f32 v108, v110, v111
	v_mfma_f32_16x16x32_bf16 v[14:17], v[196:199], v[168:171], v[14:17]
	ds_read_b128 v[148:151], v224 offset:6144
	v_mfma_f32_16x16x32_bf16 v[18:21], v[184:187], v[172:175], v[18:21]
	ds_read_b128 v[152:155], v232 offset:0
	v_cvt_pk_bf16_f32 v109, v112, v113
	v_mfma_f32_16x16x32_bf16 v[22:25], v[188:191], v[172:175], v[22:25]
	ds_read_b128 v[156:159], v232 offset:2048
	v_mfma_f32_16x16x32_bf16 v[26:29], v[192:195], v[172:175], v[26:29]
	ds_read_b128 v[160:163], v232 offset:4096
	global_store_dwordx4 v241, v[106:109], s[10:11] offset:1024
	v_mfma_f32_16x16x32_bf16 v[30:33], v[196:199], v[172:175], v[30:33]
	ds_read_b128 v[164:167], v232 offset:6144
	s_add_u32 m0, s8, 0xc000
	v_mfma_f32_16x16x32_bf16 v[34:37], v[184:187], v[176:179], v[34:37]
	global_load_lds_dwordx4 v200, s[4:5]
	s_add_u32 m0, s8, 0xc400
	v_mfma_f32_16x16x32_bf16 v[38:41], v[188:191], v[176:179], v[38:41]
	global_load_lds_dwordx4 v201, s[4:5]
	v_mul_f32_e32 v114, s12, v114
	s_add_u32 m0, s8, 0xc800
	v_mfma_f32_16x16x32_bf16 v[42:45], v[192:195], v[176:179], v[42:45]
	global_load_lds_dwordx4 v202, s[4:5]
	s_add_u32 m0, s8, 0xcc00
	v_mfma_f32_16x16x32_bf16 v[46:49], v[196:199], v[176:179], v[46:49]
	global_load_lds_dwordx4 v203, s[4:5]
	v_mul_f32_e32 v115, s12, v115
	s_add_u32 m0, s9, 0xc000
	v_mfma_f32_16x16x32_bf16 v[50:53], v[184:187], v[180:183], v[50:53]
	global_load_lds_dwordx4 v204, s[6:7]
	s_add_u32 m0, s9, 0xc400
	v_mfma_f32_16x16x32_bf16 v[54:57], v[188:191], v[180:183], v[54:57]
	global_load_lds_dwordx4 v205, s[6:7]
	v_mul_f32_e32 v116, s12, v116
	v_mfma_f32_16x16x32_bf16 v[58:61], v[192:195], v[180:183], v[58:61]
	s_add_u32 s4, s4, 0x80
	s_addc_u32 s5, s5, 0
	v_mfma_f32_16x16x32_bf16 v[62:65], v[196:199], v[180:183], v[62:65]
	s_add_u32 s6, s6, 0x80
	s_addc_u32 s7, s7, 0
	v_mul_f32_e32 v117, s12, v117
	s_waitcnt lgkmcnt(0)
	v_mfma_f32_16x16x32_bf16 v[2:5], v[152:155], v[136:139], v[2:5]
	ds_read_b128 v[168:171], v229 offset:0
	v_mfma_f32_16x16x32_bf16 v[6:9], v[156:159], v[136:139], v[6:9]
	ds_read_b128 v[172:175], v229 offset:2048
	v_mul_f32_e32 v118, s12, v118
	v_mfma_f32_16x16x32_bf16 v[10:13], v[160:163], v[136:139], v[10:13]
	ds_read_b128 v[176:179], v229 offset:4096
	v_mul_f32_e32 v119, s12, v119
	v_mfma_f32_16x16x32_bf16 v[14:17], v[164:167], v[136:139], v[14:17]
	ds_read_b128 v[180:183], v229 offset:6144
	v_mul_f32_e32 v120, s12, v120
	v_mfma_f32_16x16x32_bf16 v[18:21], v[152:155], v[140:143], v[18:21]
	ds_read_b128 v[184:187], v235 offset:0
	v_mfma_f32_16x16x32_bf16 v[22:25], v[156:159], v[140:143], v[22:25]
	ds_read_b128 v[188:191], v235 offset:2048
	v_mul_f32_e32 v121, s12, v121
	v_mfma_f32_16x16x32_bf16 v[26:29], v[160:163], v[140:143], v[26:29]
	ds_read_b128 v[192:195], v235 offset:4096
	v_exp_f32_e32 v114, v114
	v_mfma_f32_16x16x32_bf16 v[30:33], v[164:167], v[140:143], v[30:33]
	ds_read_b128 v[196:199], v235 offset:6144
	v_exp_f32_e32 v115, v115
	v_mfma_f32_16x16x32_bf16 v[34:37], v[152:155], v[144:147], v[34:37]
	v_mfma_f32_16x16x32_bf16 v[38:41], v[156:159], v[144:147], v[38:41]
	v_exp_f32_e32 v116, v116
	v_mfma_f32_16x16x32_bf16 v[42:45], v[160:163], v[144:147], v[42:45]
	v_exp_f32_e32 v117, v117
	v_mfma_f32_16x16x32_bf16 v[46:49], v[164:167], v[144:147], v[46:49]
	v_exp_f32_e32 v118, v118
	v_mfma_f32_16x16x32_bf16 v[50:53], v[152:155], v[148:151], v[50:53]
	v_mfma_f32_16x16x32_bf16 v[54:57], v[156:159], v[148:151], v[54:57]
	v_exp_f32_e32 v119, v119
	v_mfma_f32_16x16x32_bf16 v[58:61], v[160:163], v[148:151], v[58:61]
	v_exp_f32_e32 v120, v120
	v_mfma_f32_16x16x32_bf16 v[62:65], v[164:167], v[148:151], v[62:65]
	v_exp_f32_e32 v121, v121
	s_waitcnt vmcnt(7) lgkmcnt(0)
	s_barrier
	v_mfma_f32_16x16x32_bf16 v[2:5], v[184:187], v[168:171], v[2:5]
	ds_read_b128 v[136:139], v218 offset:0
	v_mfma_f32_16x16x32_bf16 v[6:9], v[188:191], v[168:171], v[6:9]
	ds_read_b128 v[140:143], v218 offset:2048
	v_mfma_f32_16x16x32_bf16 v[10:13], v[192:195], v[168:171], v[10:13]
	ds_read_b128 v[144:147], v218 offset:4096
	v_add_f32_e32 v114, 1.0, v114
	v_mfma_f32_16x16x32_bf16 v[14:17], v[196:199], v[168:171], v[14:17]
	ds_read_b128 v[148:151], v218 offset:6144
	v_mfma_f32_16x16x32_bf16 v[18:21], v[184:187], v[172:175], v[18:21]
	ds_read_b128 v[152:155], v230 offset:0
	v_add_f32_e32 v115, 1.0, v115
	v_mfma_f32_16x16x32_bf16 v[22:25], v[188:191], v[172:175], v[22:25]
	ds_read_b128 v[156:159], v230 offset:2048
	v_mfma_f32_16x16x32_bf16 v[26:29], v[192:195], v[172:175], v[26:29]
	ds_read_b128 v[160:163], v230 offset:4096
	v_add_f32_e32 v116, 1.0, v116
	v_mfma_f32_16x16x32_bf16 v[30:33], v[196:199], v[172:175], v[30:33]
	ds_read_b128 v[164:167], v230 offset:6144
	s_add_u32 m0, s8, 0x18000
	v_mfma_f32_16x16x32_bf16 v[34:37], v[184:187], v[176:179], v[34:37]
	global_load_lds_dwordx4 v200, s[4:5]
	s_add_u32 m0, s8, 0x18400
	v_mfma_f32_16x16x32_bf16 v[38:41], v[188:191], v[176:179], v[38:41]
	global_load_lds_dwordx4 v201, s[4:5]
	v_add_f32_e32 v117, 1.0, v117
	s_add_u32 m0, s8, 0x18800
	v_mfma_f32_16x16x32_bf16 v[42:45], v[192:195], v[176:179], v[42:45]
	global_load_lds_dwordx4 v202, s[4:5]
	s_add_u32 m0, s8, 0x18c00
	v_mfma_f32_16x16x32_bf16 v[46:49], v[196:199], v[176:179], v[46:49]
	global_load_lds_dwordx4 v203, s[4:5]
	v_add_f32_e32 v118, 1.0, v118
	s_add_u32 m0, s9, 0x18000
	v_mfma_f32_16x16x32_bf16 v[50:53], v[184:187], v[180:183], v[50:53]
	global_load_lds_dwordx4 v204, s[6:7]
	s_add_u32 m0, s9, 0x18400
	v_mfma_f32_16x16x32_bf16 v[54:57], v[188:191], v[180:183], v[54:57]
	global_load_lds_dwordx4 v205, s[6:7]
	v_add_f32_e32 v119, 1.0, v119
	v_mfma_f32_16x16x32_bf16 v[58:61], v[192:195], v[180:183], v[58:61]
	s_sub_u32 s4, s4, 0x780
	s_subb_u32 s5, s5, 0
	v_mfma_f32_16x16x32_bf16 v[62:65], v[196:199], v[180:183], v[62:65]
	s_add_u32 s6, s6, 0x3f880
	s_addc_u32 s7, s7, 0
	v_add_f32_e32 v120, 1.0, v120
	s_waitcnt lgkmcnt(0)
	v_mfma_f32_16x16x32_bf16 v[2:5], v[152:155], v[136:139], v[2:5]
	ds_read_b128 v[168:171], v225 offset:0
	v_mfma_f32_16x16x32_bf16 v[6:9], v[156:159], v[136:139], v[6:9]
	ds_read_b128 v[172:175], v225 offset:2048
	v_add_f32_e32 v121, 1.0, v121
	v_mfma_f32_16x16x32_bf16 v[10:13], v[160:163], v[136:139], v[10:13]
	ds_read_b128 v[176:179], v225 offset:4096
	v_rcp_f32_e32 v114, v114
	v_mfma_f32_16x16x32_bf16 v[14:17], v[164:167], v[136:139], v[14:17]
	ds_read_b128 v[180:183], v225 offset:6144
	v_rcp_f32_e32 v115, v115
	v_mfma_f32_16x16x32_bf16 v[18:21], v[152:155], v[140:143], v[18:21]
	ds_read_b128 v[184:187], v233 offset:0
	v_mfma_f32_16x16x32_bf16 v[22:25], v[156:159], v[140:143], v[22:25]
	ds_read_b128 v[188:191], v233 offset:2048
	v_rcp_f32_e32 v116, v116
	v_mfma_f32_16x16x32_bf16 v[26:29], v[160:163], v[140:143], v[26:29]
	ds_read_b128 v[192:195], v233 offset:4096
	v_rcp_f32_e32 v117, v117
	v_mfma_f32_16x16x32_bf16 v[30:33], v[164:167], v[140:143], v[30:33]
	ds_read_b128 v[196:199], v233 offset:6144
	v_rcp_f32_e32 v118, v118
	v_mfma_f32_16x16x32_bf16 v[34:37], v[152:155], v[144:147], v[34:37]
	v_mfma_f32_16x16x32_bf16 v[38:41], v[156:159], v[144:147], v[38:41]
	v_rcp_f32_e32 v119, v119
	v_mfma_f32_16x16x32_bf16 v[42:45], v[160:163], v[144:147], v[42:45]
	v_rcp_f32_e32 v120, v120
	v_mfma_f32_16x16x32_bf16 v[46:49], v[164:167], v[144:147], v[46:49]
	v_rcp_f32_e32 v121, v121
	v_mfma_f32_16x16x32_bf16 v[50:53], v[152:155], v[148:151], v[50:53]
	v_mfma_f32_16x16x32_bf16 v[54:57], v[156:159], v[148:151], v[54:57]
	v_cvt_pk_bf16_f32 v114, v114, v115
	v_mfma_f32_16x16x32_bf16 v[58:61], v[160:163], v[148:151], v[58:61]
	v_cvt_pk_bf16_f32 v115, v116, v117
	v_mfma_f32_16x16x32_bf16 v[62:65], v[164:167], v[148:151], v[62:65]
	v_cvt_pk_bf16_f32 v116, v118, v119
	s_waitcnt vmcnt(6) lgkmcnt(0)
	s_barrier
	v_mfma_f32_16x16x32_bf16 v[2:5], v[184:187], v[168:171], v[2:5]
	ds_read_b128 v[136:139], v219 offset:0
	v_mfma_f32_16x16x32_bf16 v[6:9], v[188:191], v[168:171], v[6:9]
	ds_read_b128 v[140:143], v219 offset:2048
	v_mfma_f32_16x16x32_bf16 v[10:13], v[192:195], v[168:171], v[10:13]
	ds_read_b128 v[144:147], v219 offset:4096
	v_cvt_pk_bf16_f32 v117, v120, v121
	v_mfma_f32_16x16x32_bf16 v[14:17], v[196:199], v[168:171], v[14:17]
	ds_read_b128 v[148:151], v219 offset:6144
	v_mfma_f32_16x16x32_bf16 v[18:21], v[184:187], v[172:175], v[18:21]
	ds_read_b128 v[152:155], v231 offset:0
	global_store_dwordx4 v241, v[114:117], s[10:11] offset:2048
	v_mfma_f32_16x16x32_bf16 v[22:25], v[188:191], v[172:175], v[22:25]
	ds_read_b128 v[156:159], v231 offset:2048
	v_mfma_f32_16x16x32_bf16 v[26:29], v[192:195], v[172:175], v[26:29]
	ds_read_b128 v[160:163], v231 offset:4096
	v_mul_f32_e32 v122, s12, v122
	v_mfma_f32_16x16x32_bf16 v[30:33], v[196:199], v[172:175], v[30:33]
	ds_read_b128 v[164:167], v231 offset:6144
	s_mov_b32 m0, s8
	v_mfma_f32_16x16x32_bf16 v[34:37], v[184:187], v[176:179], v[34:37]
	global_load_lds_dwordx4 v200, s[4:5]
	s_add_u32 m0, s8, 0x400
	v_mfma_f32_16x16x32_bf16 v[38:41], v[188:191], v[176:179], v[38:41]
	global_load_lds_dwordx4 v201, s[4:5]
	v_mul_f32_e32 v123, s12, v123
	s_add_u32 m0, s8, 0x800
	v_mfma_f32_16x16x32_bf16 v[42:45], v[192:195], v[176:179], v[42:45]
	global_load_lds_dwordx4 v202, s[4:5]
	s_add_u32 m0, s8, 0xc00
	v_mfma_f32_16x16x32_bf16 v[46:49], v[196:199], v[176:179], v[46:49]
	global_load_lds_dwordx4 v203, s[4:5]
	v_mul_f32_e32 v124, s12, v124
	s_mov_b32 m0, s9
	v_mfma_f32_16x16x32_bf16 v[50:53], v[184:187], v[180:183], v[50:53]
	global_load_lds_dwordx4 v204, s[6:7]
	s_add_u32 m0, s9, 0x400
	v_mfma_f32_16x16x32_bf16 v[54:57], v[188:191], v[180:183], v[54:57]
	global_load_lds_dwordx4 v205, s[6:7]
	v_mul_f32_e32 v125, s12, v125
	v_mfma_f32_16x16x32_bf16 v[58:61], v[192:195], v[180:183], v[58:61]
	s_add_u32 s4, s4, 0x80
	s_addc_u32 s5, s5, 0
	v_mfma_f32_16x16x32_bf16 v[62:65], v[196:199], v[180:183], v[62:65]
	s_add_u32 s6, s6, 0x80
	s_addc_u32 s7, s7, 0
	v_mul_f32_e32 v126, s12, v126
	s_waitcnt lgkmcnt(0)
	v_mfma_f32_16x16x32_bf16 v[2:5], v[152:155], v[136:139], v[2:5]
	ds_read_b128 v[168:171], v228 offset:0
	v_mfma_f32_16x16x32_bf16 v[6:9], v[156:159], v[136:139], v[6:9]
	ds_read_b128 v[172:175], v228 offset:2048
	v_mul_f32_e32 v127, s12, v127
	v_mfma_f32_16x16x32_bf16 v[10:13], v[160:163], v[136:139], v[10:13]
	ds_read_b128 v[176:179], v228 offset:4096
	v_mul_f32_e32 v128, s12, v128
	v_mfma_f32_16x16x32_bf16 v[14:17], v[164:167], v[136:139], v[14:17]
	ds_read_b128 v[180:183], v228 offset:6144
	v_mul_f32_e32 v129, s12, v129
	v_mfma_f32_16x16x32_bf16 v[18:21], v[152:155], v[140:143], v[18:21]
	ds_read_b128 v[184:187], v234 offset:0
	v_mfma_f32_16x16x32_bf16 v[22:25], v[156:159], v[140:143], v[22:25]
	ds_read_b128 v[188:191], v234 offset:2048
	v_exp_f32_e32 v122, v122
	v_mfma_f32_16x16x32_bf16 v[26:29], v[160:163], v[140:143], v[26:29]
	ds_read_b128 v[192:195], v234 offset:4096
	v_exp_f32_e32 v123, v123
	v_mfma_f32_16x16x32_bf16 v[30:33], v[164:167], v[140:143], v[30:33]
	ds_read_b128 v[196:199], v234 offset:6144
	v_exp_f32_e32 v124, v124
	v_mfma_f32_16x16x32_bf16 v[34:37], v[152:155], v[144:147], v[34:37]
	v_mfma_f32_16x16x32_bf16 v[38:41], v[156:159], v[144:147], v[38:41]
	v_exp_f32_e32 v125, v125
	v_mfma_f32_16x16x32_bf16 v[42:45], v[160:163], v[144:147], v[42:45]
	v_exp_f32_e32 v126, v126
	v_mfma_f32_16x16x32_bf16 v[46:49], v[164:167], v[144:147], v[46:49]
	v_exp_f32_e32 v127, v127
	v_mfma_f32_16x16x32_bf16 v[50:53], v[152:155], v[148:151], v[50:53]
	v_mfma_f32_16x16x32_bf16 v[54:57], v[156:159], v[148:151], v[54:57]
	v_exp_f32_e32 v128, v128
	v_mfma_f32_16x16x32_bf16 v[58:61], v[160:163], v[148:151], v[58:61]
	v_exp_f32_e32 v129, v129
	v_mfma_f32_16x16x32_bf16 v[62:65], v[164:167], v[148:151], v[62:65]
	v_add_f32_e32 v122, 1.0, v122
	s_waitcnt vmcnt(7) lgkmcnt(0)
	s_barrier
	v_mfma_f32_16x16x32_bf16 v[2:5], v[184:187], v[168:171], v[2:5]
	ds_read_b128 v[136:139], v224 offset:0
	v_mfma_f32_16x16x32_bf16 v[6:9], v[188:191], v[168:171], v[6:9]
	ds_read_b128 v[140:143], v224 offset:2048
	v_mfma_f32_16x16x32_bf16 v[10:13], v[192:195], v[168:171], v[10:13]
	ds_read_b128 v[144:147], v224 offset:4096
	v_add_f32_e32 v123, 1.0, v123
	v_mfma_f32_16x16x32_bf16 v[14:17], v[196:199], v[168:171], v[14:17]
	ds_read_b128 v[148:151], v224 offset:6144
	v_mfma_f32_16x16x32_bf16 v[18:21], v[184:187], v[172:175], v[18:21]
	ds_read_b128 v[152:155], v232 offset:0
	v_add_f32_e32 v124, 1.0, v124
	v_mfma_f32_16x16x32_bf16 v[22:25], v[188:191], v[172:175], v[22:25]
	ds_read_b128 v[156:159], v232 offset:2048
	v_mfma_f32_16x16x32_bf16 v[26:29], v[192:195], v[172:175], v[26:29]
	ds_read_b128 v[160:163], v232 offset:4096
	v_add_f32_e32 v125, 1.0, v125
	v_mfma_f32_16x16x32_bf16 v[30:33], v[196:199], v[172:175], v[30:33]
	ds_read_b128 v[164:167], v232 offset:6144
	s_add_u32 m0, s8, 0xc000
	v_mfma_f32_16x16x32_bf16 v[34:37], v[184:187], v[176:179], v[34:37]
	global_load_lds_dwordx4 v200, s[4:5]
	s_add_u32 m0, s8, 0xc400
	v_mfma_f32_16x16x32_bf16 v[38:41], v[188:191], v[176:179], v[38:41]
	global_load_lds_dwordx4 v201, s[4:5]
	v_add_f32_e32 v126, 1.0, v126
	s_add_u32 m0, s8, 0xc800
	v_mfma_f32_16x16x32_bf16 v[42:45], v[192:195], v[176:179], v[42:45]
	global_load_lds_dwordx4 v202, s[4:5]
	s_add_u32 m0, s8, 0xcc00
	v_mfma_f32_16x16x32_bf16 v[46:49], v[196:199], v[176:179], v[46:49]
	global_load_lds_dwordx4 v203, s[4:5]
	v_add_f32_e32 v127, 1.0, v127
	s_add_u32 m0, s9, 0xc000
	v_mfma_f32_16x16x32_bf16 v[50:53], v[184:187], v[180:183], v[50:53]
	global_load_lds_dwordx4 v204, s[6:7]
	s_add_u32 m0, s9, 0xc400
	v_mfma_f32_16x16x32_bf16 v[54:57], v[188:191], v[180:183], v[54:57]
	global_load_lds_dwordx4 v205, s[6:7]
	v_add_f32_e32 v128, 1.0, v128
	v_mfma_f32_16x16x32_bf16 v[58:61], v[192:195], v[180:183], v[58:61]
	s_add_u32 s4, s4, 0x80
	s_addc_u32 s5, s5, 0
	v_mfma_f32_16x16x32_bf16 v[62:65], v[196:199], v[180:183], v[62:65]
	s_add_u32 s6, s6, 0x80
	s_addc_u32 s7, s7, 0
	v_add_f32_e32 v129, 1.0, v129
	s_waitcnt lgkmcnt(0)
	v_mfma_f32_16x16x32_bf16 v[2:5], v[152:155], v[136:139], v[2:5]
	ds_read_b128 v[168:171], v229 offset:0
	v_mfma_f32_16x16x32_bf16 v[6:9], v[156:159], v[136:139], v[6:9]
	ds_read_b128 v[172:175], v229 offset:2048
	v_rcp_f32_e32 v122, v122
	v_mfma_f32_16x16x32_bf16 v[10:13], v[160:163], v[136:139], v[10:13]
	ds_read_b128 v[176:179], v229 offset:4096
	v_rcp_f32_e32 v123, v123
	v_mfma_f32_16x16x32_bf16 v[14:17], v[164:167], v[136:139], v[14:17]
	ds_read_b128 v[180:183], v229 offset:6144
	v_rcp_f32_e32 v124, v124
	v_mfma_f32_16x16x32_bf16 v[18:21], v[152:155], v[140:143], v[18:21]
	ds_read_b128 v[184:187], v235 offset:0
	v_mfma_f32_16x16x32_bf16 v[22:25], v[156:159], v[140:143], v[22:25]
	ds_read_b128 v[188:191], v235 offset:2048
	v_rcp_f32_e32 v125, v125
	v_mfma_f32_16x16x32_bf16 v[26:29], v[160:163], v[140:143], v[26:29]
	ds_read_b128 v[192:195], v235 offset:4096
	v_rcp_f32_e32 v126, v126
	v_mfma_f32_16x16x32_bf16 v[30:33], v[164:167], v[140:143], v[30:33]
	ds_read_b128 v[196:199], v235 offset:6144
	v_rcp_f32_e32 v127, v127
	v_mfma_f32_16x16x32_bf16 v[34:37], v[152:155], v[144:147], v[34:37]
	v_mfma_f32_16x16x32_bf16 v[38:41], v[156:159], v[144:147], v[38:41]
	v_rcp_f32_e32 v128, v128
	v_mfma_f32_16x16x32_bf16 v[42:45], v[160:163], v[144:147], v[42:45]
	v_rcp_f32_e32 v129, v129
	v_mfma_f32_16x16x32_bf16 v[46:49], v[164:167], v[144:147], v[46:49]
	v_cvt_pk_bf16_f32 v122, v122, v123
	v_mfma_f32_16x16x32_bf16 v[50:53], v[152:155], v[148:151], v[50:53]
	v_mfma_f32_16x16x32_bf16 v[54:57], v[156:159], v[148:151], v[54:57]
	v_cvt_pk_bf16_f32 v123, v124, v125
	v_mfma_f32_16x16x32_bf16 v[58:61], v[160:163], v[148:151], v[58:61]
	v_cvt_pk_bf16_f32 v124, v126, v127
	v_mfma_f32_16x16x32_bf16 v[62:65], v[164:167], v[148:151], v[62:65]
	v_cvt_pk_bf16_f32 v125, v128, v129
	s_waitcnt vmcnt(6) lgkmcnt(0)
	s_barrier
	v_mfma_f32_16x16x32_bf16 v[2:5], v[184:187], v[168:171], v[2:5]
	ds_read_b128 v[136:139], v218 offset:0
	v_mfma_f32_16x16x32_bf16 v[6:9], v[188:191], v[168:171], v[6:9]
	ds_read_b128 v[140:143], v218 offset:2048
	v_mfma_f32_16x16x32_bf16 v[10:13], v[192:195], v[168:171], v[10:13]
	ds_read_b128 v[144:147], v218 offset:4096
	v_mfma_f32_16x16x32_bf16 v[14:17], v[196:199], v[168:171], v[14:17]
	ds_read_b128 v[148:151], v218 offset:6144
	v_mfma_f32_16x16x32_bf16 v[18:21], v[184:187], v[172:175], v[18:21]
	ds_read_b128 v[152:155], v230 offset:0
	v_mfma_f32_16x16x32_bf16 v[22:25], v[188:191], v[172:175], v[22:25]
	ds_read_b128 v[156:159], v230 offset:2048
	v_mfma_f32_16x16x32_bf16 v[26:29], v[192:195], v[172:175], v[26:29]
	ds_read_b128 v[160:163], v230 offset:4096
	v_mfma_f32_16x16x32_bf16 v[30:33], v[196:199], v[172:175], v[30:33]
	ds_read_b128 v[164:167], v230 offset:6144
	s_add_u32 m0, s8, 0x18000
	v_mfma_f32_16x16x32_bf16 v[34:37], v[184:187], v[176:179], v[34:37]
	global_load_lds_dwordx4 v200, s[4:5]
	s_add_u32 m0, s8, 0x18400
	v_mfma_f32_16x16x32_bf16 v[38:41], v[188:191], v[176:179], v[38:41]
	global_load_lds_dwordx4 v201, s[4:5]
	s_add_u32 m0, s8, 0x18800
	v_mfma_f32_16x16x32_bf16 v[42:45], v[192:195], v[176:179], v[42:45]
	global_load_lds_dwordx4 v202, s[4:5]
	s_add_u32 m0, s8, 0x18c00
	v_mfma_f32_16x16x32_bf16 v[46:49], v[196:199], v[176:179], v[46:49]
	global_load_lds_dwordx4 v203, s[4:5]
	s_add_u32 m0, s9, 0x18000
	v_mfma_f32_16x16x32_bf16 v[50:53], v[184:187], v[180:183], v[50:53]
	global_load_lds_dwordx4 v204, s[6:7]
	s_add_u32 m0, s9, 0x18400
	v_mfma_f32_16x16x32_bf16 v[54:57], v[188:191], v[180:183], v[54:57]
	global_load_lds_dwordx4 v205, s[6:7]
	v_mfma_f32_16x16x32_bf16 v[58:61], v[192:195], v[180:183], v[58:61]
	s_add_u32 s4, s4, 0x80
	s_addc_u32 s5, s5, 0
	v_mfma_f32_16x16x32_bf16 v[62:65], v[196:199], v[180:183], v[62:65]
	s_add_u32 s6, s6, 0x80
	s_addc_u32 s7, s7, 0
	global_store_dwordx4 v241, v[122:125], s[10:11] offset:3072
	s_waitcnt lgkmcnt(0)
	v_mfma_f32_16x16x32_bf16 v[66:69], v[152:155], v[136:139], 0
	ds_read_b128 v[168:171], v225 offset:0
	v_mfma_f32_16x16x32_bf16 v[70:73], v[156:159], v[136:139], 0
	ds_read_b128 v[172:175], v225 offset:2048
	s_add_u32 s10, s28, s13
	s_addc_u32 s11, s29, 0
	v_mfma_f32_16x16x32_bf16 v[74:77], v[160:163], v[136:139], 0
	ds_read_b128 v[176:179], v225 offset:4096
	s_add_u32 s13, s13, 0x10000
	v_mfma_f32_16x16x32_bf16 v[78:81], v[164:167], v[136:139], 0
	ds_read_b128 v[180:183], v225 offset:6144
	v_mul_f32_e32 v2, s12, v2
	v_mfma_f32_16x16x32_bf16 v[82:85], v[152:155], v[140:143], 0
	ds_read_b128 v[184:187], v233 offset:0
	v_mfma_f32_16x16x32_bf16 v[86:89], v[156:159], v[140:143], 0
	ds_read_b128 v[188:191], v233 offset:2048
	v_mul_f32_e32 v3, s12, v3
	v_mfma_f32_16x16x32_bf16 v[90:93], v[160:163], v[140:143], 0
	ds_read_b128 v[192:195], v233 offset:4096
	v_mul_f32_e32 v4, s12, v4
	v_mfma_f32_16x16x32_bf16 v[94:97], v[164:167], v[140:143], 0
	ds_read_b128 v[196:199], v233 offset:6144
	v_mul_f32_e32 v5, s12, v5
	v_mfma_f32_16x16x32_bf16 v[98:101], v[152:155], v[144:147], 0
	v_mfma_f32_16x16x32_bf16 v[102:105], v[156:159], v[144:147], 0
	v_mul_f32_e32 v6, s12, v6
	v_mfma_f32_16x16x32_bf16 v[106:109], v[160:163], v[144:147], 0
	v_mul_f32_e32 v7, s12, v7
	v_mfma_f32_16x16x32_bf16 v[110:113], v[164:167], v[144:147], 0
	v_mul_f32_e32 v8, s12, v8
	v_mfma_f32_16x16x32_bf16 v[114:117], v[152:155], v[148:151], 0
	v_mfma_f32_16x16x32_bf16 v[118:121], v[156:159], v[148:151], 0
	v_mul_f32_e32 v9, s12, v9
	v_mfma_f32_16x16x32_bf16 v[122:125], v[160:163], v[148:151], 0
	v_exp_f32_e32 v2, v2
	v_mfma_f32_16x16x32_bf16 v[126:129], v[164:167], v[148:151], 0
	v_exp_f32_e32 v3, v3
	s_waitcnt vmcnt(7) lgkmcnt(0)
	s_barrier
	v_mfma_f32_16x16x32_bf16 v[66:69], v[184:187], v[168:171], v[66:69]
	ds_read_b128 v[136:139], v219 offset:0
	v_mfma_f32_16x16x32_bf16 v[70:73], v[188:191], v[168:171], v[70:73]
	ds_read_b128 v[140:143], v219 offset:2048
	v_mfma_f32_16x16x32_bf16 v[74:77], v[192:195], v[168:171], v[74:77]
	ds_read_b128 v[144:147], v219 offset:4096
	v_exp_f32_e32 v4, v4
	v_mfma_f32_16x16x32_bf16 v[78:81], v[196:199], v[168:171], v[78:81]
	ds_read_b128 v[148:151], v219 offset:6144
	v_mfma_f32_16x16x32_bf16 v[82:85], v[184:187], v[172:175], v[82:85]
	ds_read_b128 v[152:155], v231 offset:0
	v_exp_f32_e32 v5, v5
	v_mfma_f32_16x16x32_bf16 v[86:89], v[188:191], v[172:175], v[86:89]
	ds_read_b128 v[156:159], v231 offset:2048
	v_mfma_f32_16x16x32_bf16 v[90:93], v[192:195], v[172:175], v[90:93]
	ds_read_b128 v[160:163], v231 offset:4096
	v_exp_f32_e32 v6, v6
	v_mfma_f32_16x16x32_bf16 v[94:97], v[196:199], v[172:175], v[94:97]
	ds_read_b128 v[164:167], v231 offset:6144
	s_mov_b32 m0, s8
	v_mfma_f32_16x16x32_bf16 v[98:101], v[184:187], v[176:179], v[98:101]
	global_load_lds_dwordx4 v200, s[4:5]
	s_add_u32 m0, s8, 0x400
	v_mfma_f32_16x16x32_bf16 v[102:105], v[188:191], v[176:179], v[102:105]
	global_load_lds_dwordx4 v201, s[4:5]
	v_exp_f32_e32 v7, v7
	s_add_u32 m0, s8, 0x800
	v_mfma_f32_16x16x32_bf16 v[106:109], v[192:195], v[176:179], v[106:109]
	global_load_lds_dwordx4 v202, s[4:5]
	s_add_u32 m0, s8, 0xc00
	v_mfma_f32_16x16x32_bf16 v[110:113], v[196:199], v[176:179], v[110:113]
	global_load_lds_dwordx4 v203, s[4:5]
	v_exp_f32_e32 v8, v8
	s_mov_b32 m0, s9
	v_mfma_f32_16x16x32_bf16 v[114:117], v[184:187], v[180:183], v[114:117]
	global_load_lds_dwordx4 v204, s[6:7]
	s_add_u32 m0, s9, 0x400
	v_mfma_f32_16x16x32_bf16 v[118:121], v[188:191], v[180:183], v[118:121]
	global_load_lds_dwordx4 v205, s[6:7]
	v_exp_f32_e32 v9, v9
	v_mfma_f32_16x16x32_bf16 v[122:125], v[192:195], v[180:183], v[122:125]
	s_add_u32 s4, s4, 0x80
	s_addc_u32 s5, s5, 0
	v_mfma_f32_16x16x32_bf16 v[126:129], v[196:199], v[180:183], v[126:129]
	s_add_u32 s6, s6, 0x80
	s_addc_u32 s7, s7, 0
	v_add_f32_e32 v2, 1.0, v2
	s_waitcnt lgkmcnt(0)
	v_mfma_f32_16x16x32_bf16 v[66:69], v[152:155], v[136:139], v[66:69]
	ds_read_b128 v[168:171], v228 offset:0
	v_mfma_f32_16x16x32_bf16 v[70:73], v[156:159], v[136:139], v[70:73]
	ds_read_b128 v[172:175], v228 offset:2048
	v_add_f32_e32 v3, 1.0, v3
	v_mfma_f32_16x16x32_bf16 v[74:77], v[160:163], v[136:139], v[74:77]
	ds_read_b128 v[176:179], v228 offset:4096
	v_add_f32_e32 v4, 1.0, v4
	v_mfma_f32_16x16x32_bf16 v[78:81], v[164:167], v[136:139], v[78:81]
	ds_read_b128 v[180:183], v228 offset:6144
	v_add_f32_e32 v5, 1.0, v5
	v_mfma_f32_16x16x32_bf16 v[82:85], v[152:155], v[140:143], v[82:85]
	ds_read_b128 v[184:187], v234 offset:0
	v_mfma_f32_16x16x32_bf16 v[86:89], v[156:159], v[140:143], v[86:89]
	ds_read_b128 v[188:191], v234 offset:2048
	v_add_f32_e32 v6, 1.0, v6
	v_mfma_f32_16x16x32_bf16 v[90:93], v[160:163], v[140:143], v[90:93]
	ds_read_b128 v[192:195], v234 offset:4096
	v_add_f32_e32 v7, 1.0, v7
	v_mfma_f32_16x16x32_bf16 v[94:97], v[164:167], v[140:143], v[94:97]
	ds_read_b128 v[196:199], v234 offset:6144
	v_add_f32_e32 v8, 1.0, v8
	v_mfma_f32_16x16x32_bf16 v[98:101], v[152:155], v[144:147], v[98:101]
	v_mfma_f32_16x16x32_bf16 v[102:105], v[156:159], v[144:147], v[102:105]
	v_add_f32_e32 v9, 1.0, v9
	v_mfma_f32_16x16x32_bf16 v[106:109], v[160:163], v[144:147], v[106:109]
	v_rcp_f32_e32 v2, v2
	v_mfma_f32_16x16x32_bf16 v[110:113], v[164:167], v[144:147], v[110:113]
	v_rcp_f32_e32 v3, v3
	v_mfma_f32_16x16x32_bf16 v[114:117], v[152:155], v[148:151], v[114:117]
	v_mfma_f32_16x16x32_bf16 v[118:121], v[156:159], v[148:151], v[118:121]
	v_rcp_f32_e32 v4, v4
	v_mfma_f32_16x16x32_bf16 v[122:125], v[160:163], v[148:151], v[122:125]
	v_rcp_f32_e32 v5, v5
	v_mfma_f32_16x16x32_bf16 v[126:129], v[164:167], v[148:151], v[126:129]
	v_rcp_f32_e32 v6, v6
	s_waitcnt vmcnt(7) lgkmcnt(0)
	s_barrier
	v_mfma_f32_16x16x32_bf16 v[66:69], v[184:187], v[168:171], v[66:69]
	ds_read_b128 v[136:139], v224 offset:0
	v_mfma_f32_16x16x32_bf16 v[70:73], v[188:191], v[168:171], v[70:73]
	ds_read_b128 v[140:143], v224 offset:2048
	v_mfma_f32_16x16x32_bf16 v[74:77], v[192:195], v[168:171], v[74:77]
	ds_read_b128 v[144:147], v224 offset:4096
	v_rcp_f32_e32 v7, v7
	v_mfma_f32_16x16x32_bf16 v[78:81], v[196:199], v[168:171], v[78:81]
	ds_read_b128 v[148:151], v224 offset:6144
	v_mfma_f32_16x16x32_bf16 v[82:85], v[184:187], v[172:175], v[82:85]
	ds_read_b128 v[152:155], v232 offset:0
	v_rcp_f32_e32 v8, v8
	v_mfma_f32_16x16x32_bf16 v[86:89], v[188:191], v[172:175], v[86:89]
	ds_read_b128 v[156:159], v232 offset:2048
	v_mfma_f32_16x16x32_bf16 v[90:93], v[192:195], v[172:175], v[90:93]
	ds_read_b128 v[160:163], v232 offset:4096
	v_rcp_f32_e32 v9, v9
	v_mfma_f32_16x16x32_bf16 v[94:97], v[196:199], v[172:175], v[94:97]
	ds_read_b128 v[164:167], v232 offset:6144
	s_add_u32 m0, s8, 0xc000
	v_mfma_f32_16x16x32_bf16 v[98:101], v[184:187], v[176:179], v[98:101]
	global_load_lds_dwordx4 v200, s[4:5]
	s_add_u32 m0, s8, 0xc400
	v_mfma_f32_16x16x32_bf16 v[102:105], v[188:191], v[176:179], v[102:105]
	global_load_lds_dwordx4 v201, s[4:5]
	v_cvt_pk_bf16_f32 v2, v2, v3
	s_add_u32 m0, s8, 0xc800
	v_mfma_f32_16x16x32_bf16 v[106:109], v[192:195], v[176:179], v[106:109]
	global_load_lds_dwordx4 v202, s[4:5]
	s_add_u32 m0, s8, 0xcc00
	v_mfma_f32_16x16x32_bf16 v[110:113], v[196:199], v[176:179], v[110:113]
	global_load_lds_dwordx4 v203, s[4:5]
	v_cvt_pk_bf16_f32 v3, v4, v5
	s_add_u32 m0, s9, 0xc000
	v_mfma_f32_16x16x32_bf16 v[114:117], v[184:187], v[180:183], v[114:117]
	global_load_lds_dwordx4 v204, s[6:7]
	s_add_u32 m0, s9, 0xc400
	v_mfma_f32_16x16x32_bf16 v[118:121], v[188:191], v[180:183], v[118:121]
	global_load_lds_dwordx4 v205, s[6:7]
	v_cvt_pk_bf16_f32 v4, v6, v7
	v_mfma_f32_16x16x32_bf16 v[122:125], v[192:195], v[180:183], v[122:125]
	s_add_u32 s4, s4, 0x80
	s_addc_u32 s5, s5, 0
	v_mfma_f32_16x16x32_bf16 v[126:129], v[196:199], v[180:183], v[126:129]
	s_add_u32 s6, s6, 0x80
	s_addc_u32 s7, s7, 0
	v_cvt_pk_bf16_f32 v5, v8, v9
	s_waitcnt lgkmcnt(0)
	v_mfma_f32_16x16x32_bf16 v[66:69], v[152:155], v[136:139], v[66:69]
	ds_read_b128 v[168:171], v229 offset:0
	v_mfma_f32_16x16x32_bf16 v[70:73], v[156:159], v[136:139], v[70:73]
	ds_read_b128 v[172:175], v229 offset:2048
	global_store_dwordx4 v240, v[2:5], s[10:11] offset:0
	v_mfma_f32_16x16x32_bf16 v[74:77], v[160:163], v[136:139], v[74:77]
	ds_read_b128 v[176:179], v229 offset:4096
	v_mul_f32_e32 v10, s12, v10
	v_mfma_f32_16x16x32_bf16 v[78:81], v[164:167], v[136:139], v[78:81]
	ds_read_b128 v[180:183], v229 offset:6144
	v_mul_f32_e32 v11, s12, v11
	v_mfma_f32_16x16x32_bf16 v[82:85], v[152:155], v[140:143], v[82:85]
	ds_read_b128 v[184:187], v235 offset:0
	v_mfma_f32_16x16x32_bf16 v[86:89], v[156:159], v[140:143], v[86:89]
	ds_read_b128 v[188:191], v235 offset:2048
	v_mul_f32_e32 v12, s12, v12
	v_mfma_f32_16x16x32_bf16 v[90:93], v[160:163], v[140:143], v[90:93]
	ds_read_b128 v[192:195], v235 offset:4096
	v_mul_f32_e32 v13, s12, v13
	v_mfma_f32_16x16x32_bf16 v[94:97], v[164:167], v[140:143], v[94:97]
	ds_read_b128 v[196:199], v235 offset:6144
	v_mul_f32_e32 v14, s12, v14
	v_mfma_f32_16x16x32_bf16 v[98:101], v[152:155], v[144:147], v[98:101]
	v_mfma_f32_16x16x32_bf16 v[102:105], v[156:159], v[144:147], v[102:105]
	v_mul_f32_e32 v15, s12, v15
	v_mfma_f32_16x16x32_bf16 v[106:109], v[160:163], v[144:147], v[106:109]
	v_mul_f32_e32 v16, s12, v16
	v_mfma_f32_16x16x32_bf16 v[110:113], v[164:167], v[144:147], v[110:113]
	v_mul_f32_e32 v17, s12, v17
	v_mfma_f32_16x16x32_bf16 v[114:117], v[152:155], v[148:151], v[114:117]
	v_mfma_f32_16x16x32_bf16 v[118:121], v[156:159], v[148:151], v[118:121]
	v_exp_f32_e32 v10, v10
	v_mfma_f32_16x16x32_bf16 v[122:125], v[160:163], v[148:151], v[122:125]
	v_exp_f32_e32 v11, v11
	v_mfma_f32_16x16x32_bf16 v[126:129], v[164:167], v[148:151], v[126:129]
	v_exp_f32_e32 v12, v12
	s_waitcnt vmcnt(7) lgkmcnt(0)
	s_barrier
	v_mfma_f32_16x16x32_bf16 v[66:69], v[184:187], v[168:171], v[66:69]
	ds_read_b128 v[136:139], v218 offset:0
	v_mfma_f32_16x16x32_bf16 v[70:73], v[188:191], v[168:171], v[70:73]
	ds_read_b128 v[140:143], v218 offset:2048
	v_mfma_f32_16x16x32_bf16 v[74:77], v[192:195], v[168:171], v[74:77]
	ds_read_b128 v[144:147], v218 offset:4096
	v_exp_f32_e32 v13, v13
	v_mfma_f32_16x16x32_bf16 v[78:81], v[196:199], v[168:171], v[78:81]
	ds_read_b128 v[148:151], v218 offset:6144
	v_mfma_f32_16x16x32_bf16 v[82:85], v[184:187], v[172:175], v[82:85]
	ds_read_b128 v[152:155], v230 offset:0
	v_exp_f32_e32 v14, v14
	v_mfma_f32_16x16x32_bf16 v[86:89], v[188:191], v[172:175], v[86:89]
	ds_read_b128 v[156:159], v230 offset:2048
	v_mfma_f32_16x16x32_bf16 v[90:93], v[192:195], v[172:175], v[90:93]
	ds_read_b128 v[160:163], v230 offset:4096
	v_exp_f32_e32 v15, v15
	v_mfma_f32_16x16x32_bf16 v[94:97], v[196:199], v[172:175], v[94:97]
	ds_read_b128 v[164:167], v230 offset:6144
	s_add_u32 m0, s8, 0x18000
	v_mfma_f32_16x16x32_bf16 v[98:101], v[184:187], v[176:179], v[98:101]
	global_load_lds_dwordx4 v200, s[4:5]
	s_add_u32 m0, s8, 0x18400
	v_mfma_f32_16x16x32_bf16 v[102:105], v[188:191], v[176:179], v[102:105]
	global_load_lds_dwordx4 v201, s[4:5]
	v_exp_f32_e32 v16, v16
	s_add_u32 m0, s8, 0x18800
	v_mfma_f32_16x16x32_bf16 v[106:109], v[192:195], v[176:179], v[106:109]
	global_load_lds_dwordx4 v202, s[4:5]
	s_add_u32 m0, s8, 0x18c00
	v_mfma_f32_16x16x32_bf16 v[110:113], v[196:199], v[176:179], v[110:113]
	global_load_lds_dwordx4 v203, s[4:5]
	v_exp_f32_e32 v17, v17
	s_add_u32 m0, s9, 0x18000
	v_mfma_f32_16x16x32_bf16 v[114:117], v[184:187], v[180:183], v[114:117]
	global_load_lds_dwordx4 v204, s[6:7]
	s_add_u32 m0, s9, 0x18400
	v_mfma_f32_16x16x32_bf16 v[118:121], v[188:191], v[180:183], v[118:121]
	global_load_lds_dwordx4 v205, s[6:7]
	v_add_f32_e32 v10, 1.0, v10
	v_mfma_f32_16x16x32_bf16 v[122:125], v[192:195], v[180:183], v[122:125]
	s_add_u32 s4, s4, 0x80
	s_addc_u32 s5, s5, 0
	v_mfma_f32_16x16x32_bf16 v[126:129], v[196:199], v[180:183], v[126:129]
	s_add_u32 s6, s6, 0x80
	s_addc_u32 s7, s7, 0
	v_add_f32_e32 v11, 1.0, v11
	s_waitcnt lgkmcnt(0)
	v_mfma_f32_16x16x32_bf16 v[66:69], v[152:155], v[136:139], v[66:69]
	ds_read_b128 v[168:171], v225 offset:0
	v_mfma_f32_16x16x32_bf16 v[70:73], v[156:159], v[136:139], v[70:73]
	ds_read_b128 v[172:175], v225 offset:2048
	v_add_f32_e32 v12, 1.0, v12
	v_mfma_f32_16x16x32_bf16 v[74:77], v[160:163], v[136:139], v[74:77]
	ds_read_b128 v[176:179], v225 offset:4096
	v_add_f32_e32 v13, 1.0, v13
	v_mfma_f32_16x16x32_bf16 v[78:81], v[164:167], v[136:139], v[78:81]
	ds_read_b128 v[180:183], v225 offset:6144
	v_add_f32_e32 v14, 1.0, v14
	v_mfma_f32_16x16x32_bf16 v[82:85], v[152:155], v[140:143], v[82:85]
	ds_read_b128 v[184:187], v233 offset:0
	v_mfma_f32_16x16x32_bf16 v[86:89], v[156:159], v[140:143], v[86:89]
	ds_read_b128 v[188:191], v233 offset:2048
	v_add_f32_e32 v15, 1.0, v15
	v_mfma_f32_16x16x32_bf16 v[90:93], v[160:163], v[140:143], v[90:93]
	ds_read_b128 v[192:195], v233 offset:4096
	v_add_f32_e32 v16, 1.0, v16
	v_mfma_f32_16x16x32_bf16 v[94:97], v[164:167], v[140:143], v[94:97]
	ds_read_b128 v[196:199], v233 offset:6144
	v_add_f32_e32 v17, 1.0, v17
	v_mfma_f32_16x16x32_bf16 v[98:101], v[152:155], v[144:147], v[98:101]
	v_mfma_f32_16x16x32_bf16 v[102:105], v[156:159], v[144:147], v[102:105]
	v_rcp_f32_e32 v10, v10
	v_mfma_f32_16x16x32_bf16 v[106:109], v[160:163], v[144:147], v[106:109]
	v_rcp_f32_e32 v11, v11
	v_mfma_f32_16x16x32_bf16 v[110:113], v[164:167], v[144:147], v[110:113]
	v_rcp_f32_e32 v12, v12
	v_mfma_f32_16x16x32_bf16 v[114:117], v[152:155], v[148:151], v[114:117]
	v_mfma_f32_16x16x32_bf16 v[118:121], v[156:159], v[148:151], v[118:121]
	v_rcp_f32_e32 v13, v13
	v_mfma_f32_16x16x32_bf16 v[122:125], v[160:163], v[148:151], v[122:125]
	v_rcp_f32_e32 v14, v14
	v_mfma_f32_16x16x32_bf16 v[126:129], v[164:167], v[148:151], v[126:129]
	v_rcp_f32_e32 v15, v15
	s_waitcnt vmcnt(7) lgkmcnt(0)
	s_barrier
	v_mfma_f32_16x16x32_bf16 v[66:69], v[184:187], v[168:171], v[66:69]
	ds_read_b128 v[136:139], v219 offset:0
	v_mfma_f32_16x16x32_bf16 v[70:73], v[188:191], v[168:171], v[70:73]
	ds_read_b128 v[140:143], v219 offset:2048
	v_mfma_f32_16x16x32_bf16 v[74:77], v[192:195], v[168:171], v[74:77]
	ds_read_b128 v[144:147], v219 offset:4096
	v_rcp_f32_e32 v16, v16
	v_mfma_f32_16x16x32_bf16 v[78:81], v[196:199], v[168:171], v[78:81]
	ds_read_b128 v[148:151], v219 offset:6144
	v_mfma_f32_16x16x32_bf16 v[82:85], v[184:187], v[172:175], v[82:85]
	ds_read_b128 v[152:155], v231 offset:0
	v_rcp_f32_e32 v17, v17
	v_mfma_f32_16x16x32_bf16 v[86:89], v[188:191], v[172:175], v[86:89]
	ds_read_b128 v[156:159], v231 offset:2048
	v_mfma_f32_16x16x32_bf16 v[90:93], v[192:195], v[172:175], v[90:93]
	ds_read_b128 v[160:163], v231 offset:4096
	v_cvt_pk_bf16_f32 v10, v10, v11
	v_mfma_f32_16x16x32_bf16 v[94:97], v[196:199], v[172:175], v[94:97]
	ds_read_b128 v[164:167], v231 offset:6144
	s_mov_b32 m0, s8
	v_mfma_f32_16x16x32_bf16 v[98:101], v[184:187], v[176:179], v[98:101]
	global_load_lds_dwordx4 v200, s[4:5]
	s_add_u32 m0, s8, 0x400
	v_mfma_f32_16x16x32_bf16 v[102:105], v[188:191], v[176:179], v[102:105]
	global_load_lds_dwordx4 v201, s[4:5]
	v_cvt_pk_bf16_f32 v11, v12, v13
	s_add_u32 m0, s8, 0x800
	v_mfma_f32_16x16x32_bf16 v[106:109], v[192:195], v[176:179], v[106:109]
	global_load_lds_dwordx4 v202, s[4:5]
	s_add_u32 m0, s8, 0xc00
	v_mfma_f32_16x16x32_bf16 v[110:113], v[196:199], v[176:179], v[110:113]
	global_load_lds_dwordx4 v203, s[4:5]
	v_cvt_pk_bf16_f32 v12, v14, v15
	s_mov_b32 m0, s9
	v_mfma_f32_16x16x32_bf16 v[114:117], v[184:187], v[180:183], v[114:117]
	global_load_lds_dwordx4 v204, s[6:7]
	s_add_u32 m0, s9, 0x400
	v_mfma_f32_16x16x32_bf16 v[118:121], v[188:191], v[180:183], v[118:121]
	global_load_lds_dwordx4 v205, s[6:7]
	v_cvt_pk_bf16_f32 v13, v16, v17
	v_mfma_f32_16x16x32_bf16 v[122:125], v[192:195], v[180:183], v[122:125]
	s_add_u32 s4, s4, 0x80
	s_addc_u32 s5, s5, 0
	v_mfma_f32_16x16x32_bf16 v[126:129], v[196:199], v[180:183], v[126:129]
	s_add_u32 s6, s6, 0x80
	s_addc_u32 s7, s7, 0
	global_store_dwordx4 v240, v[10:13], s[10:11] offset:1024
	s_waitcnt lgkmcnt(0)
	v_mfma_f32_16x16x32_bf16 v[66:69], v[152:155], v[136:139], v[66:69]
	ds_read_b128 v[168:171], v228 offset:0
	v_mfma_f32_16x16x32_bf16 v[70:73], v[156:159], v[136:139], v[70:73]
	ds_read_b128 v[172:175], v228 offset:2048
	v_mul_f32_e32 v18, s12, v18
	v_mfma_f32_16x16x32_bf16 v[74:77], v[160:163], v[136:139], v[74:77]
	ds_read_b128 v[176:179], v228 offset:4096
	v_mul_f32_e32 v19, s12, v19
	v_mfma_f32_16x16x32_bf16 v[78:81], v[164:167], v[136:139], v[78:81]
	ds_read_b128 v[180:183], v228 offset:6144
	v_mul_f32_e32 v20, s12, v20
	v_mfma_f32_16x16x32_bf16 v[82:85], v[152:155], v[140:143], v[82:85]
	ds_read_b128 v[184:187], v234 offset:0
	v_mfma_f32_16x16x32_bf16 v[86:89], v[156:159], v[140:143], v[86:89]
	ds_read_b128 v[188:191], v234 offset:2048
	v_mul_f32_e32 v21, s12, v21
	v_mfma_f32_16x16x32_bf16 v[90:93], v[160:163], v[140:143], v[90:93]
	ds_read_b128 v[192:195], v234 offset:4096
	v_mul_f32_e32 v22, s12, v22
	v_mfma_f32_16x16x32_bf16 v[94:97], v[164:167], v[140:143], v[94:97]
	ds_read_b128 v[196:199], v234 offset:6144
	v_mul_f32_e32 v23, s12, v23
	v_mfma_f32_16x16x32_bf16 v[98:101], v[152:155], v[144:147], v[98:101]
	v_mfma_f32_16x16x32_bf16 v[102:105], v[156:159], v[144:147], v[102:105]
	v_mul_f32_e32 v24, s12, v24
	v_mfma_f32_16x16x32_bf16 v[106:109], v[160:163], v[144:147], v[106:109]
	v_mul_f32_e32 v25, s12, v25
	v_mfma_f32_16x16x32_bf16 v[110:113], v[164:167], v[144:147], v[110:113]
	v_exp_f32_e32 v18, v18
	v_mfma_f32_16x16x32_bf16 v[114:117], v[152:155], v[148:151], v[114:117]
	v_mfma_f32_16x16x32_bf16 v[118:121], v[156:159], v[148:151], v[118:121]
	v_exp_f32_e32 v19, v19
	v_mfma_f32_16x16x32_bf16 v[122:125], v[160:163], v[148:151], v[122:125]
	v_exp_f32_e32 v20, v20
	v_mfma_f32_16x16x32_bf16 v[126:129], v[164:167], v[148:151], v[126:129]
	v_exp_f32_e32 v21, v21
	s_waitcnt vmcnt(7) lgkmcnt(0)
	s_barrier
	v_mfma_f32_16x16x32_bf16 v[66:69], v[184:187], v[168:171], v[66:69]
	ds_read_b128 v[136:139], v224 offset:0
	v_mfma_f32_16x16x32_bf16 v[70:73], v[188:191], v[168:171], v[70:73]
	ds_read_b128 v[140:143], v224 offset:2048
	v_mfma_f32_16x16x32_bf16 v[74:77], v[192:195], v[168:171], v[74:77]
	ds_read_b128 v[144:147], v224 offset:4096
	v_exp_f32_e32 v22, v22
	v_mfma_f32_16x16x32_bf16 v[78:81], v[196:199], v[168:171], v[78:81]
	ds_read_b128 v[148:151], v224 offset:6144
	v_mfma_f32_16x16x32_bf16 v[82:85], v[184:187], v[172:175], v[82:85]
	ds_read_b128 v[152:155], v232 offset:0
	v_exp_f32_e32 v23, v23
	v_mfma_f32_16x16x32_bf16 v[86:89], v[188:191], v[172:175], v[86:89]
	ds_read_b128 v[156:159], v232 offset:2048
	v_mfma_f32_16x16x32_bf16 v[90:93], v[192:195], v[172:175], v[90:93]
	ds_read_b128 v[160:163], v232 offset:4096
	v_exp_f32_e32 v24, v24
	v_mfma_f32_16x16x32_bf16 v[94:97], v[196:199], v[172:175], v[94:97]
	ds_read_b128 v[164:167], v232 offset:6144
	s_add_u32 m0, s8, 0xc000
	v_mfma_f32_16x16x32_bf16 v[98:101], v[184:187], v[176:179], v[98:101]
	global_load_lds_dwordx4 v200, s[4:5]
	s_add_u32 m0, s8, 0xc400
	v_mfma_f32_16x16x32_bf16 v[102:105], v[188:191], v[176:179], v[102:105]
	global_load_lds_dwordx4 v201, s[4:5]
	v_exp_f32_e32 v25, v25
	s_add_u32 m0, s8, 0xc800
	v_mfma_f32_16x16x32_bf16 v[106:109], v[192:195], v[176:179], v[106:109]
	global_load_lds_dwordx4 v202, s[4:5]
	s_add_u32 m0, s8, 0xcc00
	v_mfma_f32_16x16x32_bf16 v[110:113], v[196:199], v[176:179], v[110:113]
	global_load_lds_dwordx4 v203, s[4:5]
	v_add_f32_e32 v18, 1.0, v18
	s_add_u32 m0, s9, 0xc000
	v_mfma_f32_16x16x32_bf16 v[114:117], v[184:187], v[180:183], v[114:117]
	global_load_lds_dwordx4 v204, s[6:7]
	s_add_u32 m0, s9, 0xc400
	v_mfma_f32_16x16x32_bf16 v[118:121], v[188:191], v[180:183], v[118:121]
	global_load_lds_dwordx4 v205, s[6:7]
	v_add_f32_e32 v19, 1.0, v19
	v_mfma_f32_16x16x32_bf16 v[122:125], v[192:195], v[180:183], v[122:125]
	s_add_u32 s4, s4, 0x80
	s_addc_u32 s5, s5, 0
	v_mfma_f32_16x16x32_bf16 v[126:129], v[196:199], v[180:183], v[126:129]
	s_add_u32 s6, s6, 0x80
	s_addc_u32 s7, s7, 0
	v_add_f32_e32 v20, 1.0, v20
	s_waitcnt lgkmcnt(0)
	v_mfma_f32_16x16x32_bf16 v[66:69], v[152:155], v[136:139], v[66:69]
	ds_read_b128 v[168:171], v229 offset:0
	v_mfma_f32_16x16x32_bf16 v[70:73], v[156:159], v[136:139], v[70:73]
	ds_read_b128 v[172:175], v229 offset:2048
	v_add_f32_e32 v21, 1.0, v21
	v_mfma_f32_16x16x32_bf16 v[74:77], v[160:163], v[136:139], v[74:77]
	ds_read_b128 v[176:179], v229 offset:4096
	v_add_f32_e32 v22, 1.0, v22
	v_mfma_f32_16x16x32_bf16 v[78:81], v[164:167], v[136:139], v[78:81]
	ds_read_b128 v[180:183], v229 offset:6144
	v_add_f32_e32 v23, 1.0, v23
	v_mfma_f32_16x16x32_bf16 v[82:85], v[152:155], v[140:143], v[82:85]
	ds_read_b128 v[184:187], v235 offset:0
	v_mfma_f32_16x16x32_bf16 v[86:89], v[156:159], v[140:143], v[86:89]
	ds_read_b128 v[188:191], v235 offset:2048
	v_add_f32_e32 v24, 1.0, v24
	v_mfma_f32_16x16x32_bf16 v[90:93], v[160:163], v[140:143], v[90:93]
	ds_read_b128 v[192:195], v235 offset:4096
	v_add_f32_e32 v25, 1.0, v25
	v_mfma_f32_16x16x32_bf16 v[94:97], v[164:167], v[140:143], v[94:97]
	ds_read_b128 v[196:199], v235 offset:6144
	v_rcp_f32_e32 v18, v18
	v_mfma_f32_16x16x32_bf16 v[98:101], v[152:155], v[144:147], v[98:101]
	v_mfma_f32_16x16x32_bf16 v[102:105], v[156:159], v[144:147], v[102:105]
	v_rcp_f32_e32 v19, v19
	v_mfma_f32_16x16x32_bf16 v[106:109], v[160:163], v[144:147], v[106:109]
	v_rcp_f32_e32 v20, v20
	v_mfma_f32_16x16x32_bf16 v[110:113], v[164:167], v[144:147], v[110:113]
	v_rcp_f32_e32 v21, v21
	v_mfma_f32_16x16x32_bf16 v[114:117], v[152:155], v[148:151], v[114:117]
	v_mfma_f32_16x16x32_bf16 v[118:121], v[156:159], v[148:151], v[118:121]
	v_rcp_f32_e32 v22, v22
	v_mfma_f32_16x16x32_bf16 v[122:125], v[160:163], v[148:151], v[122:125]
	v_rcp_f32_e32 v23, v23
	v_mfma_f32_16x16x32_bf16 v[126:129], v[164:167], v[148:151], v[126:129]
	v_rcp_f32_e32 v24, v24
	s_waitcnt vmcnt(7) lgkmcnt(0)
	s_barrier
	v_mfma_f32_16x16x32_bf16 v[66:69], v[184:187], v[168:171], v[66:69]
	ds_read_b128 v[136:139], v218 offset:0
	v_mfma_f32_16x16x32_bf16 v[70:73], v[188:191], v[168:171], v[70:73]
	ds_read_b128 v[140:143], v218 offset:2048
	v_mfma_f32_16x16x32_bf16 v[74:77], v[192:195], v[168:171], v[74:77]
	ds_read_b128 v[144:147], v218 offset:4096
	v_rcp_f32_e32 v25, v25
	v_mfma_f32_16x16x32_bf16 v[78:81], v[196:199], v[168:171], v[78:81]
	ds_read_b128 v[148:151], v218 offset:6144
	v_mfma_f32_16x16x32_bf16 v[82:85], v[184:187], v[172:175], v[82:85]
	ds_read_b128 v[152:155], v230 offset:0
	v_cvt_pk_bf16_f32 v18, v18, v19
	v_mfma_f32_16x16x32_bf16 v[86:89], v[188:191], v[172:175], v[86:89]
	ds_read_b128 v[156:159], v230 offset:2048
	v_mfma_f32_16x16x32_bf16 v[90:93], v[192:195], v[172:175], v[90:93]
	ds_read_b128 v[160:163], v230 offset:4096
	v_cvt_pk_bf16_f32 v19, v20, v21
	v_mfma_f32_16x16x32_bf16 v[94:97], v[196:199], v[172:175], v[94:97]
	ds_read_b128 v[164:167], v230 offset:6144
	s_add_u32 m0, s8, 0x18000
	v_mfma_f32_16x16x32_bf16 v[98:101], v[184:187], v[176:179], v[98:101]
	global_load_lds_dwordx4 v200, s[4:5]
	s_add_u32 m0, s8, 0x18400
	v_mfma_f32_16x16x32_bf16 v[102:105], v[188:191], v[176:179], v[102:105]
	global_load_lds_dwordx4 v201, s[4:5]
	v_cvt_pk_bf16_f32 v20, v22, v23
	s_add_u32 m0, s8, 0x18800
	v_mfma_f32_16x16x32_bf16 v[106:109], v[192:195], v[176:179], v[106:109]
	global_load_lds_dwordx4 v202, s[4:5]
	s_add_u32 m0, s8, 0x18c00
	v_mfma_f32_16x16x32_bf16 v[110:113], v[196:199], v[176:179], v[110:113]
	global_load_lds_dwordx4 v203, s[4:5]
	v_cvt_pk_bf16_f32 v21, v24, v25
	s_add_u32 m0, s9, 0x18000
	v_mfma_f32_16x16x32_bf16 v[114:117], v[184:187], v[180:183], v[114:117]
	global_load_lds_dwordx4 v204, s[6:7]
	s_add_u32 m0, s9, 0x18400
	v_mfma_f32_16x16x32_bf16 v[118:121], v[188:191], v[180:183], v[118:121]
	global_load_lds_dwordx4 v205, s[6:7]
	global_store_dwordx4 v240, v[18:21], s[10:11] offset:2048
	v_mfma_f32_16x16x32_bf16 v[122:125], v[192:195], v[180:183], v[122:125]
	s_add_u32 s4, s4, 0x80
	s_addc_u32 s5, s5, 0
	v_mfma_f32_16x16x32_bf16 v[126:129], v[196:199], v[180:183], v[126:129]
	s_add_u32 s6, s6, 0x80
	s_addc_u32 s7, s7, 0
	v_mul_f32_e32 v26, s12, v26
	s_waitcnt lgkmcnt(0)
	v_mfma_f32_16x16x32_bf16 v[66:69], v[152:155], v[136:139], v[66:69]
	ds_read_b128 v[168:171], v225 offset:0
	v_mfma_f32_16x16x32_bf16 v[70:73], v[156:159], v[136:139], v[70:73]
	ds_read_b128 v[172:175], v225 offset:2048
	v_mul_f32_e32 v27, s12, v27
	v_mfma_f32_16x16x32_bf16 v[74:77], v[160:163], v[136:139], v[74:77]
	ds_read_b128 v[176:179], v225 offset:4096
	v_mul_f32_e32 v28, s12, v28
	v_mfma_f32_16x16x32_bf16 v[78:81], v[164:167], v[136:139], v[78:81]
	ds_read_b128 v[180:183], v225 offset:6144
	v_mul_f32_e32 v29, s12, v29
	v_mfma_f32_16x16x32_bf16 v[82:85], v[152:155], v[140:143], v[82:85]
	ds_read_b128 v[184:187], v233 offset:0
	v_mfma_f32_16x16x32_bf16 v[86:89], v[156:159], v[140:143], v[86:89]
	ds_read_b128 v[188:191], v233 offset:2048
	v_mul_f32_e32 v30, s12, v30
	v_mfma_f32_16x16x32_bf16 v[90:93], v[160:163], v[140:143], v[90:93]
	ds_read_b128 v[192:195], v233 offset:4096
	v_mul_f32_e32 v31, s12, v31
	v_mfma_f32_16x16x32_bf16 v[94:97], v[164:167], v[140:143], v[94:97]
	ds_read_b128 v[196:199], v233 offset:6144
	v_mul_f32_e32 v32, s12, v32
	v_mfma_f32_16x16x32_bf16 v[98:101], v[152:155], v[144:147], v[98:101]
	v_mfma_f32_16x16x32_bf16 v[102:105], v[156:159], v[144:147], v[102:105]
	v_mul_f32_e32 v33, s12, v33
	v_mfma_f32_16x16x32_bf16 v[106:109], v[160:163], v[144:147], v[106:109]
	v_exp_f32_e32 v26, v26
	v_mfma_f32_16x16x32_bf16 v[110:113], v[164:167], v[144:147], v[110:113]
	v_exp_f32_e32 v27, v27
	v_mfma_f32_16x16x32_bf16 v[114:117], v[152:155], v[148:151], v[114:117]
	v_mfma_f32_16x16x32_bf16 v[118:121], v[156:159], v[148:151], v[118:121]
	v_exp_f32_e32 v28, v28
	v_mfma_f32_16x16x32_bf16 v[122:125], v[160:163], v[148:151], v[122:125]
	v_exp_f32_e32 v29, v29
	v_mfma_f32_16x16x32_bf16 v[126:129], v[164:167], v[148:151], v[126:129]
	v_exp_f32_e32 v30, v30
	s_waitcnt vmcnt(7) lgkmcnt(0)
	s_barrier
	v_mfma_f32_16x16x32_bf16 v[66:69], v[184:187], v[168:171], v[66:69]
	ds_read_b128 v[136:139], v219 offset:0
	v_mfma_f32_16x16x32_bf16 v[70:73], v[188:191], v[168:171], v[70:73]
	ds_read_b128 v[140:143], v219 offset:2048
	v_mfma_f32_16x16x32_bf16 v[74:77], v[192:195], v[168:171], v[74:77]
	ds_read_b128 v[144:147], v219 offset:4096
	v_exp_f32_e32 v31, v31
	v_mfma_f32_16x16x32_bf16 v[78:81], v[196:199], v[168:171], v[78:81]
	ds_read_b128 v[148:151], v219 offset:6144
	v_mfma_f32_16x16x32_bf16 v[82:85], v[184:187], v[172:175], v[82:85]
	ds_read_b128 v[152:155], v231 offset:0
	v_exp_f32_e32 v32, v32
	v_mfma_f32_16x16x32_bf16 v[86:89], v[188:191], v[172:175], v[86:89]
	ds_read_b128 v[156:159], v231 offset:2048
	v_mfma_f32_16x16x32_bf16 v[90:93], v[192:195], v[172:175], v[90:93]
	ds_read_b128 v[160:163], v231 offset:4096
	v_exp_f32_e32 v33, v33
	v_mfma_f32_16x16x32_bf16 v[94:97], v[196:199], v[172:175], v[94:97]
	ds_read_b128 v[164:167], v231 offset:6144
	s_mov_b32 m0, s8
	v_mfma_f32_16x16x32_bf16 v[98:101], v[184:187], v[176:179], v[98:101]
	global_load_lds_dwordx4 v200, s[4:5]
	s_add_u32 m0, s8, 0x400
	v_mfma_f32_16x16x32_bf16 v[102:105], v[188:191], v[176:179], v[102:105]
	global_load_lds_dwordx4 v201, s[4:5]
	v_add_f32_e32 v26, 1.0, v26
	s_add_u32 m0, s8, 0x800
	v_mfma_f32_16x16x32_bf16 v[106:109], v[192:195], v[176:179], v[106:109]
	global_load_lds_dwordx4 v202, s[4:5]
	s_add_u32 m0, s8, 0xc00
	v_mfma_f32_16x16x32_bf16 v[110:113], v[196:199], v[176:179], v[110:113]
	global_load_lds_dwordx4 v203, s[4:5]
	v_add_f32_e32 v27, 1.0, v27
	s_mov_b32 m0, s9
	v_mfma_f32_16x16x32_bf16 v[114:117], v[184:187], v[180:183], v[114:117]
	global_load_lds_dwordx4 v204, s[6:7]
	s_add_u32 m0, s9, 0x400
	v_mfma_f32_16x16x32_bf16 v[118:121], v[188:191], v[180:183], v[118:121]
	global_load_lds_dwordx4 v205, s[6:7]
	v_add_f32_e32 v28, 1.0, v28
	v_mfma_f32_16x16x32_bf16 v[122:125], v[192:195], v[180:183], v[122:125]
	s_add_u32 s4, s4, 0x80
	s_addc_u32 s5, s5, 0
	v_mfma_f32_16x16x32_bf16 v[126:129], v[196:199], v[180:183], v[126:129]
	s_add_u32 s6, s6, 0x80
	s_addc_u32 s7, s7, 0
	v_add_f32_e32 v29, 1.0, v29
	s_waitcnt lgkmcnt(0)
	v_mfma_f32_16x16x32_bf16 v[66:69], v[152:155], v[136:139], v[66:69]
	ds_read_b128 v[168:171], v228 offset:0
	v_mfma_f32_16x16x32_bf16 v[70:73], v[156:159], v[136:139], v[70:73]
	ds_read_b128 v[172:175], v228 offset:2048
	v_add_f32_e32 v30, 1.0, v30
	v_mfma_f32_16x16x32_bf16 v[74:77], v[160:163], v[136:139], v[74:77]
	ds_read_b128 v[176:179], v228 offset:4096
	v_add_f32_e32 v31, 1.0, v31
	v_mfma_f32_16x16x32_bf16 v[78:81], v[164:167], v[136:139], v[78:81]
	ds_read_b128 v[180:183], v228 offset:6144
	v_add_f32_e32 v32, 1.0, v32
	v_mfma_f32_16x16x32_bf16 v[82:85], v[152:155], v[140:143], v[82:85]
	ds_read_b128 v[184:187], v234 offset:0
	v_mfma_f32_16x16x32_bf16 v[86:89], v[156:159], v[140:143], v[86:89]
	ds_read_b128 v[188:191], v234 offset:2048
	v_add_f32_e32 v33, 1.0, v33
	v_mfma_f32_16x16x32_bf16 v[90:93], v[160:163], v[140:143], v[90:93]
	ds_read_b128 v[192:195], v234 offset:4096
	v_rcp_f32_e32 v26, v26
	v_mfma_f32_16x16x32_bf16 v[94:97], v[164:167], v[140:143], v[94:97]
	ds_read_b128 v[196:199], v234 offset:6144
	v_rcp_f32_e32 v27, v27
	v_mfma_f32_16x16x32_bf16 v[98:101], v[152:155], v[144:147], v[98:101]
	v_mfma_f32_16x16x32_bf16 v[102:105], v[156:159], v[144:147], v[102:105]
	v_rcp_f32_e32 v28, v28
	v_mfma_f32_16x16x32_bf16 v[106:109], v[160:163], v[144:147], v[106:109]
	v_rcp_f32_e32 v29, v29
	v_mfma_f32_16x16x32_bf16 v[110:113], v[164:167], v[144:147], v[110:113]
	v_rcp_f32_e32 v30, v30
	v_mfma_f32_16x16x32_bf16 v[114:117], v[152:155], v[148:151], v[114:117]
	v_mfma_f32_16x16x32_bf16 v[118:121], v[156:159], v[148:151], v[118:121]
	v_rcp_f32_e32 v31, v31
	v_mfma_f32_16x16x32_bf16 v[122:125], v[160:163], v[148:151], v[122:125]
	v_rcp_f32_e32 v32, v32
	v_mfma_f32_16x16x32_bf16 v[126:129], v[164:167], v[148:151], v[126:129]
	v_rcp_f32_e32 v33, v33
	s_waitcnt vmcnt(7) lgkmcnt(0)
	s_barrier
	v_mfma_f32_16x16x32_bf16 v[66:69], v[184:187], v[168:171], v[66:69]
	ds_read_b128 v[136:139], v224 offset:0
	v_mfma_f32_16x16x32_bf16 v[70:73], v[188:191], v[168:171], v[70:73]
	ds_read_b128 v[140:143], v224 offset:2048
	v_mfma_f32_16x16x32_bf16 v[74:77], v[192:195], v[168:171], v[74:77]
	ds_read_b128 v[144:147], v224 offset:4096
	v_cvt_pk_bf16_f32 v26, v26, v27
	v_mfma_f32_16x16x32_bf16 v[78:81], v[196:199], v[168:171], v[78:81]
	ds_read_b128 v[148:151], v224 offset:6144
	v_mfma_f32_16x16x32_bf16 v[82:85], v[184:187], v[172:175], v[82:85]
	ds_read_b128 v[152:155], v232 offset:0
	v_cvt_pk_bf16_f32 v27, v28, v29
	v_mfma_f32_16x16x32_bf16 v[86:89], v[188:191], v[172:175], v[86:89]
	ds_read_b128 v[156:159], v232 offset:2048
	v_mfma_f32_16x16x32_bf16 v[90:93], v[192:195], v[172:175], v[90:93]
	ds_read_b128 v[160:163], v232 offset:4096
	v_cvt_pk_bf16_f32 v28, v30, v31
	v_mfma_f32_16x16x32_bf16 v[94:97], v[196:199], v[172:175], v[94:97]
	ds_read_b128 v[164:167], v232 offset:6144
	s_add_u32 m0, s8, 0xc000
	v_mfma_f32_16x16x32_bf16 v[98:101], v[184:187], v[176:179], v[98:101]
	global_load_lds_dwordx4 v200, s[4:5]
	s_add_u32 m0, s8, 0xc400
	v_mfma_f32_16x16x32_bf16 v[102:105], v[188:191], v[176:179], v[102:105]
	global_load_lds_dwordx4 v201, s[4:5]
	v_cvt_pk_bf16_f32 v29, v32, v33
	s_add_u32 m0, s8, 0xc800
	v_mfma_f32_16x16x32_bf16 v[106:109], v[192:195], v[176:179], v[106:109]
	global_load_lds_dwordx4 v202, s[4:5]
	s_add_u32 m0, s8, 0xcc00
	v_mfma_f32_16x16x32_bf16 v[110:113], v[196:199], v[176:179], v[110:113]
	global_load_lds_dwordx4 v203, s[4:5]
	global_store_dwordx4 v240, v[26:29], s[10:11] offset:3072
	s_add_u32 m0, s9, 0xc000
	v_mfma_f32_16x16x32_bf16 v[114:117], v[184:187], v[180:183], v[114:117]
	global_load_lds_dwordx4 v204, s[6:7]
	s_add_u32 m0, s9, 0xc400
	v_mfma_f32_16x16x32_bf16 v[118:121], v[188:191], v[180:183], v[118:121]
	global_load_lds_dwordx4 v205, s[6:7]
	v_mul_f32_e32 v34, s12, v34
	v_mfma_f32_16x16x32_bf16 v[122:125], v[192:195], v[180:183], v[122:125]
	s_add_u32 s4, s4, 0x80
	s_addc_u32 s5, s5, 0
	v_mfma_f32_16x16x32_bf16 v[126:129], v[196:199], v[180:183], v[126:129]
	s_add_u32 s6, s6, 0x80
	s_addc_u32 s7, s7, 0
	v_mul_f32_e32 v35, s12, v35
	s_waitcnt lgkmcnt(0)
	v_mfma_f32_16x16x32_bf16 v[66:69], v[152:155], v[136:139], v[66:69]
	ds_read_b128 v[168:171], v229 offset:0
	v_mfma_f32_16x16x32_bf16 v[70:73], v[156:159], v[136:139], v[70:73]
	ds_read_b128 v[172:175], v229 offset:2048
	v_mul_f32_e32 v36, s12, v36
	v_mfma_f32_16x16x32_bf16 v[74:77], v[160:163], v[136:139], v[74:77]
	ds_read_b128 v[176:179], v229 offset:4096
	v_mul_f32_e32 v37, s12, v37
	v_mfma_f32_16x16x32_bf16 v[78:81], v[164:167], v[136:139], v[78:81]
	ds_read_b128 v[180:183], v229 offset:6144
	v_mul_f32_e32 v38, s12, v38
	v_mfma_f32_16x16x32_bf16 v[82:85], v[152:155], v[140:143], v[82:85]
	ds_read_b128 v[184:187], v235 offset:0
	v_mfma_f32_16x16x32_bf16 v[86:89], v[156:159], v[140:143], v[86:89]
	ds_read_b128 v[188:191], v235 offset:2048
	v_mul_f32_e32 v39, s12, v39
	v_mfma_f32_16x16x32_bf16 v[90:93], v[160:163], v[140:143], v[90:93]
	ds_read_b128 v[192:195], v235 offset:4096
	v_mul_f32_e32 v40, s12, v40
	v_mfma_f32_16x16x32_bf16 v[94:97], v[164:167], v[140:143], v[94:97]
	ds_read_b128 v[196:199], v235 offset:6144
	v_mul_f32_e32 v41, s12, v41
	v_mfma_f32_16x16x32_bf16 v[98:101], v[152:155], v[144:147], v[98:101]
	v_mfma_f32_16x16x32_bf16 v[102:105], v[156:159], v[144:147], v[102:105]
	v_exp_f32_e32 v34, v34
	v_mfma_f32_16x16x32_bf16 v[106:109], v[160:163], v[144:147], v[106:109]
	v_exp_f32_e32 v35, v35
	v_mfma_f32_16x16x32_bf16 v[110:113], v[164:167], v[144:147], v[110:113]
	v_exp_f32_e32 v36, v36
	v_mfma_f32_16x16x32_bf16 v[114:117], v[152:155], v[148:151], v[114:117]
	v_mfma_f32_16x16x32_bf16 v[118:121], v[156:159], v[148:151], v[118:121]
	v_exp_f32_e32 v37, v37
	v_mfma_f32_16x16x32_bf16 v[122:125], v[160:163], v[148:151], v[122:125]
	v_exp_f32_e32 v38, v38
	v_mfma_f32_16x16x32_bf16 v[126:129], v[164:167], v[148:151], v[126:129]
	v_exp_f32_e32 v39, v39
	s_waitcnt vmcnt(7) lgkmcnt(0)
	s_barrier
	v_mfma_f32_16x16x32_bf16 v[66:69], v[184:187], v[168:171], v[66:69]
	ds_read_b128 v[136:139], v218 offset:0
	v_mfma_f32_16x16x32_bf16 v[70:73], v[188:191], v[168:171], v[70:73]
	ds_read_b128 v[140:143], v218 offset:2048
	v_mfma_f32_16x16x32_bf16 v[74:77], v[192:195], v[168:171], v[74:77]
	ds_read_b128 v[144:147], v218 offset:4096
	v_exp_f32_e32 v40, v40
	v_mfma_f32_16x16x32_bf16 v[78:81], v[196:199], v[168:171], v[78:81]
	ds_read_b128 v[148:151], v218 offset:6144
	v_mfma_f32_16x16x32_bf16 v[82:85], v[184:187], v[172:175], v[82:85]
	ds_read_b128 v[152:155], v230 offset:0
	v_exp_f32_e32 v41, v41
	v_mfma_f32_16x16x32_bf16 v[86:89], v[188:191], v[172:175], v[86:89]
	ds_read_b128 v[156:159], v230 offset:2048
	v_mfma_f32_16x16x32_bf16 v[90:93], v[192:195], v[172:175], v[90:93]
	ds_read_b128 v[160:163], v230 offset:4096
	v_add_f32_e32 v34, 1.0, v34
	v_mfma_f32_16x16x32_bf16 v[94:97], v[196:199], v[172:175], v[94:97]
	ds_read_b128 v[164:167], v230 offset:6144
	s_add_u32 m0, s8, 0x18000
	v_mfma_f32_16x16x32_bf16 v[98:101], v[184:187], v[176:179], v[98:101]
	global_load_lds_dwordx4 v200, s[4:5]
	s_add_u32 m0, s8, 0x18400
	v_mfma_f32_16x16x32_bf16 v[102:105], v[188:191], v[176:179], v[102:105]
	global_load_lds_dwordx4 v201, s[4:5]
	v_add_f32_e32 v35, 1.0, v35
	s_add_u32 m0, s8, 0x18800
	v_mfma_f32_16x16x32_bf16 v[106:109], v[192:195], v[176:179], v[106:109]
	global_load_lds_dwordx4 v202, s[4:5]
	s_add_u32 m0, s8, 0x18c00
	v_mfma_f32_16x16x32_bf16 v[110:113], v[196:199], v[176:179], v[110:113]
	global_load_lds_dwordx4 v203, s[4:5]
	v_add_f32_e32 v36, 1.0, v36
	s_add_u32 m0, s9, 0x18000
	v_mfma_f32_16x16x32_bf16 v[114:117], v[184:187], v[180:183], v[114:117]
	global_load_lds_dwordx4 v204, s[6:7]
	s_add_u32 m0, s9, 0x18400
	v_mfma_f32_16x16x32_bf16 v[118:121], v[188:191], v[180:183], v[118:121]
	global_load_lds_dwordx4 v205, s[6:7]
	v_add_f32_e32 v37, 1.0, v37
	v_mfma_f32_16x16x32_bf16 v[122:125], v[192:195], v[180:183], v[122:125]
	s_add_u32 s4, s4, 0x80
	s_addc_u32 s5, s5, 0
	v_mfma_f32_16x16x32_bf16 v[126:129], v[196:199], v[180:183], v[126:129]
	s_add_u32 s6, s6, 0x80
	s_addc_u32 s7, s7, 0
	v_add_f32_e32 v38, 1.0, v38
	s_waitcnt lgkmcnt(0)
	v_mfma_f32_16x16x32_bf16 v[66:69], v[152:155], v[136:139], v[66:69]
	ds_read_b128 v[168:171], v225 offset:0
	v_mfma_f32_16x16x32_bf16 v[70:73], v[156:159], v[136:139], v[70:73]
	ds_read_b128 v[172:175], v225 offset:2048
	v_add_f32_e32 v39, 1.0, v39
	v_mfma_f32_16x16x32_bf16 v[74:77], v[160:163], v[136:139], v[74:77]
	ds_read_b128 v[176:179], v225 offset:4096
	v_add_f32_e32 v40, 1.0, v40
	v_mfma_f32_16x16x32_bf16 v[78:81], v[164:167], v[136:139], v[78:81]
	ds_read_b128 v[180:183], v225 offset:6144
	v_add_f32_e32 v41, 1.0, v41
	v_mfma_f32_16x16x32_bf16 v[82:85], v[152:155], v[140:143], v[82:85]
	ds_read_b128 v[184:187], v233 offset:0
	v_mfma_f32_16x16x32_bf16 v[86:89], v[156:159], v[140:143], v[86:89]
	ds_read_b128 v[188:191], v233 offset:2048
	v_rcp_f32_e32 v34, v34
	v_mfma_f32_16x16x32_bf16 v[90:93], v[160:163], v[140:143], v[90:93]
	ds_read_b128 v[192:195], v233 offset:4096
	v_rcp_f32_e32 v35, v35
	v_mfma_f32_16x16x32_bf16 v[94:97], v[164:167], v[140:143], v[94:97]
	ds_read_b128 v[196:199], v233 offset:6144
	v_rcp_f32_e32 v36, v36
	v_mfma_f32_16x16x32_bf16 v[98:101], v[152:155], v[144:147], v[98:101]
	v_mfma_f32_16x16x32_bf16 v[102:105], v[156:159], v[144:147], v[102:105]
	v_rcp_f32_e32 v37, v37
	v_mfma_f32_16x16x32_bf16 v[106:109], v[160:163], v[144:147], v[106:109]
	v_rcp_f32_e32 v38, v38
	v_mfma_f32_16x16x32_bf16 v[110:113], v[164:167], v[144:147], v[110:113]
	v_rcp_f32_e32 v39, v39
	v_mfma_f32_16x16x32_bf16 v[114:117], v[152:155], v[148:151], v[114:117]
	v_mfma_f32_16x16x32_bf16 v[118:121], v[156:159], v[148:151], v[118:121]
	v_rcp_f32_e32 v40, v40
	v_mfma_f32_16x16x32_bf16 v[122:125], v[160:163], v[148:151], v[122:125]
	v_rcp_f32_e32 v41, v41
	v_mfma_f32_16x16x32_bf16 v[126:129], v[164:167], v[148:151], v[126:129]
	v_cvt_pk_bf16_f32 v34, v34, v35
	s_waitcnt vmcnt(6) lgkmcnt(0)
	s_barrier
	v_mfma_f32_16x16x32_bf16 v[66:69], v[184:187], v[168:171], v[66:69]
	ds_read_b128 v[136:139], v219 offset:0
	v_mfma_f32_16x16x32_bf16 v[70:73], v[188:191], v[168:171], v[70:73]
	ds_read_b128 v[140:143], v219 offset:2048
	v_mfma_f32_16x16x32_bf16 v[74:77], v[192:195], v[168:171], v[74:77]
	ds_read_b128 v[144:147], v219 offset:4096
	v_cvt_pk_bf16_f32 v35, v36, v37
	v_mfma_f32_16x16x32_bf16 v[78:81], v[196:199], v[168:171], v[78:81]
	ds_read_b128 v[148:151], v219 offset:6144
	v_mfma_f32_16x16x32_bf16 v[82:85], v[184:187], v[172:175], v[82:85]
	ds_read_b128 v[152:155], v231 offset:0
	v_cvt_pk_bf16_f32 v36, v38, v39
	v_mfma_f32_16x16x32_bf16 v[86:89], v[188:191], v[172:175], v[86:89]
	ds_read_b128 v[156:159], v231 offset:2048
	v_mfma_f32_16x16x32_bf16 v[90:93], v[192:195], v[172:175], v[90:93]
	ds_read_b128 v[160:163], v231 offset:4096
	v_cvt_pk_bf16_f32 v37, v40, v41
	v_mfma_f32_16x16x32_bf16 v[94:97], v[196:199], v[172:175], v[94:97]
	ds_read_b128 v[164:167], v231 offset:6144
	s_mov_b32 m0, s8
	v_mfma_f32_16x16x32_bf16 v[98:101], v[184:187], v[176:179], v[98:101]
	global_load_lds_dwordx4 v200, s[4:5]
	s_add_u32 m0, s8, 0x400
	v_mfma_f32_16x16x32_bf16 v[102:105], v[188:191], v[176:179], v[102:105]
	global_load_lds_dwordx4 v201, s[4:5]
	global_store_dwordx4 v241, v[34:37], s[10:11] offset:0
	s_add_u32 m0, s8, 0x800
	v_mfma_f32_16x16x32_bf16 v[106:109], v[192:195], v[176:179], v[106:109]
	global_load_lds_dwordx4 v202, s[4:5]
	s_add_u32 m0, s8, 0xc00
	v_mfma_f32_16x16x32_bf16 v[110:113], v[196:199], v[176:179], v[110:113]
	global_load_lds_dwordx4 v203, s[4:5]
	v_mul_f32_e32 v42, s12, v42
	s_mov_b32 m0, s9
	v_mfma_f32_16x16x32_bf16 v[114:117], v[184:187], v[180:183], v[114:117]
	global_load_lds_dwordx4 v204, s[6:7]
	s_add_u32 m0, s9, 0x400
	v_mfma_f32_16x16x32_bf16 v[118:121], v[188:191], v[180:183], v[118:121]
	global_load_lds_dwordx4 v205, s[6:7]
	v_mul_f32_e32 v43, s12, v43
	v_mfma_f32_16x16x32_bf16 v[122:125], v[192:195], v[180:183], v[122:125]
	s_add_u32 s4, s4, 0x80
	s_addc_u32 s5, s5, 0
	v_mfma_f32_16x16x32_bf16 v[126:129], v[196:199], v[180:183], v[126:129]
	s_add_u32 s6, s6, 0x80
	s_addc_u32 s7, s7, 0
	v_mul_f32_e32 v44, s12, v44
	s_waitcnt lgkmcnt(0)
	v_mfma_f32_16x16x32_bf16 v[66:69], v[152:155], v[136:139], v[66:69]
	ds_read_b128 v[168:171], v228 offset:0
	v_mfma_f32_16x16x32_bf16 v[70:73], v[156:159], v[136:139], v[70:73]
	ds_read_b128 v[172:175], v228 offset:2048
	v_mul_f32_e32 v45, s12, v45
	v_mfma_f32_16x16x32_bf16 v[74:77], v[160:163], v[136:139], v[74:77]
	ds_read_b128 v[176:179], v228 offset:4096
	v_mul_f32_e32 v46, s12, v46
	v_mfma_f32_16x16x32_bf16 v[78:81], v[164:167], v[136:139], v[78:81]
	ds_read_b128 v[180:183], v228 offset:6144
	v_mul_f32_e32 v47, s12, v47
	v_mfma_f32_16x16x32_bf16 v[82:85], v[152:155], v[140:143], v[82:85]
	ds_read_b128 v[184:187], v234 offset:0
	v_mfma_f32_16x16x32_bf16 v[86:89], v[156:159], v[140:143], v[86:89]
	ds_read_b128 v[188:191], v234 offset:2048
	v_mul_f32_e32 v48, s12, v48
	v_mfma_f32_16x16x32_bf16 v[90:93], v[160:163], v[140:143], v[90:93]
	ds_read_b128 v[192:195], v234 offset:4096
	v_mul_f32_e32 v49, s12, v49
	v_mfma_f32_16x16x32_bf16 v[94:97], v[164:167], v[140:143], v[94:97]
	ds_read_b128 v[196:199], v234 offset:6144
	v_exp_f32_e32 v42, v42
	v_mfma_f32_16x16x32_bf16 v[98:101], v[152:155], v[144:147], v[98:101]
	v_mfma_f32_16x16x32_bf16 v[102:105], v[156:159], v[144:147], v[102:105]
	v_exp_f32_e32 v43, v43
	v_mfma_f32_16x16x32_bf16 v[106:109], v[160:163], v[144:147], v[106:109]
	v_exp_f32_e32 v44, v44
	v_mfma_f32_16x16x32_bf16 v[110:113], v[164:167], v[144:147], v[110:113]
	v_exp_f32_e32 v45, v45
	v_mfma_f32_16x16x32_bf16 v[114:117], v[152:155], v[148:151], v[114:117]
	v_mfma_f32_16x16x32_bf16 v[118:121], v[156:159], v[148:151], v[118:121]
	v_exp_f32_e32 v46, v46
	v_mfma_f32_16x16x32_bf16 v[122:125], v[160:163], v[148:151], v[122:125]
	v_exp_f32_e32 v47, v47
	v_mfma_f32_16x16x32_bf16 v[126:129], v[164:167], v[148:151], v[126:129]
	v_exp_f32_e32 v48, v48
	s_waitcnt vmcnt(7) lgkmcnt(0)
	s_barrier
	v_mfma_f32_16x16x32_bf16 v[66:69], v[184:187], v[168:171], v[66:69]
	ds_read_b128 v[136:139], v224 offset:0
	v_mfma_f32_16x16x32_bf16 v[70:73], v[188:191], v[168:171], v[70:73]
	ds_read_b128 v[140:143], v224 offset:2048
	v_mfma_f32_16x16x32_bf16 v[74:77], v[192:195], v[168:171], v[74:77]
	ds_read_b128 v[144:147], v224 offset:4096
	v_exp_f32_e32 v49, v49
	v_mfma_f32_16x16x32_bf16 v[78:81], v[196:199], v[168:171], v[78:81]
	ds_read_b128 v[148:151], v224 offset:6144
	v_mfma_f32_16x16x32_bf16 v[82:85], v[184:187], v[172:175], v[82:85]
	ds_read_b128 v[152:155], v232 offset:0
	v_add_f32_e32 v42, 1.0, v42
	v_mfma_f32_16x16x32_bf16 v[86:89], v[188:191], v[172:175], v[86:89]
	ds_read_b128 v[156:159], v232 offset:2048
	v_mfma_f32_16x16x32_bf16 v[90:93], v[192:195], v[172:175], v[90:93]
	ds_read_b128 v[160:163], v232 offset:4096
	v_add_f32_e32 v43, 1.0, v43
	v_mfma_f32_16x16x32_bf16 v[94:97], v[196:199], v[172:175], v[94:97]
	ds_read_b128 v[164:167], v232 offset:6144
	s_add_u32 m0, s8, 0xc000
	v_mfma_f32_16x16x32_bf16 v[98:101], v[184:187], v[176:179], v[98:101]
	global_load_lds_dwordx4 v200, s[4:5]
	s_add_u32 m0, s8, 0xc400
	v_mfma_f32_16x16x32_bf16 v[102:105], v[188:191], v[176:179], v[102:105]
	global_load_lds_dwordx4 v201, s[4:5]
	v_add_f32_e32 v44, 1.0, v44
	s_add_u32 m0, s8, 0xc800
	v_mfma_f32_16x16x32_bf16 v[106:109], v[192:195], v[176:179], v[106:109]
	global_load_lds_dwordx4 v202, s[4:5]
	s_add_u32 m0, s8, 0xcc00
	v_mfma_f32_16x16x32_bf16 v[110:113], v[196:199], v[176:179], v[110:113]
	global_load_lds_dwordx4 v203, s[4:5]
	v_add_f32_e32 v45, 1.0, v45
	s_add_u32 m0, s9, 0xc000
	v_mfma_f32_16x16x32_bf16 v[114:117], v[184:187], v[180:183], v[114:117]
	global_load_lds_dwordx4 v204, s[6:7]
	s_add_u32 m0, s9, 0xc400
	v_mfma_f32_16x16x32_bf16 v[118:121], v[188:191], v[180:183], v[118:121]
	global_load_lds_dwordx4 v205, s[6:7]
	v_add_f32_e32 v46, 1.0, v46
	v_mfma_f32_16x16x32_bf16 v[122:125], v[192:195], v[180:183], v[122:125]
	s_add_u32 s4, s4, 0x80
	s_addc_u32 s5, s5, 0
	v_mfma_f32_16x16x32_bf16 v[126:129], v[196:199], v[180:183], v[126:129]
	s_add_u32 s6, s6, 0x80
	s_addc_u32 s7, s7, 0
	v_add_f32_e32 v47, 1.0, v47
	s_waitcnt lgkmcnt(0)
	v_mfma_f32_16x16x32_bf16 v[66:69], v[152:155], v[136:139], v[66:69]
	ds_read_b128 v[168:171], v229 offset:0
	v_mfma_f32_16x16x32_bf16 v[70:73], v[156:159], v[136:139], v[70:73]
	ds_read_b128 v[172:175], v229 offset:2048
	v_add_f32_e32 v48, 1.0, v48
	v_mfma_f32_16x16x32_bf16 v[74:77], v[160:163], v[136:139], v[74:77]
	ds_read_b128 v[176:179], v229 offset:4096
	v_add_f32_e32 v49, 1.0, v49
	v_mfma_f32_16x16x32_bf16 v[78:81], v[164:167], v[136:139], v[78:81]
	ds_read_b128 v[180:183], v229 offset:6144
	v_rcp_f32_e32 v42, v42
	v_mfma_f32_16x16x32_bf16 v[82:85], v[152:155], v[140:143], v[82:85]
	ds_read_b128 v[184:187], v235 offset:0
	v_mfma_f32_16x16x32_bf16 v[86:89], v[156:159], v[140:143], v[86:89]
	ds_read_b128 v[188:191], v235 offset:2048
	v_rcp_f32_e32 v43, v43
	v_mfma_f32_16x16x32_bf16 v[90:93], v[160:163], v[140:143], v[90:93]
	ds_read_b128 v[192:195], v235 offset:4096
	v_rcp_f32_e32 v44, v44
	v_mfma_f32_16x16x32_bf16 v[94:97], v[164:167], v[140:143], v[94:97]
	ds_read_b128 v[196:199], v235 offset:6144
	v_rcp_f32_e32 v45, v45
	v_mfma_f32_16x16x32_bf16 v[98:101], v[152:155], v[144:147], v[98:101]
	v_mfma_f32_16x16x32_bf16 v[102:105], v[156:159], v[144:147], v[102:105]
	v_rcp_f32_e32 v46, v46
	v_mfma_f32_16x16x32_bf16 v[106:109], v[160:163], v[144:147], v[106:109]
	v_rcp_f32_e32 v47, v47
	v_mfma_f32_16x16x32_bf16 v[110:113], v[164:167], v[144:147], v[110:113]
	v_rcp_f32_e32 v48, v48
	v_mfma_f32_16x16x32_bf16 v[114:117], v[152:155], v[148:151], v[114:117]
	v_mfma_f32_16x16x32_bf16 v[118:121], v[156:159], v[148:151], v[118:121]
	v_rcp_f32_e32 v49, v49
	v_mfma_f32_16x16x32_bf16 v[122:125], v[160:163], v[148:151], v[122:125]
	v_cvt_pk_bf16_f32 v42, v42, v43
	v_mfma_f32_16x16x32_bf16 v[126:129], v[164:167], v[148:151], v[126:129]
	v_cvt_pk_bf16_f32 v43, v44, v45
	s_waitcnt vmcnt(6) lgkmcnt(0)
	s_barrier
	v_mfma_f32_16x16x32_bf16 v[66:69], v[184:187], v[168:171], v[66:69]
	ds_read_b128 v[136:139], v218 offset:0
	v_mfma_f32_16x16x32_bf16 v[70:73], v[188:191], v[168:171], v[70:73]
	ds_read_b128 v[140:143], v218 offset:2048
	v_mfma_f32_16x16x32_bf16 v[74:77], v[192:195], v[168:171], v[74:77]
	ds_read_b128 v[144:147], v218 offset:4096
	v_cvt_pk_bf16_f32 v44, v46, v47
	v_mfma_f32_16x16x32_bf16 v[78:81], v[196:199], v[168:171], v[78:81]
	ds_read_b128 v[148:151], v218 offset:6144
	v_mfma_f32_16x16x32_bf16 v[82:85], v[184:187], v[172:175], v[82:85]
	ds_read_b128 v[152:155], v230 offset:0
	v_cvt_pk_bf16_f32 v45, v48, v49
	v_mfma_f32_16x16x32_bf16 v[86:89], v[188:191], v[172:175], v[86:89]
	ds_read_b128 v[156:159], v230 offset:2048
	v_mfma_f32_16x16x32_bf16 v[90:93], v[192:195], v[172:175], v[90:93]
	ds_read_b128 v[160:163], v230 offset:4096
	global_store_dwordx4 v241, v[42:45], s[10:11] offset:1024
	v_mfma_f32_16x16x32_bf16 v[94:97], v[196:199], v[172:175], v[94:97]
	ds_read_b128 v[164:167], v230 offset:6144
	s_add_u32 m0, s8, 0x18000
	v_mfma_f32_16x16x32_bf16 v[98:101], v[184:187], v[176:179], v[98:101]
	global_load_lds_dwordx4 v200, s[4:5]
	s_add_u32 m0, s8, 0x18400
	v_mfma_f32_16x16x32_bf16 v[102:105], v[188:191], v[176:179], v[102:105]
	global_load_lds_dwordx4 v201, s[4:5]
	v_mul_f32_e32 v50, s12, v50
	s_add_u32 m0, s8, 0x18800
	v_mfma_f32_16x16x32_bf16 v[106:109], v[192:195], v[176:179], v[106:109]
	global_load_lds_dwordx4 v202, s[4:5]
	s_add_u32 m0, s8, 0x18c00
	v_mfma_f32_16x16x32_bf16 v[110:113], v[196:199], v[176:179], v[110:113]
	global_load_lds_dwordx4 v203, s[4:5]
	v_mul_f32_e32 v51, s12, v51
	s_add_u32 m0, s9, 0x18000
	v_mfma_f32_16x16x32_bf16 v[114:117], v[184:187], v[180:183], v[114:117]
	global_load_lds_dwordx4 v204, s[6:7]
	s_add_u32 m0, s9, 0x18400
	v_mfma_f32_16x16x32_bf16 v[118:121], v[188:191], v[180:183], v[118:121]
	global_load_lds_dwordx4 v205, s[6:7]
	v_mul_f32_e32 v52, s12, v52
	v_mfma_f32_16x16x32_bf16 v[122:125], v[192:195], v[180:183], v[122:125]
	s_add_u32 s4, s4, 0x80
	s_addc_u32 s5, s5, 0
	v_mfma_f32_16x16x32_bf16 v[126:129], v[196:199], v[180:183], v[126:129]
	s_add_u32 s6, s6, 0x80
	s_addc_u32 s7, s7, 0
	v_mul_f32_e32 v53, s12, v53
	s_waitcnt lgkmcnt(0)
	v_mfma_f32_16x16x32_bf16 v[66:69], v[152:155], v[136:139], v[66:69]
	ds_read_b128 v[168:171], v225 offset:0
	v_mfma_f32_16x16x32_bf16 v[70:73], v[156:159], v[136:139], v[70:73]
	ds_read_b128 v[172:175], v225 offset:2048
	v_mul_f32_e32 v54, s12, v54
	v_mfma_f32_16x16x32_bf16 v[74:77], v[160:163], v[136:139], v[74:77]
	ds_read_b128 v[176:179], v225 offset:4096
	v_mul_f32_e32 v55, s12, v55
	v_mfma_f32_16x16x32_bf16 v[78:81], v[164:167], v[136:139], v[78:81]
	ds_read_b128 v[180:183], v225 offset:6144
	v_mul_f32_e32 v56, s12, v56
	v_mfma_f32_16x16x32_bf16 v[82:85], v[152:155], v[140:143], v[82:85]
	ds_read_b128 v[184:187], v233 offset:0
	v_mfma_f32_16x16x32_bf16 v[86:89], v[156:159], v[140:143], v[86:89]
	ds_read_b128 v[188:191], v233 offset:2048
	v_mul_f32_e32 v57, s12, v57
	v_mfma_f32_16x16x32_bf16 v[90:93], v[160:163], v[140:143], v[90:93]
	ds_read_b128 v[192:195], v233 offset:4096
	v_exp_f32_e32 v50, v50
	v_mfma_f32_16x16x32_bf16 v[94:97], v[164:167], v[140:143], v[94:97]
	ds_read_b128 v[196:199], v233 offset:6144
	v_exp_f32_e32 v51, v51
	v_mfma_f32_16x16x32_bf16 v[98:101], v[152:155], v[144:147], v[98:101]
	v_mfma_f32_16x16x32_bf16 v[102:105], v[156:159], v[144:147], v[102:105]
	v_exp_f32_e32 v52, v52
	v_mfma_f32_16x16x32_bf16 v[106:109], v[160:163], v[144:147], v[106:109]
	v_exp_f32_e32 v53, v53
	v_mfma_f32_16x16x32_bf16 v[110:113], v[164:167], v[144:147], v[110:113]
	v_exp_f32_e32 v54, v54
	v_mfma_f32_16x16x32_bf16 v[114:117], v[152:155], v[148:151], v[114:117]
	v_mfma_f32_16x16x32_bf16 v[118:121], v[156:159], v[148:151], v[118:121]
	v_exp_f32_e32 v55, v55
	v_mfma_f32_16x16x32_bf16 v[122:125], v[160:163], v[148:151], v[122:125]
	v_exp_f32_e32 v56, v56
	v_mfma_f32_16x16x32_bf16 v[126:129], v[164:167], v[148:151], v[126:129]
	v_exp_f32_e32 v57, v57
	s_waitcnt vmcnt(7) lgkmcnt(0)
	s_barrier
	v_mfma_f32_16x16x32_bf16 v[66:69], v[184:187], v[168:171], v[66:69]
	ds_read_b128 v[136:139], v219 offset:0
	v_mfma_f32_16x16x32_bf16 v[70:73], v[188:191], v[168:171], v[70:73]
	ds_read_b128 v[140:143], v219 offset:2048
	v_mfma_f32_16x16x32_bf16 v[74:77], v[192:195], v[168:171], v[74:77]
	ds_read_b128 v[144:147], v219 offset:4096
	v_add_f32_e32 v50, 1.0, v50
	v_mfma_f32_16x16x32_bf16 v[78:81], v[196:199], v[168:171], v[78:81]
	ds_read_b128 v[148:151], v219 offset:6144
	v_mfma_f32_16x16x32_bf16 v[82:85], v[184:187], v[172:175], v[82:85]
	ds_read_b128 v[152:155], v231 offset:0
	v_add_f32_e32 v51, 1.0, v51
	v_mfma_f32_16x16x32_bf16 v[86:89], v[188:191], v[172:175], v[86:89]
	ds_read_b128 v[156:159], v231 offset:2048
	v_mfma_f32_16x16x32_bf16 v[90:93], v[192:195], v[172:175], v[90:93]
	ds_read_b128 v[160:163], v231 offset:4096
	v_add_f32_e32 v52, 1.0, v52
	v_mfma_f32_16x16x32_bf16 v[94:97], v[196:199], v[172:175], v[94:97]
	ds_read_b128 v[164:167], v231 offset:6144
	s_mov_b32 m0, s8
	v_mfma_f32_16x16x32_bf16 v[98:101], v[184:187], v[176:179], v[98:101]
	global_load_lds_dwordx4 v200, s[4:5]
	s_add_u32 m0, s8, 0x400
	v_mfma_f32_16x16x32_bf16 v[102:105], v[188:191], v[176:179], v[102:105]
	global_load_lds_dwordx4 v201, s[4:5]
	v_add_f32_e32 v53, 1.0, v53
	s_add_u32 m0, s8, 0x800
	v_mfma_f32_16x16x32_bf16 v[106:109], v[192:195], v[176:179], v[106:109]
	global_load_lds_dwordx4 v202, s[4:5]
	s_add_u32 m0, s8, 0xc00
	v_mfma_f32_16x16x32_bf16 v[110:113], v[196:199], v[176:179], v[110:113]
	global_load_lds_dwordx4 v203, s[4:5]
	v_add_f32_e32 v54, 1.0, v54
	s_mov_b32 m0, s9
	v_mfma_f32_16x16x32_bf16 v[114:117], v[184:187], v[180:183], v[114:117]
	global_load_lds_dwordx4 v204, s[6:7]
	s_add_u32 m0, s9, 0x400
	v_mfma_f32_16x16x32_bf16 v[118:121], v[188:191], v[180:183], v[118:121]
	global_load_lds_dwordx4 v205, s[6:7]
	v_add_f32_e32 v55, 1.0, v55
	v_mfma_f32_16x16x32_bf16 v[122:125], v[192:195], v[180:183], v[122:125]
	s_sub_u32 s4, s4, 0x780
	s_subb_u32 s5, s5, 0
	v_mfma_f32_16x16x32_bf16 v[126:129], v[196:199], v[180:183], v[126:129]
	s_add_u32 s6, s6, 0x3f880
	s_addc_u32 s7, s7, 0
	v_add_f32_e32 v56, 1.0, v56
	s_waitcnt lgkmcnt(0)
	v_mfma_f32_16x16x32_bf16 v[66:69], v[152:155], v[136:139], v[66:69]
	ds_read_b128 v[168:171], v228 offset:0
	v_mfma_f32_16x16x32_bf16 v[70:73], v[156:159], v[136:139], v[70:73]
	ds_read_b128 v[172:175], v228 offset:2048
	v_add_f32_e32 v57, 1.0, v57
	v_mfma_f32_16x16x32_bf16 v[74:77], v[160:163], v[136:139], v[74:77]
	ds_read_b128 v[176:179], v228 offset:4096
	v_rcp_f32_e32 v50, v50
	v_mfma_f32_16x16x32_bf16 v[78:81], v[164:167], v[136:139], v[78:81]
	ds_read_b128 v[180:183], v228 offset:6144
	v_rcp_f32_e32 v51, v51
	v_mfma_f32_16x16x32_bf16 v[82:85], v[152:155], v[140:143], v[82:85]
	ds_read_b128 v[184:187], v234 offset:0
	v_mfma_f32_16x16x32_bf16 v[86:89], v[156:159], v[140:143], v[86:89]
	ds_read_b128 v[188:191], v234 offset:2048
	v_rcp_f32_e32 v52, v52
	v_mfma_f32_16x16x32_bf16 v[90:93], v[160:163], v[140:143], v[90:93]
	ds_read_b128 v[192:195], v234 offset:4096
	v_rcp_f32_e32 v53, v53
	v_mfma_f32_16x16x32_bf16 v[94:97], v[164:167], v[140:143], v[94:97]
	ds_read_b128 v[196:199], v234 offset:6144
	v_rcp_f32_e32 v54, v54
	v_mfma_f32_16x16x32_bf16 v[98:101], v[152:155], v[144:147], v[98:101]
	v_mfma_f32_16x16x32_bf16 v[102:105], v[156:159], v[144:147], v[102:105]
	v_rcp_f32_e32 v55, v55
	v_mfma_f32_16x16x32_bf16 v[106:109], v[160:163], v[144:147], v[106:109]
	v_rcp_f32_e32 v56, v56
	v_mfma_f32_16x16x32_bf16 v[110:113], v[164:167], v[144:147], v[110:113]
	v_rcp_f32_e32 v57, v57
	v_mfma_f32_16x16x32_bf16 v[114:117], v[152:155], v[148:151], v[114:117]
	v_mfma_f32_16x16x32_bf16 v[118:121], v[156:159], v[148:151], v[118:121]
	v_cvt_pk_bf16_f32 v50, v50, v51
	v_mfma_f32_16x16x32_bf16 v[122:125], v[160:163], v[148:151], v[122:125]
	v_cvt_pk_bf16_f32 v51, v52, v53
	v_mfma_f32_16x16x32_bf16 v[126:129], v[164:167], v[148:151], v[126:129]
	v_cvt_pk_bf16_f32 v52, v54, v55
	s_waitcnt vmcnt(6) lgkmcnt(0)
	s_barrier
	v_mfma_f32_16x16x32_bf16 v[66:69], v[184:187], v[168:171], v[66:69]
	ds_read_b128 v[136:139], v224 offset:0
	v_mfma_f32_16x16x32_bf16 v[70:73], v[188:191], v[168:171], v[70:73]
	ds_read_b128 v[140:143], v224 offset:2048
	v_mfma_f32_16x16x32_bf16 v[74:77], v[192:195], v[168:171], v[74:77]
	ds_read_b128 v[144:147], v224 offset:4096
	v_cvt_pk_bf16_f32 v53, v56, v57
	v_mfma_f32_16x16x32_bf16 v[78:81], v[196:199], v[168:171], v[78:81]
	ds_read_b128 v[148:151], v224 offset:6144
	v_mfma_f32_16x16x32_bf16 v[82:85], v[184:187], v[172:175], v[82:85]
	ds_read_b128 v[152:155], v232 offset:0
	global_store_dwordx4 v241, v[50:53], s[10:11] offset:2048
	v_mfma_f32_16x16x32_bf16 v[86:89], v[188:191], v[172:175], v[86:89]
	ds_read_b128 v[156:159], v232 offset:2048
	v_mfma_f32_16x16x32_bf16 v[90:93], v[192:195], v[172:175], v[90:93]
	ds_read_b128 v[160:163], v232 offset:4096
	v_mul_f32_e32 v58, s12, v58
	v_mfma_f32_16x16x32_bf16 v[94:97], v[196:199], v[172:175], v[94:97]
	ds_read_b128 v[164:167], v232 offset:6144
	v_mfma_f32_16x16x32_bf16 v[98:101], v[184:187], v[176:179], v[98:101]
	v_mfma_f32_16x16x32_bf16 v[102:105], v[188:191], v[176:179], v[102:105]
	v_mul_f32_e32 v59, s12, v59
	v_mfma_f32_16x16x32_bf16 v[106:109], v[192:195], v[176:179], v[106:109]
	v_mfma_f32_16x16x32_bf16 v[110:113], v[196:199], v[176:179], v[110:113]
	v_mul_f32_e32 v60, s12, v60
	v_mfma_f32_16x16x32_bf16 v[114:117], v[184:187], v[180:183], v[114:117]
	v_mfma_f32_16x16x32_bf16 v[118:121], v[188:191], v[180:183], v[118:121]
	v_mul_f32_e32 v61, s12, v61
	v_mfma_f32_16x16x32_bf16 v[122:125], v[192:195], v[180:183], v[122:125]
	v_mfma_f32_16x16x32_bf16 v[126:129], v[196:199], v[180:183], v[126:129]
	v_mul_f32_e32 v62, s12, v62
	s_waitcnt lgkmcnt(0)
	v_mfma_f32_16x16x32_bf16 v[66:69], v[152:155], v[136:139], v[66:69]
	ds_read_b128 v[168:171], v229 offset:0
	v_mfma_f32_16x16x32_bf16 v[70:73], v[156:159], v[136:139], v[70:73]
	ds_read_b128 v[172:175], v229 offset:2048
	v_mul_f32_e32 v63, s12, v63
	v_mfma_f32_16x16x32_bf16 v[74:77], v[160:163], v[136:139], v[74:77]
	ds_read_b128 v[176:179], v229 offset:4096
	v_mul_f32_e32 v64, s12, v64
	v_mfma_f32_16x16x32_bf16 v[78:81], v[164:167], v[136:139], v[78:81]
	ds_read_b128 v[180:183], v229 offset:6144
	v_mul_f32_e32 v65, s12, v65
	v_mfma_f32_16x16x32_bf16 v[82:85], v[152:155], v[140:143], v[82:85]
	ds_read_b128 v[184:187], v235 offset:0
	v_mfma_f32_16x16x32_bf16 v[86:89], v[156:159], v[140:143], v[86:89]
	ds_read_b128 v[188:191], v235 offset:2048
	v_exp_f32_e32 v58, v58
	v_mfma_f32_16x16x32_bf16 v[90:93], v[160:163], v[140:143], v[90:93]
	ds_read_b128 v[192:195], v235 offset:4096
	v_exp_f32_e32 v59, v59
	v_mfma_f32_16x16x32_bf16 v[94:97], v[164:167], v[140:143], v[94:97]
	ds_read_b128 v[196:199], v235 offset:6144
	v_exp_f32_e32 v60, v60
	v_mfma_f32_16x16x32_bf16 v[98:101], v[152:155], v[144:147], v[98:101]
	v_mfma_f32_16x16x32_bf16 v[102:105], v[156:159], v[144:147], v[102:105]
	v_exp_f32_e32 v61, v61
	v_mfma_f32_16x16x32_bf16 v[106:109], v[160:163], v[144:147], v[106:109]
	v_exp_f32_e32 v62, v62
	v_mfma_f32_16x16x32_bf16 v[110:113], v[164:167], v[144:147], v[110:113]
	v_exp_f32_e32 v63, v63
	v_mfma_f32_16x16x32_bf16 v[114:117], v[152:155], v[148:151], v[114:117]
	v_mfma_f32_16x16x32_bf16 v[118:121], v[156:159], v[148:151], v[118:121]
	v_exp_f32_e32 v64, v64
	v_mfma_f32_16x16x32_bf16 v[122:125], v[160:163], v[148:151], v[122:125]
	v_exp_f32_e32 v65, v65
	v_mfma_f32_16x16x32_bf16 v[126:129], v[164:167], v[148:151], v[126:129]
	v_add_f32_e32 v58, 1.0, v58
	s_waitcnt vmcnt(1) lgkmcnt(0)
	s_barrier
	v_mfma_f32_16x16x32_bf16 v[66:69], v[184:187], v[168:171], v[66:69]
	ds_read_b128 v[136:139], v218 offset:0
	v_mfma_f32_16x16x32_bf16 v[70:73], v[188:191], v[168:171], v[70:73]
	ds_read_b128 v[140:143], v218 offset:2048
	v_mfma_f32_16x16x32_bf16 v[74:77], v[192:195], v[168:171], v[74:77]
	ds_read_b128 v[144:147], v218 offset:4096
	v_add_f32_e32 v59, 1.0, v59
	v_mfma_f32_16x16x32_bf16 v[78:81], v[196:199], v[168:171], v[78:81]
	ds_read_b128 v[148:151], v218 offset:6144
	v_mfma_f32_16x16x32_bf16 v[82:85], v[184:187], v[172:175], v[82:85]
	ds_read_b128 v[152:155], v230 offset:0
	v_add_f32_e32 v60, 1.0, v60
	v_mfma_f32_16x16x32_bf16 v[86:89], v[188:191], v[172:175], v[86:89]
	ds_read_b128 v[156:159], v230 offset:2048
	v_mfma_f32_16x16x32_bf16 v[90:93], v[192:195], v[172:175], v[90:93]
	ds_read_b128 v[160:163], v230 offset:4096
	v_add_f32_e32 v61, 1.0, v61
	v_mfma_f32_16x16x32_bf16 v[94:97], v[196:199], v[172:175], v[94:97]
	ds_read_b128 v[164:167], v230 offset:6144
	v_mfma_f32_16x16x32_bf16 v[98:101], v[184:187], v[176:179], v[98:101]
	v_mfma_f32_16x16x32_bf16 v[102:105], v[188:191], v[176:179], v[102:105]
	v_add_f32_e32 v62, 1.0, v62
	v_mfma_f32_16x16x32_bf16 v[106:109], v[192:195], v[176:179], v[106:109]
	v_mfma_f32_16x16x32_bf16 v[110:113], v[196:199], v[176:179], v[110:113]
	v_add_f32_e32 v63, 1.0, v63
	v_mfma_f32_16x16x32_bf16 v[114:117], v[184:187], v[180:183], v[114:117]
	v_mfma_f32_16x16x32_bf16 v[118:121], v[188:191], v[180:183], v[118:121]
	v_add_f32_e32 v64, 1.0, v64
	v_mfma_f32_16x16x32_bf16 v[122:125], v[192:195], v[180:183], v[122:125]
	v_mfma_f32_16x16x32_bf16 v[126:129], v[196:199], v[180:183], v[126:129]
	v_add_f32_e32 v65, 1.0, v65
	s_waitcnt lgkmcnt(0)
	v_mfma_f32_16x16x32_bf16 v[66:69], v[152:155], v[136:139], v[66:69]
	ds_read_b128 v[168:171], v225 offset:0
	v_mfma_f32_16x16x32_bf16 v[70:73], v[156:159], v[136:139], v[70:73]
	ds_read_b128 v[172:175], v225 offset:2048
	v_rcp_f32_e32 v58, v58
	v_mfma_f32_16x16x32_bf16 v[74:77], v[160:163], v[136:139], v[74:77]
	ds_read_b128 v[176:179], v225 offset:4096
	v_rcp_f32_e32 v59, v59
	v_mfma_f32_16x16x32_bf16 v[78:81], v[164:167], v[136:139], v[78:81]
	ds_read_b128 v[180:183], v225 offset:6144
	v_rcp_f32_e32 v60, v60
	v_mfma_f32_16x16x32_bf16 v[82:85], v[152:155], v[140:143], v[82:85]
	ds_read_b128 v[184:187], v233 offset:0
	v_mfma_f32_16x16x32_bf16 v[86:89], v[156:159], v[140:143], v[86:89]
	ds_read_b128 v[188:191], v233 offset:2048
	v_rcp_f32_e32 v61, v61
	v_mfma_f32_16x16x32_bf16 v[90:93], v[160:163], v[140:143], v[90:93]
	ds_read_b128 v[192:195], v233 offset:4096
	v_rcp_f32_e32 v62, v62
	v_mfma_f32_16x16x32_bf16 v[94:97], v[164:167], v[140:143], v[94:97]
	ds_read_b128 v[196:199], v233 offset:6144
	v_rcp_f32_e32 v63, v63
	v_mfma_f32_16x16x32_bf16 v[98:101], v[152:155], v[144:147], v[98:101]
	v_mfma_f32_16x16x32_bf16 v[102:105], v[156:159], v[144:147], v[102:105]
	v_rcp_f32_e32 v64, v64
	v_mfma_f32_16x16x32_bf16 v[106:109], v[160:163], v[144:147], v[106:109]
	v_rcp_f32_e32 v65, v65
	v_mfma_f32_16x16x32_bf16 v[110:113], v[164:167], v[144:147], v[110:113]
	v_cvt_pk_bf16_f32 v58, v58, v59
	v_mfma_f32_16x16x32_bf16 v[114:117], v[152:155], v[148:151], v[114:117]
	v_mfma_f32_16x16x32_bf16 v[118:121], v[156:159], v[148:151], v[118:121]
	v_cvt_pk_bf16_f32 v59, v60, v61
	v_mfma_f32_16x16x32_bf16 v[122:125], v[160:163], v[148:151], v[122:125]
	v_cvt_pk_bf16_f32 v60, v62, v63
	v_mfma_f32_16x16x32_bf16 v[126:129], v[164:167], v[148:151], v[126:129]
	v_cvt_pk_bf16_f32 v61, v64, v65
	s_waitcnt lgkmcnt(0)
	v_mfma_f32_16x16x32_bf16 v[66:69], v[184:187], v[168:171], v[66:69]
	v_mfma_f32_16x16x32_bf16 v[70:73], v[188:191], v[168:171], v[70:73]
	v_mfma_f32_16x16x32_bf16 v[74:77], v[192:195], v[168:171], v[74:77]
	v_mfma_f32_16x16x32_bf16 v[78:81], v[196:199], v[168:171], v[78:81]
	v_mfma_f32_16x16x32_bf16 v[82:85], v[184:187], v[172:175], v[82:85]
	v_mfma_f32_16x16x32_bf16 v[86:89], v[188:191], v[172:175], v[86:89]
	v_mfma_f32_16x16x32_bf16 v[90:93], v[192:195], v[172:175], v[90:93]
	v_mfma_f32_16x16x32_bf16 v[94:97], v[196:199], v[172:175], v[94:97]
	v_mfma_f32_16x16x32_bf16 v[98:101], v[184:187], v[176:179], v[98:101]
	v_mfma_f32_16x16x32_bf16 v[102:105], v[188:191], v[176:179], v[102:105]
	v_mfma_f32_16x16x32_bf16 v[106:109], v[192:195], v[176:179], v[106:109]
	v_mfma_f32_16x16x32_bf16 v[110:113], v[196:199], v[176:179], v[110:113]
	v_mfma_f32_16x16x32_bf16 v[114:117], v[184:187], v[180:183], v[114:117]
	v_mfma_f32_16x16x32_bf16 v[118:121], v[188:191], v[180:183], v[118:121]
	v_mfma_f32_16x16x32_bf16 v[122:125], v[192:195], v[180:183], v[122:125]
	v_mfma_f32_16x16x32_bf16 v[126:129], v[196:199], v[180:183], v[126:129]
	global_store_dwordx4 v241, v[58:61], s[10:11] offset:3072
	s_add_u32 s10, s28, s13
	s_addc_u32 s11, s29, 0
	s_add_u32 s13, s13, 0x10000
	v_mul_f32_e32 v66, s12, v66
	v_mul_f32_e32 v67, s12, v67
	v_mul_f32_e32 v68, s12, v68
	v_mul_f32_e32 v69, s12, v69
	v_mul_f32_e32 v70, s12, v70
	v_mul_f32_e32 v71, s12, v71
	v_mul_f32_e32 v72, s12, v72
	v_mul_f32_e32 v73, s12, v73
	v_exp_f32_e32 v66, v66
	v_exp_f32_e32 v67, v67
	v_exp_f32_e32 v68, v68
	v_exp_f32_e32 v69, v69
	v_exp_f32_e32 v70, v70
	v_exp_f32_e32 v71, v71
	v_exp_f32_e32 v72, v72
	v_exp_f32_e32 v73, v73
	v_add_f32_e32 v66, 1.0, v66
	v_add_f32_e32 v67, 1.0, v67
	v_add_f32_e32 v68, 1.0, v68
	v_add_f32_e32 v69, 1.0, v69
	v_add_f32_e32 v70, 1.0, v70
	v_add_f32_e32 v71, 1.0, v71
	v_add_f32_e32 v72, 1.0, v72
	v_add_f32_e32 v73, 1.0, v73
	v_rcp_f32_e32 v66, v66
	v_rcp_f32_e32 v67, v67
	v_rcp_f32_e32 v68, v68
	v_rcp_f32_e32 v69, v69
	v_rcp_f32_e32 v70, v70
	v_rcp_f32_e32 v71, v71
	v_rcp_f32_e32 v72, v72
	v_rcp_f32_e32 v73, v73
	v_cvt_pk_bf16_f32 v66, v66, v67
	v_cvt_pk_bf16_f32 v67, v68, v69
	v_cvt_pk_bf16_f32 v68, v70, v71
	v_cvt_pk_bf16_f32 v69, v72, v73
	global_store_dwordx4 v240, v[66:69], s[10:11] offset:0
	v_mul_f32_e32 v74, s12, v74
	v_mul_f32_e32 v75, s12, v75
	v_mul_f32_e32 v76, s12, v76
	v_mul_f32_e32 v77, s12, v77
	v_mul_f32_e32 v78, s12, v78
	v_mul_f32_e32 v79, s12, v79
	v_mul_f32_e32 v80, s12, v80
	v_mul_f32_e32 v81, s12, v81
	v_exp_f32_e32 v74, v74
	v_exp_f32_e32 v75, v75
	v_exp_f32_e32 v76, v76
	v_exp_f32_e32 v77, v77
	v_exp_f32_e32 v78, v78
	v_exp_f32_e32 v79, v79
	v_exp_f32_e32 v80, v80
	v_exp_f32_e32 v81, v81
	v_add_f32_e32 v74, 1.0, v74
	v_add_f32_e32 v75, 1.0, v75
	v_add_f32_e32 v76, 1.0, v76
	v_add_f32_e32 v77, 1.0, v77
	v_add_f32_e32 v78, 1.0, v78
	v_add_f32_e32 v79, 1.0, v79
	v_add_f32_e32 v80, 1.0, v80
	v_add_f32_e32 v81, 1.0, v81
	v_rcp_f32_e32 v74, v74
	v_rcp_f32_e32 v75, v75
	v_rcp_f32_e32 v76, v76
	v_rcp_f32_e32 v77, v77
	v_rcp_f32_e32 v78, v78
	v_rcp_f32_e32 v79, v79
	v_rcp_f32_e32 v80, v80
	v_rcp_f32_e32 v81, v81
	v_cvt_pk_bf16_f32 v74, v74, v75
	v_cvt_pk_bf16_f32 v75, v76, v77
	v_cvt_pk_bf16_f32 v76, v78, v79
	v_cvt_pk_bf16_f32 v77, v80, v81
	global_store_dwordx4 v240, v[74:77], s[10:11] offset:1024
	v_mul_f32_e32 v82, s12, v82
	v_mul_f32_e32 v83, s12, v83
	v_mul_f32_e32 v84, s12, v84
	v_mul_f32_e32 v85, s12, v85
	v_mul_f32_e32 v86, s12, v86
	v_mul_f32_e32 v87, s12, v87
	v_mul_f32_e32 v88, s12, v88
	v_mul_f32_e32 v89, s12, v89
	v_exp_f32_e32 v82, v82
	v_exp_f32_e32 v83, v83
	v_exp_f32_e32 v84, v84
	v_exp_f32_e32 v85, v85
	v_exp_f32_e32 v86, v86
	v_exp_f32_e32 v87, v87
	v_exp_f32_e32 v88, v88
	v_exp_f32_e32 v89, v89
	v_add_f32_e32 v82, 1.0, v82
	v_add_f32_e32 v83, 1.0, v83
	v_add_f32_e32 v84, 1.0, v84
	v_add_f32_e32 v85, 1.0, v85
	v_add_f32_e32 v86, 1.0, v86
	v_add_f32_e32 v87, 1.0, v87
	v_add_f32_e32 v88, 1.0, v88
	v_add_f32_e32 v89, 1.0, v89
	v_rcp_f32_e32 v82, v82
	v_rcp_f32_e32 v83, v83
	v_rcp_f32_e32 v84, v84
	v_rcp_f32_e32 v85, v85
	v_rcp_f32_e32 v86, v86
	v_rcp_f32_e32 v87, v87
	v_rcp_f32_e32 v88, v88
	v_rcp_f32_e32 v89, v89
	v_cvt_pk_bf16_f32 v82, v82, v83
	v_cvt_pk_bf16_f32 v83, v84, v85
	v_cvt_pk_bf16_f32 v84, v86, v87
	v_cvt_pk_bf16_f32 v85, v88, v89
	global_store_dwordx4 v240, v[82:85], s[10:11] offset:2048
	v_mul_f32_e32 v90, s12, v90
	v_mul_f32_e32 v91, s12, v91
	v_mul_f32_e32 v92, s12, v92
	v_mul_f32_e32 v93, s12, v93
	v_mul_f32_e32 v94, s12, v94
	v_mul_f32_e32 v95, s12, v95
	v_mul_f32_e32 v96, s12, v96
	v_mul_f32_e32 v97, s12, v97
	v_exp_f32_e32 v90, v90
	v_exp_f32_e32 v91, v91
	v_exp_f32_e32 v92, v92
	v_exp_f32_e32 v93, v93
	v_exp_f32_e32 v94, v94
	v_exp_f32_e32 v95, v95
	v_exp_f32_e32 v96, v96
	v_exp_f32_e32 v97, v97
	v_add_f32_e32 v90, 1.0, v90
	v_add_f32_e32 v91, 1.0, v91
	v_add_f32_e32 v92, 1.0, v92
	v_add_f32_e32 v93, 1.0, v93
	v_add_f32_e32 v94, 1.0, v94
	v_add_f32_e32 v95, 1.0, v95
	v_add_f32_e32 v96, 1.0, v96
	v_add_f32_e32 v97, 1.0, v97
	v_rcp_f32_e32 v90, v90
	v_rcp_f32_e32 v91, v91
	v_rcp_f32_e32 v92, v92
	v_rcp_f32_e32 v93, v93
	v_rcp_f32_e32 v94, v94
	v_rcp_f32_e32 v95, v95
	v_rcp_f32_e32 v96, v96
	v_rcp_f32_e32 v97, v97
	v_cvt_pk_bf16_f32 v90, v90, v91
	v_cvt_pk_bf16_f32 v91, v92, v93
	v_cvt_pk_bf16_f32 v92, v94, v95
	v_cvt_pk_bf16_f32 v93, v96, v97
	global_store_dwordx4 v240, v[90:93], s[10:11] offset:3072
	v_mul_f32_e32 v98, s12, v98
	v_mul_f32_e32 v99, s12, v99
	v_mul_f32_e32 v100, s12, v100
	v_mul_f32_e32 v101, s12, v101
	v_mul_f32_e32 v102, s12, v102
	v_mul_f32_e32 v103, s12, v103
	v_mul_f32_e32 v104, s12, v104
	v_mul_f32_e32 v105, s12, v105
	v_exp_f32_e32 v98, v98
	v_exp_f32_e32 v99, v99
	v_exp_f32_e32 v100, v100
	v_exp_f32_e32 v101, v101
	v_exp_f32_e32 v102, v102
	v_exp_f32_e32 v103, v103
	v_exp_f32_e32 v104, v104
	v_exp_f32_e32 v105, v105
	v_add_f32_e32 v98, 1.0, v98
	v_add_f32_e32 v99, 1.0, v99
	v_add_f32_e32 v100, 1.0, v100
	v_add_f32_e32 v101, 1.0, v101
	v_add_f32_e32 v102, 1.0, v102
	v_add_f32_e32 v103, 1.0, v103
	v_add_f32_e32 v104, 1.0, v104
	v_add_f32_e32 v105, 1.0, v105
	v_rcp_f32_e32 v98, v98
	v_rcp_f32_e32 v99, v99
	v_rcp_f32_e32 v100, v100
	v_rcp_f32_e32 v101, v101
	v_rcp_f32_e32 v102, v102
	v_rcp_f32_e32 v103, v103
	v_rcp_f32_e32 v104, v104
	v_rcp_f32_e32 v105, v105
	v_cvt_pk_bf16_f32 v98, v98, v99
	v_cvt_pk_bf16_f32 v99, v100, v101
	v_cvt_pk_bf16_f32 v100, v102, v103
	v_cvt_pk_bf16_f32 v101, v104, v105
	global_store_dwordx4 v241, v[98:101], s[10:11] offset:0
	v_mul_f32_e32 v106, s12, v106
	v_mul_f32_e32 v107, s12, v107
	v_mul_f32_e32 v108, s12, v108
	v_mul_f32_e32 v109, s12, v109
	v_mul_f32_e32 v110, s12, v110
	v_mul_f32_e32 v111, s12, v111
	v_mul_f32_e32 v112, s12, v112
	v_mul_f32_e32 v113, s12, v113
	v_exp_f32_e32 v106, v106
	v_exp_f32_e32 v107, v107
	v_exp_f32_e32 v108, v108
	v_exp_f32_e32 v109, v109
	v_exp_f32_e32 v110, v110
	v_exp_f32_e32 v111, v111
	v_exp_f32_e32 v112, v112
	v_exp_f32_e32 v113, v113
	v_add_f32_e32 v106, 1.0, v106
	v_add_f32_e32 v107, 1.0, v107
	v_add_f32_e32 v108, 1.0, v108
	v_add_f32_e32 v109, 1.0, v109
	v_add_f32_e32 v110, 1.0, v110
	v_add_f32_e32 v111, 1.0, v111
	v_add_f32_e32 v112, 1.0, v112
	v_add_f32_e32 v113, 1.0, v113
	v_rcp_f32_e32 v106, v106
	v_rcp_f32_e32 v107, v107
	v_rcp_f32_e32 v108, v108
	v_rcp_f32_e32 v109, v109
	v_rcp_f32_e32 v110, v110
	v_rcp_f32_e32 v111, v111
	v_rcp_f32_e32 v112, v112
	v_rcp_f32_e32 v113, v113
	v_cvt_pk_bf16_f32 v106, v106, v107
	v_cvt_pk_bf16_f32 v107, v108, v109
	v_cvt_pk_bf16_f32 v108, v110, v111
	v_cvt_pk_bf16_f32 v109, v112, v113
	global_store_dwordx4 v241, v[106:109], s[10:11] offset:1024
	v_mul_f32_e32 v114, s12, v114
	v_mul_f32_e32 v115, s12, v115
	v_mul_f32_e32 v116, s12, v116
	v_mul_f32_e32 v117, s12, v117
	v_mul_f32_e32 v118, s12, v118
	v_mul_f32_e32 v119, s12, v119
	v_mul_f32_e32 v120, s12, v120
	v_mul_f32_e32 v121, s12, v121
	v_exp_f32_e32 v114, v114
	v_exp_f32_e32 v115, v115
	v_exp_f32_e32 v116, v116
	v_exp_f32_e32 v117, v117
	v_exp_f32_e32 v118, v118
	v_exp_f32_e32 v119, v119
	v_exp_f32_e32 v120, v120
	v_exp_f32_e32 v121, v121
	v_add_f32_e32 v114, 1.0, v114
	v_add_f32_e32 v115, 1.0, v115
	v_add_f32_e32 v116, 1.0, v116
	v_add_f32_e32 v117, 1.0, v117
	v_add_f32_e32 v118, 1.0, v118
	v_add_f32_e32 v119, 1.0, v119
	v_add_f32_e32 v120, 1.0, v120
	v_add_f32_e32 v121, 1.0, v121
	v_rcp_f32_e32 v114, v114
	v_rcp_f32_e32 v115, v115
	v_rcp_f32_e32 v116, v116
	v_rcp_f32_e32 v117, v117
	v_rcp_f32_e32 v118, v118
	v_rcp_f32_e32 v119, v119
	v_rcp_f32_e32 v120, v120
	v_rcp_f32_e32 v121, v121
	v_cvt_pk_bf16_f32 v114, v114, v115
	v_cvt_pk_bf16_f32 v115, v116, v117
	v_cvt_pk_bf16_f32 v116, v118, v119
	v_cvt_pk_bf16_f32 v117, v120, v121
	global_store_dwordx4 v241, v[114:117], s[10:11] offset:2048
	v_mul_f32_e32 v122, s12, v122
	v_mul_f32_e32 v123, s12, v123
	v_mul_f32_e32 v124, s12, v124
	v_mul_f32_e32 v125, s12, v125
	v_mul_f32_e32 v126, s12, v126
	v_mul_f32_e32 v127, s12, v127
	v_mul_f32_e32 v128, s12, v128
	v_mul_f32_e32 v129, s12, v129
	v_exp_f32_e32 v122, v122
	v_exp_f32_e32 v123, v123
	v_exp_f32_e32 v124, v124
	v_exp_f32_e32 v125, v125
	v_exp_f32_e32 v126, v126
	v_exp_f32_e32 v127, v127
	v_exp_f32_e32 v128, v128
	v_exp_f32_e32 v129, v129
	v_add_f32_e32 v122, 1.0, v122
	v_add_f32_e32 v123, 1.0, v123
	v_add_f32_e32 v124, 1.0, v124
	v_add_f32_e32 v125, 1.0, v125
	v_add_f32_e32 v126, 1.0, v126
	v_add_f32_e32 v127, 1.0, v127
	v_add_f32_e32 v128, 1.0, v128
	v_add_f32_e32 v129, 1.0, v129
	v_rcp_f32_e32 v122, v122
	v_rcp_f32_e32 v123, v123
	v_rcp_f32_e32 v124, v124
	v_rcp_f32_e32 v125, v125
	v_rcp_f32_e32 v126, v126
	v_rcp_f32_e32 v127, v127
	v_rcp_f32_e32 v128, v128
	v_rcp_f32_e32 v129, v129
	v_cvt_pk_bf16_f32 v122, v122, v123
	v_cvt_pk_bf16_f32 v123, v124, v125
	v_cvt_pk_bf16_f32 v124, v126, v127
	v_cvt_pk_bf16_f32 v125, v128, v129
	global_store_dwordx4 v241, v[122:125], s[10:11] offset:3072
	s_waitcnt vmcnt(0)
	s_barrier
	v_mov_b32_e32 v236, s20
	v_mov_b32_e32 v237, s21
	v_mov_b32_e32 v238, 0x200f0
	ds_write_b64 v238, v[236:237]
	s_waitcnt vmcnt(0)
	v_readlane_b32 s60, v254, 32
	v_readlane_b32 s58, v254, 46
	s_mov_b32 s64, s44
	s_mov_b32 s72, s67
	s_cmpk_gt_u32 s50, 0xff
	v_readlane_b32 s61, v254, 33
	v_readlane_b32 s59, v254, 47
	s_movk_i32 s73, 0xf0
	v_readlane_b32 s79, v254, 50

.LBB0_880:
	s_andn2_b64 vcc, exec, s[0:1]
	s_cbranch_vccnz .LBB0_891
	s_lshl_b32 s96, s80, 20
	s_mov_b64 s[4:5], s[96:97]
	s_mov_b32 s13, s2
	v_mov_b32_e32 v205, 0x200f0
	ds_read_b64 v[250:251], v205
	v_and_b32_e32 v198, 63, v0
	v_lshrrev_b32_e32 v199, 6, v0
	v_lshrrev_b32_e32 v200, 3, v198
	v_lshrrev_b32_e32 v201, 4, v198
	s_nop 0
	v_readfirstlane_b32 s0, v199
	v_add_u32_e32 v132, 0, v201
	v_xor_b32_e32 v132, v132, v198
	v_and_b32_e32 v132, 7, v132
	v_lshlrev_b32_e32 v132, 4, v132
	v_lshl_add_u32 v130, v199, 5, v200
	v_add_u32_e32 v130, 0, v130
	v_mul_u32_u24_e32 v130, 0x800, v130
	v_add_u32_e32 v132, v132, v130
	v_add_u32_e32 v133, 4, v201
	v_xor_b32_e32 v133, v133, v198
	v_and_b32_e32 v133, 7, v133
	v_lshlrev_b32_e32 v133, 4, v133
	v_lshl_add_u32 v130, v199, 5, v200
	v_add_u32_e32 v130, 8, v130
	v_mul_u32_u24_e32 v130, 0x800, v130
	v_add_u32_e32 v133, v133, v130
	v_add_u32_e32 v134, 8, v201
	v_xor_b32_e32 v134, v134, v198
	v_and_b32_e32 v134, 7, v134
	v_lshlrev_b32_e32 v134, 4, v134
	v_lshl_add_u32 v130, v199, 5, v200
	v_add_u32_e32 v130, 16, v130
	v_mul_u32_u24_e32 v130, 0x800, v130
	v_add_u32_e32 v134, v134, v130
	v_add_u32_e32 v135, 12, v201
	v_xor_b32_e32 v135, v135, v198
	v_and_b32_e32 v135, 7, v135
	v_lshlrev_b32_e32 v135, 4, v135
	v_lshl_add_u32 v130, v199, 5, v200
	v_add_u32_e32 v130, 24, v130
	v_mul_u32_u24_e32 v130, 0x800, v130
	v_add_u32_e32 v135, v135, v130
	v_add_u32_e32 v136, 0, v201
	v_xor_b32_e32 v136, v136, v198
	v_and_b32_e32 v136, 7, v136
	v_lshlrev_b32_e32 v136, 4, v136
	v_lshl_add_u32 v130, v199, 4, v200
	v_add_u32_e32 v130, 0, v130
	v_mul_u32_u24_e32 v130, 0x200, v130
	v_add_u32_e32 v136, v136, v130
	v_add_u32_e32 v137, 4, v201
	v_xor_b32_e32 v137, v137, v198
	v_and_b32_e32 v137, 7, v137
	v_lshlrev_b32_e32 v137, 4, v137
	v_lshl_add_u32 v130, v199, 4, v200
	v_add_u32_e32 v130, 8, v130
	v_mul_u32_u24_e32 v130, 0x200, v130
	v_add_u32_e32 v137, v137, v130
	v_and_b32_e32 v200, 15, v198
	v_lshrrev_b32_e32 v130, 1, v200
	v_xor_b32_e32 v130, v130, v201
	v_lshlrev_b32_e32 v130, 4, v130
	v_lshrrev_b32_e32 v198, 1, v199
	v_lshl_add_u32 v198, v198, 6, v200
	v_lshl_add_u32 v198, v198, 7, v130
	v_and_b32_e32 v199, 1, v199
	v_lshl_add_u32 v199, v199, 6, v200
	v_lshl_add_u32 v199, v199, 7, v130
	v_add_u32_e32 v138, 0x100, v198
	v_xor_b32_e32 v141, 64, v138
	v_add_u32_e32 v144, 0x8100, v199
	v_xor_b32_e32 v147, 64, v144
	v_add_u32_e32 v139, 0xc100, v198
	v_xor_b32_e32 v142, 64, v139
	v_add_u32_e32 v145, 0x14100, v199
	v_xor_b32_e32 v196, 64, v145
	v_add_u32_e32 v140, 0x18100, v198
	v_xor_b32_e32 v143, 64, v140
	v_add_u32_e32 v146, 0x20100, v199
	v_xor_b32_e32 v197, 64, v146
	s_lshl_b32 s1, s0, 12
	s_add_u32 s10, s1, 0x100
	s_lshl_b32 s1, s0, 11
	s_add_u32 s11, s1, 0x8100
	v_mov_b32_e32 v2, 0
	v_mov_b32_e32 v3, 0
	v_mov_b32_e32 v4, 0
	v_mov_b32_e32 v5, 0
	v_mov_b32_e32 v6, 0
	v_mov_b32_e32 v7, 0
	v_mov_b32_e32 v8, 0
	v_mov_b32_e32 v9, 0
	v_mov_b32_e32 v10, 0
	v_mov_b32_e32 v11, 0
	v_mov_b32_e32 v12, 0
	v_mov_b32_e32 v13, 0
	v_mov_b32_e32 v14, 0
	v_mov_b32_e32 v15, 0
	v_mov_b32_e32 v16, 0
	v_mov_b32_e32 v17, 0
	v_mov_b32_e32 v18, 0
	v_mov_b32_e32 v19, 0
	v_mov_b32_e32 v20, 0
	v_mov_b32_e32 v21, 0
	v_mov_b32_e32 v22, 0
	v_mov_b32_e32 v23, 0
	v_mov_b32_e32 v24, 0
	v_mov_b32_e32 v25, 0
	v_mov_b32_e32 v26, 0
	v_mov_b32_e32 v27, 0
	v_mov_b32_e32 v28, 0
	v_mov_b32_e32 v29, 0
	v_mov_b32_e32 v30, 0
	v_mov_b32_e32 v31, 0
	v_mov_b32_e32 v32, 0
	v_mov_b32_e32 v33, 0
	v_mov_b32_e32 v34, 0
	v_mov_b32_e32 v35, 0
	v_mov_b32_e32 v36, 0
	v_mov_b32_e32 v37, 0
	v_mov_b32_e32 v38, 0
	v_mov_b32_e32 v39, 0
	v_mov_b32_e32 v40, 0
	v_mov_b32_e32 v41, 0
	v_mov_b32_e32 v42, 0
	v_mov_b32_e32 v43, 0
	v_mov_b32_e32 v44, 0
	v_mov_b32_e32 v45, 0
	v_mov_b32_e32 v46, 0
	v_mov_b32_e32 v47, 0
	v_mov_b32_e32 v48, 0
	v_mov_b32_e32 v49, 0
	v_mov_b32_e32 v50, 0
	v_mov_b32_e32 v51, 0
	v_mov_b32_e32 v52, 0
	v_mov_b32_e32 v53, 0
	v_mov_b32_e32 v54, 0
	v_mov_b32_e32 v55, 0
	v_mov_b32_e32 v56, 0
	v_mov_b32_e32 v57, 0
	v_mov_b32_e32 v58, 0
	v_mov_b32_e32 v59, 0
	v_mov_b32_e32 v60, 0
	v_mov_b32_e32 v61, 0
	v_mov_b32_e32 v62, 0
	v_mov_b32_e32 v63, 0
	v_mov_b32_e32 v64, 0
	v_mov_b32_e32 v65, 0
	s_waitcnt lgkmcnt(0)
	s_barrier
	v_and_b32_e32 v198, 63, v0
	v_lshrrev_b32_e32 v199, 6, v0
	v_and_b32_e32 v200, 15, v198
	v_lshrrev_b32_e32 v201, 4, v198
	v_lshlrev_b32_e32 v202, 13, v199
	v_lshl_add_u32 v245, v198, 5, v202
	v_lshl_add_u32 v202, v198, 4, v202
	v_add_u32_e32 v203, 0x1000, v202
	v_lshrrev_b32_e32 v130, 1, v199
	v_lshl_add_u32 v130, v130, 6, v200
	v_lshlrev_b32_e32 v204, 11, v130
	v_and_b32_e32 v130, 1, v199
	v_lshl_add_u32 v204, v130, 7, v204
	v_lshl_add_u32 v204, v201, 3, v204
	v_add_u32_e32 v199, 0x1000, v245
.Lc2_unit:
	s_cmpk_lt_i32 s13, 0x100
	s_cbranch_scc0 .Lc2_exit
	v_mov_b32_e32 v66, 0
	v_mov_b32_e32 v67, 0
	v_mov_b32_e32 v68, 0
	v_mov_b32_e32 v69, 0
	v_mov_b32_e32 v70, 0
	v_mov_b32_e32 v71, 0
	v_mov_b32_e32 v72, 0
	v_mov_b32_e32 v73, 0
	v_mov_b32_e32 v74, 0
	v_mov_b32_e32 v75, 0
	v_mov_b32_e32 v76, 0
	v_mov_b32_e32 v77, 0
	v_mov_b32_e32 v78, 0
	v_mov_b32_e32 v79, 0
	v_mov_b32_e32 v80, 0
	v_mov_b32_e32 v81, 0
	v_mov_b32_e32 v82, 0
	v_mov_b32_e32 v83, 0
	v_mov_b32_e32 v84, 0
	v_mov_b32_e32 v85, 0
	v_mov_b32_e32 v86, 0
	v_mov_b32_e32 v87, 0
	v_mov_b32_e32 v88, 0
	v_mov_b32_e32 v89, 0
	v_mov_b32_e32 v90, 0
	v_mov_b32_e32 v91, 0
	v_mov_b32_e32 v92, 0
	v_mov_b32_e32 v93, 0
	v_mov_b32_e32 v94, 0
	v_mov_b32_e32 v95, 0
	v_mov_b32_e32 v96, 0
	v_mov_b32_e32 v97, 0
	v_mov_b32_e32 v98, 0
	v_mov_b32_e32 v99, 0
	v_mov_b32_e32 v100, 0
	v_mov_b32_e32 v101, 0
	v_mov_b32_e32 v102, 0
	v_mov_b32_e32 v103, 0
	v_mov_b32_e32 v104, 0
	v_mov_b32_e32 v105, 0
	v_mov_b32_e32 v106, 0
	v_mov_b32_e32 v107, 0
	v_mov_b32_e32 v108, 0
	v_mov_b32_e32 v109, 0
	v_mov_b32_e32 v110, 0
	v_mov_b32_e32 v111, 0
	v_mov_b32_e32 v112, 0
	v_mov_b32_e32 v113, 0
	v_mov_b32_e32 v114, 0
	v_mov_b32_e32 v115, 0
	v_mov_b32_e32 v116, 0
	v_mov_b32_e32 v117, 0
	v_mov_b32_e32 v118, 0
	v_mov_b32_e32 v119, 0
	v_mov_b32_e32 v120, 0
	v_mov_b32_e32 v121, 0
	v_mov_b32_e32 v122, 0
	v_mov_b32_e32 v123, 0
	v_mov_b32_e32 v124, 0
	v_mov_b32_e32 v125, 0
	v_mov_b32_e32 v126, 0
	v_mov_b32_e32 v127, 0
	v_mov_b32_e32 v128, 0
	v_mov_b32_e32 v129, 0
	s_and_b32 s0, s13, 31
	s_lshr_b32 s1, s13, 5
	v_readlane_b32 s6, v253, 55
	v_readlane_b32 s7, v253, 56
	s_lshl_b32 s20, s0, 19
	s_nop 0
	s_add_u32 s6, s6, s20
	s_addc_u32 s7, s7, 0
	v_readlane_b32 s8, v254, 2
	v_readlane_b32 s9, v254, 3
	s_lshl_b32 s20, s80, 21
	s_lshl_b32 s21, s1, 16
	s_add_u32 s20, s20, s21
	s_add_u32 s8, s8, s20
	s_addc_u32 s9, s9, 0
	s_lshl_b32 s20, s0, 3
	s_add_u32 s20, s20, s1
	s_lshl_b32 s20, s20, 16
	s_add_u32 s14, s28, s20
	s_addc_u32 s15, s29, 0
	s_mov_b32 m0, s10
	s_nop 0
	global_load_lds_dwordx4 v132, s[6:7]
	s_add_u32 m0, s10, 0x400
	s_nop 0
	global_load_lds_dwordx4 v133, s[6:7]
	s_add_u32 m0, s10, 0x800
	s_nop 0
	global_load_lds_dwordx4 v134, s[6:7]
	s_add_u32 m0, s10, 0xc00
	s_nop 0
	global_load_lds_dwordx4 v135, s[6:7]
	s_mov_b32 m0, s11
	s_nop 0
	global_load_lds_dwordx4 v136, s[8:9]
	s_add_u32 m0, s11, 0x400
	s_nop 0
	global_load_lds_dwordx4 v137, s[8:9]
	s_add_u32 s6, s6, 0x80
	s_addc_u32 s7, s7, 0
	s_add_u32 s8, s8, 0x80
	s_addc_u32 s9, s9, 0
	s_add_u32 m0, s10, 0xc000
	s_nop 0
	global_load_lds_dwordx4 v132, s[6:7]
	s_add_u32 m0, s10, 0xc400
	s_nop 0
	global_load_lds_dwordx4 v133, s[6:7]
	s_add_u32 m0, s10, 0xc800
	s_nop 0
	global_load_lds_dwordx4 v134, s[6:7]
	s_add_u32 m0, s10, 0xcc00
	s_nop 0
	global_load_lds_dwordx4 v135, s[6:7]
	s_add_u32 m0, s11, 0xc000
	s_nop 0
	global_load_lds_dwordx4 v136, s[8:9]
	s_add_u32 m0, s11, 0xc400
	s_nop 0
	global_load_lds_dwordx4 v137, s[8:9]
	s_add_u32 s6, s6, 0x80
	s_addc_u32 s7, s7, 0
	s_add_u32 s8, s8, 0x80
	s_addc_u32 s9, s9, 0
	s_add_u32 s20, s14, 0x1000000
	s_addc_u32 s21, s15, 0
	global_load_dword v244, v245, s[14:15] offset:0
	global_load_dword v244, v245, s[14:15] offset:2048
	global_load_dword v244, v199, s[14:15] offset:0
	global_load_dword v244, v199, s[14:15] offset:2048
	s_waitcnt vmcnt(10)
	s_barrier
	ds_read_b128 v[148:151], v138 offset:0
	ds_read_b128 v[152:155], v138 offset:2048
	ds_read_b128 v[156:159], v138 offset:4096
	ds_read_b128 v[160:163], v138 offset:6144
	ds_read_b128 v[164:167], v144 offset:0
	ds_read_b128 v[168:171], v144 offset:2048
	ds_read_b128 v[172:175], v144 offset:4096
	ds_read_b128 v[176:179], v144 offset:6144
	ds_read_b128 v[180:183], v141 offset:0
	ds_read_b128 v[184:187], v141 offset:2048
	ds_read_b128 v[188:191], v141 offset:4096
	ds_read_b128 v[192:195], v141 offset:6144
	ds_read_b128 v[228:231], v147 offset:0
	ds_read_b128 v[232:235], v147 offset:2048
	ds_read_b128 v[236:239], v147 offset:4096
	ds_read_b128 v[240:243], v147 offset:6144
	s_waitcnt lgkmcnt(8)
	v_mfma_f32_16x16x32_bf16 v[2:5], v[164:167], v[148:151], v[2:5]
	s_add_u32 m0, s10, 0x18000
	v_mfma_f32_16x16x32_bf16 v[6:9], v[168:171], v[148:151], v[6:9]
	global_load_lds_dwordx4 v132, s[6:7]
	v_mfma_f32_16x16x32_bf16 v[10:13], v[172:175], v[148:151], v[10:13]
	s_add_u32 m0, s10, 0x18400
	v_mfma_f32_16x16x32_bf16 v[14:17], v[176:179], v[148:151], v[14:17]
	global_load_lds_dwordx4 v133, s[6:7]
	v_mfma_f32_16x16x32_bf16 v[18:21], v[164:167], v[152:155], v[18:21]
	s_add_u32 m0, s10, 0x18800
	v_mfma_f32_16x16x32_bf16 v[22:25], v[168:171], v[152:155], v[22:25]
	global_load_lds_dwordx4 v134, s[6:7]
	v_mfma_f32_16x16x32_bf16 v[26:29], v[172:175], v[152:155], v[26:29]
	s_add_u32 m0, s10, 0x18c00
	v_mfma_f32_16x16x32_bf16 v[30:33], v[176:179], v[152:155], v[30:33]
	global_load_lds_dwordx4 v135, s[6:7]
	v_mfma_f32_16x16x32_bf16 v[34:37], v[164:167], v[156:159], v[34:37]
	s_add_u32 m0, s11, 0x18000
	v_mfma_f32_16x16x32_bf16 v[38:41], v[168:171], v[156:159], v[38:41]
	global_load_lds_dwordx4 v136, s[8:9]
	v_mfma_f32_16x16x32_bf16 v[42:45], v[172:175], v[156:159], v[42:45]
	s_add_u32 m0, s11, 0x18400
	v_mfma_f32_16x16x32_bf16 v[46:49], v[176:179], v[156:159], v[46:49]
	global_load_lds_dwordx4 v137, s[8:9]
	v_mfma_f32_16x16x32_bf16 v[50:53], v[164:167], v[160:163], v[50:53]
	v_mfma_f32_16x16x32_bf16 v[54:57], v[168:171], v[160:163], v[54:57]
	v_mfma_f32_16x16x32_bf16 v[58:61], v[172:175], v[160:163], v[58:61]
	v_mfma_f32_16x16x32_bf16 v[62:65], v[176:179], v[160:163], v[62:65]
	s_waitcnt lgkmcnt(0)
	v_mfma_f32_16x16x32_bf16 v[2:5], v[228:231], v[180:183], v[2:5]
	v_mfma_f32_16x16x32_bf16 v[6:9], v[232:235], v[180:183], v[6:9]
	v_mfma_f32_16x16x32_bf16 v[10:13], v[236:239], v[180:183], v[10:13]
	v_mfma_f32_16x16x32_bf16 v[14:17], v[240:243], v[180:183], v[14:17]
	v_mfma_f32_16x16x32_bf16 v[18:21], v[228:231], v[184:187], v[18:21]
	v_mfma_f32_16x16x32_bf16 v[22:25], v[232:235], v[184:187], v[22:25]
	v_mfma_f32_16x16x32_bf16 v[26:29], v[236:239], v[184:187], v[26:29]
	v_mfma_f32_16x16x32_bf16 v[30:33], v[240:243], v[184:187], v[30:33]
	v_mfma_f32_16x16x32_bf16 v[34:37], v[228:231], v[188:191], v[34:37]
	v_mfma_f32_16x16x32_bf16 v[38:41], v[232:235], v[188:191], v[38:41]
	v_mfma_f32_16x16x32_bf16 v[42:45], v[236:239], v[188:191], v[42:45]
	v_mfma_f32_16x16x32_bf16 v[46:49], v[240:243], v[188:191], v[46:49]
	v_mfma_f32_16x16x32_bf16 v[50:53], v[228:231], v[192:195], v[50:53]
	v_mfma_f32_16x16x32_bf16 v[54:57], v[232:235], v[192:195], v[54:57]
	v_mfma_f32_16x16x32_bf16 v[58:61], v[236:239], v[192:195], v[58:61]
	v_mfma_f32_16x16x32_bf16 v[62:65], v[240:243], v[192:195], v[62:65]
	s_add_u32 s6, s6, 0x80
	s_addc_u32 s7, s7, 0
	s_add_u32 s8, s8, 0x80
	s_addc_u32 s9, s9, 0
	global_load_dword v244, v245, s[20:21] offset:0
	s_waitcnt vmcnt(11)
	s_barrier
	ds_read_b128 v[148:151], v139 offset:0
	ds_read_b128 v[152:155], v139 offset:2048
	ds_read_b128 v[156:159], v139 offset:4096
	ds_read_b128 v[160:163], v139 offset:6144
	ds_read_b128 v[164:167], v145 offset:0
	ds_read_b128 v[168:171], v145 offset:2048
	ds_read_b128 v[172:175], v145 offset:4096
	ds_read_b128 v[176:179], v145 offset:6144
	ds_read_b128 v[180:183], v142 offset:0
	ds_read_b128 v[184:187], v142 offset:2048
	ds_read_b128 v[188:191], v142 offset:4096
	ds_read_b128 v[192:195], v142 offset:6144
	ds_read_b128 v[228:231], v196 offset:0
	ds_read_b128 v[232:235], v196 offset:2048
	ds_read_b128 v[236:239], v196 offset:4096
	ds_read_b128 v[240:243], v196 offset:6144
	s_waitcnt lgkmcnt(8)
	v_mfma_f32_16x16x32_bf16 v[2:5], v[164:167], v[148:151], v[2:5]
	s_mov_b32 m0, s10
	v_mfma_f32_16x16x32_bf16 v[6:9], v[168:171], v[148:151], v[6:9]
	global_load_lds_dwordx4 v132, s[6:7]
	v_mfma_f32_16x16x32_bf16 v[10:13], v[172:175], v[148:151], v[10:13]
	s_add_u32 m0, s10, 0x400
	v_mfma_f32_16x16x32_bf16 v[14:17], v[176:179], v[148:151], v[14:17]
	global_load_lds_dwordx4 v133, s[6:7]
	v_mfma_f32_16x16x32_bf16 v[18:21], v[164:167], v[152:155], v[18:21]
	s_add_u32 m0, s10, 0x800
	v_mfma_f32_16x16x32_bf16 v[22:25], v[168:171], v[152:155], v[22:25]
	global_load_lds_dwordx4 v134, s[6:7]
	v_mfma_f32_16x16x32_bf16 v[26:29], v[172:175], v[152:155], v[26:29]
	s_add_u32 m0, s10, 0xc00
	v_mfma_f32_16x16x32_bf16 v[30:33], v[176:179], v[152:155], v[30:33]
	global_load_lds_dwordx4 v135, s[6:7]
	v_mfma_f32_16x16x32_bf16 v[34:37], v[164:167], v[156:159], v[34:37]
	s_mov_b32 m0, s11
	v_mfma_f32_16x16x32_bf16 v[38:41], v[168:171], v[156:159], v[38:41]
	global_load_lds_dwordx4 v136, s[8:9]
	v_mfma_f32_16x16x32_bf16 v[42:45], v[172:175], v[156:159], v[42:45]
	s_add_u32 m0, s11, 0x400
	v_mfma_f32_16x16x32_bf16 v[46:49], v[176:179], v[156:159], v[46:49]
	global_load_lds_dwordx4 v137, s[8:9]
	v_mfma_f32_16x16x32_bf16 v[50:53], v[164:167], v[160:163], v[50:53]
	v_mfma_f32_16x16x32_bf16 v[54:57], v[168:171], v[160:163], v[54:57]
	v_mfma_f32_16x16x32_bf16 v[58:61], v[172:175], v[160:163], v[58:61]
	v_mfma_f32_16x16x32_bf16 v[62:65], v[176:179], v[160:163], v[62:65]
	s_waitcnt lgkmcnt(0)
	v_mfma_f32_16x16x32_bf16 v[2:5], v[228:231], v[180:183], v[2:5]
	v_mfma_f32_16x16x32_bf16 v[6:9], v[232:235], v[180:183], v[6:9]
	v_mfma_f32_16x16x32_bf16 v[10:13], v[236:239], v[180:183], v[10:13]
	v_mfma_f32_16x16x32_bf16 v[14:17], v[240:243], v[180:183], v[14:17]
	v_mfma_f32_16x16x32_bf16 v[18:21], v[228:231], v[184:187], v[18:21]
	v_mfma_f32_16x16x32_bf16 v[22:25], v[232:235], v[184:187], v[22:25]
	v_mfma_f32_16x16x32_bf16 v[26:29], v[236:239], v[184:187], v[26:29]
	v_mfma_f32_16x16x32_bf16 v[30:33], v[240:243], v[184:187], v[30:33]
	v_mfma_f32_16x16x32_bf16 v[34:37], v[228:231], v[188:191], v[34:37]
	v_mfma_f32_16x16x32_bf16 v[38:41], v[232:235], v[188:191], v[38:41]
	v_mfma_f32_16x16x32_bf16 v[42:45], v[236:239], v[188:191], v[42:45]
	v_mfma_f32_16x16x32_bf16 v[46:49], v[240:243], v[188:191], v[46:49]
	v_mfma_f32_16x16x32_bf16 v[50:53], v[228:231], v[192:195], v[50:53]
	v_mfma_f32_16x16x32_bf16 v[54:57], v[232:235], v[192:195], v[54:57]
	v_mfma_f32_16x16x32_bf16 v[58:61], v[236:239], v[192:195], v[58:61]
	v_mfma_f32_16x16x32_bf16 v[62:65], v[240:243], v[192:195], v[62:65]
	s_add_u32 s6, s6, 0x80
	s_addc_u32 s7, s7, 0
	s_add_u32 s8, s8, 0x7fe80
	s_addc_u32 s9, s9, 0
	global_load_dword v244, v245, s[20:21] offset:2048
	s_waitcnt vmcnt(8)
	s_barrier
	ds_read_b128 v[148:151], v140 offset:0
	ds_read_b128 v[152:155], v140 offset:2048
	ds_read_b128 v[156:159], v140 offset:4096
	ds_read_b128 v[160:163], v140 offset:6144
	ds_read_b128 v[164:167], v146 offset:0
	ds_read_b128 v[168:171], v146 offset:2048
	ds_read_b128 v[172:175], v146 offset:4096
	ds_read_b128 v[176:179], v146 offset:6144
	ds_read_b128 v[180:183], v143 offset:0
	ds_read_b128 v[184:187], v143 offset:2048
	ds_read_b128 v[188:191], v143 offset:4096
	ds_read_b128 v[192:195], v143 offset:6144
	ds_read_b128 v[228:231], v197 offset:0
	ds_read_b128 v[232:235], v197 offset:2048
	ds_read_b128 v[236:239], v197 offset:4096
	ds_read_b128 v[240:243], v197 offset:6144
	s_waitcnt lgkmcnt(8)
	v_mfma_f32_16x16x32_bf16 v[2:5], v[164:167], v[148:151], v[2:5]
	s_add_u32 m0, s10, 0xc000
	v_mfma_f32_16x16x32_bf16 v[6:9], v[168:171], v[148:151], v[6:9]
	global_load_lds_dwordx4 v132, s[6:7]
	v_mfma_f32_16x16x32_bf16 v[10:13], v[172:175], v[148:151], v[10:13]
	s_add_u32 m0, s10, 0xc400
	v_mfma_f32_16x16x32_bf16 v[14:17], v[176:179], v[148:151], v[14:17]
	global_load_lds_dwordx4 v133, s[6:7]
	v_mfma_f32_16x16x32_bf16 v[18:21], v[164:167], v[152:155], v[18:21]
	s_add_u32 m0, s10, 0xc800
	v_mfma_f32_16x16x32_bf16 v[22:25], v[168:171], v[152:155], v[22:25]
	global_load_lds_dwordx4 v134, s[6:7]
	v_mfma_f32_16x16x32_bf16 v[26:29], v[172:175], v[152:155], v[26:29]
	s_add_u32 m0, s10, 0xcc00
	v_mfma_f32_16x16x32_bf16 v[30:33], v[176:179], v[152:155], v[30:33]
	global_load_lds_dwordx4 v135, s[6:7]
	v_mfma_f32_16x16x32_bf16 v[34:37], v[164:167], v[156:159], v[34:37]
	s_add_u32 m0, s11, 0xc000
	v_mfma_f32_16x16x32_bf16 v[38:41], v[168:171], v[156:159], v[38:41]
	global_load_lds_dwordx4 v136, s[8:9]
	v_mfma_f32_16x16x32_bf16 v[42:45], v[172:175], v[156:159], v[42:45]
	s_add_u32 m0, s11, 0xc400
	v_mfma_f32_16x16x32_bf16 v[46:49], v[176:179], v[156:159], v[46:49]
	global_load_lds_dwordx4 v137, s[8:9]
	v_mfma_f32_16x16x32_bf16 v[50:53], v[164:167], v[160:163], v[50:53]
	v_mfma_f32_16x16x32_bf16 v[54:57], v[168:171], v[160:163], v[54:57]
	v_mfma_f32_16x16x32_bf16 v[58:61], v[172:175], v[160:163], v[58:61]
	v_mfma_f32_16x16x32_bf16 v[62:65], v[176:179], v[160:163], v[62:65]
	s_waitcnt lgkmcnt(0)
	v_mfma_f32_16x16x32_bf16 v[2:5], v[228:231], v[180:183], v[2:5]
	v_mfma_f32_16x16x32_bf16 v[6:9], v[232:235], v[180:183], v[6:9]
	v_mfma_f32_16x16x32_bf16 v[10:13], v[236:239], v[180:183], v[10:13]
	v_mfma_f32_16x16x32_bf16 v[14:17], v[240:243], v[180:183], v[14:17]
	v_mfma_f32_16x16x32_bf16 v[18:21], v[228:231], v[184:187], v[18:21]
	v_mfma_f32_16x16x32_bf16 v[22:25], v[232:235], v[184:187], v[22:25]
	v_mfma_f32_16x16x32_bf16 v[26:29], v[236:239], v[184:187], v[26:29]
	v_mfma_f32_16x16x32_bf16 v[30:33], v[240:243], v[184:187], v[30:33]
	v_mfma_f32_16x16x32_bf16 v[34:37], v[228:231], v[188:191], v[34:37]
	v_mfma_f32_16x16x32_bf16 v[38:41], v[232:235], v[188:191], v[38:41]
	v_mfma_f32_16x16x32_bf16 v[42:45], v[236:239], v[188:191], v[42:45]
	v_mfma_f32_16x16x32_bf16 v[46:49], v[240:243], v[188:191], v[46:49]
	v_mfma_f32_16x16x32_bf16 v[50:53], v[228:231], v[192:195], v[50:53]
	v_mfma_f32_16x16x32_bf16 v[54:57], v[232:235], v[192:195], v[54:57]
	v_mfma_f32_16x16x32_bf16 v[58:61], v[236:239], v[192:195], v[58:61]
	v_mfma_f32_16x16x32_bf16 v[62:65], v[240:243], v[192:195], v[62:65]
	s_add_u32 s6, s6, 0x80
	s_addc_u32 s7, s7, 0
	s_add_u32 s8, s8, 0x80
	s_addc_u32 s9, s9, 0
	global_load_dword v244, v199, s[20:21] offset:0
	s_waitcnt vmcnt(8)
	s_barrier
	ds_read_b128 v[148:151], v138 offset:0
	ds_read_b128 v[152:155], v138 offset:2048
	ds_read_b128 v[156:159], v138 offset:4096
	ds_read_b128 v[160:163], v138 offset:6144
	ds_read_b128 v[164:167], v144 offset:0
	ds_read_b128 v[168:171], v144 offset:2048
	ds_read_b128 v[172:175], v144 offset:4096
	ds_read_b128 v[176:179], v144 offset:6144
	ds_read_b128 v[180:183], v141 offset:0
	ds_read_b128 v[184:187], v141 offset:2048
	ds_read_b128 v[188:191], v141 offset:4096
	ds_read_b128 v[192:195], v141 offset:6144
	ds_read_b128 v[228:231], v147 offset:0
	ds_read_b128 v[232:235], v147 offset:2048
	ds_read_b128 v[236:239], v147 offset:4096
	ds_read_b128 v[240:243], v147 offset:6144
	s_waitcnt lgkmcnt(8)
	v_mfma_f32_16x16x32_bf16 v[2:5], v[164:167], v[148:151], v[2:5]
	v_mfma_f32_16x16x32_bf16 v[6:9], v[168:171], v[148:151], v[6:9]
	v_mfma_f32_16x16x32_bf16 v[10:13], v[172:175], v[148:151], v[10:13]
	v_mfma_f32_16x16x32_bf16 v[14:17], v[176:179], v[148:151], v[14:17]
	v_mfma_f32_16x16x32_bf16 v[18:21], v[164:167], v[152:155], v[18:21]
	v_mfma_f32_16x16x32_bf16 v[22:25], v[168:171], v[152:155], v[22:25]
	v_mfma_f32_16x16x32_bf16 v[26:29], v[172:175], v[152:155], v[26:29]
	v_mfma_f32_16x16x32_bf16 v[30:33], v[176:179], v[152:155], v[30:33]
	v_mfma_f32_16x16x32_bf16 v[34:37], v[164:167], v[156:159], v[34:37]
	v_mfma_f32_16x16x32_bf16 v[38:41], v[168:171], v[156:159], v[38:41]
	v_mfma_f32_16x16x32_bf16 v[42:45], v[172:175], v[156:159], v[42:45]
	v_mfma_f32_16x16x32_bf16 v[46:49], v[176:179], v[156:159], v[46:49]
	v_mfma_f32_16x16x32_bf16 v[50:53], v[164:167], v[160:163], v[50:53]
	v_mfma_f32_16x16x32_bf16 v[54:57], v[168:171], v[160:163], v[54:57]
	v_mfma_f32_16x16x32_bf16 v[58:61], v[172:175], v[160:163], v[58:61]
	v_mfma_f32_16x16x32_bf16 v[62:65], v[176:179], v[160:163], v[62:65]
	global_load_dwordx4 v[148:151], v202, s[14:15] offset:0
	global_load_dwordx4 v[152:155], v202, s[14:15] offset:1024
	global_load_dwordx4 v[156:159], v202, s[14:15] offset:2048
	global_load_dwordx4 v[160:163], v202, s[14:15] offset:3072
	global_load_dwordx4 v[164:167], v203, s[14:15] offset:0
	global_load_dwordx4 v[168:171], v203, s[14:15] offset:1024
	global_load_dwordx4 v[172:175], v203, s[14:15] offset:2048
	global_load_dwordx4 v[176:179], v203, s[14:15] offset:3072
	s_waitcnt lgkmcnt(0)
	v_mfma_f32_16x16x32_bf16 v[2:5], v[228:231], v[180:183], v[2:5]
	s_add_u32 m0, s10, 0x18000
	v_mfma_f32_16x16x32_bf16 v[6:9], v[232:235], v[180:183], v[6:9]
	global_load_lds_dwordx4 v132, s[6:7]
	v_mfma_f32_16x16x32_bf16 v[10:13], v[236:239], v[180:183], v[10:13]
	s_add_u32 m0, s10, 0x18400
	v_mfma_f32_16x16x32_bf16 v[14:17], v[240:243], v[180:183], v[14:17]
	global_load_lds_dwordx4 v133, s[6:7]
	v_mfma_f32_16x16x32_bf16 v[18:21], v[228:231], v[184:187], v[18:21]
	s_add_u32 m0, s10, 0x18800
	v_mfma_f32_16x16x32_bf16 v[22:25], v[232:235], v[184:187], v[22:25]
	global_load_lds_dwordx4 v134, s[6:7]
	v_mfma_f32_16x16x32_bf16 v[26:29], v[236:239], v[184:187], v[26:29]
	s_add_u32 m0, s10, 0x18c00
	v_mfma_f32_16x16x32_bf16 v[30:33], v[240:243], v[184:187], v[30:33]
	global_load_lds_dwordx4 v135, s[6:7]
	v_mfma_f32_16x16x32_bf16 v[34:37], v[228:231], v[188:191], v[34:37]
	s_add_u32 m0, s11, 0x18000
	v_mfma_f32_16x16x32_bf16 v[38:41], v[232:235], v[188:191], v[38:41]
	global_load_lds_dwordx4 v136, s[8:9]
	v_mfma_f32_16x16x32_bf16 v[42:45], v[236:239], v[188:191], v[42:45]
	s_add_u32 m0, s11, 0x18400
	v_mfma_f32_16x16x32_bf16 v[46:49], v[240:243], v[188:191], v[46:49]
	global_load_lds_dwordx4 v137, s[8:9]
	v_mfma_f32_16x16x32_bf16 v[50:53], v[228:231], v[192:195], v[50:53]
	v_mfma_f32_16x16x32_bf16 v[54:57], v[232:235], v[192:195], v[54:57]
	v_mfma_f32_16x16x32_bf16 v[58:61], v[236:239], v[192:195], v[58:61]
	v_mfma_f32_16x16x32_bf16 v[62:65], v[240:243], v[192:195], v[62:65]
	s_add_u32 s6, s6, 0x80
	s_addc_u32 s7, s7, 0
	s_add_u32 s8, s8, 0x80
	s_addc_u32 s9, s9, 0
	s_add_u32 s14, s14, 0x1000000
	s_addc_u32 s15, s15, 0
	global_load_dword v244, v199, s[20:21] offset:2048
	s_add_u32 s20, s20, 0x1000000
	s_addc_u32 s21, s21, 0
	s_nop 7
	s_nop 3
	s_waitcnt vmcnt(7)
	v_lshlrev_b32_e32 v246, 16, v148
	v_and_b32_e32 v247, 0xffff0000, v148
	v_pk_fma_f32 v[66:67], v[2:3], v[246:247], v[66:67]
	v_lshlrev_b32_e32 v248, 16, v149
	v_and_b32_e32 v249, 0xffff0000, v149
	v_pk_fma_f32 v[68:69], v[4:5], v[248:249], v[68:69]
	v_lshlrev_b32_e32 v246, 16, v150
	v_and_b32_e32 v247, 0xffff0000, v150
	v_pk_fma_f32 v[70:71], v[6:7], v[246:247], v[70:71]
	v_lshlrev_b32_e32 v248, 16, v151
	v_and_b32_e32 v249, 0xffff0000, v151
	v_pk_fma_f32 v[72:73], v[8:9], v[248:249], v[72:73]
	v_lshlrev_b32_e32 v246, 16, v152
	v_and_b32_e32 v247, 0xffff0000, v152
	v_pk_fma_f32 v[74:75], v[10:11], v[246:247], v[74:75]
	v_lshlrev_b32_e32 v248, 16, v153
	v_and_b32_e32 v249, 0xffff0000, v153
	v_pk_fma_f32 v[76:77], v[12:13], v[248:249], v[76:77]
	v_lshlrev_b32_e32 v246, 16, v154
	v_and_b32_e32 v247, 0xffff0000, v154
	v_pk_fma_f32 v[78:79], v[14:15], v[246:247], v[78:79]
	v_lshlrev_b32_e32 v248, 16, v155
	v_and_b32_e32 v249, 0xffff0000, v155
	v_pk_fma_f32 v[80:81], v[16:17], v[248:249], v[80:81]
	v_lshlrev_b32_e32 v246, 16, v156
	v_and_b32_e32 v247, 0xffff0000, v156
	v_pk_fma_f32 v[82:83], v[18:19], v[246:247], v[82:83]
	v_lshlrev_b32_e32 v248, 16, v157
	v_and_b32_e32 v249, 0xffff0000, v157
	v_pk_fma_f32 v[84:85], v[20:21], v[248:249], v[84:85]
	v_lshlrev_b32_e32 v246, 16, v158
	v_and_b32_e32 v247, 0xffff0000, v158
	v_pk_fma_f32 v[86:87], v[22:23], v[246:247], v[86:87]
	v_lshlrev_b32_e32 v248, 16, v159
	v_and_b32_e32 v249, 0xffff0000, v159
	v_pk_fma_f32 v[88:89], v[24:25], v[248:249], v[88:89]
	v_lshlrev_b32_e32 v246, 16, v160
	v_and_b32_e32 v247, 0xffff0000, v160
	v_pk_fma_f32 v[90:91], v[26:27], v[246:247], v[90:91]
	v_lshlrev_b32_e32 v248, 16, v161
	v_and_b32_e32 v249, 0xffff0000, v161
	v_pk_fma_f32 v[92:93], v[28:29], v[248:249], v[92:93]
	v_lshlrev_b32_e32 v246, 16, v162
	v_and_b32_e32 v247, 0xffff0000, v162
	v_pk_fma_f32 v[94:95], v[30:31], v[246:247], v[94:95]
	v_lshlrev_b32_e32 v248, 16, v163
	v_and_b32_e32 v249, 0xffff0000, v163
	v_pk_fma_f32 v[96:97], v[32:33], v[248:249], v[96:97]
	v_lshlrev_b32_e32 v246, 16, v164
	v_and_b32_e32 v247, 0xffff0000, v164
	v_pk_fma_f32 v[98:99], v[34:35], v[246:247], v[98:99]
	v_lshlrev_b32_e32 v248, 16, v165
	v_and_b32_e32 v249, 0xffff0000, v165
	v_pk_fma_f32 v[100:101], v[36:37], v[248:249], v[100:101]
	v_lshlrev_b32_e32 v246, 16, v166
	v_and_b32_e32 v247, 0xffff0000, v166
	v_pk_fma_f32 v[102:103], v[38:39], v[246:247], v[102:103]
	v_lshlrev_b32_e32 v248, 16, v167
	v_and_b32_e32 v249, 0xffff0000, v167
	v_pk_fma_f32 v[104:105], v[40:41], v[248:249], v[104:105]
	v_lshlrev_b32_e32 v246, 16, v168
	v_and_b32_e32 v247, 0xffff0000, v168
	v_pk_fma_f32 v[106:107], v[42:43], v[246:247], v[106:107]
	v_lshlrev_b32_e32 v248, 16, v169
	v_and_b32_e32 v249, 0xffff0000, v169
	v_pk_fma_f32 v[108:109], v[44:45], v[248:249], v[108:109]
	v_lshlrev_b32_e32 v246, 16, v170
	v_and_b32_e32 v247, 0xffff0000, v170
	v_pk_fma_f32 v[110:111], v[46:47], v[246:247], v[110:111]
	v_lshlrev_b32_e32 v248, 16, v171
	v_and_b32_e32 v249, 0xffff0000, v171
	v_pk_fma_f32 v[112:113], v[48:49], v[248:249], v[112:113]
	v_lshlrev_b32_e32 v246, 16, v172
	v_and_b32_e32 v247, 0xffff0000, v172
	v_pk_fma_f32 v[114:115], v[50:51], v[246:247], v[114:115]
	v_lshlrev_b32_e32 v248, 16, v173
	v_and_b32_e32 v249, 0xffff0000, v173
	v_pk_fma_f32 v[116:117], v[52:53], v[248:249], v[116:117]
	v_lshlrev_b32_e32 v246, 16, v174
	v_and_b32_e32 v247, 0xffff0000, v174
	v_pk_fma_f32 v[118:119], v[54:55], v[246:247], v[118:119]
	v_lshlrev_b32_e32 v248, 16, v175
	v_and_b32_e32 v249, 0xffff0000, v175
	v_pk_fma_f32 v[120:121], v[56:57], v[248:249], v[120:121]
	v_lshlrev_b32_e32 v246, 16, v176
	v_and_b32_e32 v247, 0xffff0000, v176
	v_pk_fma_f32 v[122:123], v[58:59], v[246:247], v[122:123]
	v_lshlrev_b32_e32 v248, 16, v177
	v_and_b32_e32 v249, 0xffff0000, v177
	v_pk_fma_f32 v[124:125], v[60:61], v[248:249], v[124:125]
	v_lshlrev_b32_e32 v246, 16, v178
	v_and_b32_e32 v247, 0xffff0000, v178
	v_pk_fma_f32 v[126:127], v[62:63], v[246:247], v[126:127]
	v_lshlrev_b32_e32 v248, 16, v179
	v_and_b32_e32 v249, 0xffff0000, v179
	v_pk_fma_f32 v[128:129], v[64:65], v[248:249], v[128:129]
	v_mov_b32_e32 v2, 0
	v_mov_b32_e32 v3, 0
	v_mov_b32_e32 v4, 0
	v_mov_b32_e32 v5, 0
	v_mov_b32_e32 v6, 0
	v_mov_b32_e32 v7, 0
	v_mov_b32_e32 v8, 0
	v_mov_b32_e32 v9, 0
	v_mov_b32_e32 v10, 0
	v_mov_b32_e32 v11, 0
	v_mov_b32_e32 v12, 0
	v_mov_b32_e32 v13, 0
	v_mov_b32_e32 v14, 0
	v_mov_b32_e32 v15, 0
	v_mov_b32_e32 v16, 0
	v_mov_b32_e32 v17, 0
	v_mov_b32_e32 v18, 0
	v_mov_b32_e32 v19, 0
	v_mov_b32_e32 v20, 0
	v_mov_b32_e32 v21, 0
	v_mov_b32_e32 v22, 0
	v_mov_b32_e32 v23, 0
	v_mov_b32_e32 v24, 0
	v_mov_b32_e32 v25, 0
	v_mov_b32_e32 v26, 0
	v_mov_b32_e32 v27, 0
	v_mov_b32_e32 v28, 0
	v_mov_b32_e32 v29, 0
	v_mov_b32_e32 v30, 0
	v_mov_b32_e32 v31, 0
	v_mov_b32_e32 v32, 0
	v_mov_b32_e32 v33, 0
	v_mov_b32_e32 v34, 0
	v_mov_b32_e32 v35, 0
	v_mov_b32_e32 v36, 0
	v_mov_b32_e32 v37, 0
	v_mov_b32_e32 v38, 0
	v_mov_b32_e32 v39, 0
	v_mov_b32_e32 v40, 0
	v_mov_b32_e32 v41, 0
	v_mov_b32_e32 v42, 0
	v_mov_b32_e32 v43, 0
	v_mov_b32_e32 v44, 0
	v_mov_b32_e32 v45, 0
	v_mov_b32_e32 v46, 0
	v_mov_b32_e32 v47, 0
	v_mov_b32_e32 v48, 0
	v_mov_b32_e32 v49, 0
	v_mov_b32_e32 v50, 0
	v_mov_b32_e32 v51, 0
	v_mov_b32_e32 v52, 0
	v_mov_b32_e32 v53, 0
	v_mov_b32_e32 v54, 0
	v_mov_b32_e32 v55, 0
	v_mov_b32_e32 v56, 0
	v_mov_b32_e32 v57, 0
	v_mov_b32_e32 v58, 0
	v_mov_b32_e32 v59, 0
	v_mov_b32_e32 v60, 0
	v_mov_b32_e32 v61, 0
	v_mov_b32_e32 v62, 0
	v_mov_b32_e32 v63, 0
	v_mov_b32_e32 v64, 0
	v_mov_b32_e32 v65, 0
	s_waitcnt vmcnt(16)
	s_barrier
	ds_read_b128 v[148:151], v139 offset:0
	ds_read_b128 v[152:155], v139 offset:2048
	ds_read_b128 v[156:159], v139 offset:4096
	ds_read_b128 v[160:163], v139 offset:6144
	ds_read_b128 v[164:167], v145 offset:0
	ds_read_b128 v[168:171], v145 offset:2048
	ds_read_b128 v[172:175], v145 offset:4096
	ds_read_b128 v[176:179], v145 offset:6144
	ds_read_b128 v[180:183], v142 offset:0
	ds_read_b128 v[184:187], v142 offset:2048
	ds_read_b128 v[188:191], v142 offset:4096
	ds_read_b128 v[192:195], v142 offset:6144
	ds_read_b128 v[228:231], v196 offset:0
	ds_read_b128 v[232:235], v196 offset:2048
	ds_read_b128 v[236:239], v196 offset:4096
	ds_read_b128 v[240:243], v196 offset:6144
	s_waitcnt lgkmcnt(8)
	v_mfma_f32_16x16x32_bf16 v[2:5], v[164:167], v[148:151], v[2:5]
	s_mov_b32 m0, s10
	v_mfma_f32_16x16x32_bf16 v[6:9], v[168:171], v[148:151], v[6:9]
	global_load_lds_dwordx4 v132, s[6:7]
	v_mfma_f32_16x16x32_bf16 v[10:13], v[172:175], v[148:151], v[10:13]
	s_add_u32 m0, s10, 0x400
	v_mfma_f32_16x16x32_bf16 v[14:17], v[176:179], v[148:151], v[14:17]
	global_load_lds_dwordx4 v133, s[6:7]
	v_mfma_f32_16x16x32_bf16 v[18:21], v[164:167], v[152:155], v[18:21]
	s_add_u32 m0, s10, 0x800
	v_mfma_f32_16x16x32_bf16 v[22:25], v[168:171], v[152:155], v[22:25]
	global_load_lds_dwordx4 v134, s[6:7]
	v_mfma_f32_16x16x32_bf16 v[26:29], v[172:175], v[152:155], v[26:29]
	s_add_u32 m0, s10, 0xc00
	v_mfma_f32_16x16x32_bf16 v[30:33], v[176:179], v[152:155], v[30:33]
	global_load_lds_dwordx4 v135, s[6:7]
	v_mfma_f32_16x16x32_bf16 v[34:37], v[164:167], v[156:159], v[34:37]
	s_mov_b32 m0, s11
	v_mfma_f32_16x16x32_bf16 v[38:41], v[168:171], v[156:159], v[38:41]
	global_load_lds_dwordx4 v136, s[8:9]
	v_mfma_f32_16x16x32_bf16 v[42:45], v[172:175], v[156:159], v[42:45]
	s_add_u32 m0, s11, 0x400
	v_mfma_f32_16x16x32_bf16 v[46:49], v[176:179], v[156:159], v[46:49]
	global_load_lds_dwordx4 v137, s[8:9]
	v_mfma_f32_16x16x32_bf16 v[50:53], v[164:167], v[160:163], v[50:53]
	v_mfma_f32_16x16x32_bf16 v[54:57], v[168:171], v[160:163], v[54:57]
	v_mfma_f32_16x16x32_bf16 v[58:61], v[172:175], v[160:163], v[58:61]
	v_mfma_f32_16x16x32_bf16 v[62:65], v[176:179], v[160:163], v[62:65]
	s_waitcnt lgkmcnt(0)
	v_mfma_f32_16x16x32_bf16 v[2:5], v[228:231], v[180:183], v[2:5]
	v_mfma_f32_16x16x32_bf16 v[6:9], v[232:235], v[180:183], v[6:9]
	v_mfma_f32_16x16x32_bf16 v[10:13], v[236:239], v[180:183], v[10:13]
	v_mfma_f32_16x16x32_bf16 v[14:17], v[240:243], v[180:183], v[14:17]
	v_mfma_f32_16x16x32_bf16 v[18:21], v[228:231], v[184:187], v[18:21]
	v_mfma_f32_16x16x32_bf16 v[22:25], v[232:235], v[184:187], v[22:25]
	v_mfma_f32_16x16x32_bf16 v[26:29], v[236:239], v[184:187], v[26:29]
	v_mfma_f32_16x16x32_bf16 v[30:33], v[240:243], v[184:187], v[30:33]
	v_mfma_f32_16x16x32_bf16 v[34:37], v[228:231], v[188:191], v[34:37]
	v_mfma_f32_16x16x32_bf16 v[38:41], v[232:235], v[188:191], v[38:41]
	v_mfma_f32_16x16x32_bf16 v[42:45], v[236:239], v[188:191], v[42:45]
	v_mfma_f32_16x16x32_bf16 v[46:49], v[240:243], v[188:191], v[46:49]
	v_mfma_f32_16x16x32_bf16 v[50:53], v[228:231], v[192:195], v[50:53]
	v_mfma_f32_16x16x32_bf16 v[54:57], v[232:235], v[192:195], v[54:57]
	v_mfma_f32_16x16x32_bf16 v[58:61], v[236:239], v[192:195], v[58:61]
	v_mfma_f32_16x16x32_bf16 v[62:65], v[240:243], v[192:195], v[62:65]
	s_add_u32 s6, s6, 0x80
	s_addc_u32 s7, s7, 0
	s_add_u32 s8, s8, 0x80
	s_addc_u32 s9, s9, 0
	global_load_dword v244, v245, s[20:21] offset:0
	s_waitcnt vmcnt(8)
	s_barrier
	ds_read_b128 v[148:151], v140 offset:0
	ds_read_b128 v[152:155], v140 offset:2048
	ds_read_b128 v[156:159], v140 offset:4096
	ds_read_b128 v[160:163], v140 offset:6144
	ds_read_b128 v[164:167], v146 offset:0
	ds_read_b128 v[168:171], v146 offset:2048
	ds_read_b128 v[172:175], v146 offset:4096
	ds_read_b128 v[176:179], v146 offset:6144
	ds_read_b128 v[180:183], v143 offset:0
	ds_read_b128 v[184:187], v143 offset:2048
	ds_read_b128 v[188:191], v143 offset:4096
	ds_read_b128 v[192:195], v143 offset:6144
	ds_read_b128 v[228:231], v197 offset:0
	ds_read_b128 v[232:235], v197 offset:2048
	ds_read_b128 v[236:239], v197 offset:4096
	ds_read_b128 v[240:243], v197 offset:6144
	s_waitcnt lgkmcnt(8)
	v_mfma_f32_16x16x32_bf16 v[2:5], v[164:167], v[148:151], v[2:5]
	s_add_u32 m0, s10, 0xc000
	v_mfma_f32_16x16x32_bf16 v[6:9], v[168:171], v[148:151], v[6:9]
	global_load_lds_dwordx4 v132, s[6:7]
	v_mfma_f32_16x16x32_bf16 v[10:13], v[172:175], v[148:151], v[10:13]
	s_add_u32 m0, s10, 0xc400
	v_mfma_f32_16x16x32_bf16 v[14:17], v[176:179], v[148:151], v[14:17]
	global_load_lds_dwordx4 v133, s[6:7]
	v_mfma_f32_16x16x32_bf16 v[18:21], v[164:167], v[152:155], v[18:21]
	s_add_u32 m0, s10, 0xc800
	v_mfma_f32_16x16x32_bf16 v[22:25], v[168:171], v[152:155], v[22:25]
	global_load_lds_dwordx4 v134, s[6:7]
	v_mfma_f32_16x16x32_bf16 v[26:29], v[172:175], v[152:155], v[26:29]
	s_add_u32 m0, s10, 0xcc00
	v_mfma_f32_16x16x32_bf16 v[30:33], v[176:179], v[152:155], v[30:33]
	global_load_lds_dwordx4 v135, s[6:7]
	v_mfma_f32_16x16x32_bf16 v[34:37], v[164:167], v[156:159], v[34:37]
	s_add_u32 m0, s11, 0xc000
	v_mfma_f32_16x16x32_bf16 v[38:41], v[168:171], v[156:159], v[38:41]
	global_load_lds_dwordx4 v136, s[8:9]
	v_mfma_f32_16x16x32_bf16 v[42:45], v[172:175], v[156:159], v[42:45]
	s_add_u32 m0, s11, 0xc400
	v_mfma_f32_16x16x32_bf16 v[46:49], v[176:179], v[156:159], v[46:49]
	global_load_lds_dwordx4 v137, s[8:9]
	v_mfma_f32_16x16x32_bf16 v[50:53], v[164:167], v[160:163], v[50:53]
	v_mfma_f32_16x16x32_bf16 v[54:57], v[168:171], v[160:163], v[54:57]
	v_mfma_f32_16x16x32_bf16 v[58:61], v[172:175], v[160:163], v[58:61]
	v_mfma_f32_16x16x32_bf16 v[62:65], v[176:179], v[160:163], v[62:65]
	s_waitcnt lgkmcnt(0)
	v_mfma_f32_16x16x32_bf16 v[2:5], v[228:231], v[180:183], v[2:5]
	v_mfma_f32_16x16x32_bf16 v[6:9], v[232:235], v[180:183], v[6:9]
	v_mfma_f32_16x16x32_bf16 v[10:13], v[236:239], v[180:183], v[10:13]
	v_mfma_f32_16x16x32_bf16 v[14:17], v[240:243], v[180:183], v[14:17]
	v_mfma_f32_16x16x32_bf16 v[18:21], v[228:231], v[184:187], v[18:21]
	v_mfma_f32_16x16x32_bf16 v[22:25], v[232:235], v[184:187], v[22:25]
	v_mfma_f32_16x16x32_bf16 v[26:29], v[236:239], v[184:187], v[26:29]
	v_mfma_f32_16x16x32_bf16 v[30:33], v[240:243], v[184:187], v[30:33]
	v_mfma_f32_16x16x32_bf16 v[34:37], v[228:231], v[188:191], v[34:37]
	v_mfma_f32_16x16x32_bf16 v[38:41], v[232:235], v[188:191], v[38:41]
	v_mfma_f32_16x16x32_bf16 v[42:45], v[236:239], v[188:191], v[42:45]
	v_mfma_f32_16x16x32_bf16 v[46:49], v[240:243], v[188:191], v[46:49]
	v_mfma_f32_16x16x32_bf16 v[50:53], v[228:231], v[192:195], v[50:53]
	v_mfma_f32_16x16x32_bf16 v[54:57], v[232:235], v[192:195], v[54:57]
	v_mfma_f32_16x16x32_bf16 v[58:61], v[236:239], v[192:195], v[58:61]
	v_mfma_f32_16x16x32_bf16 v[62:65], v[240:243], v[192:195], v[62:65]
	s_add_u32 s6, s6, 0x80
	s_addc_u32 s7, s7, 0
	s_add_u32 s8, s8, 0x7fe80
	s_addc_u32 s9, s9, 0
	global_load_dword v244, v245, s[20:21] offset:2048
	s_waitcnt vmcnt(8)
	s_barrier
	ds_read_b128 v[148:151], v138 offset:0
	ds_read_b128 v[152:155], v138 offset:2048
	ds_read_b128 v[156:159], v138 offset:4096
	ds_read_b128 v[160:163], v138 offset:6144
	ds_read_b128 v[164:167], v144 offset:0
	ds_read_b128 v[168:171], v144 offset:2048
	ds_read_b128 v[172:175], v144 offset:4096
	ds_read_b128 v[176:179], v144 offset:6144
	ds_read_b128 v[180:183], v141 offset:0
	ds_read_b128 v[184:187], v141 offset:2048
	ds_read_b128 v[188:191], v141 offset:4096
	ds_read_b128 v[192:195], v141 offset:6144
	ds_read_b128 v[228:231], v147 offset:0
	ds_read_b128 v[232:235], v147 offset:2048
	ds_read_b128 v[236:239], v147 offset:4096
	ds_read_b128 v[240:243], v147 offset:6144
	s_waitcnt lgkmcnt(8)
	v_mfma_f32_16x16x32_bf16 v[2:5], v[164:167], v[148:151], v[2:5]
	s_add_u32 m0, s10, 0x18000
	v_mfma_f32_16x16x32_bf16 v[6:9], v[168:171], v[148:151], v[6:9]
	global_load_lds_dwordx4 v132, s[6:7]
	v_mfma_f32_16x16x32_bf16 v[10:13], v[172:175], v[148:151], v[10:13]
	s_add_u32 m0, s10, 0x18400
	v_mfma_f32_16x16x32_bf16 v[14:17], v[176:179], v[148:151], v[14:17]
	global_load_lds_dwordx4 v133, s[6:7]
	v_mfma_f32_16x16x32_bf16 v[18:21], v[164:167], v[152:155], v[18:21]
	s_add_u32 m0, s10, 0x18800
	v_mfma_f32_16x16x32_bf16 v[22:25], v[168:171], v[152:155], v[22:25]
	global_load_lds_dwordx4 v134, s[6:7]
	v_mfma_f32_16x16x32_bf16 v[26:29], v[172:175], v[152:155], v[26:29]
	s_add_u32 m0, s10, 0x18c00
	v_mfma_f32_16x16x32_bf16 v[30:33], v[176:179], v[152:155], v[30:33]
	global_load_lds_dwordx4 v135, s[6:7]
	v_mfma_f32_16x16x32_bf16 v[34:37], v[164:167], v[156:159], v[34:37]
	s_add_u32 m0, s11, 0x18000
	v_mfma_f32_16x16x32_bf16 v[38:41], v[168:171], v[156:159], v[38:41]
	global_load_lds_dwordx4 v136, s[8:9]
	v_mfma_f32_16x16x32_bf16 v[42:45], v[172:175], v[156:159], v[42:45]
	s_add_u32 m0, s11, 0x18400
	v_mfma_f32_16x16x32_bf16 v[46:49], v[176:179], v[156:159], v[46:49]
	global_load_lds_dwordx4 v137, s[8:9]
	v_mfma_f32_16x16x32_bf16 v[50:53], v[164:167], v[160:163], v[50:53]
	v_mfma_f32_16x16x32_bf16 v[54:57], v[168:171], v[160:163], v[54:57]
	v_mfma_f32_16x16x32_bf16 v[58:61], v[172:175], v[160:163], v[58:61]
	v_mfma_f32_16x16x32_bf16 v[62:65], v[176:179], v[160:163], v[62:65]
	s_waitcnt lgkmcnt(0)
	v_mfma_f32_16x16x32_bf16 v[2:5], v[228:231], v[180:183], v[2:5]
	v_mfma_f32_16x16x32_bf16 v[6:9], v[232:235], v[180:183], v[6:9]
	v_mfma_f32_16x16x32_bf16 v[10:13], v[236:239], v[180:183], v[10:13]
	v_mfma_f32_16x16x32_bf16 v[14:17], v[240:243], v[180:183], v[14:17]
	v_mfma_f32_16x16x32_bf16 v[18:21], v[228:231], v[184:187], v[18:21]
	v_mfma_f32_16x16x32_bf16 v[22:25], v[232:235], v[184:187], v[22:25]
	v_mfma_f32_16x16x32_bf16 v[26:29], v[236:239], v[184:187], v[26:29]
	v_mfma_f32_16x16x32_bf16 v[30:33], v[240:243], v[184:187], v[30:33]
	v_mfma_f32_16x16x32_bf16 v[34:37], v[228:231], v[188:191], v[34:37]
	v_mfma_f32_16x16x32_bf16 v[38:41], v[232:235], v[188:191], v[38:41]
	v_mfma_f32_16x16x32_bf16 v[42:45], v[236:239], v[188:191], v[42:45]
	v_mfma_f32_16x16x32_bf16 v[46:49], v[240:243], v[188:191], v[46:49]
	v_mfma_f32_16x16x32_bf16 v[50:53], v[228:231], v[192:195], v[50:53]
	v_mfma_f32_16x16x32_bf16 v[54:57], v[232:235], v[192:195], v[54:57]
	v_mfma_f32_16x16x32_bf16 v[58:61], v[236:239], v[192:195], v[58:61]
	v_mfma_f32_16x16x32_bf16 v[62:65], v[240:243], v[192:195], v[62:65]
	s_add_u32 s6, s6, 0x80
	s_addc_u32 s7, s7, 0
	s_add_u32 s8, s8, 0x80
	s_addc_u32 s9, s9, 0
	global_load_dword v244, v199, s[20:21] offset:0
	s_waitcnt vmcnt(8)
	s_barrier
	ds_read_b128 v[148:151], v139 offset:0
	ds_read_b128 v[152:155], v139 offset:2048
	ds_read_b128 v[156:159], v139 offset:4096
	ds_read_b128 v[160:163], v139 offset:6144
	ds_read_b128 v[164:167], v145 offset:0
	ds_read_b128 v[168:171], v145 offset:2048
	ds_read_b128 v[172:175], v145 offset:4096
	ds_read_b128 v[176:179], v145 offset:6144
	ds_read_b128 v[180:183], v142 offset:0
	ds_read_b128 v[184:187], v142 offset:2048
	ds_read_b128 v[188:191], v142 offset:4096
	ds_read_b128 v[192:195], v142 offset:6144
	ds_read_b128 v[228:231], v196 offset:0
	ds_read_b128 v[232:235], v196 offset:2048
	ds_read_b128 v[236:239], v196 offset:4096
	ds_read_b128 v[240:243], v196 offset:6144
	s_waitcnt lgkmcnt(8)
	v_mfma_f32_16x16x32_bf16 v[2:5], v[164:167], v[148:151], v[2:5]
	v_mfma_f32_16x16x32_bf16 v[6:9], v[168:171], v[148:151], v[6:9]
	v_mfma_f32_16x16x32_bf16 v[10:13], v[172:175], v[148:151], v[10:13]
	v_mfma_f32_16x16x32_bf16 v[14:17], v[176:179], v[148:151], v[14:17]
	v_mfma_f32_16x16x32_bf16 v[18:21], v[164:167], v[152:155], v[18:21]
	v_mfma_f32_16x16x32_bf16 v[22:25], v[168:171], v[152:155], v[22:25]
	v_mfma_f32_16x16x32_bf16 v[26:29], v[172:175], v[152:155], v[26:29]
	v_mfma_f32_16x16x32_bf16 v[30:33], v[176:179], v[152:155], v[30:33]
	v_mfma_f32_16x16x32_bf16 v[34:37], v[164:167], v[156:159], v[34:37]
	v_mfma_f32_16x16x32_bf16 v[38:41], v[168:171], v[156:159], v[38:41]
	v_mfma_f32_16x16x32_bf16 v[42:45], v[172:175], v[156:159], v[42:45]
	v_mfma_f32_16x16x32_bf16 v[46:49], v[176:179], v[156:159], v[46:49]
	v_mfma_f32_16x16x32_bf16 v[50:53], v[164:167], v[160:163], v[50:53]
	v_mfma_f32_16x16x32_bf16 v[54:57], v[168:171], v[160:163], v[54:57]
	v_mfma_f32_16x16x32_bf16 v[58:61], v[172:175], v[160:163], v[58:61]
	v_mfma_f32_16x16x32_bf16 v[62:65], v[176:179], v[160:163], v[62:65]
	global_load_dwordx4 v[148:151], v202, s[14:15] offset:0
	global_load_dwordx4 v[152:155], v202, s[14:15] offset:1024
	global_load_dwordx4 v[156:159], v202, s[14:15] offset:2048
	global_load_dwordx4 v[160:163], v202, s[14:15] offset:3072
	global_load_dwordx4 v[164:167], v203, s[14:15] offset:0
	global_load_dwordx4 v[168:171], v203, s[14:15] offset:1024
	global_load_dwordx4 v[172:175], v203, s[14:15] offset:2048
	global_load_dwordx4 v[176:179], v203, s[14:15] offset:3072
	s_waitcnt lgkmcnt(0)
	v_mfma_f32_16x16x32_bf16 v[2:5], v[228:231], v[180:183], v[2:5]
	s_mov_b32 m0, s10
	v_mfma_f32_16x16x32_bf16 v[6:9], v[232:235], v[180:183], v[6:9]
	global_load_lds_dwordx4 v132, s[6:7]
	v_mfma_f32_16x16x32_bf16 v[10:13], v[236:239], v[180:183], v[10:13]
	s_add_u32 m0, s10, 0x400
	v_mfma_f32_16x16x32_bf16 v[14:17], v[240:243], v[180:183], v[14:17]
	global_load_lds_dwordx4 v133, s[6:7]
	v_mfma_f32_16x16x32_bf16 v[18:21], v[228:231], v[184:187], v[18:21]
	s_add_u32 m0, s10, 0x800
	v_mfma_f32_16x16x32_bf16 v[22:25], v[232:235], v[184:187], v[22:25]
	global_load_lds_dwordx4 v134, s[6:7]
	v_mfma_f32_16x16x32_bf16 v[26:29], v[236:239], v[184:187], v[26:29]
	s_add_u32 m0, s10, 0xc00
	v_mfma_f32_16x16x32_bf16 v[30:33], v[240:243], v[184:187], v[30:33]
	global_load_lds_dwordx4 v135, s[6:7]
	v_mfma_f32_16x16x32_bf16 v[34:37], v[228:231], v[188:191], v[34:37]
	s_mov_b32 m0, s11
	v_mfma_f32_16x16x32_bf16 v[38:41], v[232:235], v[188:191], v[38:41]
	global_load_lds_dwordx4 v136, s[8:9]
	v_mfma_f32_16x16x32_bf16 v[42:45], v[236:239], v[188:191], v[42:45]
	s_add_u32 m0, s11, 0x400
	v_mfma_f32_16x16x32_bf16 v[46:49], v[240:243], v[188:191], v[46:49]
	global_load_lds_dwordx4 v137, s[8:9]
	v_mfma_f32_16x16x32_bf16 v[50:53], v[228:231], v[192:195], v[50:53]
	v_mfma_f32_16x16x32_bf16 v[54:57], v[232:235], v[192:195], v[54:57]
	v_mfma_f32_16x16x32_bf16 v[58:61], v[236:239], v[192:195], v[58:61]
	v_mfma_f32_16x16x32_bf16 v[62:65], v[240:243], v[192:195], v[62:65]
	s_add_u32 s6, s6, 0x80
	s_addc_u32 s7, s7, 0
	s_add_u32 s8, s8, 0x80
	s_addc_u32 s9, s9, 0
	s_add_u32 s14, s14, 0x1000000
	s_addc_u32 s15, s15, 0
	global_load_dword v244, v199, s[20:21] offset:2048
	s_add_u32 s20, s20, 0x1000000
	s_addc_u32 s21, s21, 0
	s_nop 7
	s_nop 3
	s_waitcnt vmcnt(7)
	v_lshlrev_b32_e32 v246, 16, v148
	v_and_b32_e32 v247, 0xffff0000, v148
	v_pk_fma_f32 v[66:67], v[2:3], v[246:247], v[66:67]
	v_lshlrev_b32_e32 v248, 16, v149
	v_and_b32_e32 v249, 0xffff0000, v149
	v_pk_fma_f32 v[68:69], v[4:5], v[248:249], v[68:69]
	v_lshlrev_b32_e32 v246, 16, v150
	v_and_b32_e32 v247, 0xffff0000, v150
	v_pk_fma_f32 v[70:71], v[6:7], v[246:247], v[70:71]
	v_lshlrev_b32_e32 v248, 16, v151
	v_and_b32_e32 v249, 0xffff0000, v151
	v_pk_fma_f32 v[72:73], v[8:9], v[248:249], v[72:73]
	v_lshlrev_b32_e32 v246, 16, v152
	v_and_b32_e32 v247, 0xffff0000, v152
	v_pk_fma_f32 v[74:75], v[10:11], v[246:247], v[74:75]
	v_lshlrev_b32_e32 v248, 16, v153
	v_and_b32_e32 v249, 0xffff0000, v153
	v_pk_fma_f32 v[76:77], v[12:13], v[248:249], v[76:77]
	v_lshlrev_b32_e32 v246, 16, v154
	v_and_b32_e32 v247, 0xffff0000, v154
	v_pk_fma_f32 v[78:79], v[14:15], v[246:247], v[78:79]
	v_lshlrev_b32_e32 v248, 16, v155
	v_and_b32_e32 v249, 0xffff0000, v155
	v_pk_fma_f32 v[80:81], v[16:17], v[248:249], v[80:81]
	v_lshlrev_b32_e32 v246, 16, v156
	v_and_b32_e32 v247, 0xffff0000, v156
	v_pk_fma_f32 v[82:83], v[18:19], v[246:247], v[82:83]
	v_lshlrev_b32_e32 v248, 16, v157
	v_and_b32_e32 v249, 0xffff0000, v157
	v_pk_fma_f32 v[84:85], v[20:21], v[248:249], v[84:85]
	v_lshlrev_b32_e32 v246, 16, v158
	v_and_b32_e32 v247, 0xffff0000, v158
	v_pk_fma_f32 v[86:87], v[22:23], v[246:247], v[86:87]
	v_lshlrev_b32_e32 v248, 16, v159
	v_and_b32_e32 v249, 0xffff0000, v159
	v_pk_fma_f32 v[88:89], v[24:25], v[248:249], v[88:89]
	v_lshlrev_b32_e32 v246, 16, v160
	v_and_b32_e32 v247, 0xffff0000, v160
	v_pk_fma_f32 v[90:91], v[26:27], v[246:247], v[90:91]
	v_lshlrev_b32_e32 v248, 16, v161
	v_and_b32_e32 v249, 0xffff0000, v161
	v_pk_fma_f32 v[92:93], v[28:29], v[248:249], v[92:93]
	v_lshlrev_b32_e32 v246, 16, v162
	v_and_b32_e32 v247, 0xffff0000, v162
	v_pk_fma_f32 v[94:95], v[30:31], v[246:247], v[94:95]
	v_lshlrev_b32_e32 v248, 16, v163
	v_and_b32_e32 v249, 0xffff0000, v163
	v_pk_fma_f32 v[96:97], v[32:33], v[248:249], v[96:97]
	v_lshlrev_b32_e32 v246, 16, v164
	v_and_b32_e32 v247, 0xffff0000, v164
	v_pk_fma_f32 v[98:99], v[34:35], v[246:247], v[98:99]
	v_lshlrev_b32_e32 v248, 16, v165
	v_and_b32_e32 v249, 0xffff0000, v165
	v_pk_fma_f32 v[100:101], v[36:37], v[248:249], v[100:101]
	v_lshlrev_b32_e32 v246, 16, v166
	v_and_b32_e32 v247, 0xffff0000, v166
	v_pk_fma_f32 v[102:103], v[38:39], v[246:247], v[102:103]
	v_lshlrev_b32_e32 v248, 16, v167
	v_and_b32_e32 v249, 0xffff0000, v167
	v_pk_fma_f32 v[104:105], v[40:41], v[248:249], v[104:105]
	v_lshlrev_b32_e32 v246, 16, v168
	v_and_b32_e32 v247, 0xffff0000, v168
	v_pk_fma_f32 v[106:107], v[42:43], v[246:247], v[106:107]
	v_lshlrev_b32_e32 v248, 16, v169
	v_and_b32_e32 v249, 0xffff0000, v169
	v_pk_fma_f32 v[108:109], v[44:45], v[248:249], v[108:109]
	v_lshlrev_b32_e32 v246, 16, v170
	v_and_b32_e32 v247, 0xffff0000, v170
	v_pk_fma_f32 v[110:111], v[46:47], v[246:247], v[110:111]
	v_lshlrev_b32_e32 v248, 16, v171
	v_and_b32_e32 v249, 0xffff0000, v171
	v_pk_fma_f32 v[112:113], v[48:49], v[248:249], v[112:113]
	v_lshlrev_b32_e32 v246, 16, v172
	v_and_b32_e32 v247, 0xffff0000, v172
	v_pk_fma_f32 v[114:115], v[50:51], v[246:247], v[114:115]
	v_lshlrev_b32_e32 v248, 16, v173
	v_and_b32_e32 v249, 0xffff0000, v173
	v_pk_fma_f32 v[116:117], v[52:53], v[248:249], v[116:117]
	v_lshlrev_b32_e32 v246, 16, v174
	v_and_b32_e32 v247, 0xffff0000, v174
	v_pk_fma_f32 v[118:119], v[54:55], v[246:247], v[118:119]
	v_lshlrev_b32_e32 v248, 16, v175
	v_and_b32_e32 v249, 0xffff0000, v175
	v_pk_fma_f32 v[120:121], v[56:57], v[248:249], v[120:121]
	v_lshlrev_b32_e32 v246, 16, v176
	v_and_b32_e32 v247, 0xffff0000, v176
	v_pk_fma_f32 v[122:123], v[58:59], v[246:247], v[122:123]
	v_lshlrev_b32_e32 v248, 16, v177
	v_and_b32_e32 v249, 0xffff0000, v177
	v_pk_fma_f32 v[124:125], v[60:61], v[248:249], v[124:125]
	v_lshlrev_b32_e32 v246, 16, v178
	v_and_b32_e32 v247, 0xffff0000, v178
	v_pk_fma_f32 v[126:127], v[62:63], v[246:247], v[126:127]
	v_lshlrev_b32_e32 v248, 16, v179
	v_and_b32_e32 v249, 0xffff0000, v179
	v_pk_fma_f32 v[128:129], v[64:65], v[248:249], v[128:129]
	v_mov_b32_e32 v2, 0
	v_mov_b32_e32 v3, 0
	v_mov_b32_e32 v4, 0
	v_mov_b32_e32 v5, 0
	v_mov_b32_e32 v6, 0
	v_mov_b32_e32 v7, 0
	v_mov_b32_e32 v8, 0
	v_mov_b32_e32 v9, 0
	v_mov_b32_e32 v10, 0
	v_mov_b32_e32 v11, 0
	v_mov_b32_e32 v12, 0
	v_mov_b32_e32 v13, 0
	v_mov_b32_e32 v14, 0
	v_mov_b32_e32 v15, 0
	v_mov_b32_e32 v16, 0
	v_mov_b32_e32 v17, 0
	v_mov_b32_e32 v18, 0
	v_mov_b32_e32 v19, 0
	v_mov_b32_e32 v20, 0
	v_mov_b32_e32 v21, 0
	v_mov_b32_e32 v22, 0
	v_mov_b32_e32 v23, 0
	v_mov_b32_e32 v24, 0
	v_mov_b32_e32 v25, 0
	v_mov_b32_e32 v26, 0
	v_mov_b32_e32 v27, 0
	v_mov_b32_e32 v28, 0
	v_mov_b32_e32 v29, 0
	v_mov_b32_e32 v30, 0
	v_mov_b32_e32 v31, 0
	v_mov_b32_e32 v32, 0
	v_mov_b32_e32 v33, 0
	v_mov_b32_e32 v34, 0
	v_mov_b32_e32 v35, 0
	v_mov_b32_e32 v36, 0
	v_mov_b32_e32 v37, 0
	v_mov_b32_e32 v38, 0
	v_mov_b32_e32 v39, 0
	v_mov_b32_e32 v40, 0
	v_mov_b32_e32 v41, 0
	v_mov_b32_e32 v42, 0
	v_mov_b32_e32 v43, 0
	v_mov_b32_e32 v44, 0
	v_mov_b32_e32 v45, 0
	v_mov_b32_e32 v46, 0
	v_mov_b32_e32 v47, 0
	v_mov_b32_e32 v48, 0
	v_mov_b32_e32 v49, 0
	v_mov_b32_e32 v50, 0
	v_mov_b32_e32 v51, 0
	v_mov_b32_e32 v52, 0
	v_mov_b32_e32 v53, 0
	v_mov_b32_e32 v54, 0
	v_mov_b32_e32 v55, 0
	v_mov_b32_e32 v56, 0
	v_mov_b32_e32 v57, 0
	v_mov_b32_e32 v58, 0
	v_mov_b32_e32 v59, 0
	v_mov_b32_e32 v60, 0
	v_mov_b32_e32 v61, 0
	v_mov_b32_e32 v62, 0
	v_mov_b32_e32 v63, 0
	v_mov_b32_e32 v64, 0
	v_mov_b32_e32 v65, 0
	s_waitcnt vmcnt(16)
	s_barrier
	ds_read_b128 v[148:151], v140 offset:0
	ds_read_b128 v[152:155], v140 offset:2048
	ds_read_b128 v[156:159], v140 offset:4096
	ds_read_b128 v[160:163], v140 offset:6144
	ds_read_b128 v[164:167], v146 offset:0
	ds_read_b128 v[168:171], v146 offset:2048
	ds_read_b128 v[172:175], v146 offset:4096
	ds_read_b128 v[176:179], v146 offset:6144
	ds_read_b128 v[180:183], v143 offset:0
	ds_read_b128 v[184:187], v143 offset:2048
	ds_read_b128 v[188:191], v143 offset:4096
	ds_read_b128 v[192:195], v143 offset:6144
	ds_read_b128 v[228:231], v197 offset:0
	ds_read_b128 v[232:235], v197 offset:2048
	ds_read_b128 v[236:239], v197 offset:4096
	ds_read_b128 v[240:243], v197 offset:6144
	s_waitcnt lgkmcnt(8)
	v_mfma_f32_16x16x32_bf16 v[2:5], v[164:167], v[148:151], v[2:5]
	s_add_u32 m0, s10, 0xc000
	v_mfma_f32_16x16x32_bf16 v[6:9], v[168:171], v[148:151], v[6:9]
	global_load_lds_dwordx4 v132, s[6:7]
	v_mfma_f32_16x16x32_bf16 v[10:13], v[172:175], v[148:151], v[10:13]
	s_add_u32 m0, s10, 0xc400
	v_mfma_f32_16x16x32_bf16 v[14:17], v[176:179], v[148:151], v[14:17]
	global_load_lds_dwordx4 v133, s[6:7]
	v_mfma_f32_16x16x32_bf16 v[18:21], v[164:167], v[152:155], v[18:21]
	s_add_u32 m0, s10, 0xc800
	v_mfma_f32_16x16x32_bf16 v[22:25], v[168:171], v[152:155], v[22:25]
	global_load_lds_dwordx4 v134, s[6:7]
	v_mfma_f32_16x16x32_bf16 v[26:29], v[172:175], v[152:155], v[26:29]
	s_add_u32 m0, s10, 0xcc00
	v_mfma_f32_16x16x32_bf16 v[30:33], v[176:179], v[152:155], v[30:33]
	global_load_lds_dwordx4 v135, s[6:7]
	v_mfma_f32_16x16x32_bf16 v[34:37], v[164:167], v[156:159], v[34:37]
	s_add_u32 m0, s11, 0xc000
	v_mfma_f32_16x16x32_bf16 v[38:41], v[168:171], v[156:159], v[38:41]
	global_load_lds_dwordx4 v136, s[8:9]
	v_mfma_f32_16x16x32_bf16 v[42:45], v[172:175], v[156:159], v[42:45]
	s_add_u32 m0, s11, 0xc400
	v_mfma_f32_16x16x32_bf16 v[46:49], v[176:179], v[156:159], v[46:49]
	global_load_lds_dwordx4 v137, s[8:9]
	v_mfma_f32_16x16x32_bf16 v[50:53], v[164:167], v[160:163], v[50:53]
	v_mfma_f32_16x16x32_bf16 v[54:57], v[168:171], v[160:163], v[54:57]
	v_mfma_f32_16x16x32_bf16 v[58:61], v[172:175], v[160:163], v[58:61]
	v_mfma_f32_16x16x32_bf16 v[62:65], v[176:179], v[160:163], v[62:65]
	s_waitcnt lgkmcnt(0)
	v_mfma_f32_16x16x32_bf16 v[2:5], v[228:231], v[180:183], v[2:5]
	v_mfma_f32_16x16x32_bf16 v[6:9], v[232:235], v[180:183], v[6:9]
	v_mfma_f32_16x16x32_bf16 v[10:13], v[236:239], v[180:183], v[10:13]
	v_mfma_f32_16x16x32_bf16 v[14:17], v[240:243], v[180:183], v[14:17]
	v_mfma_f32_16x16x32_bf16 v[18:21], v[228:231], v[184:187], v[18:21]
	v_mfma_f32_16x16x32_bf16 v[22:25], v[232:235], v[184:187], v[22:25]
	v_mfma_f32_16x16x32_bf16 v[26:29], v[236:239], v[184:187], v[26:29]
	v_mfma_f32_16x16x32_bf16 v[30:33], v[240:243], v[184:187], v[30:33]
	v_mfma_f32_16x16x32_bf16 v[34:37], v[228:231], v[188:191], v[34:37]
	v_mfma_f32_16x16x32_bf16 v[38:41], v[232:235], v[188:191], v[38:41]
	v_mfma_f32_16x16x32_bf16 v[42:45], v[236:239], v[188:191], v[42:45]
	v_mfma_f32_16x16x32_bf16 v[46:49], v[240:243], v[188:191], v[46:49]
	v_mfma_f32_16x16x32_bf16 v[50:53], v[228:231], v[192:195], v[50:53]
	v_mfma_f32_16x16x32_bf16 v[54:57], v[232:235], v[192:195], v[54:57]
	v_mfma_f32_16x16x32_bf16 v[58:61], v[236:239], v[192:195], v[58:61]
	v_mfma_f32_16x16x32_bf16 v[62:65], v[240:243], v[192:195], v[62:65]
	s_add_u32 s6, s6, 0x80
	s_addc_u32 s7, s7, 0
	s_add_u32 s8, s8, 0x80
	s_addc_u32 s9, s9, 0
	global_load_dword v244, v245, s[20:21] offset:0
	s_waitcnt vmcnt(8)
	s_barrier
	ds_read_b128 v[148:151], v138 offset:0
	ds_read_b128 v[152:155], v138 offset:2048
	ds_read_b128 v[156:159], v138 offset:4096
	ds_read_b128 v[160:163], v138 offset:6144
	ds_read_b128 v[164:167], v144 offset:0
	ds_read_b128 v[168:171], v144 offset:2048
	ds_read_b128 v[172:175], v144 offset:4096
	ds_read_b128 v[176:179], v144 offset:6144
	ds_read_b128 v[180:183], v141 offset:0
	ds_read_b128 v[184:187], v141 offset:2048
	ds_read_b128 v[188:191], v141 offset:4096
	ds_read_b128 v[192:195], v141 offset:6144
	ds_read_b128 v[228:231], v147 offset:0
	ds_read_b128 v[232:235], v147 offset:2048
	ds_read_b128 v[236:239], v147 offset:4096
	ds_read_b128 v[240:243], v147 offset:6144
	s_waitcnt lgkmcnt(8)
	v_mfma_f32_16x16x32_bf16 v[2:5], v[164:167], v[148:151], v[2:5]
	s_add_u32 m0, s10, 0x18000
	v_mfma_f32_16x16x32_bf16 v[6:9], v[168:171], v[148:151], v[6:9]
	global_load_lds_dwordx4 v132, s[6:7]
	v_mfma_f32_16x16x32_bf16 v[10:13], v[172:175], v[148:151], v[10:13]
	s_add_u32 m0, s10, 0x18400
	v_mfma_f32_16x16x32_bf16 v[14:17], v[176:179], v[148:151], v[14:17]
	global_load_lds_dwordx4 v133, s[6:7]
	v_mfma_f32_16x16x32_bf16 v[18:21], v[164:167], v[152:155], v[18:21]
	s_add_u32 m0, s10, 0x18800
	v_mfma_f32_16x16x32_bf16 v[22:25], v[168:171], v[152:155], v[22:25]
	global_load_lds_dwordx4 v134, s[6:7]
	v_mfma_f32_16x16x32_bf16 v[26:29], v[172:175], v[152:155], v[26:29]
	s_add_u32 m0, s10, 0x18c00
	v_mfma_f32_16x16x32_bf16 v[30:33], v[176:179], v[152:155], v[30:33]
	global_load_lds_dwordx4 v135, s[6:7]
	v_mfma_f32_16x16x32_bf16 v[34:37], v[164:167], v[156:159], v[34:37]
	s_add_u32 m0, s11, 0x18000
	v_mfma_f32_16x16x32_bf16 v[38:41], v[168:171], v[156:159], v[38:41]
	global_load_lds_dwordx4 v136, s[8:9]
	v_mfma_f32_16x16x32_bf16 v[42:45], v[172:175], v[156:159], v[42:45]
	s_add_u32 m0, s11, 0x18400
	v_mfma_f32_16x16x32_bf16 v[46:49], v[176:179], v[156:159], v[46:49]
	global_load_lds_dwordx4 v137, s[8:9]
	v_mfma_f32_16x16x32_bf16 v[50:53], v[164:167], v[160:163], v[50:53]
	v_mfma_f32_16x16x32_bf16 v[54:57], v[168:171], v[160:163], v[54:57]
	v_mfma_f32_16x16x32_bf16 v[58:61], v[172:175], v[160:163], v[58:61]
	v_mfma_f32_16x16x32_bf16 v[62:65], v[176:179], v[160:163], v[62:65]
	s_waitcnt lgkmcnt(0)
	v_mfma_f32_16x16x32_bf16 v[2:5], v[228:231], v[180:183], v[2:5]
	v_mfma_f32_16x16x32_bf16 v[6:9], v[232:235], v[180:183], v[6:9]
	v_mfma_f32_16x16x32_bf16 v[10:13], v[236:239], v[180:183], v[10:13]
	v_mfma_f32_16x16x32_bf16 v[14:17], v[240:243], v[180:183], v[14:17]
	v_mfma_f32_16x16x32_bf16 v[18:21], v[228:231], v[184:187], v[18:21]
	v_mfma_f32_16x16x32_bf16 v[22:25], v[232:235], v[184:187], v[22:25]
	v_mfma_f32_16x16x32_bf16 v[26:29], v[236:239], v[184:187], v[26:29]
	v_mfma_f32_16x16x32_bf16 v[30:33], v[240:243], v[184:187], v[30:33]
	v_mfma_f32_16x16x32_bf16 v[34:37], v[228:231], v[188:191], v[34:37]
	v_mfma_f32_16x16x32_bf16 v[38:41], v[232:235], v[188:191], v[38:41]
	v_mfma_f32_16x16x32_bf16 v[42:45], v[236:239], v[188:191], v[42:45]
	v_mfma_f32_16x16x32_bf16 v[46:49], v[240:243], v[188:191], v[46:49]
	v_mfma_f32_16x16x32_bf16 v[50:53], v[228:231], v[192:195], v[50:53]
	v_mfma_f32_16x16x32_bf16 v[54:57], v[232:235], v[192:195], v[54:57]
	v_mfma_f32_16x16x32_bf16 v[58:61], v[236:239], v[192:195], v[58:61]
	v_mfma_f32_16x16x32_bf16 v[62:65], v[240:243], v[192:195], v[62:65]
	s_add_u32 s6, s6, 0x80
	s_addc_u32 s7, s7, 0
	s_add_u32 s8, s8, 0x7fe80
	s_addc_u32 s9, s9, 0
	global_load_dword v244, v245, s[20:21] offset:2048
	s_waitcnt vmcnt(8)
	s_barrier
	ds_read_b128 v[148:151], v139 offset:0
	ds_read_b128 v[152:155], v139 offset:2048
	ds_read_b128 v[156:159], v139 offset:4096
	ds_read_b128 v[160:163], v139 offset:6144
	ds_read_b128 v[164:167], v145 offset:0
	ds_read_b128 v[168:171], v145 offset:2048
	ds_read_b128 v[172:175], v145 offset:4096
	ds_read_b128 v[176:179], v145 offset:6144
	ds_read_b128 v[180:183], v142 offset:0
	ds_read_b128 v[184:187], v142 offset:2048
	ds_read_b128 v[188:191], v142 offset:4096
	ds_read_b128 v[192:195], v142 offset:6144
	ds_read_b128 v[228:231], v196 offset:0
	ds_read_b128 v[232:235], v196 offset:2048
	ds_read_b128 v[236:239], v196 offset:4096
	ds_read_b128 v[240:243], v196 offset:6144
	s_waitcnt lgkmcnt(8)
	v_mfma_f32_16x16x32_bf16 v[2:5], v[164:167], v[148:151], v[2:5]
	s_mov_b32 m0, s10
	v_mfma_f32_16x16x32_bf16 v[6:9], v[168:171], v[148:151], v[6:9]
	global_load_lds_dwordx4 v132, s[6:7]
	v_mfma_f32_16x16x32_bf16 v[10:13], v[172:175], v[148:151], v[10:13]
	s_add_u32 m0, s10, 0x400
	v_mfma_f32_16x16x32_bf16 v[14:17], v[176:179], v[148:151], v[14:17]
	global_load_lds_dwordx4 v133, s[6:7]
	v_mfma_f32_16x16x32_bf16 v[18:21], v[164:167], v[152:155], v[18:21]
	s_add_u32 m0, s10, 0x800
	v_mfma_f32_16x16x32_bf16 v[22:25], v[168:171], v[152:155], v[22:25]
	global_load_lds_dwordx4 v134, s[6:7]
	v_mfma_f32_16x16x32_bf16 v[26:29], v[172:175], v[152:155], v[26:29]
	s_add_u32 m0, s10, 0xc00
	v_mfma_f32_16x16x32_bf16 v[30:33], v[176:179], v[152:155], v[30:33]
	global_load_lds_dwordx4 v135, s[6:7]
	v_mfma_f32_16x16x32_bf16 v[34:37], v[164:167], v[156:159], v[34:37]
	s_mov_b32 m0, s11
	v_mfma_f32_16x16x32_bf16 v[38:41], v[168:171], v[156:159], v[38:41]
	global_load_lds_dwordx4 v136, s[8:9]
	v_mfma_f32_16x16x32_bf16 v[42:45], v[172:175], v[156:159], v[42:45]
	s_add_u32 m0, s11, 0x400
	v_mfma_f32_16x16x32_bf16 v[46:49], v[176:179], v[156:159], v[46:49]
	global_load_lds_dwordx4 v137, s[8:9]
	v_mfma_f32_16x16x32_bf16 v[50:53], v[164:167], v[160:163], v[50:53]
	v_mfma_f32_16x16x32_bf16 v[54:57], v[168:171], v[160:163], v[54:57]
	v_mfma_f32_16x16x32_bf16 v[58:61], v[172:175], v[160:163], v[58:61]
	v_mfma_f32_16x16x32_bf16 v[62:65], v[176:179], v[160:163], v[62:65]
	s_waitcnt lgkmcnt(0)
	v_mfma_f32_16x16x32_bf16 v[2:5], v[228:231], v[180:183], v[2:5]
	v_mfma_f32_16x16x32_bf16 v[6:9], v[232:235], v[180:183], v[6:9]
	v_mfma_f32_16x16x32_bf16 v[10:13], v[236:239], v[180:183], v[10:13]
	v_mfma_f32_16x16x32_bf16 v[14:17], v[240:243], v[180:183], v[14:17]
	v_mfma_f32_16x16x32_bf16 v[18:21], v[228:231], v[184:187], v[18:21]
	v_mfma_f32_16x16x32_bf16 v[22:25], v[232:235], v[184:187], v[22:25]
	v_mfma_f32_16x16x32_bf16 v[26:29], v[236:239], v[184:187], v[26:29]
	v_mfma_f32_16x16x32_bf16 v[30:33], v[240:243], v[184:187], v[30:33]
	v_mfma_f32_16x16x32_bf16 v[34:37], v[228:231], v[188:191], v[34:37]
	v_mfma_f32_16x16x32_bf16 v[38:41], v[232:235], v[188:191], v[38:41]
	v_mfma_f32_16x16x32_bf16 v[42:45], v[236:239], v[188:191], v[42:45]
	v_mfma_f32_16x16x32_bf16 v[46:49], v[240:243], v[188:191], v[46:49]
	v_mfma_f32_16x16x32_bf16 v[50:53], v[228:231], v[192:195], v[50:53]
	v_mfma_f32_16x16x32_bf16 v[54:57], v[232:235], v[192:195], v[54:57]
	v_mfma_f32_16x16x32_bf16 v[58:61], v[236:239], v[192:195], v[58:61]
	v_mfma_f32_16x16x32_bf16 v[62:65], v[240:243], v[192:195], v[62:65]
	s_add_u32 s6, s6, 0x80
	s_addc_u32 s7, s7, 0
	s_add_u32 s8, s8, 0x80
	s_addc_u32 s9, s9, 0
	global_load_dword v244, v199, s[20:21] offset:0
	s_waitcnt vmcnt(8)
	s_barrier
	ds_read_b128 v[148:151], v140 offset:0
	ds_read_b128 v[152:155], v140 offset:2048
	ds_read_b128 v[156:159], v140 offset:4096
	ds_read_b128 v[160:163], v140 offset:6144
	ds_read_b128 v[164:167], v146 offset:0
	ds_read_b128 v[168:171], v146 offset:2048
	ds_read_b128 v[172:175], v146 offset:4096
	ds_read_b128 v[176:179], v146 offset:6144
	ds_read_b128 v[180:183], v143 offset:0
	ds_read_b128 v[184:187], v143 offset:2048
	ds_read_b128 v[188:191], v143 offset:4096
	ds_read_b128 v[192:195], v143 offset:6144
	ds_read_b128 v[228:231], v197 offset:0
	ds_read_b128 v[232:235], v197 offset:2048
	ds_read_b128 v[236:239], v197 offset:4096
	ds_read_b128 v[240:243], v197 offset:6144
	s_waitcnt lgkmcnt(8)
	v_mfma_f32_16x16x32_bf16 v[2:5], v[164:167], v[148:151], v[2:5]
	v_mfma_f32_16x16x32_bf16 v[6:9], v[168:171], v[148:151], v[6:9]
	v_mfma_f32_16x16x32_bf16 v[10:13], v[172:175], v[148:151], v[10:13]
	v_mfma_f32_16x16x32_bf16 v[14:17], v[176:179], v[148:151], v[14:17]
	v_mfma_f32_16x16x32_bf16 v[18:21], v[164:167], v[152:155], v[18:21]
	v_mfma_f32_16x16x32_bf16 v[22:25], v[168:171], v[152:155], v[22:25]
	v_mfma_f32_16x16x32_bf16 v[26:29], v[172:175], v[152:155], v[26:29]
	v_mfma_f32_16x16x32_bf16 v[30:33], v[176:179], v[152:155], v[30:33]
	v_mfma_f32_16x16x32_bf16 v[34:37], v[164:167], v[156:159], v[34:37]
	v_mfma_f32_16x16x32_bf16 v[38:41], v[168:171], v[156:159], v[38:41]
	v_mfma_f32_16x16x32_bf16 v[42:45], v[172:175], v[156:159], v[42:45]
	v_mfma_f32_16x16x32_bf16 v[46:49], v[176:179], v[156:159], v[46:49]
	v_mfma_f32_16x16x32_bf16 v[50:53], v[164:167], v[160:163], v[50:53]
	v_mfma_f32_16x16x32_bf16 v[54:57], v[168:171], v[160:163], v[54:57]
	v_mfma_f32_16x16x32_bf16 v[58:61], v[172:175], v[160:163], v[58:61]
	v_mfma_f32_16x16x32_bf16 v[62:65], v[176:179], v[160:163], v[62:65]
	global_load_dwordx4 v[148:151], v202, s[14:15] offset:0
	global_load_dwordx4 v[152:155], v202, s[14:15] offset:1024
	global_load_dwordx4 v[156:159], v202, s[14:15] offset:2048
	global_load_dwordx4 v[160:163], v202, s[14:15] offset:3072
	global_load_dwordx4 v[164:167], v203, s[14:15] offset:0
	global_load_dwordx4 v[168:171], v203, s[14:15] offset:1024
	global_load_dwordx4 v[172:175], v203, s[14:15] offset:2048
	global_load_dwordx4 v[176:179], v203, s[14:15] offset:3072
	s_waitcnt lgkmcnt(0)
	v_mfma_f32_16x16x32_bf16 v[2:5], v[228:231], v[180:183], v[2:5]
	s_add_u32 m0, s10, 0xc000
	v_mfma_f32_16x16x32_bf16 v[6:9], v[232:235], v[180:183], v[6:9]
	global_load_lds_dwordx4 v132, s[6:7]
	v_mfma_f32_16x16x32_bf16 v[10:13], v[236:239], v[180:183], v[10:13]
	s_add_u32 m0, s10, 0xc400
	v_mfma_f32_16x16x32_bf16 v[14:17], v[240:243], v[180:183], v[14:17]
	global_load_lds_dwordx4 v133, s[6:7]
	v_mfma_f32_16x16x32_bf16 v[18:21], v[228:231], v[184:187], v[18:21]
	s_add_u32 m0, s10, 0xc800
	v_mfma_f32_16x16x32_bf16 v[22:25], v[232:235], v[184:187], v[22:25]
	global_load_lds_dwordx4 v134, s[6:7]
	v_mfma_f32_16x16x32_bf16 v[26:29], v[236:239], v[184:187], v[26:29]
	s_add_u32 m0, s10, 0xcc00
	v_mfma_f32_16x16x32_bf16 v[30:33], v[240:243], v[184:187], v[30:33]
	global_load_lds_dwordx4 v135, s[6:7]
	v_mfma_f32_16x16x32_bf16 v[34:37], v[228:231], v[188:191], v[34:37]
	s_add_u32 m0, s11, 0xc000
	v_mfma_f32_16x16x32_bf16 v[38:41], v[232:235], v[188:191], v[38:41]
	global_load_lds_dwordx4 v136, s[8:9]
	v_mfma_f32_16x16x32_bf16 v[42:45], v[236:239], v[188:191], v[42:45]
	s_add_u32 m0, s11, 0xc400
	v_mfma_f32_16x16x32_bf16 v[46:49], v[240:243], v[188:191], v[46:49]
	global_load_lds_dwordx4 v137, s[8:9]
	v_mfma_f32_16x16x32_bf16 v[50:53], v[228:231], v[192:195], v[50:53]
	v_mfma_f32_16x16x32_bf16 v[54:57], v[232:235], v[192:195], v[54:57]
	v_mfma_f32_16x16x32_bf16 v[58:61], v[236:239], v[192:195], v[58:61]
	v_mfma_f32_16x16x32_bf16 v[62:65], v[240:243], v[192:195], v[62:65]
	s_add_u32 s6, s6, 0x80
	s_addc_u32 s7, s7, 0
	s_add_u32 s8, s8, 0x80
	s_addc_u32 s9, s9, 0
	s_add_u32 s14, s14, 0x1000000
	s_addc_u32 s15, s15, 0
	global_load_dword v244, v199, s[20:21] offset:2048
	s_add_u32 s20, s20, 0x1000000
	s_addc_u32 s21, s21, 0
	s_nop 7
	s_nop 3
	s_waitcnt vmcnt(7)
	v_lshlrev_b32_e32 v246, 16, v148
	v_and_b32_e32 v247, 0xffff0000, v148
	v_pk_fma_f32 v[66:67], v[2:3], v[246:247], v[66:67]
	v_lshlrev_b32_e32 v248, 16, v149
	v_and_b32_e32 v249, 0xffff0000, v149
	v_pk_fma_f32 v[68:69], v[4:5], v[248:249], v[68:69]
	v_lshlrev_b32_e32 v246, 16, v150
	v_and_b32_e32 v247, 0xffff0000, v150
	v_pk_fma_f32 v[70:71], v[6:7], v[246:247], v[70:71]
	v_lshlrev_b32_e32 v248, 16, v151
	v_and_b32_e32 v249, 0xffff0000, v151
	v_pk_fma_f32 v[72:73], v[8:9], v[248:249], v[72:73]
	v_lshlrev_b32_e32 v246, 16, v152
	v_and_b32_e32 v247, 0xffff0000, v152
	v_pk_fma_f32 v[74:75], v[10:11], v[246:247], v[74:75]
	v_lshlrev_b32_e32 v248, 16, v153
	v_and_b32_e32 v249, 0xffff0000, v153
	v_pk_fma_f32 v[76:77], v[12:13], v[248:249], v[76:77]
	v_lshlrev_b32_e32 v246, 16, v154
	v_and_b32_e32 v247, 0xffff0000, v154
	v_pk_fma_f32 v[78:79], v[14:15], v[246:247], v[78:79]
	v_lshlrev_b32_e32 v248, 16, v155
	v_and_b32_e32 v249, 0xffff0000, v155
	v_pk_fma_f32 v[80:81], v[16:17], v[248:249], v[80:81]
	v_lshlrev_b32_e32 v246, 16, v156
	v_and_b32_e32 v247, 0xffff0000, v156
	v_pk_fma_f32 v[82:83], v[18:19], v[246:247], v[82:83]
	v_lshlrev_b32_e32 v248, 16, v157
	v_and_b32_e32 v249, 0xffff0000, v157
	v_pk_fma_f32 v[84:85], v[20:21], v[248:249], v[84:85]
	v_lshlrev_b32_e32 v246, 16, v158
	v_and_b32_e32 v247, 0xffff0000, v158
	v_pk_fma_f32 v[86:87], v[22:23], v[246:247], v[86:87]
	v_lshlrev_b32_e32 v248, 16, v159
	v_and_b32_e32 v249, 0xffff0000, v159
	v_pk_fma_f32 v[88:89], v[24:25], v[248:249], v[88:89]
	v_lshlrev_b32_e32 v246, 16, v160
	v_and_b32_e32 v247, 0xffff0000, v160
	v_pk_fma_f32 v[90:91], v[26:27], v[246:247], v[90:91]
	v_lshlrev_b32_e32 v248, 16, v161
	v_and_b32_e32 v249, 0xffff0000, v161
	v_pk_fma_f32 v[92:93], v[28:29], v[248:249], v[92:93]
	v_lshlrev_b32_e32 v246, 16, v162
	v_and_b32_e32 v247, 0xffff0000, v162
	v_pk_fma_f32 v[94:95], v[30:31], v[246:247], v[94:95]
	v_lshlrev_b32_e32 v248, 16, v163
	v_and_b32_e32 v249, 0xffff0000, v163
	v_pk_fma_f32 v[96:97], v[32:33], v[248:249], v[96:97]
	v_lshlrev_b32_e32 v246, 16, v164
	v_and_b32_e32 v247, 0xffff0000, v164
	v_pk_fma_f32 v[98:99], v[34:35], v[246:247], v[98:99]
	v_lshlrev_b32_e32 v248, 16, v165
	v_and_b32_e32 v249, 0xffff0000, v165
	v_pk_fma_f32 v[100:101], v[36:37], v[248:249], v[100:101]
	v_lshlrev_b32_e32 v246, 16, v166
	v_and_b32_e32 v247, 0xffff0000, v166
	v_pk_fma_f32 v[102:103], v[38:39], v[246:247], v[102:103]
	v_lshlrev_b32_e32 v248, 16, v167
	v_and_b32_e32 v249, 0xffff0000, v167
	v_pk_fma_f32 v[104:105], v[40:41], v[248:249], v[104:105]
	v_lshlrev_b32_e32 v246, 16, v168
	v_and_b32_e32 v247, 0xffff0000, v168
	v_pk_fma_f32 v[106:107], v[42:43], v[246:247], v[106:107]
	v_lshlrev_b32_e32 v248, 16, v169
	v_and_b32_e32 v249, 0xffff0000, v169
	v_pk_fma_f32 v[108:109], v[44:45], v[248:249], v[108:109]
	v_lshlrev_b32_e32 v246, 16, v170
	v_and_b32_e32 v247, 0xffff0000, v170
	v_pk_fma_f32 v[110:111], v[46:47], v[246:247], v[110:111]
	v_lshlrev_b32_e32 v248, 16, v171
	v_and_b32_e32 v249, 0xffff0000, v171
	v_pk_fma_f32 v[112:113], v[48:49], v[248:249], v[112:113]
	v_lshlrev_b32_e32 v246, 16, v172
	v_and_b32_e32 v247, 0xffff0000, v172
	v_pk_fma_f32 v[114:115], v[50:51], v[246:247], v[114:115]
	v_lshlrev_b32_e32 v248, 16, v173
	v_and_b32_e32 v249, 0xffff0000, v173
	v_pk_fma_f32 v[116:117], v[52:53], v[248:249], v[116:117]
	v_lshlrev_b32_e32 v246, 16, v174
	v_and_b32_e32 v247, 0xffff0000, v174
	v_pk_fma_f32 v[118:119], v[54:55], v[246:247], v[118:119]
	v_lshlrev_b32_e32 v248, 16, v175
	v_and_b32_e32 v249, 0xffff0000, v175
	v_pk_fma_f32 v[120:121], v[56:57], v[248:249], v[120:121]
	v_lshlrev_b32_e32 v246, 16, v176
	v_and_b32_e32 v247, 0xffff0000, v176
	v_pk_fma_f32 v[122:123], v[58:59], v[246:247], v[122:123]
	v_lshlrev_b32_e32 v248, 16, v177
	v_and_b32_e32 v249, 0xffff0000, v177
	v_pk_fma_f32 v[124:125], v[60:61], v[248:249], v[124:125]
	v_lshlrev_b32_e32 v246, 16, v178
	v_and_b32_e32 v247, 0xffff0000, v178
	v_pk_fma_f32 v[126:127], v[62:63], v[246:247], v[126:127]
	v_lshlrev_b32_e32 v248, 16, v179
	v_and_b32_e32 v249, 0xffff0000, v179
	v_pk_fma_f32 v[128:129], v[64:65], v[248:249], v[128:129]
	v_mov_b32_e32 v2, 0
	v_mov_b32_e32 v3, 0
	v_mov_b32_e32 v4, 0
	v_mov_b32_e32 v5, 0
	v_mov_b32_e32 v6, 0
	v_mov_b32_e32 v7, 0
	v_mov_b32_e32 v8, 0
	v_mov_b32_e32 v9, 0
	v_mov_b32_e32 v10, 0
	v_mov_b32_e32 v11, 0
	v_mov_b32_e32 v12, 0
	v_mov_b32_e32 v13, 0
	v_mov_b32_e32 v14, 0
	v_mov_b32_e32 v15, 0
	v_mov_b32_e32 v16, 0
	v_mov_b32_e32 v17, 0
	v_mov_b32_e32 v18, 0
	v_mov_b32_e32 v19, 0
	v_mov_b32_e32 v20, 0
	v_mov_b32_e32 v21, 0
	v_mov_b32_e32 v22, 0
	v_mov_b32_e32 v23, 0
	v_mov_b32_e32 v24, 0
	v_mov_b32_e32 v25, 0
	v_mov_b32_e32 v26, 0
	v_mov_b32_e32 v27, 0
	v_mov_b32_e32 v28, 0
	v_mov_b32_e32 v29, 0
	v_mov_b32_e32 v30, 0
	v_mov_b32_e32 v31, 0
	v_mov_b32_e32 v32, 0
	v_mov_b32_e32 v33, 0
	v_mov_b32_e32 v34, 0
	v_mov_b32_e32 v35, 0
	v_mov_b32_e32 v36, 0
	v_mov_b32_e32 v37, 0
	v_mov_b32_e32 v38, 0
	v_mov_b32_e32 v39, 0
	v_mov_b32_e32 v40, 0
	v_mov_b32_e32 v41, 0
	v_mov_b32_e32 v42, 0
	v_mov_b32_e32 v43, 0
	v_mov_b32_e32 v44, 0
	v_mov_b32_e32 v45, 0
	v_mov_b32_e32 v46, 0
	v_mov_b32_e32 v47, 0
	v_mov_b32_e32 v48, 0
	v_mov_b32_e32 v49, 0
	v_mov_b32_e32 v50, 0
	v_mov_b32_e32 v51, 0
	v_mov_b32_e32 v52, 0
	v_mov_b32_e32 v53, 0
	v_mov_b32_e32 v54, 0
	v_mov_b32_e32 v55, 0
	v_mov_b32_e32 v56, 0
	v_mov_b32_e32 v57, 0
	v_mov_b32_e32 v58, 0
	v_mov_b32_e32 v59, 0
	v_mov_b32_e32 v60, 0
	v_mov_b32_e32 v61, 0
	v_mov_b32_e32 v62, 0
	v_mov_b32_e32 v63, 0
	v_mov_b32_e32 v64, 0
	v_mov_b32_e32 v65, 0
	s_waitcnt vmcnt(16)
	s_barrier
	ds_read_b128 v[148:151], v138 offset:0
	ds_read_b128 v[152:155], v138 offset:2048
	ds_read_b128 v[156:159], v138 offset:4096
	ds_read_b128 v[160:163], v138 offset:6144
	ds_read_b128 v[164:167], v144 offset:0
	ds_read_b128 v[168:171], v144 offset:2048
	ds_read_b128 v[172:175], v144 offset:4096
	ds_read_b128 v[176:179], v144 offset:6144
	ds_read_b128 v[180:183], v141 offset:0
	ds_read_b128 v[184:187], v141 offset:2048
	ds_read_b128 v[188:191], v141 offset:4096
	ds_read_b128 v[192:195], v141 offset:6144
	ds_read_b128 v[228:231], v147 offset:0
	ds_read_b128 v[232:235], v147 offset:2048
	ds_read_b128 v[236:239], v147 offset:4096
	ds_read_b128 v[240:243], v147 offset:6144
	s_waitcnt lgkmcnt(8)
	v_mfma_f32_16x16x32_bf16 v[2:5], v[164:167], v[148:151], v[2:5]
	s_add_u32 m0, s10, 0x18000
	v_mfma_f32_16x16x32_bf16 v[6:9], v[168:171], v[148:151], v[6:9]
	global_load_lds_dwordx4 v132, s[6:7]
	v_mfma_f32_16x16x32_bf16 v[10:13], v[172:175], v[148:151], v[10:13]
	s_add_u32 m0, s10, 0x18400
	v_mfma_f32_16x16x32_bf16 v[14:17], v[176:179], v[148:151], v[14:17]
	global_load_lds_dwordx4 v133, s[6:7]
	v_mfma_f32_16x16x32_bf16 v[18:21], v[164:167], v[152:155], v[18:21]
	s_add_u32 m0, s10, 0x18800
	v_mfma_f32_16x16x32_bf16 v[22:25], v[168:171], v[152:155], v[22:25]
	global_load_lds_dwordx4 v134, s[6:7]
	v_mfma_f32_16x16x32_bf16 v[26:29], v[172:175], v[152:155], v[26:29]
	s_add_u32 m0, s10, 0x18c00
	v_mfma_f32_16x16x32_bf16 v[30:33], v[176:179], v[152:155], v[30:33]
	global_load_lds_dwordx4 v135, s[6:7]
	v_mfma_f32_16x16x32_bf16 v[34:37], v[164:167], v[156:159], v[34:37]
	s_add_u32 m0, s11, 0x18000
	v_mfma_f32_16x16x32_bf16 v[38:41], v[168:171], v[156:159], v[38:41]
	global_load_lds_dwordx4 v136, s[8:9]
	v_mfma_f32_16x16x32_bf16 v[42:45], v[172:175], v[156:159], v[42:45]
	s_add_u32 m0, s11, 0x18400
	v_mfma_f32_16x16x32_bf16 v[46:49], v[176:179], v[156:159], v[46:49]
	global_load_lds_dwordx4 v137, s[8:9]
	v_mfma_f32_16x16x32_bf16 v[50:53], v[164:167], v[160:163], v[50:53]
	v_mfma_f32_16x16x32_bf16 v[54:57], v[168:171], v[160:163], v[54:57]
	v_mfma_f32_16x16x32_bf16 v[58:61], v[172:175], v[160:163], v[58:61]
	v_mfma_f32_16x16x32_bf16 v[62:65], v[176:179], v[160:163], v[62:65]
	s_waitcnt lgkmcnt(0)
	v_mfma_f32_16x16x32_bf16 v[2:5], v[228:231], v[180:183], v[2:5]
	v_mfma_f32_16x16x32_bf16 v[6:9], v[232:235], v[180:183], v[6:9]
	v_mfma_f32_16x16x32_bf16 v[10:13], v[236:239], v[180:183], v[10:13]
	v_mfma_f32_16x16x32_bf16 v[14:17], v[240:243], v[180:183], v[14:17]
	v_mfma_f32_16x16x32_bf16 v[18:21], v[228:231], v[184:187], v[18:21]
	v_mfma_f32_16x16x32_bf16 v[22:25], v[232:235], v[184:187], v[22:25]
	v_mfma_f32_16x16x32_bf16 v[26:29], v[236:239], v[184:187], v[26:29]
	v_mfma_f32_16x16x32_bf16 v[30:33], v[240:243], v[184:187], v[30:33]
	v_mfma_f32_16x16x32_bf16 v[34:37], v[228:231], v[188:191], v[34:37]
	v_mfma_f32_16x16x32_bf16 v[38:41], v[232:235], v[188:191], v[38:41]
	v_mfma_f32_16x16x32_bf16 v[42:45], v[236:239], v[188:191], v[42:45]
	v_mfma_f32_16x16x32_bf16 v[46:49], v[240:243], v[188:191], v[46:49]
	v_mfma_f32_16x16x32_bf16 v[50:53], v[228:231], v[192:195], v[50:53]
	v_mfma_f32_16x16x32_bf16 v[54:57], v[232:235], v[192:195], v[54:57]
	v_mfma_f32_16x16x32_bf16 v[58:61], v[236:239], v[192:195], v[58:61]
	v_mfma_f32_16x16x32_bf16 v[62:65], v[240:243], v[192:195], v[62:65]
	s_add_u32 s6, s6, 0x80
	s_addc_u32 s7, s7, 0
	s_add_u32 s8, s8, 0x80
	s_addc_u32 s9, s9, 0
	s_waitcnt vmcnt(7)
	s_barrier
	ds_read_b128 v[148:151], v139 offset:0
	ds_read_b128 v[152:155], v139 offset:2048
	ds_read_b128 v[156:159], v139 offset:4096
	ds_read_b128 v[160:163], v139 offset:6144
	ds_read_b128 v[164:167], v145 offset:0
	ds_read_b128 v[168:171], v145 offset:2048
	ds_read_b128 v[172:175], v145 offset:4096
	ds_read_b128 v[176:179], v145 offset:6144
	ds_read_b128 v[180:183], v142 offset:0
	ds_read_b128 v[184:187], v142 offset:2048
	ds_read_b128 v[188:191], v142 offset:4096
	ds_read_b128 v[192:195], v142 offset:6144
	ds_read_b128 v[228:231], v196 offset:0
	ds_read_b128 v[232:235], v196 offset:2048
	ds_read_b128 v[236:239], v196 offset:4096
	ds_read_b128 v[240:243], v196 offset:6144
	s_waitcnt lgkmcnt(8)
	v_mfma_f32_16x16x32_bf16 v[2:5], v[164:167], v[148:151], v[2:5]
	s_mov_b32 m0, s10
	v_mfma_f32_16x16x32_bf16 v[6:9], v[168:171], v[148:151], v[6:9]
	global_load_lds_dwordx4 v132, s[6:7]
	v_mfma_f32_16x16x32_bf16 v[10:13], v[172:175], v[148:151], v[10:13]
	s_add_u32 m0, s10, 0x400
	v_mfma_f32_16x16x32_bf16 v[14:17], v[176:179], v[148:151], v[14:17]
	global_load_lds_dwordx4 v133, s[6:7]
	v_mfma_f32_16x16x32_bf16 v[18:21], v[164:167], v[152:155], v[18:21]
	s_add_u32 m0, s10, 0x800
	v_mfma_f32_16x16x32_bf16 v[22:25], v[168:171], v[152:155], v[22:25]
	global_load_lds_dwordx4 v134, s[6:7]
	v_mfma_f32_16x16x32_bf16 v[26:29], v[172:175], v[152:155], v[26:29]
	s_add_u32 m0, s10, 0xc00
	v_mfma_f32_16x16x32_bf16 v[30:33], v[176:179], v[152:155], v[30:33]
	global_load_lds_dwordx4 v135, s[6:7]
	v_mfma_f32_16x16x32_bf16 v[34:37], v[164:167], v[156:159], v[34:37]
	s_mov_b32 m0, s11
	v_mfma_f32_16x16x32_bf16 v[38:41], v[168:171], v[156:159], v[38:41]
	global_load_lds_dwordx4 v136, s[8:9]
	v_mfma_f32_16x16x32_bf16 v[42:45], v[172:175], v[156:159], v[42:45]
	s_add_u32 m0, s11, 0x400
	v_mfma_f32_16x16x32_bf16 v[46:49], v[176:179], v[156:159], v[46:49]
	global_load_lds_dwordx4 v137, s[8:9]
	v_mfma_f32_16x16x32_bf16 v[50:53], v[164:167], v[160:163], v[50:53]
	v_mfma_f32_16x16x32_bf16 v[54:57], v[168:171], v[160:163], v[54:57]
	v_mfma_f32_16x16x32_bf16 v[58:61], v[172:175], v[160:163], v[58:61]
	v_mfma_f32_16x16x32_bf16 v[62:65], v[176:179], v[160:163], v[62:65]
	s_waitcnt lgkmcnt(0)
	v_mfma_f32_16x16x32_bf16 v[2:5], v[228:231], v[180:183], v[2:5]
	v_mfma_f32_16x16x32_bf16 v[6:9], v[232:235], v[180:183], v[6:9]
	v_mfma_f32_16x16x32_bf16 v[10:13], v[236:239], v[180:183], v[10:13]
	v_mfma_f32_16x16x32_bf16 v[14:17], v[240:243], v[180:183], v[14:17]
	v_mfma_f32_16x16x32_bf16 v[18:21], v[228:231], v[184:187], v[18:21]
	v_mfma_f32_16x16x32_bf16 v[22:25], v[232:235], v[184:187], v[22:25]
	v_mfma_f32_16x16x32_bf16 v[26:29], v[236:239], v[184:187], v[26:29]
	v_mfma_f32_16x16x32_bf16 v[30:33], v[240:243], v[184:187], v[30:33]
	v_mfma_f32_16x16x32_bf16 v[34:37], v[228:231], v[188:191], v[34:37]
	v_mfma_f32_16x16x32_bf16 v[38:41], v[232:235], v[188:191], v[38:41]
	v_mfma_f32_16x16x32_bf16 v[42:45], v[236:239], v[188:191], v[42:45]
	v_mfma_f32_16x16x32_bf16 v[46:49], v[240:243], v[188:191], v[46:49]
	v_mfma_f32_16x16x32_bf16 v[50:53], v[228:231], v[192:195], v[50:53]
	v_mfma_f32_16x16x32_bf16 v[54:57], v[232:235], v[192:195], v[54:57]
	v_mfma_f32_16x16x32_bf16 v[58:61], v[236:239], v[192:195], v[58:61]
	v_mfma_f32_16x16x32_bf16 v[62:65], v[240:243], v[192:195], v[62:65]
	s_add_u32 s6, s6, 0x80
	s_addc_u32 s7, s7, 0
	s_add_u32 s8, s8, 0x7fe80
	s_addc_u32 s9, s9, 0
	s_waitcnt vmcnt(6)
	s_barrier
	ds_read_b128 v[148:151], v140 offset:0
	ds_read_b128 v[152:155], v140 offset:2048
	ds_read_b128 v[156:159], v140 offset:4096
	ds_read_b128 v[160:163], v140 offset:6144
	ds_read_b128 v[164:167], v146 offset:0
	ds_read_b128 v[168:171], v146 offset:2048
	ds_read_b128 v[172:175], v146 offset:4096
	ds_read_b128 v[176:179], v146 offset:6144
	ds_read_b128 v[180:183], v143 offset:0
	ds_read_b128 v[184:187], v143 offset:2048
	ds_read_b128 v[188:191], v143 offset:4096
	ds_read_b128 v[192:195], v143 offset:6144
	ds_read_b128 v[228:231], v197 offset:0
	ds_read_b128 v[232:235], v197 offset:2048
	ds_read_b128 v[236:239], v197 offset:4096
	ds_read_b128 v[240:243], v197 offset:6144
	s_waitcnt lgkmcnt(8)
	v_mfma_f32_16x16x32_bf16 v[2:5], v[164:167], v[148:151], v[2:5]
	v_mfma_f32_16x16x32_bf16 v[6:9], v[168:171], v[148:151], v[6:9]
	v_mfma_f32_16x16x32_bf16 v[10:13], v[172:175], v[148:151], v[10:13]
	v_mfma_f32_16x16x32_bf16 v[14:17], v[176:179], v[148:151], v[14:17]
	v_mfma_f32_16x16x32_bf16 v[18:21], v[164:167], v[152:155], v[18:21]
	v_mfma_f32_16x16x32_bf16 v[22:25], v[168:171], v[152:155], v[22:25]
	v_mfma_f32_16x16x32_bf16 v[26:29], v[172:175], v[152:155], v[26:29]
	v_mfma_f32_16x16x32_bf16 v[30:33], v[176:179], v[152:155], v[30:33]
	v_mfma_f32_16x16x32_bf16 v[34:37], v[164:167], v[156:159], v[34:37]
	v_mfma_f32_16x16x32_bf16 v[38:41], v[168:171], v[156:159], v[38:41]
	v_mfma_f32_16x16x32_bf16 v[42:45], v[172:175], v[156:159], v[42:45]
	v_mfma_f32_16x16x32_bf16 v[46:49], v[176:179], v[156:159], v[46:49]
	v_mfma_f32_16x16x32_bf16 v[50:53], v[164:167], v[160:163], v[50:53]
	v_mfma_f32_16x16x32_bf16 v[54:57], v[168:171], v[160:163], v[54:57]
	v_mfma_f32_16x16x32_bf16 v[58:61], v[172:175], v[160:163], v[58:61]
	v_mfma_f32_16x16x32_bf16 v[62:65], v[176:179], v[160:163], v[62:65]
	s_waitcnt lgkmcnt(0)
	v_mfma_f32_16x16x32_bf16 v[2:5], v[228:231], v[180:183], v[2:5]
	v_mfma_f32_16x16x32_bf16 v[6:9], v[232:235], v[180:183], v[6:9]
	v_mfma_f32_16x16x32_bf16 v[10:13], v[236:239], v[180:183], v[10:13]
	v_mfma_f32_16x16x32_bf16 v[14:17], v[240:243], v[180:183], v[14:17]
	v_mfma_f32_16x16x32_bf16 v[18:21], v[228:231], v[184:187], v[18:21]
	v_mfma_f32_16x16x32_bf16 v[22:25], v[232:235], v[184:187], v[22:25]
	v_mfma_f32_16x16x32_bf16 v[26:29], v[236:239], v[184:187], v[26:29]
	v_mfma_f32_16x16x32_bf16 v[30:33], v[240:243], v[184:187], v[30:33]
	v_mfma_f32_16x16x32_bf16 v[34:37], v[228:231], v[188:191], v[34:37]
	v_mfma_f32_16x16x32_bf16 v[38:41], v[232:235], v[188:191], v[38:41]
	v_mfma_f32_16x16x32_bf16 v[42:45], v[236:239], v[188:191], v[42:45]
	v_mfma_f32_16x16x32_bf16 v[46:49], v[240:243], v[188:191], v[46:49]
	v_mfma_f32_16x16x32_bf16 v[50:53], v[228:231], v[192:195], v[50:53]
	v_mfma_f32_16x16x32_bf16 v[54:57], v[232:235], v[192:195], v[54:57]
	v_mfma_f32_16x16x32_bf16 v[58:61], v[236:239], v[192:195], v[58:61]
	v_mfma_f32_16x16x32_bf16 v[62:65], v[240:243], v[192:195], v[62:65]
	s_waitcnt vmcnt(0)
	s_barrier
	ds_read_b128 v[148:151], v138 offset:0
	ds_read_b128 v[152:155], v138 offset:2048
	ds_read_b128 v[156:159], v138 offset:4096
	ds_read_b128 v[160:163], v138 offset:6144
	ds_read_b128 v[164:167], v144 offset:0
	ds_read_b128 v[168:171], v144 offset:2048
	ds_read_b128 v[172:175], v144 offset:4096
	ds_read_b128 v[176:179], v144 offset:6144
	ds_read_b128 v[180:183], v141 offset:0
	ds_read_b128 v[184:187], v141 offset:2048
	ds_read_b128 v[188:191], v141 offset:4096
	ds_read_b128 v[192:195], v141 offset:6144
	ds_read_b128 v[228:231], v147 offset:0
	ds_read_b128 v[232:235], v147 offset:2048
	ds_read_b128 v[236:239], v147 offset:4096
	ds_read_b128 v[240:243], v147 offset:6144
	s_waitcnt lgkmcnt(8)
	v_mfma_f32_16x16x32_bf16 v[2:5], v[164:167], v[148:151], v[2:5]
	v_mfma_f32_16x16x32_bf16 v[6:9], v[168:171], v[148:151], v[6:9]
	v_mfma_f32_16x16x32_bf16 v[10:13], v[172:175], v[148:151], v[10:13]
	v_mfma_f32_16x16x32_bf16 v[14:17], v[176:179], v[148:151], v[14:17]
	v_mfma_f32_16x16x32_bf16 v[18:21], v[164:167], v[152:155], v[18:21]
	v_mfma_f32_16x16x32_bf16 v[22:25], v[168:171], v[152:155], v[22:25]
	v_mfma_f32_16x16x32_bf16 v[26:29], v[172:175], v[152:155], v[26:29]
	v_mfma_f32_16x16x32_bf16 v[30:33], v[176:179], v[152:155], v[30:33]
	v_mfma_f32_16x16x32_bf16 v[34:37], v[164:167], v[156:159], v[34:37]
	v_mfma_f32_16x16x32_bf16 v[38:41], v[168:171], v[156:159], v[38:41]
	v_mfma_f32_16x16x32_bf16 v[42:45], v[172:175], v[156:159], v[42:45]
	v_mfma_f32_16x16x32_bf16 v[46:49], v[176:179], v[156:159], v[46:49]
	v_mfma_f32_16x16x32_bf16 v[50:53], v[164:167], v[160:163], v[50:53]
	v_mfma_f32_16x16x32_bf16 v[54:57], v[168:171], v[160:163], v[54:57]
	v_mfma_f32_16x16x32_bf16 v[58:61], v[172:175], v[160:163], v[58:61]
	v_mfma_f32_16x16x32_bf16 v[62:65], v[176:179], v[160:163], v[62:65]
	global_load_dwordx4 v[148:151], v202, s[14:15] offset:0
	global_load_dwordx4 v[152:155], v202, s[14:15] offset:1024
	global_load_dwordx4 v[156:159], v202, s[14:15] offset:2048
	global_load_dwordx4 v[160:163], v202, s[14:15] offset:3072
	global_load_dwordx4 v[164:167], v203, s[14:15] offset:0
	global_load_dwordx4 v[168:171], v203, s[14:15] offset:1024
	global_load_dwordx4 v[172:175], v203, s[14:15] offset:2048
	global_load_dwordx4 v[176:179], v203, s[14:15] offset:3072
	s_waitcnt lgkmcnt(0)
	v_mfma_f32_16x16x32_bf16 v[2:5], v[228:231], v[180:183], v[2:5]
	v_mfma_f32_16x16x32_bf16 v[6:9], v[232:235], v[180:183], v[6:9]
	v_mfma_f32_16x16x32_bf16 v[10:13], v[236:239], v[180:183], v[10:13]
	v_mfma_f32_16x16x32_bf16 v[14:17], v[240:243], v[180:183], v[14:17]
	v_mfma_f32_16x16x32_bf16 v[18:21], v[228:231], v[184:187], v[18:21]
	v_mfma_f32_16x16x32_bf16 v[22:25], v[232:235], v[184:187], v[22:25]
	v_mfma_f32_16x16x32_bf16 v[26:29], v[236:239], v[184:187], v[26:29]
	v_mfma_f32_16x16x32_bf16 v[30:33], v[240:243], v[184:187], v[30:33]
	v_mfma_f32_16x16x32_bf16 v[34:37], v[228:231], v[188:191], v[34:37]
	v_mfma_f32_16x16x32_bf16 v[38:41], v[232:235], v[188:191], v[38:41]
	v_mfma_f32_16x16x32_bf16 v[42:45], v[236:239], v[188:191], v[42:45]
	v_mfma_f32_16x16x32_bf16 v[46:49], v[240:243], v[188:191], v[46:49]
	v_mfma_f32_16x16x32_bf16 v[50:53], v[228:231], v[192:195], v[50:53]
	v_mfma_f32_16x16x32_bf16 v[54:57], v[232:235], v[192:195], v[54:57]
	v_mfma_f32_16x16x32_bf16 v[58:61], v[236:239], v[192:195], v[58:61]
	v_mfma_f32_16x16x32_bf16 v[62:65], v[240:243], v[192:195], v[62:65]
	s_add_u32 s14, s14, 0x1000000
	s_addc_u32 s15, s15, 0
	s_nop 7
	s_nop 3
	s_waitcnt vmcnt(0)
	v_lshlrev_b32_e32 v246, 16, v148
	v_and_b32_e32 v247, 0xffff0000, v148
	v_pk_fma_f32 v[66:67], v[2:3], v[246:247], v[66:67]
	v_lshlrev_b32_e32 v248, 16, v149
	v_and_b32_e32 v249, 0xffff0000, v149
	v_pk_fma_f32 v[68:69], v[4:5], v[248:249], v[68:69]
	v_lshlrev_b32_e32 v246, 16, v150
	v_and_b32_e32 v247, 0xffff0000, v150
	v_pk_fma_f32 v[70:71], v[6:7], v[246:247], v[70:71]
	v_lshlrev_b32_e32 v248, 16, v151
	v_and_b32_e32 v249, 0xffff0000, v151
	v_pk_fma_f32 v[72:73], v[8:9], v[248:249], v[72:73]
	v_lshlrev_b32_e32 v246, 16, v152
	v_and_b32_e32 v247, 0xffff0000, v152
	v_pk_fma_f32 v[74:75], v[10:11], v[246:247], v[74:75]
	v_lshlrev_b32_e32 v248, 16, v153
	v_and_b32_e32 v249, 0xffff0000, v153
	v_pk_fma_f32 v[76:77], v[12:13], v[248:249], v[76:77]
	v_lshlrev_b32_e32 v246, 16, v154
	v_and_b32_e32 v247, 0xffff0000, v154
	v_pk_fma_f32 v[78:79], v[14:15], v[246:247], v[78:79]
	v_lshlrev_b32_e32 v248, 16, v155
	v_and_b32_e32 v249, 0xffff0000, v155
	v_pk_fma_f32 v[80:81], v[16:17], v[248:249], v[80:81]
	v_lshlrev_b32_e32 v246, 16, v156
	v_and_b32_e32 v247, 0xffff0000, v156
	v_pk_fma_f32 v[82:83], v[18:19], v[246:247], v[82:83]
	v_lshlrev_b32_e32 v248, 16, v157
	v_and_b32_e32 v249, 0xffff0000, v157
	v_pk_fma_f32 v[84:85], v[20:21], v[248:249], v[84:85]
	v_lshlrev_b32_e32 v246, 16, v158
	v_and_b32_e32 v247, 0xffff0000, v158
	v_pk_fma_f32 v[86:87], v[22:23], v[246:247], v[86:87]
	v_lshlrev_b32_e32 v248, 16, v159
	v_and_b32_e32 v249, 0xffff0000, v159
	v_pk_fma_f32 v[88:89], v[24:25], v[248:249], v[88:89]
	v_lshlrev_b32_e32 v246, 16, v160
	v_and_b32_e32 v247, 0xffff0000, v160
	v_pk_fma_f32 v[90:91], v[26:27], v[246:247], v[90:91]
	v_lshlrev_b32_e32 v248, 16, v161
	v_and_b32_e32 v249, 0xffff0000, v161
	v_pk_fma_f32 v[92:93], v[28:29], v[248:249], v[92:93]
	v_lshlrev_b32_e32 v246, 16, v162
	v_and_b32_e32 v247, 0xffff0000, v162
	v_pk_fma_f32 v[94:95], v[30:31], v[246:247], v[94:95]
	v_lshlrev_b32_e32 v248, 16, v163
	v_and_b32_e32 v249, 0xffff0000, v163
	v_pk_fma_f32 v[96:97], v[32:33], v[248:249], v[96:97]
	v_lshlrev_b32_e32 v246, 16, v164
	v_and_b32_e32 v247, 0xffff0000, v164
	v_pk_fma_f32 v[98:99], v[34:35], v[246:247], v[98:99]
	v_lshlrev_b32_e32 v248, 16, v165
	v_and_b32_e32 v249, 0xffff0000, v165
	v_pk_fma_f32 v[100:101], v[36:37], v[248:249], v[100:101]
	v_lshlrev_b32_e32 v246, 16, v166
	v_and_b32_e32 v247, 0xffff0000, v166
	v_pk_fma_f32 v[102:103], v[38:39], v[246:247], v[102:103]
	v_lshlrev_b32_e32 v248, 16, v167
	v_and_b32_e32 v249, 0xffff0000, v167
	v_pk_fma_f32 v[104:105], v[40:41], v[248:249], v[104:105]
	v_lshlrev_b32_e32 v246, 16, v168
	v_and_b32_e32 v247, 0xffff0000, v168
	v_pk_fma_f32 v[106:107], v[42:43], v[246:247], v[106:107]
	v_lshlrev_b32_e32 v248, 16, v169
	v_and_b32_e32 v249, 0xffff0000, v169
	v_pk_fma_f32 v[108:109], v[44:45], v[248:249], v[108:109]
	v_lshlrev_b32_e32 v246, 16, v170
	v_and_b32_e32 v247, 0xffff0000, v170
	v_pk_fma_f32 v[110:111], v[46:47], v[246:247], v[110:111]
	v_lshlrev_b32_e32 v248, 16, v171
	v_and_b32_e32 v249, 0xffff0000, v171
	v_pk_fma_f32 v[112:113], v[48:49], v[248:249], v[112:113]
	v_lshlrev_b32_e32 v246, 16, v172
	v_and_b32_e32 v247, 0xffff0000, v172
	v_pk_fma_f32 v[114:115], v[50:51], v[246:247], v[114:115]
	v_lshlrev_b32_e32 v248, 16, v173
	v_and_b32_e32 v249, 0xffff0000, v173
	v_pk_fma_f32 v[116:117], v[52:53], v[248:249], v[116:117]
	v_lshlrev_b32_e32 v246, 16, v174
	v_and_b32_e32 v247, 0xffff0000, v174
	v_pk_fma_f32 v[118:119], v[54:55], v[246:247], v[118:119]
	v_lshlrev_b32_e32 v248, 16, v175
	v_and_b32_e32 v249, 0xffff0000, v175
	v_pk_fma_f32 v[120:121], v[56:57], v[248:249], v[120:121]
	v_lshlrev_b32_e32 v246, 16, v176
	v_and_b32_e32 v247, 0xffff0000, v176
	v_pk_fma_f32 v[122:123], v[58:59], v[246:247], v[122:123]
	v_lshlrev_b32_e32 v248, 16, v177
	v_and_b32_e32 v249, 0xffff0000, v177
	v_pk_fma_f32 v[124:125], v[60:61], v[248:249], v[124:125]
	v_lshlrev_b32_e32 v246, 16, v178
	v_and_b32_e32 v247, 0xffff0000, v178
	v_pk_fma_f32 v[126:127], v[62:63], v[246:247], v[126:127]
	v_lshlrev_b32_e32 v248, 16, v179
	v_and_b32_e32 v249, 0xffff0000, v179
	v_pk_fma_f32 v[128:129], v[64:65], v[248:249], v[128:129]
	v_readlane_b32 s20, v253, 28
	v_readlane_b32 s21, v253, 29
	s_and_b32 s0, s13, 31
	s_lshr_b32 s1, s13, 5
	s_lshl_b32 s22, s0, 19
	s_lshl_b32 s1, s1, 8
	s_add_u32 s22, s22, s1
	s_add_u32 s20, s20, s22
	s_addc_u32 s21, s21, 0
	v_mov_b32_e32 v246, v204
	v_cvt_pk_bf16_f32 v66, v66, v67
	v_cvt_pk_bf16_f32 v67, v68, v69
	global_store_dwordx2 v246, v[66:67], s[20:21] offset:0 sc1
	v_cvt_pk_bf16_f32 v70, v70, v71
	v_cvt_pk_bf16_f32 v71, v72, v73
	global_store_dwordx2 v246, v[70:71], s[20:21] offset:32 sc1
	v_cvt_pk_bf16_f32 v74, v74, v75
	v_cvt_pk_bf16_f32 v75, v76, v77
	global_store_dwordx2 v246, v[74:75], s[20:21] offset:64 sc1
	v_cvt_pk_bf16_f32 v78, v78, v79
	v_cvt_pk_bf16_f32 v79, v80, v81
	global_store_dwordx2 v246, v[78:79], s[20:21] offset:96 sc1
	v_add_u32_e32 v246, 0x8000, v246
	v_cvt_pk_bf16_f32 v82, v82, v83
	v_cvt_pk_bf16_f32 v83, v84, v85
	global_store_dwordx2 v246, v[82:83], s[20:21] offset:0 sc1
	v_cvt_pk_bf16_f32 v86, v86, v87
	v_cvt_pk_bf16_f32 v87, v88, v89
	global_store_dwordx2 v246, v[86:87], s[20:21] offset:32 sc1
	v_cvt_pk_bf16_f32 v90, v90, v91
	v_cvt_pk_bf16_f32 v91, v92, v93
	global_store_dwordx2 v246, v[90:91], s[20:21] offset:64 sc1
	v_cvt_pk_bf16_f32 v94, v94, v95
	v_cvt_pk_bf16_f32 v95, v96, v97
	global_store_dwordx2 v246, v[94:95], s[20:21] offset:96 sc1
	v_add_u32_e32 v246, 0x8000, v246
	v_cvt_pk_bf16_f32 v98, v98, v99
	v_cvt_pk_bf16_f32 v99, v100, v101
	global_store_dwordx2 v246, v[98:99], s[20:21] offset:0 sc1
	v_cvt_pk_bf16_f32 v102, v102, v103
	v_cvt_pk_bf16_f32 v103, v104, v105
	global_store_dwordx2 v246, v[102:103], s[20:21] offset:32 sc1
	v_cvt_pk_bf16_f32 v106, v106, v107
	v_cvt_pk_bf16_f32 v107, v108, v109
	global_store_dwordx2 v246, v[106:107], s[20:21] offset:64 sc1
	v_cvt_pk_bf16_f32 v110, v110, v111
	v_cvt_pk_bf16_f32 v111, v112, v113
	global_store_dwordx2 v246, v[110:111], s[20:21] offset:96 sc1
	v_add_u32_e32 v246, 0x8000, v246
	v_cvt_pk_bf16_f32 v114, v114, v115
	v_cvt_pk_bf16_f32 v115, v116, v117
	global_store_dwordx2 v246, v[114:115], s[20:21] offset:0 sc1
	v_cvt_pk_bf16_f32 v118, v118, v119
	v_cvt_pk_bf16_f32 v119, v120, v121
	global_store_dwordx2 v246, v[118:119], s[20:21] offset:32 sc1
	v_cvt_pk_bf16_f32 v122, v122, v123
	v_cvt_pk_bf16_f32 v123, v124, v125
	global_store_dwordx2 v246, v[122:123], s[20:21] offset:64 sc1
	v_cvt_pk_bf16_f32 v126, v126, v127
	v_cvt_pk_bf16_f32 v127, v128, v129
	global_store_dwordx2 v246, v[126:127], s[20:21] offset:96 sc1
	s_waitcnt vmcnt(0)
	s_barrier
	v_cmp_eq_u32_e32 vcc, 0, v0
	s_and_saveexec_b64 s[20:21], vcc
	s_cbranch_execz .Lc2_noarr
	s_lshl_b32 s1, s80, 5
	s_add_u32 s1, s1, 64
	s_add_u32 s1, s1, s0
	s_lshl_b32 s1, s1, 8
	v_readlane_b32 s0, v254, 4
	v_readlane_b32 s22, v254, 5
	s_nop 3
	s_add_u32 s0, s0, s1
	s_addc_u32 s1, s22, 0
	v_mov_b32_e32 v247, 1
	s_nop 3
	global_atomic_add v131, v247, s[0:1]
